# on top of v15: GEMM K-loops, each group of 8 independent MFMAs reordered so the src0 fragment is reused by 4 consecutive MFMAs
# baseline (speedup 1.0000x reference)
.LBB0_274:
	ds_read_b128 v[146:149], v153
	ds_read_b128 v[156:159], v153 offset:1024
	ds_read_b128 v[160:163], v153 offset:2048
	ds_read_b128 v[164:167], v153 offset:3072
	ds_read_b128 v[168:171], v154
	ds_read_b128 v[172:175], v154 offset:1024
	ds_read_b128 v[176:179], v154 offset:2048
	ds_read_b128 v[180:183], v154 offset:3072
	s_add_u32 s34, s76, 0xfff80080
	s_addc_u32 s35, s77, -1
	s_cmp_eq_u32 s85, 28
	s_cselect_b32 s79, s0, s35
	s_cselect_b32 s78, s1, s34
	s_cselect_b32 s35, s67, s84
	s_cselect_b32 s34, s69, s83
	v_lshl_add_u64 v[218:219], s[76:77], 0, v[138:139]
	s_add_i32 m0, s54, 0xc000
	ds_read_b128 v[184:187], v155
	ds_read_b128 v[188:191], v155 offset:1024
	ds_read_b128 v[192:195], v155 offset:2048
	ds_read_b128 v[196:199], v155 offset:3072
	ds_read_b128 v[200:203], v155 offset:4096
	ds_read_b128 v[204:207], v155 offset:5120
	ds_read_b128 v[208:211], v155 offset:6144
	ds_read_b128 v[212:215], v155 offset:7168
	global_load_lds_dwordx4 v[218:219], off
	v_lshl_add_u64 v[218:219], s[76:77], 0, v[140:141]
	s_add_i32 m0, s54, 0xe000
	s_nop 0
	global_load_lds_dwordx4 v[218:219], off
	s_waitcnt vmcnt(8)
	s_waitcnt lgkmcnt(0)
	s_barrier
	s_setprio 1
	s_waitcnt lgkmcnt(0)
	v_mfma_f32_16x16x32_bf16 v[126:129], v[146:149], v[184:187], v[126:129]
	v_mfma_f32_16x16x32_bf16 v[110:113], v[146:149], v[192:195], v[110:113]
	v_mfma_f32_16x16x32_bf16 v[94:97], v[146:149], v[200:203], v[94:97]
	v_mfma_f32_16x16x32_bf16 v[78:81], v[146:149], v[208:211], v[78:81]
	v_mfma_f32_16x16x32_bf16 v[118:121], v[160:163], v[184:187], v[118:121]
	v_mfma_f32_16x16x32_bf16 v[102:105], v[160:163], v[192:195], v[102:105]
	v_mfma_f32_16x16x32_bf16 v[86:89], v[160:163], v[200:203], v[86:89]
	v_mfma_f32_16x16x32_bf16 v[70:73], v[160:163], v[208:211], v[70:73]
	v_mfma_f32_16x16x32_bf16 v[126:129], v[156:159], v[188:191], v[126:129]
	v_mfma_f32_16x16x32_bf16 v[110:113], v[156:159], v[196:199], v[110:113]
	v_mfma_f32_16x16x32_bf16 v[94:97], v[156:159], v[204:207], v[94:97]
	v_mfma_f32_16x16x32_bf16 v[78:81], v[156:159], v[212:215], v[78:81]
	v_mfma_f32_16x16x32_bf16 v[118:121], v[164:167], v[188:191], v[118:121]
	v_mfma_f32_16x16x32_bf16 v[102:105], v[164:167], v[196:199], v[102:105]
	v_mfma_f32_16x16x32_bf16 v[86:89], v[164:167], v[204:207], v[86:89]
	v_mfma_f32_16x16x32_bf16 v[70:73], v[164:167], v[212:215], v[70:73]
	s_setprio 0
	s_setprio 1
	v_mfma_f32_16x16x32_bf16 v[122:125], v[168:171], v[184:187], v[122:125]
	v_mfma_f32_16x16x32_bf16 v[106:109], v[168:171], v[192:195], v[106:109]
	v_mfma_f32_16x16x32_bf16 v[90:93], v[168:171], v[200:203], v[90:93]
	v_mfma_f32_16x16x32_bf16 v[74:77], v[168:171], v[208:211], v[74:77]
	v_mfma_f32_16x16x32_bf16 v[114:117], v[176:179], v[184:187], v[114:117]
	v_mfma_f32_16x16x32_bf16 v[98:101], v[176:179], v[192:195], v[98:101]
	v_mfma_f32_16x16x32_bf16 v[82:85], v[176:179], v[200:203], v[82:85]
	v_mfma_f32_16x16x32_bf16 v[66:69], v[176:179], v[208:211], v[66:69]
	v_mfma_f32_16x16x32_bf16 v[122:125], v[172:175], v[188:191], v[122:125]
	v_mfma_f32_16x16x32_bf16 v[106:109], v[172:175], v[196:199], v[106:109]
	v_mfma_f32_16x16x32_bf16 v[90:93], v[172:175], v[204:207], v[90:93]
	v_mfma_f32_16x16x32_bf16 v[74:77], v[172:175], v[212:215], v[74:77]
	v_mfma_f32_16x16x32_bf16 v[114:117], v[180:183], v[188:191], v[114:117]
	v_mfma_f32_16x16x32_bf16 v[98:101], v[180:183], v[196:199], v[98:101]
	v_mfma_f32_16x16x32_bf16 v[82:85], v[180:183], v[204:207], v[82:85]
	v_mfma_f32_16x16x32_bf16 v[66:69], v[180:183], v[212:215], v[66:69]
	s_setprio 0
	s_barrier
	s_add_i32 s62, s75, s33
	v_lshl_add_u64 v[218:219], s[34:35], 0, v[134:135]
	s_mov_b32 m0, s62
	ds_read_b128 v[184:187], v155 offset:16384
	ds_read_b128 v[188:191], v155 offset:17408
	ds_read_b128 v[192:195], v155 offset:18432
	ds_read_b128 v[196:199], v155 offset:19456
	ds_read_b128 v[200:203], v155 offset:20480
	ds_read_b128 v[204:207], v155 offset:21504
	ds_read_b128 v[208:211], v155 offset:22528
	ds_read_b128 v[212:215], v155 offset:23552
	global_load_lds_dwordx4 v[218:219], off
	s_add_i32 m0, s62, 0x2000
	s_add_u32 s62, s34, 0x80000
	v_lshl_add_u64 v[220:221], s[34:35], 0, v[130:131]
	s_addc_u32 s63, s35, 0
	s_add_i32 s86, s80, s33
	global_load_lds_dwordx4 v[220:221], off
	v_lshl_add_u64 v[222:223], s[62:63], 0, v[134:135]
	s_mov_b32 m0, s86
	v_lshl_add_u64 v[224:225], s[78:79], 0, v[132:133]
	global_load_lds_dwordx4 v[222:223], off
	v_lshl_add_u64 v[222:223], s[62:63], 0, v[130:131]
	s_add_i32 m0, s86, 0x2000
	s_nop 0
	global_load_lds_dwordx4 v[222:223], off
	v_lshl_add_u64 v[222:223], s[78:79], 0, v[136:137]
	s_mov_b32 m0, s54
	s_nop 0
	global_load_lds_dwordx4 v[222:223], off
	s_mov_b32 m0, s55
	s_nop 0
	global_load_lds_dwordx4 v[224:225], off
	s_waitcnt vmcnt(8)
	s_waitcnt lgkmcnt(0)
	s_barrier
	s_setprio 1
	s_waitcnt lgkmcnt(0)
	v_mfma_f32_16x16x32_bf16 v[62:65], v[146:149], v[184:187], v[62:65]
	v_mfma_f32_16x16x32_bf16 v[46:49], v[146:149], v[192:195], v[46:49]
	v_mfma_f32_16x16x32_bf16 v[30:33], v[146:149], v[200:203], v[30:33]
	v_mfma_f32_16x16x32_bf16 v[14:17], v[146:149], v[208:211], v[14:17]
	v_mfma_f32_16x16x32_bf16 v[54:57], v[160:163], v[184:187], v[54:57]
	v_mfma_f32_16x16x32_bf16 v[38:41], v[160:163], v[192:195], v[38:41]
	v_mfma_f32_16x16x32_bf16 v[22:25], v[160:163], v[200:203], v[22:25]
	v_mfma_f32_16x16x32_bf16 v[6:9], v[160:163], v[208:211], v[6:9]
	v_mfma_f32_16x16x32_bf16 v[62:65], v[156:159], v[188:191], v[62:65]
	v_mfma_f32_16x16x32_bf16 v[46:49], v[156:159], v[196:199], v[46:49]
	v_mfma_f32_16x16x32_bf16 v[30:33], v[156:159], v[204:207], v[30:33]
	v_mfma_f32_16x16x32_bf16 v[14:17], v[156:159], v[212:215], v[14:17]
	v_mfma_f32_16x16x32_bf16 v[54:57], v[164:167], v[188:191], v[54:57]
	v_mfma_f32_16x16x32_bf16 v[38:41], v[164:167], v[196:199], v[38:41]
	v_mfma_f32_16x16x32_bf16 v[22:25], v[164:167], v[204:207], v[22:25]
	v_mfma_f32_16x16x32_bf16 v[6:9], v[164:167], v[212:215], v[6:9]
	s_setprio 0
	s_setprio 1
	v_mfma_f32_16x16x32_bf16 v[58:61], v[168:171], v[184:187], v[58:61]
	v_mfma_f32_16x16x32_bf16 v[42:45], v[168:171], v[192:195], v[42:45]
	v_mfma_f32_16x16x32_bf16 v[26:29], v[168:171], v[200:203], v[26:29]
	v_mfma_f32_16x16x32_bf16 v[10:13], v[168:171], v[208:211], v[10:13]
	v_mfma_f32_16x16x32_bf16 v[50:53], v[176:179], v[184:187], v[50:53]
	v_mfma_f32_16x16x32_bf16 v[34:37], v[176:179], v[192:195], v[34:37]
	v_mfma_f32_16x16x32_bf16 v[18:21], v[176:179], v[200:203], v[18:21]
	v_mfma_f32_16x16x32_bf16 v[2:5], v[176:179], v[208:211], v[2:5]
	v_mfma_f32_16x16x32_bf16 v[58:61], v[172:175], v[188:191], v[58:61]
	v_mfma_f32_16x16x32_bf16 v[42:45], v[172:175], v[196:199], v[42:45]
	v_mfma_f32_16x16x32_bf16 v[26:29], v[172:175], v[204:207], v[26:29]
	v_mfma_f32_16x16x32_bf16 v[10:13], v[172:175], v[212:215], v[10:13]
	v_mfma_f32_16x16x32_bf16 v[50:53], v[180:183], v[188:191], v[50:53]
	v_mfma_f32_16x16x32_bf16 v[34:37], v[180:183], v[196:199], v[34:37]
	v_mfma_f32_16x16x32_bf16 v[18:21], v[180:183], v[204:207], v[18:21]
	v_mfma_f32_16x16x32_bf16 v[2:5], v[180:183], v[212:215], v[2:5]
	s_setprio 0
	s_barrier
	s_add_i32 s86, 0, 0x18000
	s_add_i32 s87, 0, 0x1c000
	v_add_u32_e32 v164, s86, v151
	v_add_u32_e32 v180, s87, v151
	ds_read_b128 v[146:149], v164
	ds_read_b128 v[156:159], v164 offset:1024
	ds_read_b128 v[160:163], v164 offset:2048
	ds_read_b128 v[164:167], v164 offset:3072
	ds_read_b128 v[168:171], v180
	ds_read_b128 v[172:175], v180 offset:1024
	ds_read_b128 v[176:179], v180 offset:2048
	ds_read_b128 v[180:183], v180 offset:3072
	s_add_u32 s62, s78, 0x80000
	s_addc_u32 s63, s79, 0
	s_mov_b32 m0, s56
	v_lshl_add_u64 v[226:227], s[62:63], 0, v[136:137]
	ds_read_b128 v[184:187], v155 offset:32768
	ds_read_b128 v[188:191], v155 offset:33792
	ds_read_b128 v[192:195], v155 offset:34816
	ds_read_b128 v[196:199], v155 offset:35840
	ds_read_b128 v[200:203], v155 offset:36864
	ds_read_b128 v[204:207], v155 offset:37888
	ds_read_b128 v[208:211], v155 offset:38912
	ds_read_b128 v[212:215], v155 offset:39936
	global_load_lds_dwordx4 v[226:227], off
	v_lshl_add_u64 v[226:227], s[62:63], 0, v[132:133]
	s_mov_b32 m0, s57
	s_nop 0
	global_load_lds_dwordx4 v[226:227], off
	s_waitcnt vmcnt(8)
	s_waitcnt lgkmcnt(0)
	s_barrier
	s_setprio 1
	s_waitcnt lgkmcnt(0)
	v_mfma_f32_16x16x32_bf16 v[126:129], v[146:149], v[184:187], v[126:129]
	v_mfma_f32_16x16x32_bf16 v[110:113], v[146:149], v[192:195], v[110:113]
	v_mfma_f32_16x16x32_bf16 v[94:97], v[146:149], v[200:203], v[94:97]
	v_mfma_f32_16x16x32_bf16 v[78:81], v[146:149], v[208:211], v[78:81]
	v_mfma_f32_16x16x32_bf16 v[118:121], v[160:163], v[184:187], v[118:121]
	v_mfma_f32_16x16x32_bf16 v[102:105], v[160:163], v[192:195], v[102:105]
	v_mfma_f32_16x16x32_bf16 v[86:89], v[160:163], v[200:203], v[86:89]
	v_mfma_f32_16x16x32_bf16 v[70:73], v[160:163], v[208:211], v[70:73]
	v_mfma_f32_16x16x32_bf16 v[126:129], v[156:159], v[188:191], v[126:129]
	v_mfma_f32_16x16x32_bf16 v[110:113], v[156:159], v[196:199], v[110:113]
	v_mfma_f32_16x16x32_bf16 v[94:97], v[156:159], v[204:207], v[94:97]
	v_mfma_f32_16x16x32_bf16 v[78:81], v[156:159], v[212:215], v[78:81]
	v_mfma_f32_16x16x32_bf16 v[118:121], v[164:167], v[188:191], v[118:121]
	v_mfma_f32_16x16x32_bf16 v[102:105], v[164:167], v[196:199], v[102:105]
	v_mfma_f32_16x16x32_bf16 v[86:89], v[164:167], v[204:207], v[86:89]
	v_mfma_f32_16x16x32_bf16 v[70:73], v[164:167], v[212:215], v[70:73]
	s_setprio 0
	s_setprio 1
	v_mfma_f32_16x16x32_bf16 v[122:125], v[168:171], v[184:187], v[122:125]
	v_mfma_f32_16x16x32_bf16 v[106:109], v[168:171], v[192:195], v[106:109]
	v_mfma_f32_16x16x32_bf16 v[90:93], v[168:171], v[200:203], v[90:93]
	v_mfma_f32_16x16x32_bf16 v[74:77], v[168:171], v[208:211], v[74:77]
	v_mfma_f32_16x16x32_bf16 v[114:117], v[176:179], v[184:187], v[114:117]
	v_mfma_f32_16x16x32_bf16 v[98:101], v[176:179], v[192:195], v[98:101]
	v_mfma_f32_16x16x32_bf16 v[82:85], v[176:179], v[200:203], v[82:85]
	v_mfma_f32_16x16x32_bf16 v[66:69], v[176:179], v[208:211], v[66:69]
	v_mfma_f32_16x16x32_bf16 v[122:125], v[172:175], v[188:191], v[122:125]
	v_mfma_f32_16x16x32_bf16 v[106:109], v[172:175], v[196:199], v[106:109]
	v_mfma_f32_16x16x32_bf16 v[90:93], v[172:175], v[204:207], v[90:93]
	v_mfma_f32_16x16x32_bf16 v[74:77], v[172:175], v[212:215], v[74:77]
	v_mfma_f32_16x16x32_bf16 v[114:117], v[180:183], v[188:191], v[114:117]
	v_mfma_f32_16x16x32_bf16 v[98:101], v[180:183], v[196:199], v[98:101]
	v_mfma_f32_16x16x32_bf16 v[82:85], v[180:183], v[204:207], v[82:85]
	v_mfma_f32_16x16x32_bf16 v[66:69], v[180:183], v[212:215], v[66:69]
	s_setprio 0
	s_barrier
	s_add_i32 s62, s86, s33
	v_lshl_add_u64 v[218:219], v[218:219], 0, s[8:9]
	s_mov_b32 m0, s62
	ds_read_b128 v[184:187], v155 offset:49152
	ds_read_b128 v[188:191], v155 offset:50176
	ds_read_b128 v[192:195], v155 offset:51200
	ds_read_b128 v[196:199], v155 offset:52224
	ds_read_b128 v[200:203], v155 offset:53248
	ds_read_b128 v[204:207], v155 offset:54272
	ds_read_b128 v[208:211], v155 offset:55296
	ds_read_b128 v[212:215], v155 offset:56320
	global_load_lds_dwordx4 v[218:219], off
	s_add_i32 m0, s62, 0x2000
	s_add_u32 s34, s34, 0x80080
	v_lshl_add_u64 v[218:219], v[220:221], 0, s[8:9]
	s_addc_u32 s35, s35, 0
	s_add_i32 s62, s87, s33
	global_load_lds_dwordx4 v[218:219], off
	v_lshl_add_u64 v[218:219], s[34:35], 0, v[134:135]
	s_mov_b32 m0, s62
	s_nop 0
	global_load_lds_dwordx4 v[218:219], off
	v_lshl_add_u64 v[218:219], s[34:35], 0, v[130:131]
	s_add_i32 m0, s62, 0x2000
	s_nop 0
	global_load_lds_dwordx4 v[218:219], off
	v_lshl_add_u64 v[218:219], v[222:223], 0, s[8:9]
	s_mov_b32 m0, s59
	s_nop 0
	global_load_lds_dwordx4 v[218:219], off
	v_lshl_add_u64 v[218:219], v[224:225], 0, s[8:9]
	s_mov_b32 m0, s60
	s_nop 0
	global_load_lds_dwordx4 v[218:219], off
	s_waitcnt vmcnt(8)
	s_waitcnt lgkmcnt(0)
	s_barrier
	s_setprio 1
	s_waitcnt lgkmcnt(0)
	v_mfma_f32_16x16x32_bf16 v[62:65], v[146:149], v[184:187], v[62:65]
	v_mfma_f32_16x16x32_bf16 v[46:49], v[146:149], v[192:195], v[46:49]
	v_mfma_f32_16x16x32_bf16 v[30:33], v[146:149], v[200:203], v[30:33]
	v_mfma_f32_16x16x32_bf16 v[14:17], v[146:149], v[208:211], v[14:17]
	v_mfma_f32_16x16x32_bf16 v[54:57], v[160:163], v[184:187], v[54:57]
	v_mfma_f32_16x16x32_bf16 v[38:41], v[160:163], v[192:195], v[38:41]
	v_mfma_f32_16x16x32_bf16 v[22:25], v[160:163], v[200:203], v[22:25]
	v_mfma_f32_16x16x32_bf16 v[6:9], v[160:163], v[208:211], v[6:9]
	v_mfma_f32_16x16x32_bf16 v[62:65], v[156:159], v[188:191], v[62:65]
	v_mfma_f32_16x16x32_bf16 v[46:49], v[156:159], v[196:199], v[46:49]
	v_mfma_f32_16x16x32_bf16 v[30:33], v[156:159], v[204:207], v[30:33]
	v_mfma_f32_16x16x32_bf16 v[14:17], v[156:159], v[212:215], v[14:17]
	v_mfma_f32_16x16x32_bf16 v[54:57], v[164:167], v[188:191], v[54:57]
	v_mfma_f32_16x16x32_bf16 v[38:41], v[164:167], v[196:199], v[38:41]
	v_mfma_f32_16x16x32_bf16 v[22:25], v[164:167], v[204:207], v[22:25]
	v_mfma_f32_16x16x32_bf16 v[6:9], v[164:167], v[212:215], v[6:9]
	s_setprio 0
	s_setprio 1
	v_mfma_f32_16x16x32_bf16 v[58:61], v[168:171], v[184:187], v[58:61]
	v_mfma_f32_16x16x32_bf16 v[42:45], v[168:171], v[192:195], v[42:45]
	v_mfma_f32_16x16x32_bf16 v[26:29], v[168:171], v[200:203], v[26:29]
	v_mfma_f32_16x16x32_bf16 v[10:13], v[168:171], v[208:211], v[10:13]
	v_mfma_f32_16x16x32_bf16 v[50:53], v[176:179], v[184:187], v[50:53]
	v_mfma_f32_16x16x32_bf16 v[34:37], v[176:179], v[192:195], v[34:37]
	v_mfma_f32_16x16x32_bf16 v[18:21], v[176:179], v[200:203], v[18:21]
	v_mfma_f32_16x16x32_bf16 v[2:5], v[176:179], v[208:211], v[2:5]
	v_mfma_f32_16x16x32_bf16 v[58:61], v[172:175], v[188:191], v[58:61]
	v_mfma_f32_16x16x32_bf16 v[42:45], v[172:175], v[196:199], v[42:45]
	v_mfma_f32_16x16x32_bf16 v[26:29], v[172:175], v[204:207], v[26:29]
	v_mfma_f32_16x16x32_bf16 v[10:13], v[172:175], v[212:215], v[10:13]
	v_mfma_f32_16x16x32_bf16 v[50:53], v[180:183], v[188:191], v[50:53]
	v_mfma_f32_16x16x32_bf16 v[34:37], v[180:183], v[196:199], v[34:37]
	v_mfma_f32_16x16x32_bf16 v[18:21], v[180:183], v[204:207], v[18:21]
	v_mfma_f32_16x16x32_bf16 v[2:5], v[180:183], v[212:215], v[2:5]
	s_setprio 0
	s_barrier
	s_add_i32 s85, s85, 2
	s_add_u32 s76, s76, 0x100
	s_addc_u32 s77, s77, 0
	s_add_u32 s83, s83, 0x100
	s_addc_u32 s84, s84, 0
	s_cmp_gt_u32 s85, 29
	s_cbranch_scc0 .LBB0_274
	s_and_b64 vcc, exec, s[64:65]
	s_cbranch_vccz .LBB0_277
	s_barrier

.LBB0_387:
	ds_read_b128 v[146:149], v154
	ds_read_b128 v[158:161], v154 offset:1024
	ds_read_b128 v[162:165], v154 offset:2048
	ds_read_b128 v[166:169], v154 offset:3072
	ds_read_b128 v[170:173], v155
	ds_read_b128 v[174:177], v155 offset:1024
	ds_read_b128 v[178:181], v155 offset:2048
	ds_read_b128 v[182:185], v155 offset:3072
	s_add_u32 s34, s72, 0xffea0080
	s_addc_u32 s35, s73, -1
	s_cmpk_eq_i32 s81, 0x54
	s_cselect_b32 s75, s5, s35
	s_cselect_b32 s74, s4, s34
	s_cselect_b32 s35, s71, s1
	s_cselect_b32 s34, s70, s0
	v_lshl_add_u64 v[150:151], s[72:73], 0, v[138:139]
	s_add_i32 m0, s53, 0xc000
	ds_read_b128 v[186:189], v156
	ds_read_b128 v[190:193], v156 offset:1024
	ds_read_b128 v[194:197], v156 offset:2048
	ds_read_b128 v[198:201], v156 offset:3072
	ds_read_b128 v[202:205], v156 offset:4096
	ds_read_b128 v[206:209], v156 offset:5120
	ds_read_b128 v[210:213], v156 offset:6144
	ds_read_b128 v[218:221], v156 offset:7168
	global_load_lds_dwordx4 v[150:151], off
	v_lshl_add_u64 v[150:151], s[72:73], 0, v[140:141]
	s_add_i32 m0, s53, 0xe000
	s_nop 0
	global_load_lds_dwordx4 v[150:151], off
	s_waitcnt vmcnt(8)
	s_waitcnt lgkmcnt(0)
	s_barrier
	s_setprio 1
	s_waitcnt lgkmcnt(0)
	v_mfma_f32_16x16x32_bf16 v[126:129], v[146:149], v[186:189], v[126:129]
	v_mfma_f32_16x16x32_bf16 v[118:121], v[146:149], v[194:197], v[118:121]
	v_mfma_f32_16x16x32_bf16 v[94:97], v[146:149], v[202:205], v[94:97]
	v_mfma_f32_16x16x32_bf16 v[86:89], v[146:149], v[210:213], v[86:89]
	v_mfma_f32_16x16x32_bf16 v[122:125], v[162:165], v[186:189], v[122:125]
	v_mfma_f32_16x16x32_bf16 v[114:117], v[162:165], v[194:197], v[114:117]
	v_mfma_f32_16x16x32_bf16 v[90:93], v[162:165], v[202:205], v[90:93]
	v_mfma_f32_16x16x32_bf16 v[82:85], v[162:165], v[210:213], v[82:85]
	v_mfma_f32_16x16x32_bf16 v[126:129], v[158:161], v[190:193], v[126:129]
	v_mfma_f32_16x16x32_bf16 v[118:121], v[158:161], v[198:201], v[118:121]
	v_mfma_f32_16x16x32_bf16 v[94:97], v[158:161], v[206:209], v[94:97]
	v_mfma_f32_16x16x32_bf16 v[86:89], v[158:161], v[218:221], v[86:89]
	v_mfma_f32_16x16x32_bf16 v[122:125], v[166:169], v[190:193], v[122:125]
	v_mfma_f32_16x16x32_bf16 v[114:117], v[166:169], v[198:201], v[114:117]
	v_mfma_f32_16x16x32_bf16 v[90:93], v[166:169], v[206:209], v[90:93]
	v_mfma_f32_16x16x32_bf16 v[82:85], v[166:169], v[218:221], v[82:85]
	s_setprio 0
	s_setprio 1
	v_mfma_f32_16x16x32_bf16 v[110:113], v[170:173], v[186:189], v[110:113]
	v_mfma_f32_16x16x32_bf16 v[102:105], v[170:173], v[194:197], v[102:105]
	v_mfma_f32_16x16x32_bf16 v[78:81], v[170:173], v[202:205], v[78:81]
	v_mfma_f32_16x16x32_bf16 v[70:73], v[170:173], v[210:213], v[70:73]
	v_mfma_f32_16x16x32_bf16 v[106:109], v[178:181], v[186:189], v[106:109]
	v_mfma_f32_16x16x32_bf16 v[98:101], v[178:181], v[194:197], v[98:101]
	v_mfma_f32_16x16x32_bf16 v[74:77], v[178:181], v[202:205], v[74:77]
	v_mfma_f32_16x16x32_bf16 v[66:69], v[178:181], v[210:213], v[66:69]
	v_mfma_f32_16x16x32_bf16 v[110:113], v[174:177], v[190:193], v[110:113]
	v_mfma_f32_16x16x32_bf16 v[102:105], v[174:177], v[198:201], v[102:105]
	v_mfma_f32_16x16x32_bf16 v[78:81], v[174:177], v[206:209], v[78:81]
	v_mfma_f32_16x16x32_bf16 v[70:73], v[174:177], v[218:221], v[70:73]
	v_mfma_f32_16x16x32_bf16 v[106:109], v[182:185], v[190:193], v[106:109]
	v_mfma_f32_16x16x32_bf16 v[98:101], v[182:185], v[198:201], v[98:101]
	v_mfma_f32_16x16x32_bf16 v[74:77], v[182:185], v[206:209], v[74:77]
	v_mfma_f32_16x16x32_bf16 v[66:69], v[182:185], v[218:221], v[66:69]
	s_setprio 0
	s_barrier
	s_add_i32 s62, s61, s52
	v_lshl_add_u64 v[150:151], s[34:35], 0, v[132:133]
	s_mov_b32 m0, s62
	ds_read_b128 v[186:189], v156 offset:16384
	ds_read_b128 v[190:193], v156 offset:17408
	ds_read_b128 v[194:197], v156 offset:18432
	ds_read_b128 v[198:201], v156 offset:19456
	ds_read_b128 v[202:205], v156 offset:20480
	ds_read_b128 v[206:209], v156 offset:21504
	ds_read_b128 v[210:213], v156 offset:22528
	ds_read_b128 v[218:221], v156 offset:23552
	global_load_lds_dwordx4 v[150:151], off
	s_add_i32 m0, s62, 0x2000
	s_add_u32 s62, s34, 0x160000
	v_lshl_add_u64 v[214:215], s[34:35], 0, v[136:137]
	s_addc_u32 s63, s35, 0
	s_add_i32 s82, s76, s52
	global_load_lds_dwordx4 v[214:215], off
	v_lshl_add_u64 v[222:223], s[62:63], 0, v[132:133]
	s_mov_b32 m0, s82
	v_lshl_add_u64 v[224:225], s[74:75], 0, v[134:135]
	global_load_lds_dwordx4 v[222:223], off
	v_lshl_add_u64 v[222:223], s[62:63], 0, v[136:137]
	s_add_i32 m0, s82, 0x2000
	s_nop 0
	global_load_lds_dwordx4 v[222:223], off
	v_lshl_add_u64 v[222:223], s[74:75], 0, v[130:131]
	s_mov_b32 m0, s53
	s_nop 0
	global_load_lds_dwordx4 v[222:223], off
	s_mov_b32 m0, s54
	s_nop 0
	global_load_lds_dwordx4 v[224:225], off
	s_waitcnt vmcnt(8)
	s_waitcnt lgkmcnt(0)
	s_barrier
	s_setprio 1
	s_waitcnt lgkmcnt(0)
	v_mfma_f32_16x16x32_bf16 v[62:65], v[146:149], v[186:189], v[62:65]
	v_mfma_f32_16x16x32_bf16 v[54:57], v[146:149], v[194:197], v[54:57]
	v_mfma_f32_16x16x32_bf16 v[30:33], v[146:149], v[202:205], v[30:33]
	v_mfma_f32_16x16x32_bf16 v[22:25], v[146:149], v[210:213], v[22:25]
	v_mfma_f32_16x16x32_bf16 v[58:61], v[162:165], v[186:189], v[58:61]
	v_mfma_f32_16x16x32_bf16 v[50:53], v[162:165], v[194:197], v[50:53]
	v_mfma_f32_16x16x32_bf16 v[26:29], v[162:165], v[202:205], v[26:29]
	v_mfma_f32_16x16x32_bf16 v[18:21], v[162:165], v[210:213], v[18:21]
	v_mfma_f32_16x16x32_bf16 v[62:65], v[158:161], v[190:193], v[62:65]
	v_mfma_f32_16x16x32_bf16 v[54:57], v[158:161], v[198:201], v[54:57]
	v_mfma_f32_16x16x32_bf16 v[30:33], v[158:161], v[206:209], v[30:33]
	v_mfma_f32_16x16x32_bf16 v[22:25], v[158:161], v[218:221], v[22:25]
	v_mfma_f32_16x16x32_bf16 v[58:61], v[166:169], v[190:193], v[58:61]
	v_mfma_f32_16x16x32_bf16 v[50:53], v[166:169], v[198:201], v[50:53]
	v_mfma_f32_16x16x32_bf16 v[26:29], v[166:169], v[206:209], v[26:29]
	v_mfma_f32_16x16x32_bf16 v[18:21], v[166:169], v[218:221], v[18:21]
	s_setprio 0
	s_setprio 1
	v_mfma_f32_16x16x32_bf16 v[46:49], v[170:173], v[186:189], v[46:49]
	v_mfma_f32_16x16x32_bf16 v[38:41], v[170:173], v[194:197], v[38:41]
	v_mfma_f32_16x16x32_bf16 v[14:17], v[170:173], v[202:205], v[14:17]
	v_mfma_f32_16x16x32_bf16 v[6:9], v[170:173], v[210:213], v[6:9]
	v_mfma_f32_16x16x32_bf16 v[42:45], v[178:181], v[186:189], v[42:45]
	v_mfma_f32_16x16x32_bf16 v[34:37], v[178:181], v[194:197], v[34:37]
	v_mfma_f32_16x16x32_bf16 v[10:13], v[178:181], v[202:205], v[10:13]
	v_mfma_f32_16x16x32_bf16 v[2:5], v[178:181], v[210:213], v[2:5]
	v_mfma_f32_16x16x32_bf16 v[46:49], v[174:177], v[190:193], v[46:49]
	v_mfma_f32_16x16x32_bf16 v[38:41], v[174:177], v[198:201], v[38:41]
	v_mfma_f32_16x16x32_bf16 v[14:17], v[174:177], v[206:209], v[14:17]
	v_mfma_f32_16x16x32_bf16 v[6:9], v[174:177], v[218:221], v[6:9]
	v_mfma_f32_16x16x32_bf16 v[42:45], v[182:185], v[190:193], v[42:45]
	v_mfma_f32_16x16x32_bf16 v[34:37], v[182:185], v[198:201], v[34:37]
	v_mfma_f32_16x16x32_bf16 v[10:13], v[182:185], v[206:209], v[10:13]
	v_mfma_f32_16x16x32_bf16 v[2:5], v[182:185], v[218:221], v[2:5]
	s_setprio 0
	s_barrier
	s_add_i32 s82, 0, 0x18000
	v_add_u32_e32 v157, s82, v152
	s_add_i32 s83, 0, 0x1c000
	ds_read_b128 v[146:149], v157
	ds_read_b128 v[158:161], v157 offset:1024
	ds_read_b128 v[162:165], v157 offset:2048
	ds_read_b128 v[166:169], v157 offset:3072
	v_add_u32_e32 v157, s83, v152
	ds_read_b128 v[170:173], v157
	ds_read_b128 v[174:177], v157 offset:1024
	ds_read_b128 v[178:181], v157 offset:2048
	ds_read_b128 v[182:185], v157 offset:3072
	s_add_u32 s62, s74, 0x160000
	s_addc_u32 s63, s75, 0
	s_mov_b32 m0, s55
	v_lshl_add_u64 v[226:227], s[62:63], 0, v[130:131]
	ds_read_b128 v[186:189], v156 offset:32768
	ds_read_b128 v[190:193], v156 offset:33792
	ds_read_b128 v[194:197], v156 offset:34816
	ds_read_b128 v[198:201], v156 offset:35840
	ds_read_b128 v[202:205], v156 offset:36864
	ds_read_b128 v[206:209], v156 offset:37888
	ds_read_b128 v[210:213], v156 offset:38912
	ds_read_b128 v[218:221], v156 offset:39936
	global_load_lds_dwordx4 v[226:227], off
	v_lshl_add_u64 v[226:227], s[62:63], 0, v[134:135]
	s_mov_b32 m0, s56
	s_nop 0
	global_load_lds_dwordx4 v[226:227], off
	s_waitcnt vmcnt(8)
	s_waitcnt lgkmcnt(0)
	s_barrier
	s_setprio 1
	s_waitcnt lgkmcnt(0)
	v_mfma_f32_16x16x32_bf16 v[126:129], v[146:149], v[186:189], v[126:129]
	v_mfma_f32_16x16x32_bf16 v[118:121], v[146:149], v[194:197], v[118:121]
	v_mfma_f32_16x16x32_bf16 v[94:97], v[146:149], v[202:205], v[94:97]
	v_mfma_f32_16x16x32_bf16 v[86:89], v[146:149], v[210:213], v[86:89]
	v_mfma_f32_16x16x32_bf16 v[122:125], v[162:165], v[186:189], v[122:125]
	v_mfma_f32_16x16x32_bf16 v[114:117], v[162:165], v[194:197], v[114:117]
	v_mfma_f32_16x16x32_bf16 v[90:93], v[162:165], v[202:205], v[90:93]
	v_mfma_f32_16x16x32_bf16 v[82:85], v[162:165], v[210:213], v[82:85]
	v_mfma_f32_16x16x32_bf16 v[126:129], v[158:161], v[190:193], v[126:129]
	v_mfma_f32_16x16x32_bf16 v[118:121], v[158:161], v[198:201], v[118:121]
	v_mfma_f32_16x16x32_bf16 v[94:97], v[158:161], v[206:209], v[94:97]
	v_mfma_f32_16x16x32_bf16 v[86:89], v[158:161], v[218:221], v[86:89]
	v_mfma_f32_16x16x32_bf16 v[122:125], v[166:169], v[190:193], v[122:125]
	v_mfma_f32_16x16x32_bf16 v[114:117], v[166:169], v[198:201], v[114:117]
	v_mfma_f32_16x16x32_bf16 v[90:93], v[166:169], v[206:209], v[90:93]
	v_mfma_f32_16x16x32_bf16 v[82:85], v[166:169], v[218:221], v[82:85]
	s_setprio 0
	s_setprio 1
	v_mfma_f32_16x16x32_bf16 v[110:113], v[170:173], v[186:189], v[110:113]
	v_mfma_f32_16x16x32_bf16 v[102:105], v[170:173], v[194:197], v[102:105]
	v_mfma_f32_16x16x32_bf16 v[78:81], v[170:173], v[202:205], v[78:81]
	v_mfma_f32_16x16x32_bf16 v[70:73], v[170:173], v[210:213], v[70:73]
	v_mfma_f32_16x16x32_bf16 v[106:109], v[178:181], v[186:189], v[106:109]
	v_mfma_f32_16x16x32_bf16 v[98:101], v[178:181], v[194:197], v[98:101]
	v_mfma_f32_16x16x32_bf16 v[74:77], v[178:181], v[202:205], v[74:77]
	v_mfma_f32_16x16x32_bf16 v[66:69], v[178:181], v[210:213], v[66:69]
	v_mfma_f32_16x16x32_bf16 v[110:113], v[174:177], v[190:193], v[110:113]
	v_mfma_f32_16x16x32_bf16 v[102:105], v[174:177], v[198:201], v[102:105]
	v_mfma_f32_16x16x32_bf16 v[78:81], v[174:177], v[206:209], v[78:81]
	v_mfma_f32_16x16x32_bf16 v[70:73], v[174:177], v[218:221], v[70:73]
	v_mfma_f32_16x16x32_bf16 v[106:109], v[182:185], v[190:193], v[106:109]
	v_mfma_f32_16x16x32_bf16 v[98:101], v[182:185], v[198:201], v[98:101]
	v_mfma_f32_16x16x32_bf16 v[74:77], v[182:185], v[206:209], v[74:77]
	v_mfma_f32_16x16x32_bf16 v[66:69], v[182:185], v[218:221], v[66:69]
	s_setprio 0
	s_barrier
	s_add_i32 s62, s82, s52
	v_lshl_add_u64 v[150:151], v[150:151], 0, s[66:67]
	s_mov_b32 m0, s62
	ds_read_b128 v[186:189], v156 offset:49152
	ds_read_b128 v[190:193], v156 offset:50176
	ds_read_b128 v[194:197], v156 offset:51200
	ds_read_b128 v[198:201], v156 offset:52224
	ds_read_b128 v[202:205], v156 offset:53248
	ds_read_b128 v[206:209], v156 offset:54272
	ds_read_b128 v[210:213], v156 offset:55296
	ds_read_b128 v[218:221], v156 offset:56320
	global_load_lds_dwordx4 v[150:151], off
	s_add_i32 m0, s62, 0x2000
	s_add_u32 s34, s34, 0x160080
	v_lshl_add_u64 v[150:151], v[214:215], 0, s[66:67]
	s_addc_u32 s35, s35, 0
	s_add_i32 s62, s83, s52
	global_load_lds_dwordx4 v[150:151], off
	v_lshl_add_u64 v[150:151], s[34:35], 0, v[132:133]
	s_mov_b32 m0, s62
	s_nop 0
	global_load_lds_dwordx4 v[150:151], off
	v_lshl_add_u64 v[150:151], s[34:35], 0, v[136:137]
	s_add_i32 m0, s62, 0x2000
	s_nop 0
	global_load_lds_dwordx4 v[150:151], off
	v_lshl_add_u64 v[150:151], v[222:223], 0, s[66:67]
	s_mov_b32 m0, s58
	s_nop 0
	global_load_lds_dwordx4 v[150:151], off
	v_lshl_add_u64 v[150:151], v[224:225], 0, s[66:67]
	s_mov_b32 m0, s59
	s_nop 0
	global_load_lds_dwordx4 v[150:151], off
	s_waitcnt vmcnt(8)
	s_waitcnt lgkmcnt(0)
	s_barrier
	s_setprio 1
	s_waitcnt lgkmcnt(0)
	v_mfma_f32_16x16x32_bf16 v[62:65], v[146:149], v[186:189], v[62:65]
	v_mfma_f32_16x16x32_bf16 v[54:57], v[146:149], v[194:197], v[54:57]
	v_mfma_f32_16x16x32_bf16 v[30:33], v[146:149], v[202:205], v[30:33]
	v_mfma_f32_16x16x32_bf16 v[22:25], v[146:149], v[210:213], v[22:25]
	v_mfma_f32_16x16x32_bf16 v[58:61], v[162:165], v[186:189], v[58:61]
	v_mfma_f32_16x16x32_bf16 v[50:53], v[162:165], v[194:197], v[50:53]
	v_mfma_f32_16x16x32_bf16 v[26:29], v[162:165], v[202:205], v[26:29]
	v_mfma_f32_16x16x32_bf16 v[18:21], v[162:165], v[210:213], v[18:21]
	v_mfma_f32_16x16x32_bf16 v[62:65], v[158:161], v[190:193], v[62:65]
	v_mfma_f32_16x16x32_bf16 v[54:57], v[158:161], v[198:201], v[54:57]
	v_mfma_f32_16x16x32_bf16 v[30:33], v[158:161], v[206:209], v[30:33]
	v_mfma_f32_16x16x32_bf16 v[22:25], v[158:161], v[218:221], v[22:25]
	v_mfma_f32_16x16x32_bf16 v[58:61], v[166:169], v[190:193], v[58:61]
	v_mfma_f32_16x16x32_bf16 v[50:53], v[166:169], v[198:201], v[50:53]
	v_mfma_f32_16x16x32_bf16 v[26:29], v[166:169], v[206:209], v[26:29]
	v_mfma_f32_16x16x32_bf16 v[18:21], v[166:169], v[218:221], v[18:21]
	s_setprio 0
	s_setprio 1
	v_mfma_f32_16x16x32_bf16 v[46:49], v[170:173], v[186:189], v[46:49]
	v_mfma_f32_16x16x32_bf16 v[38:41], v[170:173], v[194:197], v[38:41]
	v_mfma_f32_16x16x32_bf16 v[14:17], v[170:173], v[202:205], v[14:17]
	v_mfma_f32_16x16x32_bf16 v[6:9], v[170:173], v[210:213], v[6:9]
	v_mfma_f32_16x16x32_bf16 v[42:45], v[178:181], v[186:189], v[42:45]
	v_mfma_f32_16x16x32_bf16 v[34:37], v[178:181], v[194:197], v[34:37]
	v_mfma_f32_16x16x32_bf16 v[10:13], v[178:181], v[202:205], v[10:13]
	v_mfma_f32_16x16x32_bf16 v[2:5], v[178:181], v[210:213], v[2:5]
	v_mfma_f32_16x16x32_bf16 v[46:49], v[174:177], v[190:193], v[46:49]
	v_mfma_f32_16x16x32_bf16 v[38:41], v[174:177], v[198:201], v[38:41]
	v_mfma_f32_16x16x32_bf16 v[14:17], v[174:177], v[206:209], v[14:17]
	v_mfma_f32_16x16x32_bf16 v[6:9], v[174:177], v[218:221], v[6:9]
	v_mfma_f32_16x16x32_bf16 v[42:45], v[182:185], v[190:193], v[42:45]
	v_mfma_f32_16x16x32_bf16 v[34:37], v[182:185], v[198:201], v[34:37]
	v_mfma_f32_16x16x32_bf16 v[10:13], v[182:185], v[206:209], v[10:13]
	v_mfma_f32_16x16x32_bf16 v[2:5], v[182:185], v[218:221], v[2:5]
	s_setprio 0
	s_barrier
	s_add_i32 s81, s81, 2
	s_add_u32 s72, s72, 0x100
	s_addc_u32 s73, s73, 0
	s_add_u32 s0, s0, 0x100
	s_addc_u32 s1, s1, 0
	s_cmpk_gt_u32 s81, 0x55
	s_cbranch_scc0 .LBB0_387
	s_and_b64 vcc, exec, s[68:69]
	s_cbranch_vccz .LBB0_390
	s_barrier

.LBB0_518:
	ds_read_b128 v[160:163], v155
	ds_read_b128 v[164:167], v155 offset:1024
	ds_read_b128 v[168:171], v155 offset:2048
	ds_read_b128 v[172:175], v155 offset:3072
	ds_read_b128 v[176:179], v156
	ds_read_b128 v[180:183], v156 offset:1024
	ds_read_b128 v[184:187], v156 offset:2048
	ds_read_b128 v[188:191], v156 offset:3072
	s_add_u32 s34, s90, 0xfff80080
	s_addc_u32 s35, s91, -1
	s_cmp_eq_u32 s83, 28
	s_cselect_b32 s93, s0, s35
	s_cselect_b32 s92, s1, s34
	s_cselect_b32 s35, s7, s68
	s_cselect_b32 s34, s9, s52
	v_lshl_add_u64 v[152:153], s[90:91], 0, v[144:145]
	s_add_i32 m0, s56, 0xc000
	ds_read_b128 v[192:195], v157
	ds_read_b128 v[196:199], v157 offset:1024
	ds_read_b128 v[200:203], v157 offset:2048
	ds_read_b128 v[204:207], v157 offset:3072
	ds_read_b128 v[208:211], v157 offset:4096
	ds_read_b128 v[212:215], v157 offset:5120
	ds_read_b128 v[218:221], v157 offset:6144
	ds_read_b128 v[222:225], v157 offset:7168
	global_load_lds_dwordx4 v[152:153], off
	v_lshl_add_u64 v[152:153], s[90:91], 0, v[146:147]
	s_add_i32 m0, s56, 0xe000
	s_nop 0
	global_load_lds_dwordx4 v[152:153], off
	s_waitcnt vmcnt(8)
	s_waitcnt lgkmcnt(0)
	s_barrier
	s_setprio 1
	s_waitcnt lgkmcnt(0)
	v_mfma_f32_16x16x32_bf16 v[126:129], v[160:163], v[192:195], v[126:129]
	v_mfma_f32_16x16x32_bf16 v[110:113], v[160:163], v[200:203], v[110:113]
	v_mfma_f32_16x16x32_bf16 v[94:97], v[160:163], v[208:211], v[94:97]
	v_mfma_f32_16x16x32_bf16 v[78:81], v[160:163], v[218:221], v[78:81]
	v_mfma_f32_16x16x32_bf16 v[122:125], v[168:171], v[192:195], v[122:125]
	v_mfma_f32_16x16x32_bf16 v[106:109], v[168:171], v[200:203], v[106:109]
	v_mfma_f32_16x16x32_bf16 v[90:93], v[168:171], v[208:211], v[90:93]
	v_mfma_f32_16x16x32_bf16 v[74:77], v[168:171], v[218:221], v[74:77]
	v_mfma_f32_16x16x32_bf16 v[126:129], v[164:167], v[196:199], v[126:129]
	v_mfma_f32_16x16x32_bf16 v[110:113], v[164:167], v[204:207], v[110:113]
	v_mfma_f32_16x16x32_bf16 v[94:97], v[164:167], v[212:215], v[94:97]
	v_mfma_f32_16x16x32_bf16 v[78:81], v[164:167], v[222:225], v[78:81]
	v_mfma_f32_16x16x32_bf16 v[122:125], v[172:175], v[196:199], v[122:125]
	v_mfma_f32_16x16x32_bf16 v[106:109], v[172:175], v[204:207], v[106:109]
	v_mfma_f32_16x16x32_bf16 v[90:93], v[172:175], v[212:215], v[90:93]
	v_mfma_f32_16x16x32_bf16 v[74:77], v[172:175], v[222:225], v[74:77]
	s_setprio 0
	s_setprio 1
	v_mfma_f32_16x16x32_bf16 v[118:121], v[176:179], v[192:195], v[118:121]
	v_mfma_f32_16x16x32_bf16 v[102:105], v[176:179], v[200:203], v[102:105]
	v_mfma_f32_16x16x32_bf16 v[86:89], v[176:179], v[208:211], v[86:89]
	v_mfma_f32_16x16x32_bf16 v[70:73], v[176:179], v[218:221], v[70:73]
	v_mfma_f32_16x16x32_bf16 v[114:117], v[184:187], v[192:195], v[114:117]
	v_mfma_f32_16x16x32_bf16 v[98:101], v[184:187], v[200:203], v[98:101]
	v_mfma_f32_16x16x32_bf16 v[82:85], v[184:187], v[208:211], v[82:85]
	v_mfma_f32_16x16x32_bf16 v[66:69], v[184:187], v[218:221], v[66:69]
	v_mfma_f32_16x16x32_bf16 v[118:121], v[180:183], v[196:199], v[118:121]
	v_mfma_f32_16x16x32_bf16 v[102:105], v[180:183], v[204:207], v[102:105]
	v_mfma_f32_16x16x32_bf16 v[86:89], v[180:183], v[212:215], v[86:89]
	v_mfma_f32_16x16x32_bf16 v[70:73], v[180:183], v[222:225], v[70:73]
	v_mfma_f32_16x16x32_bf16 v[114:117], v[188:191], v[196:199], v[114:117]
	v_mfma_f32_16x16x32_bf16 v[98:101], v[188:191], v[204:207], v[98:101]
	v_mfma_f32_16x16x32_bf16 v[82:85], v[188:191], v[212:215], v[82:85]
	v_mfma_f32_16x16x32_bf16 v[66:69], v[188:191], v[222:225], v[66:69]
	s_setprio 0
	s_barrier
	s_add_i32 s53, s75, s30
	v_lshl_add_u64 v[152:153], s[34:35], 0, v[132:133]
	s_mov_b32 m0, s53
	ds_read_b128 v[192:195], v157 offset:16384
	ds_read_b128 v[196:199], v157 offset:17408
	ds_read_b128 v[200:203], v157 offset:18432
	ds_read_b128 v[204:207], v157 offset:19456
	ds_read_b128 v[208:211], v157 offset:20480
	ds_read_b128 v[212:215], v157 offset:21504
	ds_read_b128 v[218:221], v157 offset:22528
	ds_read_b128 v[222:225], v157 offset:23552
	global_load_lds_dwordx4 v[152:153], off
	s_add_i32 m0, s53, 0x2000
	s_add_u32 s54, s34, 0x80000
	v_lshl_add_u64 v[226:227], s[34:35], 0, v[136:137]
	s_addc_u32 s55, s35, 0
	s_add_i32 s53, s94, s30
	global_load_lds_dwordx4 v[226:227], off
	v_lshl_add_u64 v[228:229], s[54:55], 0, v[132:133]
	s_mov_b32 m0, s53
	v_lshl_add_u64 v[230:231], s[92:93], 0, v[134:135]
	global_load_lds_dwordx4 v[228:229], off
	v_lshl_add_u64 v[228:229], s[54:55], 0, v[136:137]
	s_add_i32 m0, s53, 0x2000
	s_nop 0
	global_load_lds_dwordx4 v[228:229], off
	v_lshl_add_u64 v[228:229], s[92:93], 0, v[130:131]
	s_mov_b32 m0, s56
	s_nop 0
	global_load_lds_dwordx4 v[228:229], off
	s_mov_b32 m0, s57
	s_nop 0
	global_load_lds_dwordx4 v[230:231], off
	s_waitcnt vmcnt(8)
	s_waitcnt lgkmcnt(0)
	s_barrier
	s_setprio 1
	s_waitcnt lgkmcnt(0)
	v_mfma_f32_16x16x32_bf16 v[62:65], v[160:163], v[192:195], v[62:65]
	v_mfma_f32_16x16x32_bf16 v[46:49], v[160:163], v[200:203], v[46:49]
	v_mfma_f32_16x16x32_bf16 v[30:33], v[160:163], v[208:211], v[30:33]
	v_mfma_f32_16x16x32_bf16 v[14:17], v[160:163], v[218:221], v[14:17]
	v_mfma_f32_16x16x32_bf16 v[58:61], v[168:171], v[192:195], v[58:61]
	v_mfma_f32_16x16x32_bf16 v[42:45], v[168:171], v[200:203], v[42:45]
	v_mfma_f32_16x16x32_bf16 v[26:29], v[168:171], v[208:211], v[26:29]
	v_mfma_f32_16x16x32_bf16 v[10:13], v[168:171], v[218:221], v[10:13]
	v_mfma_f32_16x16x32_bf16 v[62:65], v[164:167], v[196:199], v[62:65]
	v_mfma_f32_16x16x32_bf16 v[46:49], v[164:167], v[204:207], v[46:49]
	v_mfma_f32_16x16x32_bf16 v[30:33], v[164:167], v[212:215], v[30:33]
	v_mfma_f32_16x16x32_bf16 v[14:17], v[164:167], v[222:225], v[14:17]
	v_mfma_f32_16x16x32_bf16 v[58:61], v[172:175], v[196:199], v[58:61]
	v_mfma_f32_16x16x32_bf16 v[42:45], v[172:175], v[204:207], v[42:45]
	v_mfma_f32_16x16x32_bf16 v[26:29], v[172:175], v[212:215], v[26:29]
	v_mfma_f32_16x16x32_bf16 v[10:13], v[172:175], v[222:225], v[10:13]
	s_setprio 0
	s_setprio 1
	v_mfma_f32_16x16x32_bf16 v[54:57], v[176:179], v[192:195], v[54:57]
	v_mfma_f32_16x16x32_bf16 v[38:41], v[176:179], v[200:203], v[38:41]
	v_mfma_f32_16x16x32_bf16 v[22:25], v[176:179], v[208:211], v[22:25]
	v_mfma_f32_16x16x32_bf16 v[6:9], v[176:179], v[218:221], v[6:9]
	v_mfma_f32_16x16x32_bf16 v[50:53], v[184:187], v[192:195], v[50:53]
	v_mfma_f32_16x16x32_bf16 v[34:37], v[184:187], v[200:203], v[34:37]
	v_mfma_f32_16x16x32_bf16 v[18:21], v[184:187], v[208:211], v[18:21]
	v_mfma_f32_16x16x32_bf16 v[2:5], v[184:187], v[218:221], v[2:5]
	v_mfma_f32_16x16x32_bf16 v[54:57], v[180:183], v[196:199], v[54:57]
	v_mfma_f32_16x16x32_bf16 v[38:41], v[180:183], v[204:207], v[38:41]
	v_mfma_f32_16x16x32_bf16 v[22:25], v[180:183], v[212:215], v[22:25]
	v_mfma_f32_16x16x32_bf16 v[6:9], v[180:183], v[222:225], v[6:9]
	v_mfma_f32_16x16x32_bf16 v[50:53], v[188:191], v[196:199], v[50:53]
	v_mfma_f32_16x16x32_bf16 v[34:37], v[188:191], v[204:207], v[34:37]
	v_mfma_f32_16x16x32_bf16 v[18:21], v[188:191], v[212:215], v[18:21]
	v_mfma_f32_16x16x32_bf16 v[2:5], v[188:191], v[222:225], v[2:5]
	s_setprio 0
	s_barrier
	s_add_i32 s53, 0, 0x18000
	v_add_u32_e32 v138, s53, v154
	s_add_i32 s62, 0, 0x1c000
	ds_read_b128 v[160:163], v138
	ds_read_b128 v[164:167], v138 offset:1024
	ds_read_b128 v[168:171], v138 offset:2048
	ds_read_b128 v[172:175], v138 offset:3072
	v_add_u32_e32 v138, s62, v154
	ds_read_b128 v[176:179], v138
	ds_read_b128 v[180:183], v138 offset:1024
	ds_read_b128 v[184:187], v138 offset:2048
	ds_read_b128 v[188:191], v138 offset:3072
	s_add_u32 s54, s92, 0x80000
	s_addc_u32 s55, s93, 0
	s_mov_b32 m0, s58
	v_lshl_add_u64 v[232:233], s[54:55], 0, v[130:131]
	ds_read_b128 v[192:195], v157 offset:32768
	ds_read_b128 v[196:199], v157 offset:33792
	ds_read_b128 v[200:203], v157 offset:34816
	ds_read_b128 v[204:207], v157 offset:35840
	ds_read_b128 v[208:211], v157 offset:36864
	ds_read_b128 v[212:215], v157 offset:37888
	ds_read_b128 v[218:221], v157 offset:38912
	ds_read_b128 v[222:225], v157 offset:39936
	global_load_lds_dwordx4 v[232:233], off
	v_lshl_add_u64 v[232:233], s[54:55], 0, v[134:135]
	s_mov_b32 m0, s59
	s_nop 0
	global_load_lds_dwordx4 v[232:233], off
	s_waitcnt vmcnt(8)
	s_waitcnt lgkmcnt(0)
	s_barrier
	s_setprio 1
	s_waitcnt lgkmcnt(0)
	v_mfma_f32_16x16x32_bf16 v[126:129], v[160:163], v[192:195], v[126:129]
	v_mfma_f32_16x16x32_bf16 v[110:113], v[160:163], v[200:203], v[110:113]
	v_mfma_f32_16x16x32_bf16 v[94:97], v[160:163], v[208:211], v[94:97]
	v_mfma_f32_16x16x32_bf16 v[78:81], v[160:163], v[218:221], v[78:81]
	v_mfma_f32_16x16x32_bf16 v[122:125], v[168:171], v[192:195], v[122:125]
	v_mfma_f32_16x16x32_bf16 v[106:109], v[168:171], v[200:203], v[106:109]
	v_mfma_f32_16x16x32_bf16 v[90:93], v[168:171], v[208:211], v[90:93]
	v_mfma_f32_16x16x32_bf16 v[74:77], v[168:171], v[218:221], v[74:77]
	v_mfma_f32_16x16x32_bf16 v[126:129], v[164:167], v[196:199], v[126:129]
	v_mfma_f32_16x16x32_bf16 v[110:113], v[164:167], v[204:207], v[110:113]
	v_mfma_f32_16x16x32_bf16 v[94:97], v[164:167], v[212:215], v[94:97]
	v_mfma_f32_16x16x32_bf16 v[78:81], v[164:167], v[222:225], v[78:81]
	v_mfma_f32_16x16x32_bf16 v[122:125], v[172:175], v[196:199], v[122:125]
	v_mfma_f32_16x16x32_bf16 v[106:109], v[172:175], v[204:207], v[106:109]
	v_mfma_f32_16x16x32_bf16 v[90:93], v[172:175], v[212:215], v[90:93]
	v_mfma_f32_16x16x32_bf16 v[74:77], v[172:175], v[222:225], v[74:77]
	s_setprio 0
	s_setprio 1
	v_mfma_f32_16x16x32_bf16 v[118:121], v[176:179], v[192:195], v[118:121]
	v_mfma_f32_16x16x32_bf16 v[102:105], v[176:179], v[200:203], v[102:105]
	v_mfma_f32_16x16x32_bf16 v[86:89], v[176:179], v[208:211], v[86:89]
	v_mfma_f32_16x16x32_bf16 v[70:73], v[176:179], v[218:221], v[70:73]
	v_mfma_f32_16x16x32_bf16 v[114:117], v[184:187], v[192:195], v[114:117]
	v_mfma_f32_16x16x32_bf16 v[98:101], v[184:187], v[200:203], v[98:101]
	v_mfma_f32_16x16x32_bf16 v[82:85], v[184:187], v[208:211], v[82:85]
	v_mfma_f32_16x16x32_bf16 v[66:69], v[184:187], v[218:221], v[66:69]
	v_mfma_f32_16x16x32_bf16 v[118:121], v[180:183], v[196:199], v[118:121]
	v_mfma_f32_16x16x32_bf16 v[102:105], v[180:183], v[204:207], v[102:105]
	v_mfma_f32_16x16x32_bf16 v[86:89], v[180:183], v[212:215], v[86:89]
	v_mfma_f32_16x16x32_bf16 v[70:73], v[180:183], v[222:225], v[70:73]
	v_mfma_f32_16x16x32_bf16 v[114:117], v[188:191], v[196:199], v[114:117]
	v_mfma_f32_16x16x32_bf16 v[98:101], v[188:191], v[204:207], v[98:101]
	v_mfma_f32_16x16x32_bf16 v[82:85], v[188:191], v[212:215], v[82:85]
	v_mfma_f32_16x16x32_bf16 v[66:69], v[188:191], v[222:225], v[66:69]
	s_setprio 0
	s_barrier
	s_add_i32 s53, s53, s30
	v_lshl_add_u64 v[152:153], v[152:153], 0, s[76:77]
	s_mov_b32 m0, s53
	ds_read_b128 v[192:195], v157 offset:49152
	ds_read_b128 v[196:199], v157 offset:50176
	ds_read_b128 v[200:203], v157 offset:51200
	ds_read_b128 v[204:207], v157 offset:52224
	ds_read_b128 v[208:211], v157 offset:53248
	ds_read_b128 v[212:215], v157 offset:54272
	ds_read_b128 v[218:221], v157 offset:55296
	ds_read_b128 v[222:225], v157 offset:56320
	global_load_lds_dwordx4 v[152:153], off
	s_add_i32 m0, s53, 0x2000
	s_add_u32 s34, s34, 0x80080
	v_lshl_add_u64 v[152:153], v[226:227], 0, s[76:77]
	s_addc_u32 s35, s35, 0
	s_add_i32 s53, s62, s30
	global_load_lds_dwordx4 v[152:153], off
	v_lshl_add_u64 v[152:153], s[34:35], 0, v[132:133]
	s_mov_b32 m0, s53
	s_nop 0
	global_load_lds_dwordx4 v[152:153], off
	v_lshl_add_u64 v[152:153], s[34:35], 0, v[136:137]
	s_add_i32 m0, s53, 0x2000
	s_nop 0
	global_load_lds_dwordx4 v[152:153], off
	v_lshl_add_u64 v[152:153], v[228:229], 0, s[76:77]
	s_mov_b32 m0, s61
	s_nop 0
	global_load_lds_dwordx4 v[152:153], off
	v_lshl_add_u64 v[152:153], v[230:231], 0, s[76:77]
	s_mov_b32 m0, s72
	s_nop 0
	global_load_lds_dwordx4 v[152:153], off
	s_waitcnt vmcnt(8)
	s_waitcnt lgkmcnt(0)
	s_barrier
	s_setprio 1
	s_waitcnt lgkmcnt(0)
	v_mfma_f32_16x16x32_bf16 v[62:65], v[160:163], v[192:195], v[62:65]
	v_mfma_f32_16x16x32_bf16 v[46:49], v[160:163], v[200:203], v[46:49]
	v_mfma_f32_16x16x32_bf16 v[30:33], v[160:163], v[208:211], v[30:33]
	v_mfma_f32_16x16x32_bf16 v[14:17], v[160:163], v[218:221], v[14:17]
	v_mfma_f32_16x16x32_bf16 v[58:61], v[168:171], v[192:195], v[58:61]
	v_mfma_f32_16x16x32_bf16 v[42:45], v[168:171], v[200:203], v[42:45]
	v_mfma_f32_16x16x32_bf16 v[26:29], v[168:171], v[208:211], v[26:29]
	v_mfma_f32_16x16x32_bf16 v[10:13], v[168:171], v[218:221], v[10:13]
	v_mfma_f32_16x16x32_bf16 v[62:65], v[164:167], v[196:199], v[62:65]
	v_mfma_f32_16x16x32_bf16 v[46:49], v[164:167], v[204:207], v[46:49]
	v_mfma_f32_16x16x32_bf16 v[30:33], v[164:167], v[212:215], v[30:33]
	v_mfma_f32_16x16x32_bf16 v[14:17], v[164:167], v[222:225], v[14:17]
	v_mfma_f32_16x16x32_bf16 v[58:61], v[172:175], v[196:199], v[58:61]
	v_mfma_f32_16x16x32_bf16 v[42:45], v[172:175], v[204:207], v[42:45]
	v_mfma_f32_16x16x32_bf16 v[26:29], v[172:175], v[212:215], v[26:29]
	v_mfma_f32_16x16x32_bf16 v[10:13], v[172:175], v[222:225], v[10:13]
	s_setprio 0
	s_setprio 1
	v_mfma_f32_16x16x32_bf16 v[54:57], v[176:179], v[192:195], v[54:57]
	v_mfma_f32_16x16x32_bf16 v[38:41], v[176:179], v[200:203], v[38:41]
	v_mfma_f32_16x16x32_bf16 v[22:25], v[176:179], v[208:211], v[22:25]
	v_mfma_f32_16x16x32_bf16 v[6:9], v[176:179], v[218:221], v[6:9]
	v_mfma_f32_16x16x32_bf16 v[50:53], v[184:187], v[192:195], v[50:53]
	v_mfma_f32_16x16x32_bf16 v[34:37], v[184:187], v[200:203], v[34:37]
	v_mfma_f32_16x16x32_bf16 v[18:21], v[184:187], v[208:211], v[18:21]
	v_mfma_f32_16x16x32_bf16 v[2:5], v[184:187], v[218:221], v[2:5]
	v_mfma_f32_16x16x32_bf16 v[54:57], v[180:183], v[196:199], v[54:57]
	v_mfma_f32_16x16x32_bf16 v[38:41], v[180:183], v[204:207], v[38:41]
	v_mfma_f32_16x16x32_bf16 v[22:25], v[180:183], v[212:215], v[22:25]
	v_mfma_f32_16x16x32_bf16 v[6:9], v[180:183], v[222:225], v[6:9]
	v_mfma_f32_16x16x32_bf16 v[50:53], v[188:191], v[196:199], v[50:53]
	v_mfma_f32_16x16x32_bf16 v[34:37], v[188:191], v[204:207], v[34:37]
	v_mfma_f32_16x16x32_bf16 v[18:21], v[188:191], v[212:215], v[18:21]
	v_mfma_f32_16x16x32_bf16 v[2:5], v[188:191], v[222:225], v[2:5]
	s_setprio 0
	s_barrier
	s_add_i32 s83, s83, 2
	s_add_u32 s90, s90, 0x100
	s_addc_u32 s91, s91, 0
	s_add_u32 s52, s52, 0x100
	s_addc_u32 s68, s68, 0
	s_cmp_gt_u32 s83, 29
	s_cbranch_scc0 .LBB0_518
	s_and_b64 vcc, exec, s[78:79]
	s_cbranch_vccz .LBB0_521
	s_barrier

.LBB0_685:
	ds_read_b128 v[146:149], v165
	ds_read_b128 v[150:153], v165 offset:1024
	ds_read_b128 v[168:171], v165 offset:2048
	ds_read_b128 v[172:175], v165 offset:3072
	ds_read_b128 v[176:179], v166
	ds_read_b128 v[180:183], v166 offset:1024
	ds_read_b128 v[184:187], v166 offset:2048
	ds_read_b128 v[188:191], v166 offset:3072
	s_add_u32 s34, s84, 0xfffe0080
	s_addc_u32 s35, s85, -1
	s_cmp_eq_u32 s89, 4
	s_cselect_b32 s87, s0, s35
	s_cselect_b32 s86, s1, s34
	s_cselect_b32 s35, s52, s88
	s_cselect_b32 s34, s71, s77
	v_lshl_add_u64 v[226:227], s[84:85], 0, v[138:139]
	s_add_i32 m0, s33, 0xc000
	ds_read_b128 v[192:195], v167
	ds_read_b128 v[196:199], v167 offset:1024
	ds_read_b128 v[200:203], v167 offset:2048
	ds_read_b128 v[204:207], v167 offset:3072
	ds_read_b128 v[208:211], v167 offset:4096
	ds_read_b128 v[212:215], v167 offset:5120
	ds_read_b128 v[218:221], v167 offset:6144
	ds_read_b128 v[222:225], v167 offset:7168
	global_load_lds_dwordx4 v[226:227], off
	v_lshl_add_u64 v[226:227], s[84:85], 0, v[140:141]
	s_add_i32 m0, s33, 0xe000
	s_nop 0
	global_load_lds_dwordx4 v[226:227], off
	s_waitcnt vmcnt(8)
	s_waitcnt lgkmcnt(0)
	s_barrier
	s_setprio 1
	s_waitcnt lgkmcnt(0)
	v_mfma_f32_16x16x32_bf16 v[126:129], v[146:149], v[192:195], v[126:129]
	v_mfma_f32_16x16x32_bf16 v[114:117], v[146:149], v[200:203], v[114:117]
	v_mfma_f32_16x16x32_bf16 v[98:101], v[146:149], v[208:211], v[98:101]
	v_mfma_f32_16x16x32_bf16 v[82:85], v[146:149], v[218:221], v[82:85]
	v_mfma_f32_16x16x32_bf16 v[122:125], v[168:171], v[192:195], v[122:125]
	v_mfma_f32_16x16x32_bf16 v[106:109], v[168:171], v[200:203], v[106:109]
	v_mfma_f32_16x16x32_bf16 v[90:93], v[168:171], v[208:211], v[90:93]
	v_mfma_f32_16x16x32_bf16 v[74:77], v[168:171], v[218:221], v[74:77]
	v_mfma_f32_16x16x32_bf16 v[126:129], v[150:153], v[196:199], v[126:129]
	v_mfma_f32_16x16x32_bf16 v[114:117], v[150:153], v[204:207], v[114:117]
	v_mfma_f32_16x16x32_bf16 v[98:101], v[150:153], v[212:215], v[98:101]
	v_mfma_f32_16x16x32_bf16 v[82:85], v[150:153], v[222:225], v[82:85]
	v_mfma_f32_16x16x32_bf16 v[122:125], v[172:175], v[196:199], v[122:125]
	v_mfma_f32_16x16x32_bf16 v[106:109], v[172:175], v[204:207], v[106:109]
	v_mfma_f32_16x16x32_bf16 v[90:93], v[172:175], v[212:215], v[90:93]
	v_mfma_f32_16x16x32_bf16 v[74:77], v[172:175], v[222:225], v[74:77]
	s_setprio 0
	s_setprio 1
	v_mfma_f32_16x16x32_bf16 v[118:121], v[176:179], v[192:195], v[118:121]
	v_mfma_f32_16x16x32_bf16 v[102:105], v[176:179], v[200:203], v[102:105]
	v_mfma_f32_16x16x32_bf16 v[86:89], v[176:179], v[208:211], v[86:89]
	v_mfma_f32_16x16x32_bf16 v[70:73], v[176:179], v[218:221], v[70:73]
	v_mfma_f32_16x16x32_bf16 v[110:113], v[184:187], v[192:195], v[110:113]
	v_mfma_f32_16x16x32_bf16 v[94:97], v[184:187], v[200:203], v[94:97]
	v_mfma_f32_16x16x32_bf16 v[78:81], v[184:187], v[208:211], v[78:81]
	v_mfma_f32_16x16x32_bf16 v[66:69], v[184:187], v[218:221], v[66:69]
	v_mfma_f32_16x16x32_bf16 v[118:121], v[180:183], v[196:199], v[118:121]
	v_mfma_f32_16x16x32_bf16 v[102:105], v[180:183], v[204:207], v[102:105]
	v_mfma_f32_16x16x32_bf16 v[86:89], v[180:183], v[212:215], v[86:89]
	v_mfma_f32_16x16x32_bf16 v[70:73], v[180:183], v[222:225], v[70:73]
	v_mfma_f32_16x16x32_bf16 v[110:113], v[188:191], v[196:199], v[110:113]
	v_mfma_f32_16x16x32_bf16 v[94:97], v[188:191], v[204:207], v[94:97]
	v_mfma_f32_16x16x32_bf16 v[78:81], v[188:191], v[212:215], v[78:81]
	v_mfma_f32_16x16x32_bf16 v[66:69], v[188:191], v[222:225], v[66:69]
	s_setprio 0
	s_barrier
	s_add_i32 s53, s73, s12
	v_lshl_add_u64 v[226:227], s[34:35], 0, v[132:133]
	s_mov_b32 m0, s53
	ds_read_b128 v[192:195], v167 offset:16384
	ds_read_b128 v[196:199], v167 offset:17408
	ds_read_b128 v[200:203], v167 offset:18432
	ds_read_b128 v[204:207], v167 offset:19456
	ds_read_b128 v[208:211], v167 offset:20480
	ds_read_b128 v[212:215], v167 offset:21504
	ds_read_b128 v[218:221], v167 offset:22528
	ds_read_b128 v[222:225], v167 offset:23552
	global_load_lds_dwordx4 v[226:227], off
	s_add_i32 m0, s53, 0x2000
	s_add_u32 s54, s34, 0x20000
	v_lshl_add_u64 v[228:229], s[34:35], 0, v[136:137]
	s_addc_u32 s55, s35, 0
	s_add_i32 s53, s74, s12
	global_load_lds_dwordx4 v[228:229], off
	v_lshl_add_u64 v[230:231], s[54:55], 0, v[132:133]
	s_mov_b32 m0, s53
	v_lshl_add_u64 v[232:233], s[86:87], 0, v[134:135]
	global_load_lds_dwordx4 v[230:231], off
	v_lshl_add_u64 v[230:231], s[54:55], 0, v[136:137]
	s_add_i32 m0, s53, 0x2000
	s_nop 0
	global_load_lds_dwordx4 v[230:231], off
	v_lshl_add_u64 v[230:231], s[86:87], 0, v[130:131]
	s_mov_b32 m0, s33
	s_nop 0
	global_load_lds_dwordx4 v[230:231], off
	s_mov_b32 m0, s56
	s_nop 0
	global_load_lds_dwordx4 v[232:233], off
	s_waitcnt vmcnt(8)
	s_waitcnt lgkmcnt(0)
	s_barrier
	s_setprio 1
	s_waitcnt lgkmcnt(0)
	v_mfma_f32_16x16x32_bf16 v[62:65], v[146:149], v[192:195], v[62:65]
	v_mfma_f32_16x16x32_bf16 v[50:53], v[146:149], v[200:203], v[50:53]
	v_mfma_f32_16x16x32_bf16 v[34:37], v[146:149], v[208:211], v[34:37]
	v_mfma_f32_16x16x32_bf16 v[18:21], v[146:149], v[218:221], v[18:21]
	v_mfma_f32_16x16x32_bf16 v[58:61], v[168:171], v[192:195], v[58:61]
	v_mfma_f32_16x16x32_bf16 v[42:45], v[168:171], v[200:203], v[42:45]
	v_mfma_f32_16x16x32_bf16 v[26:29], v[168:171], v[208:211], v[26:29]
	v_mfma_f32_16x16x32_bf16 v[10:13], v[168:171], v[218:221], v[10:13]
	v_mfma_f32_16x16x32_bf16 v[62:65], v[150:153], v[196:199], v[62:65]
	v_mfma_f32_16x16x32_bf16 v[50:53], v[150:153], v[204:207], v[50:53]
	v_mfma_f32_16x16x32_bf16 v[34:37], v[150:153], v[212:215], v[34:37]
	v_mfma_f32_16x16x32_bf16 v[18:21], v[150:153], v[222:225], v[18:21]
	v_mfma_f32_16x16x32_bf16 v[58:61], v[172:175], v[196:199], v[58:61]
	v_mfma_f32_16x16x32_bf16 v[42:45], v[172:175], v[204:207], v[42:45]
	v_mfma_f32_16x16x32_bf16 v[26:29], v[172:175], v[212:215], v[26:29]
	v_mfma_f32_16x16x32_bf16 v[10:13], v[172:175], v[222:225], v[10:13]
	s_setprio 0
	s_setprio 1
	v_mfma_f32_16x16x32_bf16 v[54:57], v[176:179], v[192:195], v[54:57]
	v_mfma_f32_16x16x32_bf16 v[38:41], v[176:179], v[200:203], v[38:41]
	v_mfma_f32_16x16x32_bf16 v[22:25], v[176:179], v[208:211], v[22:25]
	v_mfma_f32_16x16x32_bf16 v[6:9], v[176:179], v[218:221], v[6:9]
	v_mfma_f32_16x16x32_bf16 v[46:49], v[184:187], v[192:195], v[46:49]
	v_mfma_f32_16x16x32_bf16 v[30:33], v[184:187], v[200:203], v[30:33]
	v_mfma_f32_16x16x32_bf16 v[14:17], v[184:187], v[208:211], v[14:17]
	v_mfma_f32_16x16x32_bf16 v[2:5], v[184:187], v[218:221], v[2:5]
	v_mfma_f32_16x16x32_bf16 v[54:57], v[180:183], v[196:199], v[54:57]
	v_mfma_f32_16x16x32_bf16 v[38:41], v[180:183], v[204:207], v[38:41]
	v_mfma_f32_16x16x32_bf16 v[22:25], v[180:183], v[212:215], v[22:25]
	v_mfma_f32_16x16x32_bf16 v[6:9], v[180:183], v[222:225], v[6:9]
	v_mfma_f32_16x16x32_bf16 v[46:49], v[188:191], v[196:199], v[46:49]
	v_mfma_f32_16x16x32_bf16 v[30:33], v[188:191], v[204:207], v[30:33]
	v_mfma_f32_16x16x32_bf16 v[14:17], v[188:191], v[212:215], v[14:17]
	v_mfma_f32_16x16x32_bf16 v[2:5], v[188:191], v[222:225], v[2:5]
	s_setprio 0
	s_barrier
	s_add_i32 s53, 0, 0x18000
	s_add_i32 s62, 0, 0x1c000
	v_add_u32_e32 v172, s53, v162
	v_add_u32_e32 v188, s62, v162
	ds_read_b128 v[146:149], v172
	ds_read_b128 v[150:153], v172 offset:1024
	ds_read_b128 v[168:171], v172 offset:2048
	ds_read_b128 v[172:175], v172 offset:3072
	ds_read_b128 v[176:179], v188
	ds_read_b128 v[180:183], v188 offset:1024
	ds_read_b128 v[184:187], v188 offset:2048
	ds_read_b128 v[188:191], v188 offset:3072
	s_add_u32 s54, s86, 0x20000
	s_addc_u32 s55, s87, 0
	s_mov_b32 m0, s57
	v_lshl_add_u64 v[234:235], s[54:55], 0, v[130:131]
	ds_read_b128 v[192:195], v167 offset:32768
	ds_read_b128 v[196:199], v167 offset:33792
	ds_read_b128 v[200:203], v167 offset:34816
	ds_read_b128 v[204:207], v167 offset:35840
	ds_read_b128 v[208:211], v167 offset:36864
	ds_read_b128 v[212:215], v167 offset:37888
	ds_read_b128 v[218:221], v167 offset:38912
	ds_read_b128 v[222:225], v167 offset:39936
	global_load_lds_dwordx4 v[234:235], off
	v_lshl_add_u64 v[234:235], s[54:55], 0, v[134:135]
	s_mov_b32 m0, s58
	s_nop 0
	global_load_lds_dwordx4 v[234:235], off
	s_waitcnt vmcnt(8)
	s_waitcnt lgkmcnt(0)
	s_barrier
	s_setprio 1
	s_waitcnt lgkmcnt(0)
	v_mfma_f32_16x16x32_bf16 v[126:129], v[146:149], v[192:195], v[126:129]
	v_mfma_f32_16x16x32_bf16 v[114:117], v[146:149], v[200:203], v[114:117]
	v_mfma_f32_16x16x32_bf16 v[98:101], v[146:149], v[208:211], v[98:101]
	v_mfma_f32_16x16x32_bf16 v[82:85], v[146:149], v[218:221], v[82:85]
	v_mfma_f32_16x16x32_bf16 v[122:125], v[168:171], v[192:195], v[122:125]
	v_mfma_f32_16x16x32_bf16 v[106:109], v[168:171], v[200:203], v[106:109]
	v_mfma_f32_16x16x32_bf16 v[90:93], v[168:171], v[208:211], v[90:93]
	v_mfma_f32_16x16x32_bf16 v[74:77], v[168:171], v[218:221], v[74:77]
	v_mfma_f32_16x16x32_bf16 v[126:129], v[150:153], v[196:199], v[126:129]
	v_mfma_f32_16x16x32_bf16 v[114:117], v[150:153], v[204:207], v[114:117]
	v_mfma_f32_16x16x32_bf16 v[98:101], v[150:153], v[212:215], v[98:101]
	v_mfma_f32_16x16x32_bf16 v[82:85], v[150:153], v[222:225], v[82:85]
	v_mfma_f32_16x16x32_bf16 v[122:125], v[172:175], v[196:199], v[122:125]
	v_mfma_f32_16x16x32_bf16 v[106:109], v[172:175], v[204:207], v[106:109]
	v_mfma_f32_16x16x32_bf16 v[90:93], v[172:175], v[212:215], v[90:93]
	v_mfma_f32_16x16x32_bf16 v[74:77], v[172:175], v[222:225], v[74:77]
	s_setprio 0
	s_setprio 1
	v_mfma_f32_16x16x32_bf16 v[118:121], v[176:179], v[192:195], v[118:121]
	v_mfma_f32_16x16x32_bf16 v[102:105], v[176:179], v[200:203], v[102:105]
	v_mfma_f32_16x16x32_bf16 v[86:89], v[176:179], v[208:211], v[86:89]
	v_mfma_f32_16x16x32_bf16 v[70:73], v[176:179], v[218:221], v[70:73]
	v_mfma_f32_16x16x32_bf16 v[110:113], v[184:187], v[192:195], v[110:113]
	v_mfma_f32_16x16x32_bf16 v[94:97], v[184:187], v[200:203], v[94:97]
	v_mfma_f32_16x16x32_bf16 v[78:81], v[184:187], v[208:211], v[78:81]
	v_mfma_f32_16x16x32_bf16 v[66:69], v[184:187], v[218:221], v[66:69]
	v_mfma_f32_16x16x32_bf16 v[118:121], v[180:183], v[196:199], v[118:121]
	v_mfma_f32_16x16x32_bf16 v[102:105], v[180:183], v[204:207], v[102:105]
	v_mfma_f32_16x16x32_bf16 v[86:89], v[180:183], v[212:215], v[86:89]
	v_mfma_f32_16x16x32_bf16 v[70:73], v[180:183], v[222:225], v[70:73]
	v_mfma_f32_16x16x32_bf16 v[110:113], v[188:191], v[196:199], v[110:113]
	v_mfma_f32_16x16x32_bf16 v[94:97], v[188:191], v[204:207], v[94:97]
	v_mfma_f32_16x16x32_bf16 v[78:81], v[188:191], v[212:215], v[78:81]
	v_mfma_f32_16x16x32_bf16 v[66:69], v[188:191], v[222:225], v[66:69]
	s_setprio 0
	s_barrier
	s_add_i32 s53, s53, s12
	v_lshl_add_u64 v[226:227], v[226:227], 0, s[8:9]
	s_mov_b32 m0, s53
	ds_read_b128 v[192:195], v167 offset:49152
	ds_read_b128 v[196:199], v167 offset:50176
	ds_read_b128 v[200:203], v167 offset:51200
	ds_read_b128 v[204:207], v167 offset:52224
	ds_read_b128 v[208:211], v167 offset:53248
	ds_read_b128 v[212:215], v167 offset:54272
	ds_read_b128 v[218:221], v167 offset:55296
	ds_read_b128 v[222:225], v167 offset:56320
	global_load_lds_dwordx4 v[226:227], off
	s_add_i32 m0, s53, 0x2000
	s_add_u32 s34, s34, 0x20080
	v_lshl_add_u64 v[226:227], v[228:229], 0, s[8:9]
	s_addc_u32 s35, s35, 0
	s_add_i32 s53, s62, s12
	global_load_lds_dwordx4 v[226:227], off
	v_lshl_add_u64 v[226:227], s[34:35], 0, v[132:133]
	s_mov_b32 m0, s53
	s_nop 0
	global_load_lds_dwordx4 v[226:227], off
	v_lshl_add_u64 v[226:227], s[34:35], 0, v[136:137]
	s_add_i32 m0, s53, 0x2000
	s_nop 0
	global_load_lds_dwordx4 v[226:227], off
	v_lshl_add_u64 v[226:227], v[230:231], 0, s[8:9]
	s_mov_b32 m0, s60
	s_nop 0
	global_load_lds_dwordx4 v[226:227], off
	v_lshl_add_u64 v[226:227], v[232:233], 0, s[8:9]
	s_mov_b32 m0, s61
	s_nop 0
	global_load_lds_dwordx4 v[226:227], off
	s_waitcnt vmcnt(8)
	s_waitcnt lgkmcnt(0)
	s_barrier
	s_setprio 1
	s_waitcnt lgkmcnt(0)
	v_mfma_f32_16x16x32_bf16 v[62:65], v[146:149], v[192:195], v[62:65]
	v_mfma_f32_16x16x32_bf16 v[50:53], v[146:149], v[200:203], v[50:53]
	v_mfma_f32_16x16x32_bf16 v[34:37], v[146:149], v[208:211], v[34:37]
	v_mfma_f32_16x16x32_bf16 v[18:21], v[146:149], v[218:221], v[18:21]
	v_mfma_f32_16x16x32_bf16 v[58:61], v[168:171], v[192:195], v[58:61]
	v_mfma_f32_16x16x32_bf16 v[42:45], v[168:171], v[200:203], v[42:45]
	v_mfma_f32_16x16x32_bf16 v[26:29], v[168:171], v[208:211], v[26:29]
	v_mfma_f32_16x16x32_bf16 v[10:13], v[168:171], v[218:221], v[10:13]
	v_mfma_f32_16x16x32_bf16 v[62:65], v[150:153], v[196:199], v[62:65]
	v_mfma_f32_16x16x32_bf16 v[50:53], v[150:153], v[204:207], v[50:53]
	v_mfma_f32_16x16x32_bf16 v[34:37], v[150:153], v[212:215], v[34:37]
	v_mfma_f32_16x16x32_bf16 v[18:21], v[150:153], v[222:225], v[18:21]
	v_mfma_f32_16x16x32_bf16 v[58:61], v[172:175], v[196:199], v[58:61]
	v_mfma_f32_16x16x32_bf16 v[42:45], v[172:175], v[204:207], v[42:45]
	v_mfma_f32_16x16x32_bf16 v[26:29], v[172:175], v[212:215], v[26:29]
	v_mfma_f32_16x16x32_bf16 v[10:13], v[172:175], v[222:225], v[10:13]
	s_setprio 0
	s_setprio 1
	v_mfma_f32_16x16x32_bf16 v[54:57], v[176:179], v[192:195], v[54:57]
	v_mfma_f32_16x16x32_bf16 v[38:41], v[176:179], v[200:203], v[38:41]
	v_mfma_f32_16x16x32_bf16 v[22:25], v[176:179], v[208:211], v[22:25]
	v_mfma_f32_16x16x32_bf16 v[6:9], v[176:179], v[218:221], v[6:9]
	v_mfma_f32_16x16x32_bf16 v[46:49], v[184:187], v[192:195], v[46:49]
	v_mfma_f32_16x16x32_bf16 v[30:33], v[184:187], v[200:203], v[30:33]
	v_mfma_f32_16x16x32_bf16 v[14:17], v[184:187], v[208:211], v[14:17]
	v_mfma_f32_16x16x32_bf16 v[2:5], v[184:187], v[218:221], v[2:5]
	v_mfma_f32_16x16x32_bf16 v[54:57], v[180:183], v[196:199], v[54:57]
	v_mfma_f32_16x16x32_bf16 v[38:41], v[180:183], v[204:207], v[38:41]
	v_mfma_f32_16x16x32_bf16 v[22:25], v[180:183], v[212:215], v[22:25]
	v_mfma_f32_16x16x32_bf16 v[6:9], v[180:183], v[222:225], v[6:9]
	v_mfma_f32_16x16x32_bf16 v[46:49], v[188:191], v[196:199], v[46:49]
	v_mfma_f32_16x16x32_bf16 v[30:33], v[188:191], v[204:207], v[30:33]
	v_mfma_f32_16x16x32_bf16 v[14:17], v[188:191], v[212:215], v[14:17]
	v_mfma_f32_16x16x32_bf16 v[2:5], v[188:191], v[222:225], v[2:5]
	s_setprio 0
	s_barrier
	s_add_i32 s89, s89, 2
	s_add_u32 s84, s84, 0x100
	s_addc_u32 s85, s85, 0
	s_add_u32 s77, s77, 0x100
	s_addc_u32 s88, s88, 0
	s_cmp_gt_u32 s89, 5
	s_cbranch_scc0 .LBB0_685
	s_and_b64 vcc, exec, s[66:67]
	s_cbranch_vccz .LBB0_688
	s_barrier

.LBB0_715:
	ds_read_b128 v[146:149], v1
	ds_read_b128 v[160:163], v1 offset:1024
	ds_read_b128 v[164:167], v1 offset:2048
	ds_read_b128 v[168:171], v1 offset:3072
	ds_read_b128 v[172:175], v154
	ds_read_b128 v[176:179], v154 offset:1024
	ds_read_b128 v[180:183], v154 offset:2048
	ds_read_b128 v[184:187], v154 offset:3072
	s_add_u32 s34, s84, 0xfffe0080
	s_addc_u32 s35, s85, -1
	s_cmp_eq_u32 s88, 4
	s_cselect_b32 s87, s0, s35
	s_cselect_b32 s86, s1, s34
	s_cselect_b32 s35, s52, s83
	s_cselect_b32 s34, s71, s77
	v_lshl_add_u64 v[150:151], s[84:85], 0, v[138:139]
	s_add_i32 m0, s33, 0xc000
	ds_read_b128 v[188:191], v155
	ds_read_b128 v[192:195], v155 offset:1024
	ds_read_b128 v[196:199], v155 offset:2048
	ds_read_b128 v[200:203], v155 offset:3072
	ds_read_b128 v[204:207], v155 offset:4096
	ds_read_b128 v[208:211], v155 offset:5120
	ds_read_b128 v[212:215], v155 offset:6144
	ds_read_b128 v[218:221], v155 offset:7168
	global_load_lds_dwordx4 v[150:151], off
	v_lshl_add_u64 v[150:151], s[84:85], 0, v[140:141]
	s_add_i32 m0, s33, 0xe000
	s_nop 0
	global_load_lds_dwordx4 v[150:151], off
	s_waitcnt vmcnt(8)
	s_waitcnt lgkmcnt(0)
	s_barrier
	s_setprio 1
	s_waitcnt lgkmcnt(0)
	v_mfma_f32_16x16x32_bf16 v[126:129], v[146:149], v[188:191], v[126:129]
	v_mfma_f32_16x16x32_bf16 v[110:113], v[146:149], v[196:199], v[110:113]
	v_mfma_f32_16x16x32_bf16 v[94:97], v[146:149], v[204:207], v[94:97]
	v_mfma_f32_16x16x32_bf16 v[78:81], v[146:149], v[212:215], v[78:81]
	v_mfma_f32_16x16x32_bf16 v[122:125], v[164:167], v[188:191], v[122:125]
	v_mfma_f32_16x16x32_bf16 v[106:109], v[164:167], v[196:199], v[106:109]
	v_mfma_f32_16x16x32_bf16 v[90:93], v[164:167], v[204:207], v[90:93]
	v_mfma_f32_16x16x32_bf16 v[74:77], v[164:167], v[212:215], v[74:77]
	v_mfma_f32_16x16x32_bf16 v[126:129], v[160:163], v[192:195], v[126:129]
	v_mfma_f32_16x16x32_bf16 v[110:113], v[160:163], v[200:203], v[110:113]
	v_mfma_f32_16x16x32_bf16 v[94:97], v[160:163], v[208:211], v[94:97]
	v_mfma_f32_16x16x32_bf16 v[78:81], v[160:163], v[218:221], v[78:81]
	v_mfma_f32_16x16x32_bf16 v[122:125], v[168:171], v[192:195], v[122:125]
	v_mfma_f32_16x16x32_bf16 v[106:109], v[168:171], v[200:203], v[106:109]
	v_mfma_f32_16x16x32_bf16 v[90:93], v[168:171], v[208:211], v[90:93]
	v_mfma_f32_16x16x32_bf16 v[74:77], v[168:171], v[218:221], v[74:77]
	s_setprio 0
	s_setprio 1
	v_mfma_f32_16x16x32_bf16 v[118:121], v[172:175], v[188:191], v[118:121]
	v_mfma_f32_16x16x32_bf16 v[102:105], v[172:175], v[196:199], v[102:105]
	v_mfma_f32_16x16x32_bf16 v[86:89], v[172:175], v[204:207], v[86:89]
	v_mfma_f32_16x16x32_bf16 v[70:73], v[172:175], v[212:215], v[70:73]
	v_mfma_f32_16x16x32_bf16 v[114:117], v[180:183], v[188:191], v[114:117]
	v_mfma_f32_16x16x32_bf16 v[98:101], v[180:183], v[196:199], v[98:101]
	v_mfma_f32_16x16x32_bf16 v[82:85], v[180:183], v[204:207], v[82:85]
	v_mfma_f32_16x16x32_bf16 v[66:69], v[180:183], v[212:215], v[66:69]
	v_mfma_f32_16x16x32_bf16 v[118:121], v[176:179], v[192:195], v[118:121]
	v_mfma_f32_16x16x32_bf16 v[102:105], v[176:179], v[200:203], v[102:105]
	v_mfma_f32_16x16x32_bf16 v[86:89], v[176:179], v[208:211], v[86:89]
	v_mfma_f32_16x16x32_bf16 v[70:73], v[176:179], v[218:221], v[70:73]
	v_mfma_f32_16x16x32_bf16 v[114:117], v[184:187], v[192:195], v[114:117]
	v_mfma_f32_16x16x32_bf16 v[98:101], v[184:187], v[200:203], v[98:101]
	v_mfma_f32_16x16x32_bf16 v[82:85], v[184:187], v[208:211], v[82:85]
	v_mfma_f32_16x16x32_bf16 v[66:69], v[184:187], v[218:221], v[66:69]
	s_setprio 0
	s_barrier
	s_add_i32 s53, s73, s13
	v_lshl_add_u64 v[150:151], s[34:35], 0, v[132:133]
	s_mov_b32 m0, s53
	ds_read_b128 v[188:191], v155 offset:16384
	ds_read_b128 v[192:195], v155 offset:17408
	ds_read_b128 v[196:199], v155 offset:18432
	ds_read_b128 v[200:203], v155 offset:19456
	ds_read_b128 v[204:207], v155 offset:20480
	ds_read_b128 v[208:211], v155 offset:21504
	ds_read_b128 v[212:215], v155 offset:22528
	ds_read_b128 v[218:221], v155 offset:23552
	global_load_lds_dwordx4 v[150:151], off
	s_add_i32 m0, s53, 0x2000
	s_add_u32 s54, s34, 0x20000
	v_lshl_add_u64 v[222:223], s[34:35], 0, v[136:137]
	s_addc_u32 s55, s35, 0
	s_add_i32 s53, s74, s13
	global_load_lds_dwordx4 v[222:223], off
	v_lshl_add_u64 v[224:225], s[54:55], 0, v[132:133]
	s_mov_b32 m0, s53
	v_lshl_add_u64 v[226:227], s[86:87], 0, v[134:135]
	global_load_lds_dwordx4 v[224:225], off
	v_lshl_add_u64 v[224:225], s[54:55], 0, v[136:137]
	s_add_i32 m0, s53, 0x2000
	s_nop 0
	global_load_lds_dwordx4 v[224:225], off
	v_lshl_add_u64 v[224:225], s[86:87], 0, v[130:131]
	s_mov_b32 m0, s33
	s_nop 0
	global_load_lds_dwordx4 v[224:225], off
	s_mov_b32 m0, s56
	s_nop 0
	global_load_lds_dwordx4 v[226:227], off
	s_waitcnt vmcnt(8)
	s_waitcnt lgkmcnt(0)
	s_barrier
	s_setprio 1
	s_waitcnt lgkmcnt(0)
	v_mfma_f32_16x16x32_bf16 v[62:65], v[146:149], v[188:191], v[62:65]
	v_mfma_f32_16x16x32_bf16 v[50:53], v[146:149], v[196:199], v[50:53]
	v_mfma_f32_16x16x32_bf16 v[34:37], v[146:149], v[204:207], v[34:37]
	v_mfma_f32_16x16x32_bf16 v[18:21], v[146:149], v[212:215], v[18:21]
	v_mfma_f32_16x16x32_bf16 v[58:61], v[164:167], v[188:191], v[58:61]
	v_mfma_f32_16x16x32_bf16 v[42:45], v[164:167], v[196:199], v[42:45]
	v_mfma_f32_16x16x32_bf16 v[26:29], v[164:167], v[204:207], v[26:29]
	v_mfma_f32_16x16x32_bf16 v[10:13], v[164:167], v[212:215], v[10:13]
	v_mfma_f32_16x16x32_bf16 v[62:65], v[160:163], v[192:195], v[62:65]
	v_mfma_f32_16x16x32_bf16 v[50:53], v[160:163], v[200:203], v[50:53]
	v_mfma_f32_16x16x32_bf16 v[34:37], v[160:163], v[208:211], v[34:37]
	v_mfma_f32_16x16x32_bf16 v[18:21], v[160:163], v[218:221], v[18:21]
	v_mfma_f32_16x16x32_bf16 v[58:61], v[168:171], v[192:195], v[58:61]
	v_mfma_f32_16x16x32_bf16 v[42:45], v[168:171], v[200:203], v[42:45]
	v_mfma_f32_16x16x32_bf16 v[26:29], v[168:171], v[208:211], v[26:29]
	v_mfma_f32_16x16x32_bf16 v[10:13], v[168:171], v[218:221], v[10:13]
	s_setprio 0
	s_setprio 1
	v_mfma_f32_16x16x32_bf16 v[54:57], v[172:175], v[188:191], v[54:57]
	v_mfma_f32_16x16x32_bf16 v[38:41], v[172:175], v[196:199], v[38:41]
	v_mfma_f32_16x16x32_bf16 v[22:25], v[172:175], v[204:207], v[22:25]
	v_mfma_f32_16x16x32_bf16 v[6:9], v[172:175], v[212:215], v[6:9]
	v_mfma_f32_16x16x32_bf16 v[46:49], v[180:183], v[188:191], v[46:49]
	v_mfma_f32_16x16x32_bf16 v[30:33], v[180:183], v[196:199], v[30:33]
	v_mfma_f32_16x16x32_bf16 v[14:17], v[180:183], v[204:207], v[14:17]
	v_mfma_f32_16x16x32_bf16 v[2:5], v[180:183], v[212:215], v[2:5]
	v_mfma_f32_16x16x32_bf16 v[54:57], v[176:179], v[192:195], v[54:57]
	v_mfma_f32_16x16x32_bf16 v[38:41], v[176:179], v[200:203], v[38:41]
	v_mfma_f32_16x16x32_bf16 v[22:25], v[176:179], v[208:211], v[22:25]
	v_mfma_f32_16x16x32_bf16 v[6:9], v[176:179], v[218:221], v[6:9]
	v_mfma_f32_16x16x32_bf16 v[46:49], v[184:187], v[192:195], v[46:49]
	v_mfma_f32_16x16x32_bf16 v[30:33], v[184:187], v[200:203], v[30:33]
	v_mfma_f32_16x16x32_bf16 v[14:17], v[184:187], v[208:211], v[14:17]
	v_mfma_f32_16x16x32_bf16 v[2:5], v[184:187], v[218:221], v[2:5]
	s_setprio 0
	s_barrier
	s_add_i32 s53, 0, 0x18000
	v_add_u32_e32 v156, s53, v153
	s_add_i32 s62, 0, 0x1c000
	ds_read_b128 v[146:149], v156
	ds_read_b128 v[160:163], v156 offset:1024
	ds_read_b128 v[164:167], v156 offset:2048
	ds_read_b128 v[168:171], v156 offset:3072
	v_add_u32_e32 v156, s62, v153
	ds_read_b128 v[172:175], v156
	ds_read_b128 v[176:179], v156 offset:1024
	ds_read_b128 v[180:183], v156 offset:2048
	ds_read_b128 v[184:187], v156 offset:3072
	s_add_u32 s54, s86, 0x20000
	s_addc_u32 s55, s87, 0
	s_mov_b32 m0, s57
	v_lshl_add_u64 v[228:229], s[54:55], 0, v[130:131]
	ds_read_b128 v[188:191], v155 offset:32768
	ds_read_b128 v[192:195], v155 offset:33792
	ds_read_b128 v[196:199], v155 offset:34816
	ds_read_b128 v[200:203], v155 offset:35840
	ds_read_b128 v[204:207], v155 offset:36864
	ds_read_b128 v[208:211], v155 offset:37888
	ds_read_b128 v[212:215], v155 offset:38912
	ds_read_b128 v[218:221], v155 offset:39936
	global_load_lds_dwordx4 v[228:229], off
	v_lshl_add_u64 v[228:229], s[54:55], 0, v[134:135]
	s_mov_b32 m0, s58
	s_nop 0
	global_load_lds_dwordx4 v[228:229], off
	s_waitcnt vmcnt(8)
	s_waitcnt lgkmcnt(0)
	s_barrier
	s_setprio 1
	s_waitcnt lgkmcnt(0)
	v_mfma_f32_16x16x32_bf16 v[126:129], v[146:149], v[188:191], v[126:129]
	v_mfma_f32_16x16x32_bf16 v[110:113], v[146:149], v[196:199], v[110:113]
	v_mfma_f32_16x16x32_bf16 v[94:97], v[146:149], v[204:207], v[94:97]
	v_mfma_f32_16x16x32_bf16 v[78:81], v[146:149], v[212:215], v[78:81]
	v_mfma_f32_16x16x32_bf16 v[122:125], v[164:167], v[188:191], v[122:125]
	v_mfma_f32_16x16x32_bf16 v[106:109], v[164:167], v[196:199], v[106:109]
	v_mfma_f32_16x16x32_bf16 v[90:93], v[164:167], v[204:207], v[90:93]
	v_mfma_f32_16x16x32_bf16 v[74:77], v[164:167], v[212:215], v[74:77]
	v_mfma_f32_16x16x32_bf16 v[126:129], v[160:163], v[192:195], v[126:129]
	v_mfma_f32_16x16x32_bf16 v[110:113], v[160:163], v[200:203], v[110:113]
	v_mfma_f32_16x16x32_bf16 v[94:97], v[160:163], v[208:211], v[94:97]
	v_mfma_f32_16x16x32_bf16 v[78:81], v[160:163], v[218:221], v[78:81]
	v_mfma_f32_16x16x32_bf16 v[122:125], v[168:171], v[192:195], v[122:125]
	v_mfma_f32_16x16x32_bf16 v[106:109], v[168:171], v[200:203], v[106:109]
	v_mfma_f32_16x16x32_bf16 v[90:93], v[168:171], v[208:211], v[90:93]
	v_mfma_f32_16x16x32_bf16 v[74:77], v[168:171], v[218:221], v[74:77]
	s_setprio 0
	s_setprio 1
	v_mfma_f32_16x16x32_bf16 v[118:121], v[172:175], v[188:191], v[118:121]
	v_mfma_f32_16x16x32_bf16 v[102:105], v[172:175], v[196:199], v[102:105]
	v_mfma_f32_16x16x32_bf16 v[86:89], v[172:175], v[204:207], v[86:89]
	v_mfma_f32_16x16x32_bf16 v[70:73], v[172:175], v[212:215], v[70:73]
	v_mfma_f32_16x16x32_bf16 v[114:117], v[180:183], v[188:191], v[114:117]
	v_mfma_f32_16x16x32_bf16 v[98:101], v[180:183], v[196:199], v[98:101]
	v_mfma_f32_16x16x32_bf16 v[82:85], v[180:183], v[204:207], v[82:85]
	v_mfma_f32_16x16x32_bf16 v[66:69], v[180:183], v[212:215], v[66:69]
	v_mfma_f32_16x16x32_bf16 v[118:121], v[176:179], v[192:195], v[118:121]
	v_mfma_f32_16x16x32_bf16 v[102:105], v[176:179], v[200:203], v[102:105]
	v_mfma_f32_16x16x32_bf16 v[86:89], v[176:179], v[208:211], v[86:89]
	v_mfma_f32_16x16x32_bf16 v[70:73], v[176:179], v[218:221], v[70:73]
	v_mfma_f32_16x16x32_bf16 v[114:117], v[184:187], v[192:195], v[114:117]
	v_mfma_f32_16x16x32_bf16 v[98:101], v[184:187], v[200:203], v[98:101]
	v_mfma_f32_16x16x32_bf16 v[82:85], v[184:187], v[208:211], v[82:85]
	v_mfma_f32_16x16x32_bf16 v[66:69], v[184:187], v[218:221], v[66:69]
	s_setprio 0
	s_barrier
	s_add_i32 s53, s53, s13
	v_lshl_add_u64 v[150:151], v[150:151], 0, s[8:9]
	s_mov_b32 m0, s53
	ds_read_b128 v[188:191], v155 offset:49152
	ds_read_b128 v[192:195], v155 offset:50176
	ds_read_b128 v[196:199], v155 offset:51200
	ds_read_b128 v[200:203], v155 offset:52224
	ds_read_b128 v[204:207], v155 offset:53248
	ds_read_b128 v[208:211], v155 offset:54272
	ds_read_b128 v[212:215], v155 offset:55296
	ds_read_b128 v[218:221], v155 offset:56320
	global_load_lds_dwordx4 v[150:151], off
	s_add_i32 m0, s53, 0x2000
	s_add_u32 s34, s34, 0x20080
	v_lshl_add_u64 v[150:151], v[222:223], 0, s[8:9]
	s_addc_u32 s35, s35, 0
	s_add_i32 s53, s62, s13
	global_load_lds_dwordx4 v[150:151], off
	v_lshl_add_u64 v[150:151], s[34:35], 0, v[132:133]
	s_mov_b32 m0, s53
	s_nop 0
	global_load_lds_dwordx4 v[150:151], off
	v_lshl_add_u64 v[150:151], s[34:35], 0, v[136:137]
	s_add_i32 m0, s53, 0x2000
	s_nop 0
	global_load_lds_dwordx4 v[150:151], off
	v_lshl_add_u64 v[150:151], v[224:225], 0, s[8:9]
	s_mov_b32 m0, s60
	s_nop 0
	global_load_lds_dwordx4 v[150:151], off
	v_lshl_add_u64 v[150:151], v[226:227], 0, s[8:9]
	s_mov_b32 m0, s61
	s_nop 0
	global_load_lds_dwordx4 v[150:151], off
	s_waitcnt vmcnt(8)
	s_waitcnt lgkmcnt(0)
	s_barrier
	s_setprio 1
	s_waitcnt lgkmcnt(0)
	v_mfma_f32_16x16x32_bf16 v[62:65], v[146:149], v[188:191], v[62:65]
	v_mfma_f32_16x16x32_bf16 v[50:53], v[146:149], v[196:199], v[50:53]
	v_mfma_f32_16x16x32_bf16 v[34:37], v[146:149], v[204:207], v[34:37]
	v_mfma_f32_16x16x32_bf16 v[18:21], v[146:149], v[212:215], v[18:21]
	v_mfma_f32_16x16x32_bf16 v[58:61], v[164:167], v[188:191], v[58:61]
	v_mfma_f32_16x16x32_bf16 v[42:45], v[164:167], v[196:199], v[42:45]
	v_mfma_f32_16x16x32_bf16 v[26:29], v[164:167], v[204:207], v[26:29]
	v_mfma_f32_16x16x32_bf16 v[10:13], v[164:167], v[212:215], v[10:13]
	v_mfma_f32_16x16x32_bf16 v[62:65], v[160:163], v[192:195], v[62:65]
	v_mfma_f32_16x16x32_bf16 v[50:53], v[160:163], v[200:203], v[50:53]
	v_mfma_f32_16x16x32_bf16 v[34:37], v[160:163], v[208:211], v[34:37]
	v_mfma_f32_16x16x32_bf16 v[18:21], v[160:163], v[218:221], v[18:21]
	v_mfma_f32_16x16x32_bf16 v[58:61], v[168:171], v[192:195], v[58:61]
	v_mfma_f32_16x16x32_bf16 v[42:45], v[168:171], v[200:203], v[42:45]
	v_mfma_f32_16x16x32_bf16 v[26:29], v[168:171], v[208:211], v[26:29]
	v_mfma_f32_16x16x32_bf16 v[10:13], v[168:171], v[218:221], v[10:13]
	s_setprio 0
	s_setprio 1
	v_mfma_f32_16x16x32_bf16 v[54:57], v[172:175], v[188:191], v[54:57]
	v_mfma_f32_16x16x32_bf16 v[38:41], v[172:175], v[196:199], v[38:41]
	v_mfma_f32_16x16x32_bf16 v[22:25], v[172:175], v[204:207], v[22:25]
	v_mfma_f32_16x16x32_bf16 v[6:9], v[172:175], v[212:215], v[6:9]
	v_mfma_f32_16x16x32_bf16 v[46:49], v[180:183], v[188:191], v[46:49]
	v_mfma_f32_16x16x32_bf16 v[30:33], v[180:183], v[196:199], v[30:33]
	v_mfma_f32_16x16x32_bf16 v[14:17], v[180:183], v[204:207], v[14:17]
	v_mfma_f32_16x16x32_bf16 v[2:5], v[180:183], v[212:215], v[2:5]
	v_mfma_f32_16x16x32_bf16 v[54:57], v[176:179], v[192:195], v[54:57]
	v_mfma_f32_16x16x32_bf16 v[38:41], v[176:179], v[200:203], v[38:41]
	v_mfma_f32_16x16x32_bf16 v[22:25], v[176:179], v[208:211], v[22:25]
	v_mfma_f32_16x16x32_bf16 v[6:9], v[176:179], v[218:221], v[6:9]
	v_mfma_f32_16x16x32_bf16 v[46:49], v[184:187], v[192:195], v[46:49]
	v_mfma_f32_16x16x32_bf16 v[30:33], v[184:187], v[200:203], v[30:33]
	v_mfma_f32_16x16x32_bf16 v[14:17], v[184:187], v[208:211], v[14:17]
	v_mfma_f32_16x16x32_bf16 v[2:5], v[184:187], v[218:221], v[2:5]
	s_setprio 0
	s_barrier
	s_add_i32 s88, s88, 2
	s_add_u32 s84, s84, 0x100
	s_addc_u32 s85, s85, 0
	s_add_u32 s77, s77, 0x100
	s_addc_u32 s83, s83, 0
	s_cmp_gt_u32 s88, 5
	s_cbranch_scc0 .LBB0_715
	s_and_b64 vcc, exec, s[66:67]
	s_cbranch_vccz .LBB0_718
	s_barrier

.LBB0_995:
	ds_read_b128 v[146:149], v164
	ds_read_b128 v[150:153], v164 offset:1024
	ds_read_b128 v[154:157], v164 offset:2048
	ds_read_b128 v[158:161], v164 offset:3072
	ds_read_b128 v[168:171], v165
	ds_read_b128 v[172:175], v165 offset:1024
	ds_read_b128 v[176:179], v165 offset:2048
	ds_read_b128 v[180:183], v165 offset:3072
	s_add_u32 s34, s88, 0xfff80080
	s_addc_u32 s35, s89, -1
	s_cmp_eq_u32 s81, 28
	s_cselect_b32 s91, s0, s35
	s_cselect_b32 s90, s1, s34
	s_cselect_b32 s35, s52, s77
	s_cselect_b32 s34, s74, s75
	v_lshl_add_u64 v[218:219], s[88:89], 0, v[138:139]
	s_add_i32 m0, s33, 0xc000
	ds_read_b128 v[184:187], v166
	ds_read_b128 v[188:191], v166 offset:1024
	ds_read_b128 v[192:195], v166 offset:2048
	ds_read_b128 v[196:199], v166 offset:3072
	ds_read_b128 v[200:203], v166 offset:4096
	ds_read_b128 v[204:207], v166 offset:5120
	ds_read_b128 v[208:211], v166 offset:6144
	ds_read_b128 v[212:215], v166 offset:7168
	global_load_lds_dwordx4 v[218:219], off
	v_lshl_add_u64 v[218:219], s[88:89], 0, v[140:141]
	s_add_i32 m0, s33, 0xe000
	s_nop 0
	global_load_lds_dwordx4 v[218:219], off
	s_waitcnt vmcnt(8)
	s_waitcnt lgkmcnt(0)
	s_barrier
	s_setprio 1
	s_waitcnt lgkmcnt(0)
	v_mfma_f32_16x16x32_bf16 v[126:129], v[146:149], v[184:187], v[126:129]
	v_mfma_f32_16x16x32_bf16 v[110:113], v[146:149], v[192:195], v[110:113]
	v_mfma_f32_16x16x32_bf16 v[94:97], v[146:149], v[200:203], v[94:97]
	v_mfma_f32_16x16x32_bf16 v[78:81], v[146:149], v[208:211], v[78:81]
	v_mfma_f32_16x16x32_bf16 v[122:125], v[154:157], v[184:187], v[122:125]
	v_mfma_f32_16x16x32_bf16 v[106:109], v[154:157], v[192:195], v[106:109]
	v_mfma_f32_16x16x32_bf16 v[90:93], v[154:157], v[200:203], v[90:93]
	v_mfma_f32_16x16x32_bf16 v[74:77], v[154:157], v[208:211], v[74:77]
	v_mfma_f32_16x16x32_bf16 v[126:129], v[150:153], v[188:191], v[126:129]
	v_mfma_f32_16x16x32_bf16 v[110:113], v[150:153], v[196:199], v[110:113]
	v_mfma_f32_16x16x32_bf16 v[94:97], v[150:153], v[204:207], v[94:97]
	v_mfma_f32_16x16x32_bf16 v[78:81], v[150:153], v[212:215], v[78:81]
	v_mfma_f32_16x16x32_bf16 v[122:125], v[158:161], v[188:191], v[122:125]
	v_mfma_f32_16x16x32_bf16 v[106:109], v[158:161], v[196:199], v[106:109]
	v_mfma_f32_16x16x32_bf16 v[90:93], v[158:161], v[204:207], v[90:93]
	v_mfma_f32_16x16x32_bf16 v[74:77], v[158:161], v[212:215], v[74:77]
	s_setprio 0
	s_setprio 1
	v_mfma_f32_16x16x32_bf16 v[118:121], v[168:171], v[184:187], v[118:121]
	v_mfma_f32_16x16x32_bf16 v[102:105], v[168:171], v[192:195], v[102:105]
	v_mfma_f32_16x16x32_bf16 v[86:89], v[168:171], v[200:203], v[86:89]
	v_mfma_f32_16x16x32_bf16 v[70:73], v[168:171], v[208:211], v[70:73]
	v_mfma_f32_16x16x32_bf16 v[114:117], v[176:179], v[184:187], v[114:117]
	v_mfma_f32_16x16x32_bf16 v[98:101], v[176:179], v[192:195], v[98:101]
	v_mfma_f32_16x16x32_bf16 v[82:85], v[176:179], v[200:203], v[82:85]
	v_mfma_f32_16x16x32_bf16 v[66:69], v[176:179], v[208:211], v[66:69]
	v_mfma_f32_16x16x32_bf16 v[118:121], v[172:175], v[188:191], v[118:121]
	v_mfma_f32_16x16x32_bf16 v[102:105], v[172:175], v[196:199], v[102:105]
	v_mfma_f32_16x16x32_bf16 v[86:89], v[172:175], v[204:207], v[86:89]
	v_mfma_f32_16x16x32_bf16 v[70:73], v[172:175], v[212:215], v[70:73]
	v_mfma_f32_16x16x32_bf16 v[114:117], v[180:183], v[188:191], v[114:117]
	v_mfma_f32_16x16x32_bf16 v[98:101], v[180:183], v[196:199], v[98:101]
	v_mfma_f32_16x16x32_bf16 v[82:85], v[180:183], v[204:207], v[82:85]
	v_mfma_f32_16x16x32_bf16 v[66:69], v[180:183], v[212:215], v[66:69]
	s_setprio 0
	s_barrier
	s_add_i32 s53, s71, s31
	v_lshl_add_u64 v[218:219], s[34:35], 0, v[132:133]
	s_mov_b32 m0, s53
	ds_read_b128 v[184:187], v166 offset:16384
	ds_read_b128 v[188:191], v166 offset:17408
	ds_read_b128 v[192:195], v166 offset:18432
	ds_read_b128 v[196:199], v166 offset:19456
	ds_read_b128 v[200:203], v166 offset:20480
	ds_read_b128 v[204:207], v166 offset:21504
	ds_read_b128 v[208:211], v166 offset:22528
	ds_read_b128 v[212:215], v166 offset:23552
	global_load_lds_dwordx4 v[218:219], off
	s_add_i32 m0, s53, 0x2000
	s_add_u32 s54, s34, 0x80000
	v_lshl_add_u64 v[220:221], s[34:35], 0, v[136:137]
	s_addc_u32 s55, s35, 0
	s_add_i32 s53, s72, s31
	global_load_lds_dwordx4 v[220:221], off
	v_lshl_add_u64 v[222:223], s[54:55], 0, v[132:133]
	s_mov_b32 m0, s53
	v_lshl_add_u64 v[224:225], s[90:91], 0, v[134:135]
	global_load_lds_dwordx4 v[222:223], off
	v_lshl_add_u64 v[222:223], s[54:55], 0, v[136:137]
	s_add_i32 m0, s53, 0x2000
	s_nop 0
	global_load_lds_dwordx4 v[222:223], off
	v_lshl_add_u64 v[222:223], s[90:91], 0, v[130:131]
	s_mov_b32 m0, s33
	s_nop 0
	global_load_lds_dwordx4 v[222:223], off
	s_mov_b32 m0, s56
	s_nop 0
	global_load_lds_dwordx4 v[224:225], off
	s_waitcnt vmcnt(8)
	s_waitcnt lgkmcnt(0)
	s_barrier
	s_setprio 1
	s_waitcnt lgkmcnt(0)
	v_mfma_f32_16x16x32_bf16 v[62:65], v[146:149], v[184:187], v[62:65]
	v_mfma_f32_16x16x32_bf16 v[46:49], v[146:149], v[192:195], v[46:49]
	v_mfma_f32_16x16x32_bf16 v[30:33], v[146:149], v[200:203], v[30:33]
	v_mfma_f32_16x16x32_bf16 v[14:17], v[146:149], v[208:211], v[14:17]
	v_mfma_f32_16x16x32_bf16 v[58:61], v[154:157], v[184:187], v[58:61]
	v_mfma_f32_16x16x32_bf16 v[42:45], v[154:157], v[192:195], v[42:45]
	v_mfma_f32_16x16x32_bf16 v[26:29], v[154:157], v[200:203], v[26:29]
	v_mfma_f32_16x16x32_bf16 v[10:13], v[154:157], v[208:211], v[10:13]
	v_mfma_f32_16x16x32_bf16 v[62:65], v[150:153], v[188:191], v[62:65]
	v_mfma_f32_16x16x32_bf16 v[46:49], v[150:153], v[196:199], v[46:49]
	v_mfma_f32_16x16x32_bf16 v[30:33], v[150:153], v[204:207], v[30:33]
	v_mfma_f32_16x16x32_bf16 v[14:17], v[150:153], v[212:215], v[14:17]
	v_mfma_f32_16x16x32_bf16 v[58:61], v[158:161], v[188:191], v[58:61]
	v_mfma_f32_16x16x32_bf16 v[42:45], v[158:161], v[196:199], v[42:45]
	v_mfma_f32_16x16x32_bf16 v[26:29], v[158:161], v[204:207], v[26:29]
	v_mfma_f32_16x16x32_bf16 v[10:13], v[158:161], v[212:215], v[10:13]
	s_setprio 0
	s_setprio 1
	v_mfma_f32_16x16x32_bf16 v[54:57], v[168:171], v[184:187], v[54:57]
	v_mfma_f32_16x16x32_bf16 v[38:41], v[168:171], v[192:195], v[38:41]
	v_mfma_f32_16x16x32_bf16 v[22:25], v[168:171], v[200:203], v[22:25]
	v_mfma_f32_16x16x32_bf16 v[6:9], v[168:171], v[208:211], v[6:9]
	v_mfma_f32_16x16x32_bf16 v[50:53], v[176:179], v[184:187], v[50:53]
	v_mfma_f32_16x16x32_bf16 v[34:37], v[176:179], v[192:195], v[34:37]
	v_mfma_f32_16x16x32_bf16 v[18:21], v[176:179], v[200:203], v[18:21]
	v_mfma_f32_16x16x32_bf16 v[2:5], v[176:179], v[208:211], v[2:5]
	v_mfma_f32_16x16x32_bf16 v[54:57], v[172:175], v[188:191], v[54:57]
	v_mfma_f32_16x16x32_bf16 v[38:41], v[172:175], v[196:199], v[38:41]
	v_mfma_f32_16x16x32_bf16 v[22:25], v[172:175], v[204:207], v[22:25]
	v_mfma_f32_16x16x32_bf16 v[6:9], v[172:175], v[212:215], v[6:9]
	v_mfma_f32_16x16x32_bf16 v[50:53], v[180:183], v[188:191], v[50:53]
	v_mfma_f32_16x16x32_bf16 v[34:37], v[180:183], v[196:199], v[34:37]
	v_mfma_f32_16x16x32_bf16 v[18:21], v[180:183], v[204:207], v[18:21]
	v_mfma_f32_16x16x32_bf16 v[2:5], v[180:183], v[212:215], v[2:5]
	s_setprio 0
	s_barrier
	s_add_i32 s53, 0, 0x18000
	s_add_i32 s62, 0, 0x1c000
	v_add_u32_e32 v158, s53, v162
	v_add_u32_e32 v167, s62, v162
	ds_read_b128 v[146:149], v158
	ds_read_b128 v[150:153], v158 offset:1024
	ds_read_b128 v[154:157], v158 offset:2048
	ds_read_b128 v[158:161], v158 offset:3072
	ds_read_b128 v[168:171], v167
	ds_read_b128 v[172:175], v167 offset:1024
	ds_read_b128 v[176:179], v167 offset:2048
	ds_read_b128 v[180:183], v167 offset:3072
	s_add_u32 s54, s90, 0x80000
	s_addc_u32 s55, s91, 0
	s_mov_b32 m0, s57
	v_lshl_add_u64 v[226:227], s[54:55], 0, v[130:131]
	ds_read_b128 v[184:187], v166 offset:32768
	ds_read_b128 v[188:191], v166 offset:33792
	ds_read_b128 v[192:195], v166 offset:34816
	ds_read_b128 v[196:199], v166 offset:35840
	ds_read_b128 v[200:203], v166 offset:36864
	ds_read_b128 v[204:207], v166 offset:37888
	ds_read_b128 v[208:211], v166 offset:38912
	ds_read_b128 v[212:215], v166 offset:39936
	global_load_lds_dwordx4 v[226:227], off
	v_lshl_add_u64 v[226:227], s[54:55], 0, v[134:135]
	s_mov_b32 m0, s58
	s_nop 0
	global_load_lds_dwordx4 v[226:227], off
	s_waitcnt vmcnt(8)
	s_waitcnt lgkmcnt(0)
	s_barrier
	s_setprio 1
	s_waitcnt lgkmcnt(0)
	v_mfma_f32_16x16x32_bf16 v[126:129], v[146:149], v[184:187], v[126:129]
	v_mfma_f32_16x16x32_bf16 v[110:113], v[146:149], v[192:195], v[110:113]
	v_mfma_f32_16x16x32_bf16 v[94:97], v[146:149], v[200:203], v[94:97]
	v_mfma_f32_16x16x32_bf16 v[78:81], v[146:149], v[208:211], v[78:81]
	v_mfma_f32_16x16x32_bf16 v[122:125], v[154:157], v[184:187], v[122:125]
	v_mfma_f32_16x16x32_bf16 v[106:109], v[154:157], v[192:195], v[106:109]
	v_mfma_f32_16x16x32_bf16 v[90:93], v[154:157], v[200:203], v[90:93]
	v_mfma_f32_16x16x32_bf16 v[74:77], v[154:157], v[208:211], v[74:77]
	v_mfma_f32_16x16x32_bf16 v[126:129], v[150:153], v[188:191], v[126:129]
	v_mfma_f32_16x16x32_bf16 v[110:113], v[150:153], v[196:199], v[110:113]
	v_mfma_f32_16x16x32_bf16 v[94:97], v[150:153], v[204:207], v[94:97]
	v_mfma_f32_16x16x32_bf16 v[78:81], v[150:153], v[212:215], v[78:81]
	v_mfma_f32_16x16x32_bf16 v[122:125], v[158:161], v[188:191], v[122:125]
	v_mfma_f32_16x16x32_bf16 v[106:109], v[158:161], v[196:199], v[106:109]
	v_mfma_f32_16x16x32_bf16 v[90:93], v[158:161], v[204:207], v[90:93]
	v_mfma_f32_16x16x32_bf16 v[74:77], v[158:161], v[212:215], v[74:77]
	s_setprio 0
	s_setprio 1
	v_mfma_f32_16x16x32_bf16 v[118:121], v[168:171], v[184:187], v[118:121]
	v_mfma_f32_16x16x32_bf16 v[102:105], v[168:171], v[192:195], v[102:105]
	v_mfma_f32_16x16x32_bf16 v[86:89], v[168:171], v[200:203], v[86:89]
	v_mfma_f32_16x16x32_bf16 v[70:73], v[168:171], v[208:211], v[70:73]
	v_mfma_f32_16x16x32_bf16 v[114:117], v[176:179], v[184:187], v[114:117]
	v_mfma_f32_16x16x32_bf16 v[98:101], v[176:179], v[192:195], v[98:101]
	v_mfma_f32_16x16x32_bf16 v[82:85], v[176:179], v[200:203], v[82:85]
	v_mfma_f32_16x16x32_bf16 v[66:69], v[176:179], v[208:211], v[66:69]
	v_mfma_f32_16x16x32_bf16 v[118:121], v[172:175], v[188:191], v[118:121]
	v_mfma_f32_16x16x32_bf16 v[102:105], v[172:175], v[196:199], v[102:105]
	v_mfma_f32_16x16x32_bf16 v[86:89], v[172:175], v[204:207], v[86:89]
	v_mfma_f32_16x16x32_bf16 v[70:73], v[172:175], v[212:215], v[70:73]
	v_mfma_f32_16x16x32_bf16 v[114:117], v[180:183], v[188:191], v[114:117]
	v_mfma_f32_16x16x32_bf16 v[98:101], v[180:183], v[196:199], v[98:101]
	v_mfma_f32_16x16x32_bf16 v[82:85], v[180:183], v[204:207], v[82:85]
	v_mfma_f32_16x16x32_bf16 v[66:69], v[180:183], v[212:215], v[66:69]
	s_setprio 0
	s_barrier
	s_add_i32 s53, s53, s31
	v_lshl_add_u64 v[218:219], v[218:219], 0, s[8:9]
	s_mov_b32 m0, s53
	ds_read_b128 v[184:187], v166 offset:49152
	ds_read_b128 v[188:191], v166 offset:50176
	ds_read_b128 v[192:195], v166 offset:51200
	ds_read_b128 v[196:199], v166 offset:52224
	ds_read_b128 v[200:203], v166 offset:53248
	ds_read_b128 v[204:207], v166 offset:54272
	ds_read_b128 v[208:211], v166 offset:55296
	ds_read_b128 v[212:215], v166 offset:56320
	global_load_lds_dwordx4 v[218:219], off
	s_add_i32 m0, s53, 0x2000
	s_add_u32 s34, s34, 0x80080
	v_lshl_add_u64 v[218:219], v[220:221], 0, s[8:9]
	s_addc_u32 s35, s35, 0
	s_add_i32 s53, s62, s31
	global_load_lds_dwordx4 v[218:219], off
	v_lshl_add_u64 v[218:219], s[34:35], 0, v[132:133]
	s_mov_b32 m0, s53
	s_nop 0
	global_load_lds_dwordx4 v[218:219], off
	v_lshl_add_u64 v[218:219], s[34:35], 0, v[136:137]
	s_add_i32 m0, s53, 0x2000
	s_nop 0
	global_load_lds_dwordx4 v[218:219], off
	v_lshl_add_u64 v[218:219], v[222:223], 0, s[8:9]
	s_mov_b32 m0, s60
	s_nop 0
	global_load_lds_dwordx4 v[218:219], off
	v_lshl_add_u64 v[218:219], v[224:225], 0, s[8:9]
	s_mov_b32 m0, s61
	s_nop 0
	global_load_lds_dwordx4 v[218:219], off
	s_waitcnt vmcnt(8)
	s_waitcnt lgkmcnt(0)
	s_barrier
	s_setprio 1
	s_waitcnt lgkmcnt(0)
	v_mfma_f32_16x16x32_bf16 v[62:65], v[146:149], v[184:187], v[62:65]
	v_mfma_f32_16x16x32_bf16 v[46:49], v[146:149], v[192:195], v[46:49]
	v_mfma_f32_16x16x32_bf16 v[30:33], v[146:149], v[200:203], v[30:33]
	v_mfma_f32_16x16x32_bf16 v[14:17], v[146:149], v[208:211], v[14:17]
	v_mfma_f32_16x16x32_bf16 v[58:61], v[154:157], v[184:187], v[58:61]
	v_mfma_f32_16x16x32_bf16 v[42:45], v[154:157], v[192:195], v[42:45]
	v_mfma_f32_16x16x32_bf16 v[26:29], v[154:157], v[200:203], v[26:29]
	v_mfma_f32_16x16x32_bf16 v[10:13], v[154:157], v[208:211], v[10:13]
	v_mfma_f32_16x16x32_bf16 v[62:65], v[150:153], v[188:191], v[62:65]
	v_mfma_f32_16x16x32_bf16 v[46:49], v[150:153], v[196:199], v[46:49]
	v_mfma_f32_16x16x32_bf16 v[30:33], v[150:153], v[204:207], v[30:33]
	v_mfma_f32_16x16x32_bf16 v[14:17], v[150:153], v[212:215], v[14:17]
	v_mfma_f32_16x16x32_bf16 v[58:61], v[158:161], v[188:191], v[58:61]
	v_mfma_f32_16x16x32_bf16 v[42:45], v[158:161], v[196:199], v[42:45]
	v_mfma_f32_16x16x32_bf16 v[26:29], v[158:161], v[204:207], v[26:29]
	v_mfma_f32_16x16x32_bf16 v[10:13], v[158:161], v[212:215], v[10:13]
	s_setprio 0
	s_setprio 1
	v_mfma_f32_16x16x32_bf16 v[54:57], v[168:171], v[184:187], v[54:57]
	v_mfma_f32_16x16x32_bf16 v[38:41], v[168:171], v[192:195], v[38:41]
	v_mfma_f32_16x16x32_bf16 v[22:25], v[168:171], v[200:203], v[22:25]
	v_mfma_f32_16x16x32_bf16 v[6:9], v[168:171], v[208:211], v[6:9]
	v_mfma_f32_16x16x32_bf16 v[50:53], v[176:179], v[184:187], v[50:53]
	v_mfma_f32_16x16x32_bf16 v[34:37], v[176:179], v[192:195], v[34:37]
	v_mfma_f32_16x16x32_bf16 v[18:21], v[176:179], v[200:203], v[18:21]
	v_mfma_f32_16x16x32_bf16 v[2:5], v[176:179], v[208:211], v[2:5]
	v_mfma_f32_16x16x32_bf16 v[54:57], v[172:175], v[188:191], v[54:57]
	v_mfma_f32_16x16x32_bf16 v[38:41], v[172:175], v[196:199], v[38:41]
	v_mfma_f32_16x16x32_bf16 v[22:25], v[172:175], v[204:207], v[22:25]
	v_mfma_f32_16x16x32_bf16 v[6:9], v[172:175], v[212:215], v[6:9]
	v_mfma_f32_16x16x32_bf16 v[50:53], v[180:183], v[188:191], v[50:53]
	v_mfma_f32_16x16x32_bf16 v[34:37], v[180:183], v[196:199], v[34:37]
	v_mfma_f32_16x16x32_bf16 v[18:21], v[180:183], v[204:207], v[18:21]
	v_mfma_f32_16x16x32_bf16 v[2:5], v[180:183], v[212:215], v[2:5]
	s_setprio 0
	s_barrier
	s_add_i32 s81, s81, 2
	s_add_u32 s88, s88, 0x100
	s_addc_u32 s89, s89, 0
	s_add_u32 s75, s75, 0x100
	s_addc_u32 s77, s77, 0
	s_cmp_gt_u32 s81, 29
	s_cbranch_scc0 .LBB0_995
	s_and_b64 vcc, exec, s[78:79]
	s_cbranch_vccz .LBB0_998
	s_barrier

.LBB0_1124:
	ds_read_b128 v[146:149], v153
	ds_read_b128 v[156:159], v153 offset:1024
	ds_read_b128 v[160:163], v153 offset:2048
	ds_read_b128 v[164:167], v153 offset:3072
	ds_read_b128 v[168:171], v154
	ds_read_b128 v[172:175], v154 offset:1024
	ds_read_b128 v[176:179], v154 offset:2048
	ds_read_b128 v[180:183], v154 offset:3072
	s_add_u32 s34, s88, 0xfff80080
	s_addc_u32 s35, s89, -1
	s_cmp_eq_u32 s92, 28
	s_cselect_b32 s91, s0, s35
	s_cselect_b32 s90, s1, s34
	s_cselect_b32 s35, s52, s83
	s_cselect_b32 s34, s77, s81
	v_lshl_add_u64 v[218:219], s[88:89], 0, v[138:139]
	s_add_i32 m0, s56, 0xc000
	ds_read_b128 v[184:187], v155
	ds_read_b128 v[188:191], v155 offset:1024
	ds_read_b128 v[192:195], v155 offset:2048
	ds_read_b128 v[196:199], v155 offset:3072
	ds_read_b128 v[200:203], v155 offset:4096
	ds_read_b128 v[204:207], v155 offset:5120
	ds_read_b128 v[208:211], v155 offset:6144
	ds_read_b128 v[212:215], v155 offset:7168
	global_load_lds_dwordx4 v[218:219], off
	v_lshl_add_u64 v[218:219], s[88:89], 0, v[140:141]
	s_add_i32 m0, s56, 0xe000
	s_nop 0
	global_load_lds_dwordx4 v[218:219], off
	s_waitcnt vmcnt(8)
	s_waitcnt lgkmcnt(0)
	s_barrier
	s_setprio 1
	s_waitcnt lgkmcnt(0)
	v_mfma_f32_16x16x32_bf16 v[126:129], v[146:149], v[184:187], v[126:129]
	v_mfma_f32_16x16x32_bf16 v[110:113], v[146:149], v[192:195], v[110:113]
	v_mfma_f32_16x16x32_bf16 v[94:97], v[146:149], v[200:203], v[94:97]
	v_mfma_f32_16x16x32_bf16 v[78:81], v[146:149], v[208:211], v[78:81]
	v_mfma_f32_16x16x32_bf16 v[118:121], v[160:163], v[184:187], v[118:121]
	v_mfma_f32_16x16x32_bf16 v[102:105], v[160:163], v[192:195], v[102:105]
	v_mfma_f32_16x16x32_bf16 v[86:89], v[160:163], v[200:203], v[86:89]
	v_mfma_f32_16x16x32_bf16 v[70:73], v[160:163], v[208:211], v[70:73]
	v_mfma_f32_16x16x32_bf16 v[126:129], v[156:159], v[188:191], v[126:129]
	v_mfma_f32_16x16x32_bf16 v[110:113], v[156:159], v[196:199], v[110:113]
	v_mfma_f32_16x16x32_bf16 v[94:97], v[156:159], v[204:207], v[94:97]
	v_mfma_f32_16x16x32_bf16 v[78:81], v[156:159], v[212:215], v[78:81]
	v_mfma_f32_16x16x32_bf16 v[118:121], v[164:167], v[188:191], v[118:121]
	v_mfma_f32_16x16x32_bf16 v[102:105], v[164:167], v[196:199], v[102:105]
	v_mfma_f32_16x16x32_bf16 v[86:89], v[164:167], v[204:207], v[86:89]
	v_mfma_f32_16x16x32_bf16 v[70:73], v[164:167], v[212:215], v[70:73]
	s_setprio 0
	s_setprio 1
	v_mfma_f32_16x16x32_bf16 v[122:125], v[168:171], v[184:187], v[122:125]
	v_mfma_f32_16x16x32_bf16 v[106:109], v[168:171], v[192:195], v[106:109]
	v_mfma_f32_16x16x32_bf16 v[90:93], v[168:171], v[200:203], v[90:93]
	v_mfma_f32_16x16x32_bf16 v[74:77], v[168:171], v[208:211], v[74:77]
	v_mfma_f32_16x16x32_bf16 v[114:117], v[176:179], v[184:187], v[114:117]
	v_mfma_f32_16x16x32_bf16 v[98:101], v[176:179], v[192:195], v[98:101]
	v_mfma_f32_16x16x32_bf16 v[82:85], v[176:179], v[200:203], v[82:85]
	v_mfma_f32_16x16x32_bf16 v[66:69], v[176:179], v[208:211], v[66:69]
	v_mfma_f32_16x16x32_bf16 v[122:125], v[172:175], v[188:191], v[122:125]
	v_mfma_f32_16x16x32_bf16 v[106:109], v[172:175], v[196:199], v[106:109]
	v_mfma_f32_16x16x32_bf16 v[90:93], v[172:175], v[204:207], v[90:93]
	v_mfma_f32_16x16x32_bf16 v[74:77], v[172:175], v[212:215], v[74:77]
	v_mfma_f32_16x16x32_bf16 v[114:117], v[180:183], v[188:191], v[114:117]
	v_mfma_f32_16x16x32_bf16 v[98:101], v[180:183], v[196:199], v[98:101]
	v_mfma_f32_16x16x32_bf16 v[82:85], v[180:183], v[204:207], v[82:85]
	v_mfma_f32_16x16x32_bf16 v[66:69], v[180:183], v[212:215], v[66:69]
	s_setprio 0
	s_barrier
	s_add_i32 s53, s72, s30
	v_lshl_add_u64 v[218:219], s[34:35], 0, v[134:135]
	s_mov_b32 m0, s53
	ds_read_b128 v[184:187], v155 offset:16384
	ds_read_b128 v[188:191], v155 offset:17408
	ds_read_b128 v[192:195], v155 offset:18432
	ds_read_b128 v[196:199], v155 offset:19456
	ds_read_b128 v[200:203], v155 offset:20480
	ds_read_b128 v[204:207], v155 offset:21504
	ds_read_b128 v[208:211], v155 offset:22528
	ds_read_b128 v[212:215], v155 offset:23552
	global_load_lds_dwordx4 v[218:219], off
	s_add_i32 m0, s53, 0x2000
	s_add_u32 s54, s34, 0x80000
	v_lshl_add_u64 v[220:221], s[34:35], 0, v[130:131]
	s_addc_u32 s55, s35, 0
	s_add_i32 s53, s73, s30
	global_load_lds_dwordx4 v[220:221], off
	v_lshl_add_u64 v[222:223], s[54:55], 0, v[134:135]
	s_mov_b32 m0, s53
	v_lshl_add_u64 v[224:225], s[90:91], 0, v[132:133]
	global_load_lds_dwordx4 v[222:223], off
	v_lshl_add_u64 v[222:223], s[54:55], 0, v[130:131]
	s_add_i32 m0, s53, 0x2000
	s_nop 0
	global_load_lds_dwordx4 v[222:223], off
	v_lshl_add_u64 v[222:223], s[90:91], 0, v[136:137]
	s_mov_b32 m0, s56
	s_nop 0
	global_load_lds_dwordx4 v[222:223], off
	s_mov_b32 m0, s57
	s_nop 0
	global_load_lds_dwordx4 v[224:225], off
	s_waitcnt vmcnt(8)
	s_waitcnt lgkmcnt(0)
	s_barrier
	s_setprio 1
	s_waitcnt lgkmcnt(0)
	v_mfma_f32_16x16x32_bf16 v[62:65], v[146:149], v[184:187], v[62:65]
	v_mfma_f32_16x16x32_bf16 v[46:49], v[146:149], v[192:195], v[46:49]
	v_mfma_f32_16x16x32_bf16 v[30:33], v[146:149], v[200:203], v[30:33]
	v_mfma_f32_16x16x32_bf16 v[14:17], v[146:149], v[208:211], v[14:17]
	v_mfma_f32_16x16x32_bf16 v[54:57], v[160:163], v[184:187], v[54:57]
	v_mfma_f32_16x16x32_bf16 v[38:41], v[160:163], v[192:195], v[38:41]
	v_mfma_f32_16x16x32_bf16 v[22:25], v[160:163], v[200:203], v[22:25]
	v_mfma_f32_16x16x32_bf16 v[6:9], v[160:163], v[208:211], v[6:9]
	v_mfma_f32_16x16x32_bf16 v[62:65], v[156:159], v[188:191], v[62:65]
	v_mfma_f32_16x16x32_bf16 v[46:49], v[156:159], v[196:199], v[46:49]
	v_mfma_f32_16x16x32_bf16 v[30:33], v[156:159], v[204:207], v[30:33]
	v_mfma_f32_16x16x32_bf16 v[14:17], v[156:159], v[212:215], v[14:17]
	v_mfma_f32_16x16x32_bf16 v[54:57], v[164:167], v[188:191], v[54:57]
	v_mfma_f32_16x16x32_bf16 v[38:41], v[164:167], v[196:199], v[38:41]
	v_mfma_f32_16x16x32_bf16 v[22:25], v[164:167], v[204:207], v[22:25]
	v_mfma_f32_16x16x32_bf16 v[6:9], v[164:167], v[212:215], v[6:9]
	s_setprio 0
	s_setprio 1
	v_mfma_f32_16x16x32_bf16 v[58:61], v[168:171], v[184:187], v[58:61]
	v_mfma_f32_16x16x32_bf16 v[42:45], v[168:171], v[192:195], v[42:45]
	v_mfma_f32_16x16x32_bf16 v[26:29], v[168:171], v[200:203], v[26:29]
	v_mfma_f32_16x16x32_bf16 v[10:13], v[168:171], v[208:211], v[10:13]
	v_mfma_f32_16x16x32_bf16 v[50:53], v[176:179], v[184:187], v[50:53]
	v_mfma_f32_16x16x32_bf16 v[34:37], v[176:179], v[192:195], v[34:37]
	v_mfma_f32_16x16x32_bf16 v[18:21], v[176:179], v[200:203], v[18:21]
	v_mfma_f32_16x16x32_bf16 v[2:5], v[176:179], v[208:211], v[2:5]
	v_mfma_f32_16x16x32_bf16 v[58:61], v[172:175], v[188:191], v[58:61]
	v_mfma_f32_16x16x32_bf16 v[42:45], v[172:175], v[196:199], v[42:45]
	v_mfma_f32_16x16x32_bf16 v[26:29], v[172:175], v[204:207], v[26:29]
	v_mfma_f32_16x16x32_bf16 v[10:13], v[172:175], v[212:215], v[10:13]
	v_mfma_f32_16x16x32_bf16 v[50:53], v[180:183], v[188:191], v[50:53]
	v_mfma_f32_16x16x32_bf16 v[34:37], v[180:183], v[196:199], v[34:37]
	v_mfma_f32_16x16x32_bf16 v[18:21], v[180:183], v[204:207], v[18:21]
	v_mfma_f32_16x16x32_bf16 v[2:5], v[180:183], v[212:215], v[2:5]
	s_setprio 0
	s_barrier
	s_add_i32 s53, 0, 0x18000
	s_add_i32 s62, 0, 0x1c000
	v_add_u32_e32 v164, s53, v151
	v_add_u32_e32 v180, s62, v151
	ds_read_b128 v[146:149], v164
	ds_read_b128 v[156:159], v164 offset:1024
	ds_read_b128 v[160:163], v164 offset:2048
	ds_read_b128 v[164:167], v164 offset:3072
	ds_read_b128 v[168:171], v180
	ds_read_b128 v[172:175], v180 offset:1024
	ds_read_b128 v[176:179], v180 offset:2048
	ds_read_b128 v[180:183], v180 offset:3072
	s_add_u32 s54, s90, 0x80000
	s_addc_u32 s55, s91, 0
	s_mov_b32 m0, s58
	v_lshl_add_u64 v[226:227], s[54:55], 0, v[136:137]
	ds_read_b128 v[184:187], v155 offset:32768
	ds_read_b128 v[188:191], v155 offset:33792
	ds_read_b128 v[192:195], v155 offset:34816
	ds_read_b128 v[196:199], v155 offset:35840
	ds_read_b128 v[200:203], v155 offset:36864
	ds_read_b128 v[204:207], v155 offset:37888
	ds_read_b128 v[208:211], v155 offset:38912
	ds_read_b128 v[212:215], v155 offset:39936
	global_load_lds_dwordx4 v[226:227], off
	v_lshl_add_u64 v[226:227], s[54:55], 0, v[132:133]
	s_mov_b32 m0, s59
	s_nop 0
	global_load_lds_dwordx4 v[226:227], off
	s_waitcnt vmcnt(8)
	s_waitcnt lgkmcnt(0)
	s_barrier
	s_setprio 1
	s_waitcnt lgkmcnt(0)
	v_mfma_f32_16x16x32_bf16 v[126:129], v[146:149], v[184:187], v[126:129]
	v_mfma_f32_16x16x32_bf16 v[110:113], v[146:149], v[192:195], v[110:113]
	v_mfma_f32_16x16x32_bf16 v[94:97], v[146:149], v[200:203], v[94:97]
	v_mfma_f32_16x16x32_bf16 v[78:81], v[146:149], v[208:211], v[78:81]
	v_mfma_f32_16x16x32_bf16 v[118:121], v[160:163], v[184:187], v[118:121]
	v_mfma_f32_16x16x32_bf16 v[102:105], v[160:163], v[192:195], v[102:105]
	v_mfma_f32_16x16x32_bf16 v[86:89], v[160:163], v[200:203], v[86:89]
	v_mfma_f32_16x16x32_bf16 v[70:73], v[160:163], v[208:211], v[70:73]
	v_mfma_f32_16x16x32_bf16 v[126:129], v[156:159], v[188:191], v[126:129]
	v_mfma_f32_16x16x32_bf16 v[110:113], v[156:159], v[196:199], v[110:113]
	v_mfma_f32_16x16x32_bf16 v[94:97], v[156:159], v[204:207], v[94:97]
	v_mfma_f32_16x16x32_bf16 v[78:81], v[156:159], v[212:215], v[78:81]
	v_mfma_f32_16x16x32_bf16 v[118:121], v[164:167], v[188:191], v[118:121]
	v_mfma_f32_16x16x32_bf16 v[102:105], v[164:167], v[196:199], v[102:105]
	v_mfma_f32_16x16x32_bf16 v[86:89], v[164:167], v[204:207], v[86:89]
	v_mfma_f32_16x16x32_bf16 v[70:73], v[164:167], v[212:215], v[70:73]
	s_setprio 0
	s_setprio 1
	v_mfma_f32_16x16x32_bf16 v[122:125], v[168:171], v[184:187], v[122:125]
	v_mfma_f32_16x16x32_bf16 v[106:109], v[168:171], v[192:195], v[106:109]
	v_mfma_f32_16x16x32_bf16 v[90:93], v[168:171], v[200:203], v[90:93]
	v_mfma_f32_16x16x32_bf16 v[74:77], v[168:171], v[208:211], v[74:77]
	v_mfma_f32_16x16x32_bf16 v[114:117], v[176:179], v[184:187], v[114:117]
	v_mfma_f32_16x16x32_bf16 v[98:101], v[176:179], v[192:195], v[98:101]
	v_mfma_f32_16x16x32_bf16 v[82:85], v[176:179], v[200:203], v[82:85]
	v_mfma_f32_16x16x32_bf16 v[66:69], v[176:179], v[208:211], v[66:69]
	v_mfma_f32_16x16x32_bf16 v[122:125], v[172:175], v[188:191], v[122:125]
	v_mfma_f32_16x16x32_bf16 v[106:109], v[172:175], v[196:199], v[106:109]
	v_mfma_f32_16x16x32_bf16 v[90:93], v[172:175], v[204:207], v[90:93]
	v_mfma_f32_16x16x32_bf16 v[74:77], v[172:175], v[212:215], v[74:77]
	v_mfma_f32_16x16x32_bf16 v[114:117], v[180:183], v[188:191], v[114:117]
	v_mfma_f32_16x16x32_bf16 v[98:101], v[180:183], v[196:199], v[98:101]
	v_mfma_f32_16x16x32_bf16 v[82:85], v[180:183], v[204:207], v[82:85]
	v_mfma_f32_16x16x32_bf16 v[66:69], v[180:183], v[212:215], v[66:69]
	s_setprio 0
	s_barrier
	s_add_i32 s53, s53, s30
	v_lshl_add_u64 v[218:219], v[218:219], 0, s[8:9]
	s_mov_b32 m0, s53
	ds_read_b128 v[184:187], v155 offset:49152
	ds_read_b128 v[188:191], v155 offset:50176
	ds_read_b128 v[192:195], v155 offset:51200
	ds_read_b128 v[196:199], v155 offset:52224
	ds_read_b128 v[200:203], v155 offset:53248
	ds_read_b128 v[204:207], v155 offset:54272
	ds_read_b128 v[208:211], v155 offset:55296
	ds_read_b128 v[212:215], v155 offset:56320
	global_load_lds_dwordx4 v[218:219], off
	s_add_i32 m0, s53, 0x2000
	s_add_u32 s34, s34, 0x80080
	v_lshl_add_u64 v[218:219], v[220:221], 0, s[8:9]
	s_addc_u32 s35, s35, 0
	s_add_i32 s53, s62, s30
	global_load_lds_dwordx4 v[218:219], off
	v_lshl_add_u64 v[218:219], s[34:35], 0, v[134:135]
	s_mov_b32 m0, s53
	s_nop 0
	global_load_lds_dwordx4 v[218:219], off
	v_lshl_add_u64 v[218:219], s[34:35], 0, v[130:131]
	s_add_i32 m0, s53, 0x2000
	s_nop 0
	global_load_lds_dwordx4 v[218:219], off
	v_lshl_add_u64 v[218:219], v[222:223], 0, s[8:9]
	s_mov_b32 m0, s61
	s_nop 0
	global_load_lds_dwordx4 v[218:219], off
	v_lshl_add_u64 v[218:219], v[224:225], 0, s[8:9]
	s_mov_b32 m0, s70
	s_nop 0
	global_load_lds_dwordx4 v[218:219], off
	s_waitcnt vmcnt(8)
	s_waitcnt lgkmcnt(0)
	s_barrier
	s_setprio 1
	s_waitcnt lgkmcnt(0)
	v_mfma_f32_16x16x32_bf16 v[62:65], v[146:149], v[184:187], v[62:65]
	v_mfma_f32_16x16x32_bf16 v[46:49], v[146:149], v[192:195], v[46:49]
	v_mfma_f32_16x16x32_bf16 v[30:33], v[146:149], v[200:203], v[30:33]
	v_mfma_f32_16x16x32_bf16 v[14:17], v[146:149], v[208:211], v[14:17]
	v_mfma_f32_16x16x32_bf16 v[54:57], v[160:163], v[184:187], v[54:57]
	v_mfma_f32_16x16x32_bf16 v[38:41], v[160:163], v[192:195], v[38:41]
	v_mfma_f32_16x16x32_bf16 v[22:25], v[160:163], v[200:203], v[22:25]
	v_mfma_f32_16x16x32_bf16 v[6:9], v[160:163], v[208:211], v[6:9]
	v_mfma_f32_16x16x32_bf16 v[62:65], v[156:159], v[188:191], v[62:65]
	v_mfma_f32_16x16x32_bf16 v[46:49], v[156:159], v[196:199], v[46:49]
	v_mfma_f32_16x16x32_bf16 v[30:33], v[156:159], v[204:207], v[30:33]
	v_mfma_f32_16x16x32_bf16 v[14:17], v[156:159], v[212:215], v[14:17]
	v_mfma_f32_16x16x32_bf16 v[54:57], v[164:167], v[188:191], v[54:57]
	v_mfma_f32_16x16x32_bf16 v[38:41], v[164:167], v[196:199], v[38:41]
	v_mfma_f32_16x16x32_bf16 v[22:25], v[164:167], v[204:207], v[22:25]
	v_mfma_f32_16x16x32_bf16 v[6:9], v[164:167], v[212:215], v[6:9]
	s_setprio 0
	s_setprio 1
	v_mfma_f32_16x16x32_bf16 v[58:61], v[168:171], v[184:187], v[58:61]
	v_mfma_f32_16x16x32_bf16 v[42:45], v[168:171], v[192:195], v[42:45]
	v_mfma_f32_16x16x32_bf16 v[26:29], v[168:171], v[200:203], v[26:29]
	v_mfma_f32_16x16x32_bf16 v[10:13], v[168:171], v[208:211], v[10:13]
	v_mfma_f32_16x16x32_bf16 v[50:53], v[176:179], v[184:187], v[50:53]
	v_mfma_f32_16x16x32_bf16 v[34:37], v[176:179], v[192:195], v[34:37]
	v_mfma_f32_16x16x32_bf16 v[18:21], v[176:179], v[200:203], v[18:21]
	v_mfma_f32_16x16x32_bf16 v[2:5], v[176:179], v[208:211], v[2:5]
	v_mfma_f32_16x16x32_bf16 v[58:61], v[172:175], v[188:191], v[58:61]
	v_mfma_f32_16x16x32_bf16 v[42:45], v[172:175], v[196:199], v[42:45]
	v_mfma_f32_16x16x32_bf16 v[26:29], v[172:175], v[204:207], v[26:29]
	v_mfma_f32_16x16x32_bf16 v[10:13], v[172:175], v[212:215], v[10:13]
	v_mfma_f32_16x16x32_bf16 v[50:53], v[180:183], v[188:191], v[50:53]
	v_mfma_f32_16x16x32_bf16 v[34:37], v[180:183], v[196:199], v[34:37]
	v_mfma_f32_16x16x32_bf16 v[18:21], v[180:183], v[204:207], v[18:21]
	v_mfma_f32_16x16x32_bf16 v[2:5], v[180:183], v[212:215], v[2:5]
	s_setprio 0
	s_barrier
	s_add_i32 s92, s92, 2
	s_add_u32 s88, s88, 0x100
	s_addc_u32 s89, s89, 0
	s_add_u32 s81, s81, 0x100
	s_addc_u32 s83, s83, 0
	s_cmp_gt_u32 s92, 29
	s_cbranch_scc0 .LBB0_1124
	s_and_b64 vcc, exec, s[78:79]
	s_cbranch_vccz .LBB0_1127
	s_barrier

.LBB0_1237:
	ds_read_b128 v[146:149], v164
	ds_read_b128 v[150:153], v164 offset:1024
	ds_read_b128 v[154:157], v164 offset:2048
	ds_read_b128 v[158:161], v164 offset:3072
	ds_read_b128 v[168:171], v165
	ds_read_b128 v[172:175], v165 offset:1024
	ds_read_b128 v[176:179], v165 offset:2048
	ds_read_b128 v[180:183], v165 offset:3072
	s_add_u32 s34, s76, 0xffea0080
	s_addc_u32 s35, s77, -1
	s_cmpk_eq_i32 s52, 0x54
	s_cselect_b32 s85, s5, s35
	s_cselect_b32 s84, s4, s34
	s_cselect_b32 s35, s83, s1
	s_cselect_b32 s34, s82, s0
	v_lshl_add_u64 v[218:219], s[76:77], 0, v[138:139]
	s_add_i32 m0, s33, 0xc000
	ds_read_b128 v[184:187], v166
	ds_read_b128 v[188:191], v166 offset:1024
	ds_read_b128 v[192:195], v166 offset:2048
	ds_read_b128 v[196:199], v166 offset:3072
	ds_read_b128 v[200:203], v166 offset:4096
	ds_read_b128 v[204:207], v166 offset:5120
	ds_read_b128 v[208:211], v166 offset:6144
	ds_read_b128 v[212:215], v166 offset:7168
	global_load_lds_dwordx4 v[218:219], off
	v_lshl_add_u64 v[218:219], s[76:77], 0, v[140:141]
	s_add_i32 m0, s33, 0xe000
	s_nop 0
	global_load_lds_dwordx4 v[218:219], off
	s_waitcnt vmcnt(8)
	s_waitcnt lgkmcnt(0)
	s_barrier
	s_setprio 1
	s_waitcnt lgkmcnt(0)
	v_mfma_f32_16x16x32_bf16 v[126:129], v[146:149], v[184:187], v[126:129]
	v_mfma_f32_16x16x32_bf16 v[110:113], v[146:149], v[192:195], v[110:113]
	v_mfma_f32_16x16x32_bf16 v[94:97], v[146:149], v[200:203], v[94:97]
	v_mfma_f32_16x16x32_bf16 v[78:81], v[146:149], v[208:211], v[78:81]
	v_mfma_f32_16x16x32_bf16 v[122:125], v[154:157], v[184:187], v[122:125]
	v_mfma_f32_16x16x32_bf16 v[106:109], v[154:157], v[192:195], v[106:109]
	v_mfma_f32_16x16x32_bf16 v[90:93], v[154:157], v[200:203], v[90:93]
	v_mfma_f32_16x16x32_bf16 v[74:77], v[154:157], v[208:211], v[74:77]
	v_mfma_f32_16x16x32_bf16 v[126:129], v[150:153], v[188:191], v[126:129]
	v_mfma_f32_16x16x32_bf16 v[110:113], v[150:153], v[196:199], v[110:113]
	v_mfma_f32_16x16x32_bf16 v[94:97], v[150:153], v[204:207], v[94:97]
	v_mfma_f32_16x16x32_bf16 v[78:81], v[150:153], v[212:215], v[78:81]
	v_mfma_f32_16x16x32_bf16 v[122:125], v[158:161], v[188:191], v[122:125]
	v_mfma_f32_16x16x32_bf16 v[106:109], v[158:161], v[196:199], v[106:109]
	v_mfma_f32_16x16x32_bf16 v[90:93], v[158:161], v[204:207], v[90:93]
	v_mfma_f32_16x16x32_bf16 v[74:77], v[158:161], v[212:215], v[74:77]
	s_setprio 0
	s_setprio 1
	v_mfma_f32_16x16x32_bf16 v[118:121], v[168:171], v[184:187], v[118:121]
	v_mfma_f32_16x16x32_bf16 v[102:105], v[168:171], v[192:195], v[102:105]
	v_mfma_f32_16x16x32_bf16 v[86:89], v[168:171], v[200:203], v[86:89]
	v_mfma_f32_16x16x32_bf16 v[70:73], v[168:171], v[208:211], v[70:73]
	v_mfma_f32_16x16x32_bf16 v[114:117], v[176:179], v[184:187], v[114:117]
	v_mfma_f32_16x16x32_bf16 v[98:101], v[176:179], v[192:195], v[98:101]
	v_mfma_f32_16x16x32_bf16 v[82:85], v[176:179], v[200:203], v[82:85]
	v_mfma_f32_16x16x32_bf16 v[66:69], v[176:179], v[208:211], v[66:69]
	v_mfma_f32_16x16x32_bf16 v[118:121], v[172:175], v[188:191], v[118:121]
	v_mfma_f32_16x16x32_bf16 v[102:105], v[172:175], v[196:199], v[102:105]
	v_mfma_f32_16x16x32_bf16 v[86:89], v[172:175], v[204:207], v[86:89]
	v_mfma_f32_16x16x32_bf16 v[70:73], v[172:175], v[212:215], v[70:73]
	v_mfma_f32_16x16x32_bf16 v[114:117], v[180:183], v[188:191], v[114:117]
	v_mfma_f32_16x16x32_bf16 v[98:101], v[180:183], v[196:199], v[98:101]
	v_mfma_f32_16x16x32_bf16 v[82:85], v[180:183], v[204:207], v[82:85]
	v_mfma_f32_16x16x32_bf16 v[66:69], v[180:183], v[212:215], v[66:69]
	s_setprio 0
	s_barrier
	s_add_i32 s53, s71, s31
	v_lshl_add_u64 v[218:219], s[34:35], 0, v[132:133]
	s_mov_b32 m0, s53
	ds_read_b128 v[184:187], v166 offset:16384
	ds_read_b128 v[188:191], v166 offset:17408
	ds_read_b128 v[192:195], v166 offset:18432
	ds_read_b128 v[196:199], v166 offset:19456
	ds_read_b128 v[200:203], v166 offset:20480
	ds_read_b128 v[204:207], v166 offset:21504
	ds_read_b128 v[208:211], v166 offset:22528
	ds_read_b128 v[212:215], v166 offset:23552
	global_load_lds_dwordx4 v[218:219], off
	s_add_i32 m0, s53, 0x2000
	s_add_u32 s54, s34, 0x160000
	v_lshl_add_u64 v[220:221], s[34:35], 0, v[136:137]
	s_addc_u32 s55, s35, 0
	s_add_i32 s53, s72, s31
	global_load_lds_dwordx4 v[220:221], off
	v_lshl_add_u64 v[222:223], s[54:55], 0, v[132:133]
	s_mov_b32 m0, s53
	v_lshl_add_u64 v[224:225], s[84:85], 0, v[134:135]
	global_load_lds_dwordx4 v[222:223], off
	v_lshl_add_u64 v[222:223], s[54:55], 0, v[136:137]
	s_add_i32 m0, s53, 0x2000
	s_nop 0
	global_load_lds_dwordx4 v[222:223], off
	v_lshl_add_u64 v[222:223], s[84:85], 0, v[130:131]
	s_mov_b32 m0, s33
	s_nop 0
	global_load_lds_dwordx4 v[222:223], off
	s_mov_b32 m0, s56
	s_nop 0
	global_load_lds_dwordx4 v[224:225], off
	s_waitcnt vmcnt(8)
	s_waitcnt lgkmcnt(0)
	s_barrier
	s_setprio 1
	s_waitcnt lgkmcnt(0)
	v_mfma_f32_16x16x32_bf16 v[62:65], v[146:149], v[184:187], v[62:65]
	v_mfma_f32_16x16x32_bf16 v[46:49], v[146:149], v[192:195], v[46:49]
	v_mfma_f32_16x16x32_bf16 v[30:33], v[146:149], v[200:203], v[30:33]
	v_mfma_f32_16x16x32_bf16 v[14:17], v[146:149], v[208:211], v[14:17]
	v_mfma_f32_16x16x32_bf16 v[58:61], v[154:157], v[184:187], v[58:61]
	v_mfma_f32_16x16x32_bf16 v[42:45], v[154:157], v[192:195], v[42:45]
	v_mfma_f32_16x16x32_bf16 v[26:29], v[154:157], v[200:203], v[26:29]
	v_mfma_f32_16x16x32_bf16 v[10:13], v[154:157], v[208:211], v[10:13]
	v_mfma_f32_16x16x32_bf16 v[62:65], v[150:153], v[188:191], v[62:65]
	v_mfma_f32_16x16x32_bf16 v[46:49], v[150:153], v[196:199], v[46:49]
	v_mfma_f32_16x16x32_bf16 v[30:33], v[150:153], v[204:207], v[30:33]
	v_mfma_f32_16x16x32_bf16 v[14:17], v[150:153], v[212:215], v[14:17]
	v_mfma_f32_16x16x32_bf16 v[58:61], v[158:161], v[188:191], v[58:61]
	v_mfma_f32_16x16x32_bf16 v[42:45], v[158:161], v[196:199], v[42:45]
	v_mfma_f32_16x16x32_bf16 v[26:29], v[158:161], v[204:207], v[26:29]
	v_mfma_f32_16x16x32_bf16 v[10:13], v[158:161], v[212:215], v[10:13]
	s_setprio 0
	s_setprio 1
	v_mfma_f32_16x16x32_bf16 v[54:57], v[168:171], v[184:187], v[54:57]
	v_mfma_f32_16x16x32_bf16 v[38:41], v[168:171], v[192:195], v[38:41]
	v_mfma_f32_16x16x32_bf16 v[22:25], v[168:171], v[200:203], v[22:25]
	v_mfma_f32_16x16x32_bf16 v[6:9], v[168:171], v[208:211], v[6:9]
	v_mfma_f32_16x16x32_bf16 v[50:53], v[176:179], v[184:187], v[50:53]
	v_mfma_f32_16x16x32_bf16 v[34:37], v[176:179], v[192:195], v[34:37]
	v_mfma_f32_16x16x32_bf16 v[18:21], v[176:179], v[200:203], v[18:21]
	v_mfma_f32_16x16x32_bf16 v[2:5], v[176:179], v[208:211], v[2:5]
	v_mfma_f32_16x16x32_bf16 v[54:57], v[172:175], v[188:191], v[54:57]
	v_mfma_f32_16x16x32_bf16 v[38:41], v[172:175], v[196:199], v[38:41]
	v_mfma_f32_16x16x32_bf16 v[22:25], v[172:175], v[204:207], v[22:25]
	v_mfma_f32_16x16x32_bf16 v[6:9], v[172:175], v[212:215], v[6:9]
	v_mfma_f32_16x16x32_bf16 v[50:53], v[180:183], v[188:191], v[50:53]
	v_mfma_f32_16x16x32_bf16 v[34:37], v[180:183], v[196:199], v[34:37]
	v_mfma_f32_16x16x32_bf16 v[18:21], v[180:183], v[204:207], v[18:21]
	v_mfma_f32_16x16x32_bf16 v[2:5], v[180:183], v[212:215], v[2:5]
	s_setprio 0
	s_barrier
	s_add_i32 s53, 0, 0x18000
	s_add_i32 s62, 0, 0x1c000
	v_add_u32_e32 v158, s53, v162
	v_add_u32_e32 v167, s62, v162
	ds_read_b128 v[146:149], v158
	ds_read_b128 v[150:153], v158 offset:1024
	ds_read_b128 v[154:157], v158 offset:2048
	ds_read_b128 v[158:161], v158 offset:3072
	ds_read_b128 v[168:171], v167
	ds_read_b128 v[172:175], v167 offset:1024
	ds_read_b128 v[176:179], v167 offset:2048
	ds_read_b128 v[180:183], v167 offset:3072
	s_add_u32 s54, s84, 0x160000
	s_addc_u32 s55, s85, 0
	s_mov_b32 m0, s57
	v_lshl_add_u64 v[226:227], s[54:55], 0, v[130:131]
	ds_read_b128 v[184:187], v166 offset:32768
	ds_read_b128 v[188:191], v166 offset:33792
	ds_read_b128 v[192:195], v166 offset:34816
	ds_read_b128 v[196:199], v166 offset:35840
	ds_read_b128 v[200:203], v166 offset:36864
	ds_read_b128 v[204:207], v166 offset:37888
	ds_read_b128 v[208:211], v166 offset:38912
	ds_read_b128 v[212:215], v166 offset:39936
	global_load_lds_dwordx4 v[226:227], off
	v_lshl_add_u64 v[226:227], s[54:55], 0, v[134:135]
	s_mov_b32 m0, s58
	s_nop 0
	global_load_lds_dwordx4 v[226:227], off
	s_waitcnt vmcnt(8)
	s_waitcnt lgkmcnt(0)
	s_barrier
	s_setprio 1
	s_waitcnt lgkmcnt(0)
	v_mfma_f32_16x16x32_bf16 v[126:129], v[146:149], v[184:187], v[126:129]
	v_mfma_f32_16x16x32_bf16 v[110:113], v[146:149], v[192:195], v[110:113]
	v_mfma_f32_16x16x32_bf16 v[94:97], v[146:149], v[200:203], v[94:97]
	v_mfma_f32_16x16x32_bf16 v[78:81], v[146:149], v[208:211], v[78:81]
	v_mfma_f32_16x16x32_bf16 v[122:125], v[154:157], v[184:187], v[122:125]
	v_mfma_f32_16x16x32_bf16 v[106:109], v[154:157], v[192:195], v[106:109]
	v_mfma_f32_16x16x32_bf16 v[90:93], v[154:157], v[200:203], v[90:93]
	v_mfma_f32_16x16x32_bf16 v[74:77], v[154:157], v[208:211], v[74:77]
	v_mfma_f32_16x16x32_bf16 v[126:129], v[150:153], v[188:191], v[126:129]
	v_mfma_f32_16x16x32_bf16 v[110:113], v[150:153], v[196:199], v[110:113]
	v_mfma_f32_16x16x32_bf16 v[94:97], v[150:153], v[204:207], v[94:97]
	v_mfma_f32_16x16x32_bf16 v[78:81], v[150:153], v[212:215], v[78:81]
	v_mfma_f32_16x16x32_bf16 v[122:125], v[158:161], v[188:191], v[122:125]
	v_mfma_f32_16x16x32_bf16 v[106:109], v[158:161], v[196:199], v[106:109]
	v_mfma_f32_16x16x32_bf16 v[90:93], v[158:161], v[204:207], v[90:93]
	v_mfma_f32_16x16x32_bf16 v[74:77], v[158:161], v[212:215], v[74:77]
	s_setprio 0
	s_setprio 1
	v_mfma_f32_16x16x32_bf16 v[118:121], v[168:171], v[184:187], v[118:121]
	v_mfma_f32_16x16x32_bf16 v[102:105], v[168:171], v[192:195], v[102:105]
	v_mfma_f32_16x16x32_bf16 v[86:89], v[168:171], v[200:203], v[86:89]
	v_mfma_f32_16x16x32_bf16 v[70:73], v[168:171], v[208:211], v[70:73]
	v_mfma_f32_16x16x32_bf16 v[114:117], v[176:179], v[184:187], v[114:117]
	v_mfma_f32_16x16x32_bf16 v[98:101], v[176:179], v[192:195], v[98:101]
	v_mfma_f32_16x16x32_bf16 v[82:85], v[176:179], v[200:203], v[82:85]
	v_mfma_f32_16x16x32_bf16 v[66:69], v[176:179], v[208:211], v[66:69]
	v_mfma_f32_16x16x32_bf16 v[118:121], v[172:175], v[188:191], v[118:121]
	v_mfma_f32_16x16x32_bf16 v[102:105], v[172:175], v[196:199], v[102:105]
	v_mfma_f32_16x16x32_bf16 v[86:89], v[172:175], v[204:207], v[86:89]
	v_mfma_f32_16x16x32_bf16 v[70:73], v[172:175], v[212:215], v[70:73]
	v_mfma_f32_16x16x32_bf16 v[114:117], v[180:183], v[188:191], v[114:117]
	v_mfma_f32_16x16x32_bf16 v[98:101], v[180:183], v[196:199], v[98:101]
	v_mfma_f32_16x16x32_bf16 v[82:85], v[180:183], v[204:207], v[82:85]
	v_mfma_f32_16x16x32_bf16 v[66:69], v[180:183], v[212:215], v[66:69]
	s_setprio 0
	s_barrier
	s_add_i32 s53, s53, s31
	v_lshl_add_u64 v[218:219], v[218:219], 0, s[78:79]
	s_mov_b32 m0, s53
	ds_read_b128 v[184:187], v166 offset:49152
	ds_read_b128 v[188:191], v166 offset:50176
	ds_read_b128 v[192:195], v166 offset:51200
	ds_read_b128 v[196:199], v166 offset:52224
	ds_read_b128 v[200:203], v166 offset:53248
	ds_read_b128 v[204:207], v166 offset:54272
	ds_read_b128 v[208:211], v166 offset:55296
	ds_read_b128 v[212:215], v166 offset:56320
	global_load_lds_dwordx4 v[218:219], off
	s_add_i32 m0, s53, 0x2000
	s_add_u32 s34, s34, 0x160080
	v_lshl_add_u64 v[218:219], v[220:221], 0, s[78:79]
	s_addc_u32 s35, s35, 0
	s_add_i32 s53, s62, s31
	global_load_lds_dwordx4 v[218:219], off
	v_lshl_add_u64 v[218:219], s[34:35], 0, v[132:133]
	s_mov_b32 m0, s53
	s_nop 0
	global_load_lds_dwordx4 v[218:219], off
	v_lshl_add_u64 v[218:219], s[34:35], 0, v[136:137]
	s_add_i32 m0, s53, 0x2000
	s_nop 0
	global_load_lds_dwordx4 v[218:219], off
	v_lshl_add_u64 v[218:219], v[222:223], 0, s[78:79]
	s_mov_b32 m0, s60
	s_nop 0
	global_load_lds_dwordx4 v[218:219], off
	v_lshl_add_u64 v[218:219], v[224:225], 0, s[78:79]
	s_mov_b32 m0, s61
	s_nop 0
	global_load_lds_dwordx4 v[218:219], off
	s_waitcnt vmcnt(8)
	s_waitcnt lgkmcnt(0)
	s_barrier
	s_setprio 1
	s_waitcnt lgkmcnt(0)
	v_mfma_f32_16x16x32_bf16 v[62:65], v[146:149], v[184:187], v[62:65]
	v_mfma_f32_16x16x32_bf16 v[46:49], v[146:149], v[192:195], v[46:49]
	v_mfma_f32_16x16x32_bf16 v[30:33], v[146:149], v[200:203], v[30:33]
	v_mfma_f32_16x16x32_bf16 v[14:17], v[146:149], v[208:211], v[14:17]
	v_mfma_f32_16x16x32_bf16 v[58:61], v[154:157], v[184:187], v[58:61]
	v_mfma_f32_16x16x32_bf16 v[42:45], v[154:157], v[192:195], v[42:45]
	v_mfma_f32_16x16x32_bf16 v[26:29], v[154:157], v[200:203], v[26:29]
	v_mfma_f32_16x16x32_bf16 v[10:13], v[154:157], v[208:211], v[10:13]
	v_mfma_f32_16x16x32_bf16 v[62:65], v[150:153], v[188:191], v[62:65]
	v_mfma_f32_16x16x32_bf16 v[46:49], v[150:153], v[196:199], v[46:49]
	v_mfma_f32_16x16x32_bf16 v[30:33], v[150:153], v[204:207], v[30:33]
	v_mfma_f32_16x16x32_bf16 v[14:17], v[150:153], v[212:215], v[14:17]
	v_mfma_f32_16x16x32_bf16 v[58:61], v[158:161], v[188:191], v[58:61]
	v_mfma_f32_16x16x32_bf16 v[42:45], v[158:161], v[196:199], v[42:45]
	v_mfma_f32_16x16x32_bf16 v[26:29], v[158:161], v[204:207], v[26:29]
	v_mfma_f32_16x16x32_bf16 v[10:13], v[158:161], v[212:215], v[10:13]
	s_setprio 0
	s_setprio 1
	v_mfma_f32_16x16x32_bf16 v[54:57], v[168:171], v[184:187], v[54:57]
	v_mfma_f32_16x16x32_bf16 v[38:41], v[168:171], v[192:195], v[38:41]
	v_mfma_f32_16x16x32_bf16 v[22:25], v[168:171], v[200:203], v[22:25]
	v_mfma_f32_16x16x32_bf16 v[6:9], v[168:171], v[208:211], v[6:9]
	v_mfma_f32_16x16x32_bf16 v[50:53], v[176:179], v[184:187], v[50:53]
	v_mfma_f32_16x16x32_bf16 v[34:37], v[176:179], v[192:195], v[34:37]
	v_mfma_f32_16x16x32_bf16 v[18:21], v[176:179], v[200:203], v[18:21]
	v_mfma_f32_16x16x32_bf16 v[2:5], v[176:179], v[208:211], v[2:5]
	v_mfma_f32_16x16x32_bf16 v[54:57], v[172:175], v[188:191], v[54:57]
	v_mfma_f32_16x16x32_bf16 v[38:41], v[172:175], v[196:199], v[38:41]
	v_mfma_f32_16x16x32_bf16 v[22:25], v[172:175], v[204:207], v[22:25]
	v_mfma_f32_16x16x32_bf16 v[6:9], v[172:175], v[212:215], v[6:9]
	v_mfma_f32_16x16x32_bf16 v[50:53], v[180:183], v[188:191], v[50:53]
	v_mfma_f32_16x16x32_bf16 v[34:37], v[180:183], v[196:199], v[34:37]
	v_mfma_f32_16x16x32_bf16 v[18:21], v[180:183], v[204:207], v[18:21]
	v_mfma_f32_16x16x32_bf16 v[2:5], v[180:183], v[212:215], v[2:5]
	s_setprio 0
	s_barrier
	s_add_i32 s52, s52, 2
	s_add_u32 s76, s76, 0x100
	s_addc_u32 s77, s77, 0
	s_add_u32 s0, s0, 0x100
	s_addc_u32 s1, s1, 0
	s_cmpk_gt_u32 s52, 0x55
	s_cbranch_scc0 .LBB0_1237
	s_and_b64 vcc, exec, s[80:81]
	s_cbranch_vccz .LBB0_1240
	s_barrier

.LBB0_1624:
	ds_read_b128 v[154:157], v151
	ds_read_b128 v[158:161], v151 offset:1024
	ds_read_b128 v[162:165], v151 offset:2048
	ds_read_b128 v[166:169], v151 offset:3072
	ds_read_b128 v[170:173], v152
	ds_read_b128 v[174:177], v152 offset:1024
	ds_read_b128 v[178:181], v152 offset:2048
	ds_read_b128 v[182:185], v152 offset:3072
	s_add_u32 s34, s88, 0xfff80080
	s_addc_u32 s35, s89, -1
	s_cmp_eq_u32 s83, 28
	s_cselect_b32 s91, s0, s35
	s_cselect_b32 s90, s1, s34
	s_cselect_b32 s35, s52, s81
	s_cselect_b32 s34, s75, s77
	v_lshl_add_u64 v[146:147], s[88:89], 0, v[138:139]
	s_add_i32 m0, s33, 0xc000
	ds_read_b128 v[186:189], v153
	ds_read_b128 v[190:193], v153 offset:1024
	ds_read_b128 v[194:197], v153 offset:2048
	ds_read_b128 v[198:201], v153 offset:3072
	ds_read_b128 v[202:205], v153 offset:4096
	ds_read_b128 v[206:209], v153 offset:5120
	ds_read_b128 v[210:213], v153 offset:6144
	ds_read_b128 v[218:221], v153 offset:7168
	global_load_lds_dwordx4 v[146:147], off
	v_lshl_add_u64 v[146:147], s[88:89], 0, v[140:141]
	s_add_i32 m0, s33, 0xe000
	s_nop 0
	global_load_lds_dwordx4 v[146:147], off
	s_waitcnt vmcnt(8)
	s_waitcnt lgkmcnt(0)
	s_barrier
	s_setprio 1
	s_waitcnt lgkmcnt(0)
	v_mfma_f32_16x16x32_bf16 v[126:129], v[154:157], v[186:189], v[126:129]
	v_mfma_f32_16x16x32_bf16 v[114:117], v[154:157], v[194:197], v[114:117]
	v_mfma_f32_16x16x32_bf16 v[98:101], v[154:157], v[202:205], v[98:101]
	v_mfma_f32_16x16x32_bf16 v[82:85], v[154:157], v[210:213], v[82:85]
	v_mfma_f32_16x16x32_bf16 v[122:125], v[162:165], v[186:189], v[122:125]
	v_mfma_f32_16x16x32_bf16 v[106:109], v[162:165], v[194:197], v[106:109]
	v_mfma_f32_16x16x32_bf16 v[90:93], v[162:165], v[202:205], v[90:93]
	v_mfma_f32_16x16x32_bf16 v[74:77], v[162:165], v[210:213], v[74:77]
	v_mfma_f32_16x16x32_bf16 v[126:129], v[158:161], v[190:193], v[126:129]
	v_mfma_f32_16x16x32_bf16 v[114:117], v[158:161], v[198:201], v[114:117]
	v_mfma_f32_16x16x32_bf16 v[98:101], v[158:161], v[206:209], v[98:101]
	v_mfma_f32_16x16x32_bf16 v[82:85], v[158:161], v[218:221], v[82:85]
	v_mfma_f32_16x16x32_bf16 v[122:125], v[166:169], v[190:193], v[122:125]
	v_mfma_f32_16x16x32_bf16 v[106:109], v[166:169], v[198:201], v[106:109]
	v_mfma_f32_16x16x32_bf16 v[90:93], v[166:169], v[206:209], v[90:93]
	v_mfma_f32_16x16x32_bf16 v[74:77], v[166:169], v[218:221], v[74:77]
	s_setprio 0
	s_setprio 1
	v_mfma_f32_16x16x32_bf16 v[118:121], v[170:173], v[186:189], v[118:121]
	v_mfma_f32_16x16x32_bf16 v[102:105], v[170:173], v[194:197], v[102:105]
	v_mfma_f32_16x16x32_bf16 v[86:89], v[170:173], v[202:205], v[86:89]
	v_mfma_f32_16x16x32_bf16 v[70:73], v[170:173], v[210:213], v[70:73]
	v_mfma_f32_16x16x32_bf16 v[110:113], v[178:181], v[186:189], v[110:113]
	v_mfma_f32_16x16x32_bf16 v[94:97], v[178:181], v[194:197], v[94:97]
	v_mfma_f32_16x16x32_bf16 v[78:81], v[178:181], v[202:205], v[78:81]
	v_mfma_f32_16x16x32_bf16 v[66:69], v[178:181], v[210:213], v[66:69]
	v_mfma_f32_16x16x32_bf16 v[118:121], v[174:177], v[190:193], v[118:121]
	v_mfma_f32_16x16x32_bf16 v[102:105], v[174:177], v[198:201], v[102:105]
	v_mfma_f32_16x16x32_bf16 v[86:89], v[174:177], v[206:209], v[86:89]
	v_mfma_f32_16x16x32_bf16 v[70:73], v[174:177], v[218:221], v[70:73]
	v_mfma_f32_16x16x32_bf16 v[110:113], v[182:185], v[190:193], v[110:113]
	v_mfma_f32_16x16x32_bf16 v[94:97], v[182:185], v[198:201], v[94:97]
	v_mfma_f32_16x16x32_bf16 v[78:81], v[182:185], v[206:209], v[78:81]
	v_mfma_f32_16x16x32_bf16 v[66:69], v[182:185], v[218:221], v[66:69]
	s_setprio 0
	s_barrier
	s_add_i32 s53, s71, s12
	v_lshl_add_u64 v[146:147], s[34:35], 0, v[134:135]
	s_mov_b32 m0, s53
	ds_read_b128 v[186:189], v153 offset:16384
	ds_read_b128 v[190:193], v153 offset:17408
	ds_read_b128 v[194:197], v153 offset:18432
	ds_read_b128 v[198:201], v153 offset:19456
	ds_read_b128 v[202:205], v153 offset:20480
	ds_read_b128 v[206:209], v153 offset:21504
	ds_read_b128 v[210:213], v153 offset:22528
	ds_read_b128 v[218:221], v153 offset:23552
	global_load_lds_dwordx4 v[146:147], off
	s_add_i32 m0, s53, 0x2000
	s_add_u32 s54, s34, 0x80000
	v_lshl_add_u64 v[214:215], s[34:35], 0, v[130:131]
	s_addc_u32 s55, s35, 0
	s_add_i32 s53, s72, s12
	global_load_lds_dwordx4 v[214:215], off
	v_lshl_add_u64 v[222:223], s[54:55], 0, v[134:135]
	s_mov_b32 m0, s53
	v_lshl_add_u64 v[224:225], s[90:91], 0, v[132:133]
	global_load_lds_dwordx4 v[222:223], off
	v_lshl_add_u64 v[222:223], s[54:55], 0, v[130:131]
	s_add_i32 m0, s53, 0x2000
	s_nop 0
	global_load_lds_dwordx4 v[222:223], off
	v_lshl_add_u64 v[222:223], s[90:91], 0, v[136:137]
	s_mov_b32 m0, s33
	s_nop 0
	global_load_lds_dwordx4 v[222:223], off
	s_mov_b32 m0, s56
	s_nop 0
	global_load_lds_dwordx4 v[224:225], off
	s_waitcnt vmcnt(8)
	s_waitcnt lgkmcnt(0)
	s_barrier
	s_setprio 1
	s_waitcnt lgkmcnt(0)
	v_mfma_f32_16x16x32_bf16 v[62:65], v[154:157], v[186:189], v[62:65]
	v_mfma_f32_16x16x32_bf16 v[50:53], v[154:157], v[194:197], v[50:53]
	v_mfma_f32_16x16x32_bf16 v[34:37], v[154:157], v[202:205], v[34:37]
	v_mfma_f32_16x16x32_bf16 v[18:21], v[154:157], v[210:213], v[18:21]
	v_mfma_f32_16x16x32_bf16 v[58:61], v[162:165], v[186:189], v[58:61]
	v_mfma_f32_16x16x32_bf16 v[42:45], v[162:165], v[194:197], v[42:45]
	v_mfma_f32_16x16x32_bf16 v[26:29], v[162:165], v[202:205], v[26:29]
	v_mfma_f32_16x16x32_bf16 v[10:13], v[162:165], v[210:213], v[10:13]
	v_mfma_f32_16x16x32_bf16 v[62:65], v[158:161], v[190:193], v[62:65]
	v_mfma_f32_16x16x32_bf16 v[50:53], v[158:161], v[198:201], v[50:53]
	v_mfma_f32_16x16x32_bf16 v[34:37], v[158:161], v[206:209], v[34:37]
	v_mfma_f32_16x16x32_bf16 v[18:21], v[158:161], v[218:221], v[18:21]
	v_mfma_f32_16x16x32_bf16 v[58:61], v[166:169], v[190:193], v[58:61]
	v_mfma_f32_16x16x32_bf16 v[42:45], v[166:169], v[198:201], v[42:45]
	v_mfma_f32_16x16x32_bf16 v[26:29], v[166:169], v[206:209], v[26:29]
	v_mfma_f32_16x16x32_bf16 v[10:13], v[166:169], v[218:221], v[10:13]
	s_setprio 0
	s_setprio 1
	v_mfma_f32_16x16x32_bf16 v[54:57], v[170:173], v[186:189], v[54:57]
	v_mfma_f32_16x16x32_bf16 v[38:41], v[170:173], v[194:197], v[38:41]
	v_mfma_f32_16x16x32_bf16 v[22:25], v[170:173], v[202:205], v[22:25]
	v_mfma_f32_16x16x32_bf16 v[6:9], v[170:173], v[210:213], v[6:9]
	v_mfma_f32_16x16x32_bf16 v[46:49], v[178:181], v[186:189], v[46:49]
	v_mfma_f32_16x16x32_bf16 v[30:33], v[178:181], v[194:197], v[30:33]
	v_mfma_f32_16x16x32_bf16 v[14:17], v[178:181], v[202:205], v[14:17]
	v_mfma_f32_16x16x32_bf16 v[2:5], v[178:181], v[210:213], v[2:5]
	v_mfma_f32_16x16x32_bf16 v[54:57], v[174:177], v[190:193], v[54:57]
	v_mfma_f32_16x16x32_bf16 v[38:41], v[174:177], v[198:201], v[38:41]
	v_mfma_f32_16x16x32_bf16 v[22:25], v[174:177], v[206:209], v[22:25]
	v_mfma_f32_16x16x32_bf16 v[6:9], v[174:177], v[218:221], v[6:9]
	v_mfma_f32_16x16x32_bf16 v[46:49], v[182:185], v[190:193], v[46:49]
	v_mfma_f32_16x16x32_bf16 v[30:33], v[182:185], v[198:201], v[30:33]
	v_mfma_f32_16x16x32_bf16 v[14:17], v[182:185], v[206:209], v[14:17]
	v_mfma_f32_16x16x32_bf16 v[2:5], v[182:185], v[218:221], v[2:5]
	s_setprio 0
	s_barrier
	s_add_i32 s53, 0, 0x18000
	s_add_i32 s62, 0, 0x1c000
	v_add_u32_e32 v166, s53, v149
	v_add_u32_e32 v182, s62, v149
	ds_read_b128 v[154:157], v166
	ds_read_b128 v[158:161], v166 offset:1024
	ds_read_b128 v[162:165], v166 offset:2048
	ds_read_b128 v[166:169], v166 offset:3072
	ds_read_b128 v[170:173], v182
	ds_read_b128 v[174:177], v182 offset:1024
	ds_read_b128 v[178:181], v182 offset:2048
	ds_read_b128 v[182:185], v182 offset:3072
	s_add_u32 s54, s90, 0x80000
	s_addc_u32 s55, s91, 0
	s_mov_b32 m0, s57
	v_lshl_add_u64 v[226:227], s[54:55], 0, v[136:137]
	ds_read_b128 v[186:189], v153 offset:32768
	ds_read_b128 v[190:193], v153 offset:33792
	ds_read_b128 v[194:197], v153 offset:34816
	ds_read_b128 v[198:201], v153 offset:35840
	ds_read_b128 v[202:205], v153 offset:36864
	ds_read_b128 v[206:209], v153 offset:37888
	ds_read_b128 v[210:213], v153 offset:38912
	ds_read_b128 v[218:221], v153 offset:39936
	global_load_lds_dwordx4 v[226:227], off
	v_lshl_add_u64 v[226:227], s[54:55], 0, v[132:133]
	s_mov_b32 m0, s58
	s_nop 0
	global_load_lds_dwordx4 v[226:227], off
	s_waitcnt vmcnt(8)
	s_waitcnt lgkmcnt(0)
	s_barrier
	s_setprio 1
	s_waitcnt lgkmcnt(0)
	v_mfma_f32_16x16x32_bf16 v[126:129], v[154:157], v[186:189], v[126:129]
	v_mfma_f32_16x16x32_bf16 v[114:117], v[154:157], v[194:197], v[114:117]
	v_mfma_f32_16x16x32_bf16 v[98:101], v[154:157], v[202:205], v[98:101]
	v_mfma_f32_16x16x32_bf16 v[82:85], v[154:157], v[210:213], v[82:85]
	v_mfma_f32_16x16x32_bf16 v[122:125], v[162:165], v[186:189], v[122:125]
	v_mfma_f32_16x16x32_bf16 v[106:109], v[162:165], v[194:197], v[106:109]
	v_mfma_f32_16x16x32_bf16 v[90:93], v[162:165], v[202:205], v[90:93]
	v_mfma_f32_16x16x32_bf16 v[74:77], v[162:165], v[210:213], v[74:77]
	v_mfma_f32_16x16x32_bf16 v[126:129], v[158:161], v[190:193], v[126:129]
	v_mfma_f32_16x16x32_bf16 v[114:117], v[158:161], v[198:201], v[114:117]
	v_mfma_f32_16x16x32_bf16 v[98:101], v[158:161], v[206:209], v[98:101]
	v_mfma_f32_16x16x32_bf16 v[82:85], v[158:161], v[218:221], v[82:85]
	v_mfma_f32_16x16x32_bf16 v[122:125], v[166:169], v[190:193], v[122:125]
	v_mfma_f32_16x16x32_bf16 v[106:109], v[166:169], v[198:201], v[106:109]
	v_mfma_f32_16x16x32_bf16 v[90:93], v[166:169], v[206:209], v[90:93]
	v_mfma_f32_16x16x32_bf16 v[74:77], v[166:169], v[218:221], v[74:77]
	s_setprio 0
	s_setprio 1
	v_mfma_f32_16x16x32_bf16 v[118:121], v[170:173], v[186:189], v[118:121]
	v_mfma_f32_16x16x32_bf16 v[102:105], v[170:173], v[194:197], v[102:105]
	v_mfma_f32_16x16x32_bf16 v[86:89], v[170:173], v[202:205], v[86:89]
	v_mfma_f32_16x16x32_bf16 v[70:73], v[170:173], v[210:213], v[70:73]
	v_mfma_f32_16x16x32_bf16 v[110:113], v[178:181], v[186:189], v[110:113]
	v_mfma_f32_16x16x32_bf16 v[94:97], v[178:181], v[194:197], v[94:97]
	v_mfma_f32_16x16x32_bf16 v[78:81], v[178:181], v[202:205], v[78:81]
	v_mfma_f32_16x16x32_bf16 v[66:69], v[178:181], v[210:213], v[66:69]
	v_mfma_f32_16x16x32_bf16 v[118:121], v[174:177], v[190:193], v[118:121]
	v_mfma_f32_16x16x32_bf16 v[102:105], v[174:177], v[198:201], v[102:105]
	v_mfma_f32_16x16x32_bf16 v[86:89], v[174:177], v[206:209], v[86:89]
	v_mfma_f32_16x16x32_bf16 v[70:73], v[174:177], v[218:221], v[70:73]
	v_mfma_f32_16x16x32_bf16 v[110:113], v[182:185], v[190:193], v[110:113]
	v_mfma_f32_16x16x32_bf16 v[94:97], v[182:185], v[198:201], v[94:97]
	v_mfma_f32_16x16x32_bf16 v[78:81], v[182:185], v[206:209], v[78:81]
	v_mfma_f32_16x16x32_bf16 v[66:69], v[182:185], v[218:221], v[66:69]
	s_setprio 0
	s_barrier
	s_add_i32 s53, s53, s12
	v_lshl_add_u64 v[146:147], v[146:147], 0, s[8:9]
	s_mov_b32 m0, s53
	ds_read_b128 v[186:189], v153 offset:49152
	ds_read_b128 v[190:193], v153 offset:50176
	ds_read_b128 v[194:197], v153 offset:51200
	ds_read_b128 v[198:201], v153 offset:52224
	ds_read_b128 v[202:205], v153 offset:53248
	ds_read_b128 v[206:209], v153 offset:54272
	ds_read_b128 v[210:213], v153 offset:55296
	ds_read_b128 v[218:221], v153 offset:56320
	global_load_lds_dwordx4 v[146:147], off
	s_add_i32 m0, s53, 0x2000
	s_add_u32 s34, s34, 0x80080
	v_lshl_add_u64 v[146:147], v[214:215], 0, s[8:9]
	s_addc_u32 s35, s35, 0
	s_add_i32 s53, s62, s12
	global_load_lds_dwordx4 v[146:147], off
	v_lshl_add_u64 v[146:147], s[34:35], 0, v[134:135]
	s_mov_b32 m0, s53
	s_nop 0
	global_load_lds_dwordx4 v[146:147], off
	v_lshl_add_u64 v[146:147], s[34:35], 0, v[130:131]
	s_add_i32 m0, s53, 0x2000
	s_nop 0
	global_load_lds_dwordx4 v[146:147], off
	v_lshl_add_u64 v[146:147], v[222:223], 0, s[8:9]
	s_mov_b32 m0, s60
	s_nop 0
	global_load_lds_dwordx4 v[146:147], off
	v_lshl_add_u64 v[146:147], v[224:225], 0, s[8:9]
	s_mov_b32 m0, s61
	s_nop 0
	global_load_lds_dwordx4 v[146:147], off
	s_waitcnt vmcnt(8)
	s_waitcnt lgkmcnt(0)
	s_barrier
	s_setprio 1
	s_waitcnt lgkmcnt(0)
	v_mfma_f32_16x16x32_bf16 v[62:65], v[154:157], v[186:189], v[62:65]
	v_mfma_f32_16x16x32_bf16 v[50:53], v[154:157], v[194:197], v[50:53]
	v_mfma_f32_16x16x32_bf16 v[34:37], v[154:157], v[202:205], v[34:37]
	v_mfma_f32_16x16x32_bf16 v[18:21], v[154:157], v[210:213], v[18:21]
	v_mfma_f32_16x16x32_bf16 v[58:61], v[162:165], v[186:189], v[58:61]
	v_mfma_f32_16x16x32_bf16 v[42:45], v[162:165], v[194:197], v[42:45]
	v_mfma_f32_16x16x32_bf16 v[26:29], v[162:165], v[202:205], v[26:29]
	v_mfma_f32_16x16x32_bf16 v[10:13], v[162:165], v[210:213], v[10:13]
	v_mfma_f32_16x16x32_bf16 v[62:65], v[158:161], v[190:193], v[62:65]
	v_mfma_f32_16x16x32_bf16 v[50:53], v[158:161], v[198:201], v[50:53]
	v_mfma_f32_16x16x32_bf16 v[34:37], v[158:161], v[206:209], v[34:37]
	v_mfma_f32_16x16x32_bf16 v[18:21], v[158:161], v[218:221], v[18:21]
	v_mfma_f32_16x16x32_bf16 v[58:61], v[166:169], v[190:193], v[58:61]
	v_mfma_f32_16x16x32_bf16 v[42:45], v[166:169], v[198:201], v[42:45]
	v_mfma_f32_16x16x32_bf16 v[26:29], v[166:169], v[206:209], v[26:29]
	v_mfma_f32_16x16x32_bf16 v[10:13], v[166:169], v[218:221], v[10:13]
	s_setprio 0
	s_setprio 1
	v_mfma_f32_16x16x32_bf16 v[54:57], v[170:173], v[186:189], v[54:57]
	v_mfma_f32_16x16x32_bf16 v[38:41], v[170:173], v[194:197], v[38:41]
	v_mfma_f32_16x16x32_bf16 v[22:25], v[170:173], v[202:205], v[22:25]
	v_mfma_f32_16x16x32_bf16 v[6:9], v[170:173], v[210:213], v[6:9]
	v_mfma_f32_16x16x32_bf16 v[46:49], v[178:181], v[186:189], v[46:49]
	v_mfma_f32_16x16x32_bf16 v[30:33], v[178:181], v[194:197], v[30:33]
	v_mfma_f32_16x16x32_bf16 v[14:17], v[178:181], v[202:205], v[14:17]
	v_mfma_f32_16x16x32_bf16 v[2:5], v[178:181], v[210:213], v[2:5]
	v_mfma_f32_16x16x32_bf16 v[54:57], v[174:177], v[190:193], v[54:57]
	v_mfma_f32_16x16x32_bf16 v[38:41], v[174:177], v[198:201], v[38:41]
	v_mfma_f32_16x16x32_bf16 v[22:25], v[174:177], v[206:209], v[22:25]
	v_mfma_f32_16x16x32_bf16 v[6:9], v[174:177], v[218:221], v[6:9]
	v_mfma_f32_16x16x32_bf16 v[46:49], v[182:185], v[190:193], v[46:49]
	v_mfma_f32_16x16x32_bf16 v[30:33], v[182:185], v[198:201], v[30:33]
	v_mfma_f32_16x16x32_bf16 v[14:17], v[182:185], v[206:209], v[14:17]
	v_mfma_f32_16x16x32_bf16 v[2:5], v[182:185], v[218:221], v[2:5]
	s_setprio 0
	s_barrier
	s_add_i32 s83, s83, 2
	s_add_u32 s88, s88, 0x100
	s_addc_u32 s89, s89, 0
	s_add_u32 s77, s77, 0x100
	s_addc_u32 s81, s81, 0
	s_cmp_gt_u32 s83, 29
	s_cbranch_scc0 .LBB0_1624
	s_and_b64 vcc, exec, s[78:79]
	s_cbranch_vccz .LBB0_1627
	s_barrier

.LBB0_2089:
	ds_read_b128 v[130:133], v178
	ds_read_b128 v[134:137], v178 offset:1024
	ds_read_b128 v[138:141], v178 offset:2048
	ds_read_b128 v[142:145], v178 offset:3072
	ds_read_b128 v[162:165], v179
	ds_read_b128 v[166:169], v179 offset:1024
	ds_read_b128 v[170:173], v179 offset:2048
	ds_read_b128 v[182:185], v179 offset:3072
	s_add_u32 s34, s38, 0xffea0080
	s_addc_u32 s35, s39, -1
	s_cmpk_eq_i32 s52, 0x54
	s_cselect_b32 s41, s5, s35
	s_cselect_b32 s40, s4, s34
	s_cselect_b32 s35, s37, s1
	s_cselect_b32 s34, s36, s0
	v_lshl_add_u64 v[174:175], s[38:39], 0, v[154:155]
	s_add_i32 m0, s33, 0xc000
	ds_read_b128 v[186:189], v180
	ds_read_b128 v[190:193], v180 offset:1024
	ds_read_b128 v[194:197], v180 offset:2048
	ds_read_b128 v[198:201], v180 offset:3072
	ds_read_b128 v[202:205], v180 offset:4096
	ds_read_b128 v[206:209], v180 offset:5120
	ds_read_b128 v[210:213], v180 offset:6144
	ds_read_b128 v[218:221], v180 offset:7168
	global_load_lds_dwordx4 v[174:175], off
	v_lshl_add_u64 v[174:175], s[38:39], 0, v[156:157]
	s_add_i32 m0, s33, 0xe000
	s_nop 0
	global_load_lds_dwordx4 v[174:175], off
	s_waitcnt vmcnt(8)
	s_waitcnt lgkmcnt(0)
	s_barrier
	s_setprio 1
	s_waitcnt lgkmcnt(0)
	v_mfma_f32_16x16x32_bf16 v[126:129], v[130:133], v[186:189], v[126:129]
	v_mfma_f32_16x16x32_bf16 v[110:113], v[130:133], v[194:197], v[110:113]
	v_mfma_f32_16x16x32_bf16 v[94:97], v[130:133], v[202:205], v[94:97]
	v_mfma_f32_16x16x32_bf16 v[78:81], v[130:133], v[210:213], v[78:81]
	v_mfma_f32_16x16x32_bf16 v[122:125], v[138:141], v[186:189], v[122:125]
	v_mfma_f32_16x16x32_bf16 v[106:109], v[138:141], v[194:197], v[106:109]
	v_mfma_f32_16x16x32_bf16 v[90:93], v[138:141], v[202:205], v[90:93]
	v_mfma_f32_16x16x32_bf16 v[74:77], v[138:141], v[210:213], v[74:77]
	v_mfma_f32_16x16x32_bf16 v[126:129], v[134:137], v[190:193], v[126:129]
	v_mfma_f32_16x16x32_bf16 v[110:113], v[134:137], v[198:201], v[110:113]
	v_mfma_f32_16x16x32_bf16 v[94:97], v[134:137], v[206:209], v[94:97]
	v_mfma_f32_16x16x32_bf16 v[78:81], v[134:137], v[218:221], v[78:81]
	v_mfma_f32_16x16x32_bf16 v[122:125], v[142:145], v[190:193], v[122:125]
	v_mfma_f32_16x16x32_bf16 v[106:109], v[142:145], v[198:201], v[106:109]
	v_mfma_f32_16x16x32_bf16 v[90:93], v[142:145], v[206:209], v[90:93]
	v_mfma_f32_16x16x32_bf16 v[74:77], v[142:145], v[218:221], v[74:77]
	s_setprio 0
	s_setprio 1
	v_mfma_f32_16x16x32_bf16 v[118:121], v[162:165], v[186:189], v[118:121]
	v_mfma_f32_16x16x32_bf16 v[102:105], v[162:165], v[194:197], v[102:105]
	v_mfma_f32_16x16x32_bf16 v[86:89], v[162:165], v[202:205], v[86:89]
	v_mfma_f32_16x16x32_bf16 v[70:73], v[162:165], v[210:213], v[70:73]
	v_mfma_f32_16x16x32_bf16 v[114:117], v[170:173], v[186:189], v[114:117]
	v_mfma_f32_16x16x32_bf16 v[98:101], v[170:173], v[194:197], v[98:101]
	v_mfma_f32_16x16x32_bf16 v[82:85], v[170:173], v[202:205], v[82:85]
	v_mfma_f32_16x16x32_bf16 v[66:69], v[170:173], v[210:213], v[66:69]
	v_mfma_f32_16x16x32_bf16 v[118:121], v[166:169], v[190:193], v[118:121]
	v_mfma_f32_16x16x32_bf16 v[102:105], v[166:169], v[198:201], v[102:105]
	v_mfma_f32_16x16x32_bf16 v[86:89], v[166:169], v[206:209], v[86:89]
	v_mfma_f32_16x16x32_bf16 v[70:73], v[166:169], v[218:221], v[70:73]
	v_mfma_f32_16x16x32_bf16 v[114:117], v[182:185], v[190:193], v[114:117]
	v_mfma_f32_16x16x32_bf16 v[98:101], v[182:185], v[198:201], v[98:101]
	v_mfma_f32_16x16x32_bf16 v[82:85], v[182:185], v[206:209], v[82:85]
	v_mfma_f32_16x16x32_bf16 v[66:69], v[182:185], v[218:221], v[66:69]
	s_setprio 0
	s_barrier
	s_add_i32 s53, s61, s31
	v_lshl_add_u64 v[174:175], s[34:35], 0, v[148:149]
	s_mov_b32 m0, s53
	ds_read_b128 v[186:189], v180 offset:16384
	ds_read_b128 v[190:193], v180 offset:17408
	ds_read_b128 v[194:197], v180 offset:18432
	ds_read_b128 v[198:201], v180 offset:19456
	ds_read_b128 v[202:205], v180 offset:20480
	ds_read_b128 v[206:209], v180 offset:21504
	ds_read_b128 v[210:213], v180 offset:22528
	ds_read_b128 v[218:221], v180 offset:23552
	global_load_lds_dwordx4 v[174:175], off
	s_add_i32 m0, s53, 0x2000
	s_add_u32 s54, s34, 0x160000
	v_lshl_add_u64 v[214:215], s[34:35], 0, v[152:153]
	s_addc_u32 s55, s35, 0
	s_add_i32 s53, s70, s31
	global_load_lds_dwordx4 v[214:215], off
	v_lshl_add_u64 v[222:223], s[54:55], 0, v[148:149]
	s_mov_b32 m0, s53
	v_lshl_add_u64 v[224:225], s[40:41], 0, v[150:151]
	global_load_lds_dwordx4 v[222:223], off
	v_lshl_add_u64 v[222:223], s[54:55], 0, v[152:153]
	s_add_i32 m0, s53, 0x2000
	s_nop 0
	global_load_lds_dwordx4 v[222:223], off
	v_lshl_add_u64 v[222:223], s[40:41], 0, v[146:147]
	s_mov_b32 m0, s33
	s_nop 0
	global_load_lds_dwordx4 v[222:223], off
	s_mov_b32 m0, s46
	s_nop 0
	global_load_lds_dwordx4 v[224:225], off
	s_waitcnt vmcnt(8)
	s_waitcnt lgkmcnt(0)
	s_barrier
	s_setprio 1
	s_waitcnt lgkmcnt(0)
	v_mfma_f32_16x16x32_bf16 v[62:65], v[130:133], v[186:189], v[62:65]
	v_mfma_f32_16x16x32_bf16 v[50:53], v[130:133], v[194:197], v[50:53]
	v_mfma_f32_16x16x32_bf16 v[38:41], v[130:133], v[202:205], v[38:41]
	v_mfma_f32_16x16x32_bf16 v[14:17], v[130:133], v[210:213], v[14:17]
	v_mfma_f32_16x16x32_bf16 v[58:61], v[138:141], v[186:189], v[58:61]
	v_mfma_f32_16x16x32_bf16 v[42:45], v[138:141], v[194:197], v[42:45]
	v_mfma_f32_16x16x32_bf16 v[34:37], v[138:141], v[202:205], v[34:37]
	v_mfma_f32_16x16x32_bf16 v[10:13], v[138:141], v[210:213], v[10:13]
	v_mfma_f32_16x16x32_bf16 v[62:65], v[134:137], v[190:193], v[62:65]
	v_mfma_f32_16x16x32_bf16 v[50:53], v[134:137], v[198:201], v[50:53]
	v_mfma_f32_16x16x32_bf16 v[38:41], v[134:137], v[206:209], v[38:41]
	v_mfma_f32_16x16x32_bf16 v[14:17], v[134:137], v[218:221], v[14:17]
	v_mfma_f32_16x16x32_bf16 v[58:61], v[142:145], v[190:193], v[58:61]
	v_mfma_f32_16x16x32_bf16 v[42:45], v[142:145], v[198:201], v[42:45]
	v_mfma_f32_16x16x32_bf16 v[34:37], v[142:145], v[206:209], v[34:37]
	v_mfma_f32_16x16x32_bf16 v[10:13], v[142:145], v[218:221], v[10:13]
	s_setprio 0
	s_setprio 1
	v_mfma_f32_16x16x32_bf16 v[54:57], v[162:165], v[186:189], v[54:57]
	v_mfma_f32_16x16x32_bf16 v[30:33], v[162:165], v[194:197], v[30:33]
	v_mfma_f32_16x16x32_bf16 v[22:25], v[162:165], v[202:205], v[22:25]
	v_mfma_f32_16x16x32_bf16 v[6:9], v[162:165], v[210:213], v[6:9]
	v_mfma_f32_16x16x32_bf16 v[46:49], v[170:173], v[186:189], v[46:49]
	v_mfma_f32_16x16x32_bf16 v[26:29], v[170:173], v[194:197], v[26:29]
	v_mfma_f32_16x16x32_bf16 v[18:21], v[170:173], v[202:205], v[18:21]
	v_mfma_f32_16x16x32_bf16 v[2:5], v[170:173], v[210:213], v[2:5]
	v_mfma_f32_16x16x32_bf16 v[54:57], v[166:169], v[190:193], v[54:57]
	v_mfma_f32_16x16x32_bf16 v[30:33], v[166:169], v[198:201], v[30:33]
	v_mfma_f32_16x16x32_bf16 v[22:25], v[166:169], v[206:209], v[22:25]
	v_mfma_f32_16x16x32_bf16 v[6:9], v[166:169], v[218:221], v[6:9]
	v_mfma_f32_16x16x32_bf16 v[46:49], v[182:185], v[190:193], v[46:49]
	v_mfma_f32_16x16x32_bf16 v[26:29], v[182:185], v[198:201], v[26:29]
	v_mfma_f32_16x16x32_bf16 v[18:21], v[182:185], v[206:209], v[18:21]
	v_mfma_f32_16x16x32_bf16 v[2:5], v[182:185], v[218:221], v[2:5]
	s_setprio 0
	s_barrier
	s_add_i32 s53, 0, 0x18000
	s_add_i32 s54, 0, 0x1c000
	v_add_u32_e32 v142, s53, v176
	v_add_u32_e32 v181, s54, v176
	ds_read_b128 v[130:133], v142
	ds_read_b128 v[134:137], v142 offset:1024
	ds_read_b128 v[138:141], v142 offset:2048
	ds_read_b128 v[142:145], v142 offset:3072
	ds_read_b128 v[162:165], v181
	ds_read_b128 v[166:169], v181 offset:1024
	ds_read_b128 v[170:173], v181 offset:2048
	ds_read_b128 v[182:185], v181 offset:3072
	s_add_u32 s40, s40, 0x160000
	s_addc_u32 s41, s41, 0
	s_mov_b32 m0, s47
	v_lshl_add_u64 v[226:227], s[40:41], 0, v[146:147]
	ds_read_b128 v[186:189], v180 offset:32768
	ds_read_b128 v[190:193], v180 offset:33792
	ds_read_b128 v[194:197], v180 offset:34816
	ds_read_b128 v[198:201], v180 offset:35840
	ds_read_b128 v[202:205], v180 offset:36864
	ds_read_b128 v[206:209], v180 offset:37888
	ds_read_b128 v[210:213], v180 offset:38912
	ds_read_b128 v[218:221], v180 offset:39936
	global_load_lds_dwordx4 v[226:227], off
	v_lshl_add_u64 v[226:227], s[40:41], 0, v[150:151]
	s_mov_b32 m0, s56
	s_nop 0
	global_load_lds_dwordx4 v[226:227], off
	s_waitcnt vmcnt(8)
	s_waitcnt lgkmcnt(0)
	s_barrier
	s_setprio 1
	s_waitcnt lgkmcnt(0)
	v_mfma_f32_16x16x32_bf16 v[126:129], v[130:133], v[186:189], v[126:129]
	v_mfma_f32_16x16x32_bf16 v[110:113], v[130:133], v[194:197], v[110:113]
	v_mfma_f32_16x16x32_bf16 v[94:97], v[130:133], v[202:205], v[94:97]
	v_mfma_f32_16x16x32_bf16 v[78:81], v[130:133], v[210:213], v[78:81]
	v_mfma_f32_16x16x32_bf16 v[122:125], v[138:141], v[186:189], v[122:125]
	v_mfma_f32_16x16x32_bf16 v[106:109], v[138:141], v[194:197], v[106:109]
	v_mfma_f32_16x16x32_bf16 v[90:93], v[138:141], v[202:205], v[90:93]
	v_mfma_f32_16x16x32_bf16 v[74:77], v[138:141], v[210:213], v[74:77]
	v_mfma_f32_16x16x32_bf16 v[126:129], v[134:137], v[190:193], v[126:129]
	v_mfma_f32_16x16x32_bf16 v[110:113], v[134:137], v[198:201], v[110:113]
	v_mfma_f32_16x16x32_bf16 v[94:97], v[134:137], v[206:209], v[94:97]
	v_mfma_f32_16x16x32_bf16 v[78:81], v[134:137], v[218:221], v[78:81]
	v_mfma_f32_16x16x32_bf16 v[122:125], v[142:145], v[190:193], v[122:125]
	v_mfma_f32_16x16x32_bf16 v[106:109], v[142:145], v[198:201], v[106:109]
	v_mfma_f32_16x16x32_bf16 v[90:93], v[142:145], v[206:209], v[90:93]
	v_mfma_f32_16x16x32_bf16 v[74:77], v[142:145], v[218:221], v[74:77]
	s_setprio 0
	s_setprio 1
	v_mfma_f32_16x16x32_bf16 v[118:121], v[162:165], v[186:189], v[118:121]
	v_mfma_f32_16x16x32_bf16 v[102:105], v[162:165], v[194:197], v[102:105]
	v_mfma_f32_16x16x32_bf16 v[86:89], v[162:165], v[202:205], v[86:89]
	v_mfma_f32_16x16x32_bf16 v[70:73], v[162:165], v[210:213], v[70:73]
	v_mfma_f32_16x16x32_bf16 v[114:117], v[170:173], v[186:189], v[114:117]
	v_mfma_f32_16x16x32_bf16 v[98:101], v[170:173], v[194:197], v[98:101]
	v_mfma_f32_16x16x32_bf16 v[82:85], v[170:173], v[202:205], v[82:85]
	v_mfma_f32_16x16x32_bf16 v[66:69], v[170:173], v[210:213], v[66:69]
	v_mfma_f32_16x16x32_bf16 v[118:121], v[166:169], v[190:193], v[118:121]
	v_mfma_f32_16x16x32_bf16 v[102:105], v[166:169], v[198:201], v[102:105]
	v_mfma_f32_16x16x32_bf16 v[86:89], v[166:169], v[206:209], v[86:89]
	v_mfma_f32_16x16x32_bf16 v[70:73], v[166:169], v[218:221], v[70:73]
	v_mfma_f32_16x16x32_bf16 v[114:117], v[182:185], v[190:193], v[114:117]
	v_mfma_f32_16x16x32_bf16 v[98:101], v[182:185], v[198:201], v[98:101]
	v_mfma_f32_16x16x32_bf16 v[82:85], v[182:185], v[206:209], v[82:85]
	v_mfma_f32_16x16x32_bf16 v[66:69], v[182:185], v[218:221], v[66:69]
	s_setprio 0
	s_barrier
	s_add_i32 s40, s53, s31
	v_lshl_add_u64 v[174:175], v[174:175], 0, s[24:25]
	s_mov_b32 m0, s40
	ds_read_b128 v[186:189], v180 offset:49152
	ds_read_b128 v[190:193], v180 offset:50176
	ds_read_b128 v[194:197], v180 offset:51200
	ds_read_b128 v[198:201], v180 offset:52224
	ds_read_b128 v[202:205], v180 offset:53248
	ds_read_b128 v[206:209], v180 offset:54272
	ds_read_b128 v[210:213], v180 offset:55296
	ds_read_b128 v[218:221], v180 offset:56320
	global_load_lds_dwordx4 v[174:175], off
	s_add_i32 m0, s40, 0x2000
	s_add_u32 s34, s34, 0x160080
	v_lshl_add_u64 v[174:175], v[214:215], 0, s[24:25]
	s_addc_u32 s35, s35, 0
	s_add_i32 s40, s54, s31
	global_load_lds_dwordx4 v[174:175], off
	v_lshl_add_u64 v[174:175], s[34:35], 0, v[148:149]
	s_mov_b32 m0, s40
	s_nop 0
	global_load_lds_dwordx4 v[174:175], off
	v_lshl_add_u64 v[174:175], s[34:35], 0, v[152:153]
	s_add_i32 m0, s40, 0x2000
	s_nop 0
	global_load_lds_dwordx4 v[174:175], off
	v_lshl_add_u64 v[174:175], v[222:223], 0, s[24:25]
	s_mov_b32 m0, s58
	s_nop 0
	global_load_lds_dwordx4 v[174:175], off
	v_lshl_add_u64 v[174:175], v[224:225], 0, s[24:25]
	s_mov_b32 m0, s59
	s_nop 0
	global_load_lds_dwordx4 v[174:175], off
	s_waitcnt vmcnt(8)
	s_waitcnt lgkmcnt(0)
	s_barrier
	s_setprio 1
	s_waitcnt lgkmcnt(0)
	v_mfma_f32_16x16x32_bf16 v[62:65], v[130:133], v[186:189], v[62:65]
	v_mfma_f32_16x16x32_bf16 v[50:53], v[130:133], v[194:197], v[50:53]
	v_mfma_f32_16x16x32_bf16 v[38:41], v[130:133], v[202:205], v[38:41]
	v_mfma_f32_16x16x32_bf16 v[14:17], v[130:133], v[210:213], v[14:17]
	v_mfma_f32_16x16x32_bf16 v[58:61], v[138:141], v[186:189], v[58:61]
	v_mfma_f32_16x16x32_bf16 v[42:45], v[138:141], v[194:197], v[42:45]
	v_mfma_f32_16x16x32_bf16 v[34:37], v[138:141], v[202:205], v[34:37]
	v_mfma_f32_16x16x32_bf16 v[10:13], v[138:141], v[210:213], v[10:13]
	v_mfma_f32_16x16x32_bf16 v[62:65], v[134:137], v[190:193], v[62:65]
	v_mfma_f32_16x16x32_bf16 v[50:53], v[134:137], v[198:201], v[50:53]
	v_mfma_f32_16x16x32_bf16 v[38:41], v[134:137], v[206:209], v[38:41]
	v_mfma_f32_16x16x32_bf16 v[14:17], v[134:137], v[218:221], v[14:17]
	v_mfma_f32_16x16x32_bf16 v[58:61], v[142:145], v[190:193], v[58:61]
	v_mfma_f32_16x16x32_bf16 v[42:45], v[142:145], v[198:201], v[42:45]
	v_mfma_f32_16x16x32_bf16 v[34:37], v[142:145], v[206:209], v[34:37]
	v_mfma_f32_16x16x32_bf16 v[10:13], v[142:145], v[218:221], v[10:13]
	s_setprio 0
	s_setprio 1
	v_mfma_f32_16x16x32_bf16 v[54:57], v[162:165], v[186:189], v[54:57]
	v_mfma_f32_16x16x32_bf16 v[30:33], v[162:165], v[194:197], v[30:33]
	v_mfma_f32_16x16x32_bf16 v[22:25], v[162:165], v[202:205], v[22:25]
	v_mfma_f32_16x16x32_bf16 v[6:9], v[162:165], v[210:213], v[6:9]
	v_mfma_f32_16x16x32_bf16 v[46:49], v[170:173], v[186:189], v[46:49]
	v_mfma_f32_16x16x32_bf16 v[26:29], v[170:173], v[194:197], v[26:29]
	v_mfma_f32_16x16x32_bf16 v[18:21], v[170:173], v[202:205], v[18:21]
	v_mfma_f32_16x16x32_bf16 v[2:5], v[170:173], v[210:213], v[2:5]
	v_mfma_f32_16x16x32_bf16 v[54:57], v[166:169], v[190:193], v[54:57]
	v_mfma_f32_16x16x32_bf16 v[30:33], v[166:169], v[198:201], v[30:33]
	v_mfma_f32_16x16x32_bf16 v[22:25], v[166:169], v[206:209], v[22:25]
	v_mfma_f32_16x16x32_bf16 v[6:9], v[166:169], v[218:221], v[6:9]
	v_mfma_f32_16x16x32_bf16 v[46:49], v[182:185], v[190:193], v[46:49]
	v_mfma_f32_16x16x32_bf16 v[26:29], v[182:185], v[198:201], v[26:29]
	v_mfma_f32_16x16x32_bf16 v[18:21], v[182:185], v[206:209], v[18:21]
	v_mfma_f32_16x16x32_bf16 v[2:5], v[182:185], v[218:221], v[2:5]
	s_setprio 0
	s_barrier
	s_add_i32 s52, s52, 2
	s_add_u32 s38, s38, 0x100
	s_addc_u32 s39, s39, 0
	s_add_u32 s0, s0, 0x100
	s_addc_u32 s1, s1, 0
	s_cmpk_gt_u32 s52, 0x55
	s_cbranch_scc0 .LBB0_2089
	s_and_b64 vcc, exec, s[26:27]
	s_cbranch_vccz .LBB0_2092
	s_barrier

.LBB0_2218:
	ds_read_b128 v[146:149], v153
	ds_read_b128 v[156:159], v153 offset:1024
	ds_read_b128 v[160:163], v153 offset:2048
	ds_read_b128 v[164:167], v153 offset:3072
	ds_read_b128 v[168:171], v154
	ds_read_b128 v[172:175], v154 offset:1024
	ds_read_b128 v[176:179], v154 offset:2048
	ds_read_b128 v[180:183], v154 offset:3072
	s_add_u32 s34, s76, 0xfff80080
	s_addc_u32 s35, s77, -1
	s_cmp_eq_u32 s80, 28
	s_cselect_b32 s79, s0, s35
	s_cselect_b32 s78, s1, s34
	s_cselect_b32 s35, s27, s75
	s_cselect_b32 s34, s37, s52
	v_lshl_add_u64 v[218:219], s[76:77], 0, v[138:139]
	s_add_i32 m0, s47, 0xc000
	ds_read_b128 v[184:187], v155
	ds_read_b128 v[188:191], v155 offset:1024
	ds_read_b128 v[192:195], v155 offset:2048
	ds_read_b128 v[196:199], v155 offset:3072
	ds_read_b128 v[200:203], v155 offset:4096
	ds_read_b128 v[204:207], v155 offset:5120
	ds_read_b128 v[208:211], v155 offset:6144
	ds_read_b128 v[212:215], v155 offset:7168
	global_load_lds_dwordx4 v[218:219], off
	v_lshl_add_u64 v[218:219], s[76:77], 0, v[140:141]
	s_add_i32 m0, s47, 0xe000
	s_nop 0
	global_load_lds_dwordx4 v[218:219], off
	s_waitcnt vmcnt(8)
	s_waitcnt lgkmcnt(0)
	s_barrier
	s_setprio 1
	s_waitcnt lgkmcnt(0)
	v_mfma_f32_16x16x32_bf16 v[126:129], v[146:149], v[184:187], v[126:129]
	v_mfma_f32_16x16x32_bf16 v[110:113], v[146:149], v[192:195], v[110:113]
	v_mfma_f32_16x16x32_bf16 v[94:97], v[146:149], v[200:203], v[94:97]
	v_mfma_f32_16x16x32_bf16 v[78:81], v[146:149], v[208:211], v[78:81]
	v_mfma_f32_16x16x32_bf16 v[118:121], v[160:163], v[184:187], v[118:121]
	v_mfma_f32_16x16x32_bf16 v[102:105], v[160:163], v[192:195], v[102:105]
	v_mfma_f32_16x16x32_bf16 v[86:89], v[160:163], v[200:203], v[86:89]
	v_mfma_f32_16x16x32_bf16 v[70:73], v[160:163], v[208:211], v[70:73]
	v_mfma_f32_16x16x32_bf16 v[126:129], v[156:159], v[188:191], v[126:129]
	v_mfma_f32_16x16x32_bf16 v[110:113], v[156:159], v[196:199], v[110:113]
	v_mfma_f32_16x16x32_bf16 v[94:97], v[156:159], v[204:207], v[94:97]
	v_mfma_f32_16x16x32_bf16 v[78:81], v[156:159], v[212:215], v[78:81]
	v_mfma_f32_16x16x32_bf16 v[118:121], v[164:167], v[188:191], v[118:121]
	v_mfma_f32_16x16x32_bf16 v[102:105], v[164:167], v[196:199], v[102:105]
	v_mfma_f32_16x16x32_bf16 v[86:89], v[164:167], v[204:207], v[86:89]
	v_mfma_f32_16x16x32_bf16 v[70:73], v[164:167], v[212:215], v[70:73]
	s_setprio 0
	s_setprio 1
	v_mfma_f32_16x16x32_bf16 v[122:125], v[168:171], v[184:187], v[122:125]
	v_mfma_f32_16x16x32_bf16 v[106:109], v[168:171], v[192:195], v[106:109]
	v_mfma_f32_16x16x32_bf16 v[90:93], v[168:171], v[200:203], v[90:93]
	v_mfma_f32_16x16x32_bf16 v[74:77], v[168:171], v[208:211], v[74:77]
	v_mfma_f32_16x16x32_bf16 v[114:117], v[176:179], v[184:187], v[114:117]
	v_mfma_f32_16x16x32_bf16 v[98:101], v[176:179], v[192:195], v[98:101]
	v_mfma_f32_16x16x32_bf16 v[82:85], v[176:179], v[200:203], v[82:85]
	v_mfma_f32_16x16x32_bf16 v[66:69], v[176:179], v[208:211], v[66:69]
	v_mfma_f32_16x16x32_bf16 v[122:125], v[172:175], v[188:191], v[122:125]
	v_mfma_f32_16x16x32_bf16 v[106:109], v[172:175], v[196:199], v[106:109]
	v_mfma_f32_16x16x32_bf16 v[90:93], v[172:175], v[204:207], v[90:93]
	v_mfma_f32_16x16x32_bf16 v[74:77], v[172:175], v[212:215], v[74:77]
	v_mfma_f32_16x16x32_bf16 v[114:117], v[180:183], v[188:191], v[114:117]
	v_mfma_f32_16x16x32_bf16 v[98:101], v[180:183], v[196:199], v[98:101]
	v_mfma_f32_16x16x32_bf16 v[82:85], v[180:183], v[204:207], v[82:85]
	v_mfma_f32_16x16x32_bf16 v[66:69], v[180:183], v[212:215], v[66:69]
	s_setprio 0
	s_barrier
	s_add_i32 s53, s71, s30
	v_lshl_add_u64 v[218:219], s[34:35], 0, v[134:135]
	s_mov_b32 m0, s53
	ds_read_b128 v[184:187], v155 offset:16384
	ds_read_b128 v[188:191], v155 offset:17408
	ds_read_b128 v[192:195], v155 offset:18432
	ds_read_b128 v[196:199], v155 offset:19456
	ds_read_b128 v[200:203], v155 offset:20480
	ds_read_b128 v[204:207], v155 offset:21504
	ds_read_b128 v[208:211], v155 offset:22528
	ds_read_b128 v[212:215], v155 offset:23552
	global_load_lds_dwordx4 v[218:219], off
	s_add_i32 m0, s53, 0x2000
	s_add_u32 s54, s34, 0x80000
	v_lshl_add_u64 v[220:221], s[34:35], 0, v[130:131]
	s_addc_u32 s55, s35, 0
	s_add_i32 s53, s72, s30
	global_load_lds_dwordx4 v[220:221], off
	v_lshl_add_u64 v[222:223], s[54:55], 0, v[134:135]
	s_mov_b32 m0, s53
	v_lshl_add_u64 v[224:225], s[78:79], 0, v[132:133]
	global_load_lds_dwordx4 v[222:223], off
	v_lshl_add_u64 v[222:223], s[54:55], 0, v[130:131]
	s_add_i32 m0, s53, 0x2000
	s_nop 0
	global_load_lds_dwordx4 v[222:223], off
	v_lshl_add_u64 v[222:223], s[78:79], 0, v[136:137]
	s_mov_b32 m0, s47
	s_nop 0
	global_load_lds_dwordx4 v[222:223], off
	s_mov_b32 m0, s56
	s_nop 0
	global_load_lds_dwordx4 v[224:225], off
	s_waitcnt vmcnt(8)
	s_waitcnt lgkmcnt(0)
	s_barrier
	s_setprio 1
	s_waitcnt lgkmcnt(0)
	v_mfma_f32_16x16x32_bf16 v[62:65], v[146:149], v[184:187], v[62:65]
	v_mfma_f32_16x16x32_bf16 v[46:49], v[146:149], v[192:195], v[46:49]
	v_mfma_f32_16x16x32_bf16 v[30:33], v[146:149], v[200:203], v[30:33]
	v_mfma_f32_16x16x32_bf16 v[14:17], v[146:149], v[208:211], v[14:17]
	v_mfma_f32_16x16x32_bf16 v[54:57], v[160:163], v[184:187], v[54:57]
	v_mfma_f32_16x16x32_bf16 v[38:41], v[160:163], v[192:195], v[38:41]
	v_mfma_f32_16x16x32_bf16 v[22:25], v[160:163], v[200:203], v[22:25]
	v_mfma_f32_16x16x32_bf16 v[6:9], v[160:163], v[208:211], v[6:9]
	v_mfma_f32_16x16x32_bf16 v[62:65], v[156:159], v[188:191], v[62:65]
	v_mfma_f32_16x16x32_bf16 v[46:49], v[156:159], v[196:199], v[46:49]
	v_mfma_f32_16x16x32_bf16 v[30:33], v[156:159], v[204:207], v[30:33]
	v_mfma_f32_16x16x32_bf16 v[14:17], v[156:159], v[212:215], v[14:17]
	v_mfma_f32_16x16x32_bf16 v[54:57], v[164:167], v[188:191], v[54:57]
	v_mfma_f32_16x16x32_bf16 v[38:41], v[164:167], v[196:199], v[38:41]
	v_mfma_f32_16x16x32_bf16 v[22:25], v[164:167], v[204:207], v[22:25]
	v_mfma_f32_16x16x32_bf16 v[6:9], v[164:167], v[212:215], v[6:9]
	s_setprio 0
	s_setprio 1
	v_mfma_f32_16x16x32_bf16 v[58:61], v[168:171], v[184:187], v[58:61]
	v_mfma_f32_16x16x32_bf16 v[42:45], v[168:171], v[192:195], v[42:45]
	v_mfma_f32_16x16x32_bf16 v[26:29], v[168:171], v[200:203], v[26:29]
	v_mfma_f32_16x16x32_bf16 v[10:13], v[168:171], v[208:211], v[10:13]
	v_mfma_f32_16x16x32_bf16 v[50:53], v[176:179], v[184:187], v[50:53]
	v_mfma_f32_16x16x32_bf16 v[34:37], v[176:179], v[192:195], v[34:37]
	v_mfma_f32_16x16x32_bf16 v[18:21], v[176:179], v[200:203], v[18:21]
	v_mfma_f32_16x16x32_bf16 v[2:5], v[176:179], v[208:211], v[2:5]
	v_mfma_f32_16x16x32_bf16 v[58:61], v[172:175], v[188:191], v[58:61]
	v_mfma_f32_16x16x32_bf16 v[42:45], v[172:175], v[196:199], v[42:45]
	v_mfma_f32_16x16x32_bf16 v[26:29], v[172:175], v[204:207], v[26:29]
	v_mfma_f32_16x16x32_bf16 v[10:13], v[172:175], v[212:215], v[10:13]
	v_mfma_f32_16x16x32_bf16 v[50:53], v[180:183], v[188:191], v[50:53]
	v_mfma_f32_16x16x32_bf16 v[34:37], v[180:183], v[196:199], v[34:37]
	v_mfma_f32_16x16x32_bf16 v[18:21], v[180:183], v[204:207], v[18:21]
	v_mfma_f32_16x16x32_bf16 v[2:5], v[180:183], v[212:215], v[2:5]
	s_setprio 0
	s_barrier
	s_add_i32 s53, 0, 0x18000
	s_add_i32 s62, 0, 0x1c000
	v_add_u32_e32 v164, s53, v151
	v_add_u32_e32 v180, s62, v151
	ds_read_b128 v[146:149], v164
	ds_read_b128 v[156:159], v164 offset:1024
	ds_read_b128 v[160:163], v164 offset:2048
	ds_read_b128 v[164:167], v164 offset:3072
	ds_read_b128 v[168:171], v180
	ds_read_b128 v[172:175], v180 offset:1024
	ds_read_b128 v[176:179], v180 offset:2048
	ds_read_b128 v[180:183], v180 offset:3072
	s_add_u32 s54, s78, 0x80000
	s_addc_u32 s55, s79, 0
	s_mov_b32 m0, s57
	v_lshl_add_u64 v[226:227], s[54:55], 0, v[136:137]
	ds_read_b128 v[184:187], v155 offset:32768
	ds_read_b128 v[188:191], v155 offset:33792
	ds_read_b128 v[192:195], v155 offset:34816
	ds_read_b128 v[196:199], v155 offset:35840
	ds_read_b128 v[200:203], v155 offset:36864
	ds_read_b128 v[204:207], v155 offset:37888
	ds_read_b128 v[208:211], v155 offset:38912
	ds_read_b128 v[212:215], v155 offset:39936
	global_load_lds_dwordx4 v[226:227], off
	v_lshl_add_u64 v[226:227], s[54:55], 0, v[132:133]
	s_mov_b32 m0, s58
	s_nop 0
	global_load_lds_dwordx4 v[226:227], off
	s_waitcnt vmcnt(8)
	s_waitcnt lgkmcnt(0)
	s_barrier
	s_setprio 1
	s_waitcnt lgkmcnt(0)
	v_mfma_f32_16x16x32_bf16 v[126:129], v[146:149], v[184:187], v[126:129]
	v_mfma_f32_16x16x32_bf16 v[110:113], v[146:149], v[192:195], v[110:113]
	v_mfma_f32_16x16x32_bf16 v[94:97], v[146:149], v[200:203], v[94:97]
	v_mfma_f32_16x16x32_bf16 v[78:81], v[146:149], v[208:211], v[78:81]
	v_mfma_f32_16x16x32_bf16 v[118:121], v[160:163], v[184:187], v[118:121]
	v_mfma_f32_16x16x32_bf16 v[102:105], v[160:163], v[192:195], v[102:105]
	v_mfma_f32_16x16x32_bf16 v[86:89], v[160:163], v[200:203], v[86:89]
	v_mfma_f32_16x16x32_bf16 v[70:73], v[160:163], v[208:211], v[70:73]
	v_mfma_f32_16x16x32_bf16 v[126:129], v[156:159], v[188:191], v[126:129]
	v_mfma_f32_16x16x32_bf16 v[110:113], v[156:159], v[196:199], v[110:113]
	v_mfma_f32_16x16x32_bf16 v[94:97], v[156:159], v[204:207], v[94:97]
	v_mfma_f32_16x16x32_bf16 v[78:81], v[156:159], v[212:215], v[78:81]
	v_mfma_f32_16x16x32_bf16 v[118:121], v[164:167], v[188:191], v[118:121]
	v_mfma_f32_16x16x32_bf16 v[102:105], v[164:167], v[196:199], v[102:105]
	v_mfma_f32_16x16x32_bf16 v[86:89], v[164:167], v[204:207], v[86:89]
	v_mfma_f32_16x16x32_bf16 v[70:73], v[164:167], v[212:215], v[70:73]
	s_setprio 0
	s_setprio 1
	v_mfma_f32_16x16x32_bf16 v[122:125], v[168:171], v[184:187], v[122:125]
	v_mfma_f32_16x16x32_bf16 v[106:109], v[168:171], v[192:195], v[106:109]
	v_mfma_f32_16x16x32_bf16 v[90:93], v[168:171], v[200:203], v[90:93]
	v_mfma_f32_16x16x32_bf16 v[74:77], v[168:171], v[208:211], v[74:77]
	v_mfma_f32_16x16x32_bf16 v[114:117], v[176:179], v[184:187], v[114:117]
	v_mfma_f32_16x16x32_bf16 v[98:101], v[176:179], v[192:195], v[98:101]
	v_mfma_f32_16x16x32_bf16 v[82:85], v[176:179], v[200:203], v[82:85]
	v_mfma_f32_16x16x32_bf16 v[66:69], v[176:179], v[208:211], v[66:69]
	v_mfma_f32_16x16x32_bf16 v[122:125], v[172:175], v[188:191], v[122:125]
	v_mfma_f32_16x16x32_bf16 v[106:109], v[172:175], v[196:199], v[106:109]
	v_mfma_f32_16x16x32_bf16 v[90:93], v[172:175], v[204:207], v[90:93]
	v_mfma_f32_16x16x32_bf16 v[74:77], v[172:175], v[212:215], v[74:77]
	v_mfma_f32_16x16x32_bf16 v[114:117], v[180:183], v[188:191], v[114:117]
	v_mfma_f32_16x16x32_bf16 v[98:101], v[180:183], v[196:199], v[98:101]
	v_mfma_f32_16x16x32_bf16 v[82:85], v[180:183], v[204:207], v[82:85]
	v_mfma_f32_16x16x32_bf16 v[66:69], v[180:183], v[212:215], v[66:69]
	s_setprio 0
	s_barrier
	s_add_i32 s53, s53, s30
	v_lshl_add_u64 v[218:219], v[218:219], 0, s[8:9]
	s_mov_b32 m0, s53
	ds_read_b128 v[184:187], v155 offset:49152
	ds_read_b128 v[188:191], v155 offset:50176
	ds_read_b128 v[192:195], v155 offset:51200
	ds_read_b128 v[196:199], v155 offset:52224
	ds_read_b128 v[200:203], v155 offset:53248
	ds_read_b128 v[204:207], v155 offset:54272
	ds_read_b128 v[208:211], v155 offset:55296
	ds_read_b128 v[212:215], v155 offset:56320
	global_load_lds_dwordx4 v[218:219], off
	s_add_i32 m0, s53, 0x2000
	s_add_u32 s34, s34, 0x80080
	v_lshl_add_u64 v[218:219], v[220:221], 0, s[8:9]
	s_addc_u32 s35, s35, 0
	s_add_i32 s53, s62, s30
	global_load_lds_dwordx4 v[218:219], off
	v_lshl_add_u64 v[218:219], s[34:35], 0, v[134:135]
	s_mov_b32 m0, s53
	s_nop 0
	global_load_lds_dwordx4 v[218:219], off
	v_lshl_add_u64 v[218:219], s[34:35], 0, v[130:131]
	s_add_i32 m0, s53, 0x2000
	s_nop 0
	global_load_lds_dwordx4 v[218:219], off
	v_lshl_add_u64 v[218:219], v[222:223], 0, s[8:9]
	s_mov_b32 m0, s60
	s_nop 0
	global_load_lds_dwordx4 v[218:219], off
	v_lshl_add_u64 v[218:219], v[224:225], 0, s[8:9]
	s_mov_b32 m0, s61
	s_nop 0
	global_load_lds_dwordx4 v[218:219], off
	s_waitcnt vmcnt(8)
	s_waitcnt lgkmcnt(0)
	s_barrier
	s_setprio 1
	s_waitcnt lgkmcnt(0)
	v_mfma_f32_16x16x32_bf16 v[62:65], v[146:149], v[184:187], v[62:65]
	v_mfma_f32_16x16x32_bf16 v[46:49], v[146:149], v[192:195], v[46:49]
	v_mfma_f32_16x16x32_bf16 v[30:33], v[146:149], v[200:203], v[30:33]
	v_mfma_f32_16x16x32_bf16 v[14:17], v[146:149], v[208:211], v[14:17]
	v_mfma_f32_16x16x32_bf16 v[54:57], v[160:163], v[184:187], v[54:57]
	v_mfma_f32_16x16x32_bf16 v[38:41], v[160:163], v[192:195], v[38:41]
	v_mfma_f32_16x16x32_bf16 v[22:25], v[160:163], v[200:203], v[22:25]
	v_mfma_f32_16x16x32_bf16 v[6:9], v[160:163], v[208:211], v[6:9]
	v_mfma_f32_16x16x32_bf16 v[62:65], v[156:159], v[188:191], v[62:65]
	v_mfma_f32_16x16x32_bf16 v[46:49], v[156:159], v[196:199], v[46:49]
	v_mfma_f32_16x16x32_bf16 v[30:33], v[156:159], v[204:207], v[30:33]
	v_mfma_f32_16x16x32_bf16 v[14:17], v[156:159], v[212:215], v[14:17]
	v_mfma_f32_16x16x32_bf16 v[54:57], v[164:167], v[188:191], v[54:57]
	v_mfma_f32_16x16x32_bf16 v[38:41], v[164:167], v[196:199], v[38:41]
	v_mfma_f32_16x16x32_bf16 v[22:25], v[164:167], v[204:207], v[22:25]
	v_mfma_f32_16x16x32_bf16 v[6:9], v[164:167], v[212:215], v[6:9]
	s_setprio 0
	s_setprio 1
	v_mfma_f32_16x16x32_bf16 v[58:61], v[168:171], v[184:187], v[58:61]
	v_mfma_f32_16x16x32_bf16 v[42:45], v[168:171], v[192:195], v[42:45]
	v_mfma_f32_16x16x32_bf16 v[26:29], v[168:171], v[200:203], v[26:29]
	v_mfma_f32_16x16x32_bf16 v[10:13], v[168:171], v[208:211], v[10:13]
	v_mfma_f32_16x16x32_bf16 v[50:53], v[176:179], v[184:187], v[50:53]
	v_mfma_f32_16x16x32_bf16 v[34:37], v[176:179], v[192:195], v[34:37]
	v_mfma_f32_16x16x32_bf16 v[18:21], v[176:179], v[200:203], v[18:21]
	v_mfma_f32_16x16x32_bf16 v[2:5], v[176:179], v[208:211], v[2:5]
	v_mfma_f32_16x16x32_bf16 v[58:61], v[172:175], v[188:191], v[58:61]
	v_mfma_f32_16x16x32_bf16 v[42:45], v[172:175], v[196:199], v[42:45]
	v_mfma_f32_16x16x32_bf16 v[26:29], v[172:175], v[204:207], v[26:29]
	v_mfma_f32_16x16x32_bf16 v[10:13], v[172:175], v[212:215], v[10:13]
	v_mfma_f32_16x16x32_bf16 v[50:53], v[180:183], v[188:191], v[50:53]
	v_mfma_f32_16x16x32_bf16 v[34:37], v[180:183], v[196:199], v[34:37]
	v_mfma_f32_16x16x32_bf16 v[18:21], v[180:183], v[204:207], v[18:21]
	v_mfma_f32_16x16x32_bf16 v[2:5], v[180:183], v[212:215], v[2:5]
	s_setprio 0
	s_barrier
	s_add_i32 s80, s80, 2
	s_add_u32 s76, s76, 0x100
	s_addc_u32 s77, s77, 0
	s_add_u32 s52, s52, 0x100
	s_addc_u32 s75, s75, 0
	s_cmp_gt_u32 s80, 29
	s_cbranch_scc0 .LBB0_2218
	s_and_b64 vcc, exec, s[24:25]
	s_cbranch_vccz .LBB0_2221
	s_barrier

.LBB0_2462:
	ds_read_b128 v[160:163], v155
	ds_read_b128 v[164:167], v155 offset:1024
	ds_read_b128 v[168:171], v155 offset:2048
	ds_read_b128 v[172:175], v155 offset:3072
	ds_read_b128 v[176:179], v156
	ds_read_b128 v[180:183], v156 offset:1024
	ds_read_b128 v[184:187], v156 offset:2048
	ds_read_b128 v[188:191], v156 offset:3072
	s_add_u32 s34, s76, 0xfff80080
	s_addc_u32 s35, s77, -1
	s_cmp_eq_u32 s74, 28
	s_cselect_b32 s89, s0, s35
	s_cselect_b32 s88, s1, s34
	s_cselect_b32 s35, s7, s52
	s_cselect_b32 s34, s9, s36
	v_lshl_add_u64 v[152:153], s[76:77], 0, v[144:145]
	s_add_i32 m0, s31, 0xc000
	ds_read_b128 v[192:195], v157
	ds_read_b128 v[196:199], v157 offset:1024
	ds_read_b128 v[200:203], v157 offset:2048
	ds_read_b128 v[204:207], v157 offset:3072
	ds_read_b128 v[208:211], v157 offset:4096
	ds_read_b128 v[212:215], v157 offset:5120
	ds_read_b128 v[218:221], v157 offset:6144
	ds_read_b128 v[222:225], v157 offset:7168
	global_load_lds_dwordx4 v[152:153], off
	v_lshl_add_u64 v[152:153], s[76:77], 0, v[146:147]
	s_add_i32 m0, s31, 0xe000
	s_nop 0
	global_load_lds_dwordx4 v[152:153], off
	s_waitcnt vmcnt(8)
	s_waitcnt lgkmcnt(0)
	s_barrier
	s_setprio 1
	s_waitcnt lgkmcnt(0)
	v_mfma_f32_16x16x32_bf16 v[126:129], v[160:163], v[192:195], v[126:129]
	v_mfma_f32_16x16x32_bf16 v[110:113], v[160:163], v[200:203], v[110:113]
	v_mfma_f32_16x16x32_bf16 v[94:97], v[160:163], v[208:211], v[94:97]
	v_mfma_f32_16x16x32_bf16 v[78:81], v[160:163], v[218:221], v[78:81]
	v_mfma_f32_16x16x32_bf16 v[122:125], v[168:171], v[192:195], v[122:125]
	v_mfma_f32_16x16x32_bf16 v[106:109], v[168:171], v[200:203], v[106:109]
	v_mfma_f32_16x16x32_bf16 v[90:93], v[168:171], v[208:211], v[90:93]
	v_mfma_f32_16x16x32_bf16 v[74:77], v[168:171], v[218:221], v[74:77]
	v_mfma_f32_16x16x32_bf16 v[126:129], v[164:167], v[196:199], v[126:129]
	v_mfma_f32_16x16x32_bf16 v[110:113], v[164:167], v[204:207], v[110:113]
	v_mfma_f32_16x16x32_bf16 v[94:97], v[164:167], v[212:215], v[94:97]
	v_mfma_f32_16x16x32_bf16 v[78:81], v[164:167], v[222:225], v[78:81]
	v_mfma_f32_16x16x32_bf16 v[122:125], v[172:175], v[196:199], v[122:125]
	v_mfma_f32_16x16x32_bf16 v[106:109], v[172:175], v[204:207], v[106:109]
	v_mfma_f32_16x16x32_bf16 v[90:93], v[172:175], v[212:215], v[90:93]
	v_mfma_f32_16x16x32_bf16 v[74:77], v[172:175], v[222:225], v[74:77]
	s_setprio 0
	s_setprio 1
	v_mfma_f32_16x16x32_bf16 v[118:121], v[176:179], v[192:195], v[118:121]
	v_mfma_f32_16x16x32_bf16 v[102:105], v[176:179], v[200:203], v[102:105]
	v_mfma_f32_16x16x32_bf16 v[86:89], v[176:179], v[208:211], v[86:89]
	v_mfma_f32_16x16x32_bf16 v[70:73], v[176:179], v[218:221], v[70:73]
	v_mfma_f32_16x16x32_bf16 v[114:117], v[184:187], v[192:195], v[114:117]
	v_mfma_f32_16x16x32_bf16 v[98:101], v[184:187], v[200:203], v[98:101]
	v_mfma_f32_16x16x32_bf16 v[82:85], v[184:187], v[208:211], v[82:85]
	v_mfma_f32_16x16x32_bf16 v[66:69], v[184:187], v[218:221], v[66:69]
	v_mfma_f32_16x16x32_bf16 v[118:121], v[180:183], v[196:199], v[118:121]
	v_mfma_f32_16x16x32_bf16 v[102:105], v[180:183], v[204:207], v[102:105]
	v_mfma_f32_16x16x32_bf16 v[86:89], v[180:183], v[212:215], v[86:89]
	v_mfma_f32_16x16x32_bf16 v[70:73], v[180:183], v[222:225], v[70:73]
	v_mfma_f32_16x16x32_bf16 v[114:117], v[188:191], v[196:199], v[114:117]
	v_mfma_f32_16x16x32_bf16 v[98:101], v[188:191], v[204:207], v[98:101]
	v_mfma_f32_16x16x32_bf16 v[82:85], v[188:191], v[212:215], v[82:85]
	v_mfma_f32_16x16x32_bf16 v[66:69], v[188:191], v[222:225], v[66:69]
	s_setprio 0
	s_barrier
	s_add_i32 s53, s71, s12
	v_lshl_add_u64 v[152:153], s[34:35], 0, v[132:133]
	s_mov_b32 m0, s53
	ds_read_b128 v[192:195], v157 offset:16384
	ds_read_b128 v[196:199], v157 offset:17408
	ds_read_b128 v[200:203], v157 offset:18432
	ds_read_b128 v[204:207], v157 offset:19456
	ds_read_b128 v[208:211], v157 offset:20480
	ds_read_b128 v[212:215], v157 offset:21504
	ds_read_b128 v[218:221], v157 offset:22528
	ds_read_b128 v[222:225], v157 offset:23552
	global_load_lds_dwordx4 v[152:153], off
	s_add_i32 m0, s53, 0x2000
	s_add_u32 s54, s34, 0x80000
	v_lshl_add_u64 v[226:227], s[34:35], 0, v[136:137]
	s_addc_u32 s55, s35, 0
	s_add_i32 s53, s72, s12
	global_load_lds_dwordx4 v[226:227], off
	v_lshl_add_u64 v[228:229], s[54:55], 0, v[132:133]
	s_mov_b32 m0, s53
	v_lshl_add_u64 v[230:231], s[88:89], 0, v[134:135]
	global_load_lds_dwordx4 v[228:229], off
	v_lshl_add_u64 v[228:229], s[54:55], 0, v[136:137]
	s_add_i32 m0, s53, 0x2000
	s_nop 0
	global_load_lds_dwordx4 v[228:229], off
	v_lshl_add_u64 v[228:229], s[88:89], 0, v[130:131]
	s_mov_b32 m0, s31
	s_nop 0
	global_load_lds_dwordx4 v[228:229], off
	s_mov_b32 m0, s33
	s_nop 0
	global_load_lds_dwordx4 v[230:231], off
	s_waitcnt vmcnt(8)
	s_waitcnt lgkmcnt(0)
	s_barrier
	s_setprio 1
	s_waitcnt lgkmcnt(0)
	v_mfma_f32_16x16x32_bf16 v[62:65], v[160:163], v[192:195], v[62:65]
	v_mfma_f32_16x16x32_bf16 v[46:49], v[160:163], v[200:203], v[46:49]
	v_mfma_f32_16x16x32_bf16 v[30:33], v[160:163], v[208:211], v[30:33]
	v_mfma_f32_16x16x32_bf16 v[14:17], v[160:163], v[218:221], v[14:17]
	v_mfma_f32_16x16x32_bf16 v[58:61], v[168:171], v[192:195], v[58:61]
	v_mfma_f32_16x16x32_bf16 v[42:45], v[168:171], v[200:203], v[42:45]
	v_mfma_f32_16x16x32_bf16 v[26:29], v[168:171], v[208:211], v[26:29]
	v_mfma_f32_16x16x32_bf16 v[10:13], v[168:171], v[218:221], v[10:13]
	v_mfma_f32_16x16x32_bf16 v[62:65], v[164:167], v[196:199], v[62:65]
	v_mfma_f32_16x16x32_bf16 v[46:49], v[164:167], v[204:207], v[46:49]
	v_mfma_f32_16x16x32_bf16 v[30:33], v[164:167], v[212:215], v[30:33]
	v_mfma_f32_16x16x32_bf16 v[14:17], v[164:167], v[222:225], v[14:17]
	v_mfma_f32_16x16x32_bf16 v[58:61], v[172:175], v[196:199], v[58:61]
	v_mfma_f32_16x16x32_bf16 v[42:45], v[172:175], v[204:207], v[42:45]
	v_mfma_f32_16x16x32_bf16 v[26:29], v[172:175], v[212:215], v[26:29]
	v_mfma_f32_16x16x32_bf16 v[10:13], v[172:175], v[222:225], v[10:13]
	s_setprio 0
	s_setprio 1
	v_mfma_f32_16x16x32_bf16 v[54:57], v[176:179], v[192:195], v[54:57]
	v_mfma_f32_16x16x32_bf16 v[38:41], v[176:179], v[200:203], v[38:41]
	v_mfma_f32_16x16x32_bf16 v[22:25], v[176:179], v[208:211], v[22:25]
	v_mfma_f32_16x16x32_bf16 v[6:9], v[176:179], v[218:221], v[6:9]
	v_mfma_f32_16x16x32_bf16 v[50:53], v[184:187], v[192:195], v[50:53]
	v_mfma_f32_16x16x32_bf16 v[34:37], v[184:187], v[200:203], v[34:37]
	v_mfma_f32_16x16x32_bf16 v[18:21], v[184:187], v[208:211], v[18:21]
	v_mfma_f32_16x16x32_bf16 v[2:5], v[184:187], v[218:221], v[2:5]
	v_mfma_f32_16x16x32_bf16 v[54:57], v[180:183], v[196:199], v[54:57]
	v_mfma_f32_16x16x32_bf16 v[38:41], v[180:183], v[204:207], v[38:41]
	v_mfma_f32_16x16x32_bf16 v[22:25], v[180:183], v[212:215], v[22:25]
	v_mfma_f32_16x16x32_bf16 v[6:9], v[180:183], v[222:225], v[6:9]
	v_mfma_f32_16x16x32_bf16 v[50:53], v[188:191], v[196:199], v[50:53]
	v_mfma_f32_16x16x32_bf16 v[34:37], v[188:191], v[204:207], v[34:37]
	v_mfma_f32_16x16x32_bf16 v[18:21], v[188:191], v[212:215], v[18:21]
	v_mfma_f32_16x16x32_bf16 v[2:5], v[188:191], v[222:225], v[2:5]
	s_setprio 0
	s_barrier
	s_add_i32 s53, 0, 0x18000
	v_add_u32_e32 v138, s53, v154
	s_add_i32 s62, 0, 0x1c000
	ds_read_b128 v[160:163], v138
	ds_read_b128 v[164:167], v138 offset:1024
	ds_read_b128 v[168:171], v138 offset:2048
	ds_read_b128 v[172:175], v138 offset:3072
	v_add_u32_e32 v138, s62, v154
	ds_read_b128 v[176:179], v138
	ds_read_b128 v[180:183], v138 offset:1024
	ds_read_b128 v[184:187], v138 offset:2048
	ds_read_b128 v[188:191], v138 offset:3072
	s_add_u32 s54, s88, 0x80000
	s_addc_u32 s55, s89, 0
	s_mov_b32 m0, s56
	v_lshl_add_u64 v[232:233], s[54:55], 0, v[130:131]
	ds_read_b128 v[192:195], v157 offset:32768
	ds_read_b128 v[196:199], v157 offset:33792
	ds_read_b128 v[200:203], v157 offset:34816
	ds_read_b128 v[204:207], v157 offset:35840
	ds_read_b128 v[208:211], v157 offset:36864
	ds_read_b128 v[212:215], v157 offset:37888
	ds_read_b128 v[218:221], v157 offset:38912
	ds_read_b128 v[222:225], v157 offset:39936
	global_load_lds_dwordx4 v[232:233], off
	v_lshl_add_u64 v[232:233], s[54:55], 0, v[134:135]
	s_mov_b32 m0, s57
	s_nop 0
	global_load_lds_dwordx4 v[232:233], off
	s_waitcnt vmcnt(8)
	s_waitcnt lgkmcnt(0)
	s_barrier
	s_setprio 1
	s_waitcnt lgkmcnt(0)
	v_mfma_f32_16x16x32_bf16 v[126:129], v[160:163], v[192:195], v[126:129]
	v_mfma_f32_16x16x32_bf16 v[110:113], v[160:163], v[200:203], v[110:113]
	v_mfma_f32_16x16x32_bf16 v[94:97], v[160:163], v[208:211], v[94:97]
	v_mfma_f32_16x16x32_bf16 v[78:81], v[160:163], v[218:221], v[78:81]
	v_mfma_f32_16x16x32_bf16 v[122:125], v[168:171], v[192:195], v[122:125]
	v_mfma_f32_16x16x32_bf16 v[106:109], v[168:171], v[200:203], v[106:109]
	v_mfma_f32_16x16x32_bf16 v[90:93], v[168:171], v[208:211], v[90:93]
	v_mfma_f32_16x16x32_bf16 v[74:77], v[168:171], v[218:221], v[74:77]
	v_mfma_f32_16x16x32_bf16 v[126:129], v[164:167], v[196:199], v[126:129]
	v_mfma_f32_16x16x32_bf16 v[110:113], v[164:167], v[204:207], v[110:113]
	v_mfma_f32_16x16x32_bf16 v[94:97], v[164:167], v[212:215], v[94:97]
	v_mfma_f32_16x16x32_bf16 v[78:81], v[164:167], v[222:225], v[78:81]
	v_mfma_f32_16x16x32_bf16 v[122:125], v[172:175], v[196:199], v[122:125]
	v_mfma_f32_16x16x32_bf16 v[106:109], v[172:175], v[204:207], v[106:109]
	v_mfma_f32_16x16x32_bf16 v[90:93], v[172:175], v[212:215], v[90:93]
	v_mfma_f32_16x16x32_bf16 v[74:77], v[172:175], v[222:225], v[74:77]
	s_setprio 0
	s_setprio 1
	v_mfma_f32_16x16x32_bf16 v[118:121], v[176:179], v[192:195], v[118:121]
	v_mfma_f32_16x16x32_bf16 v[102:105], v[176:179], v[200:203], v[102:105]
	v_mfma_f32_16x16x32_bf16 v[86:89], v[176:179], v[208:211], v[86:89]
	v_mfma_f32_16x16x32_bf16 v[70:73], v[176:179], v[218:221], v[70:73]
	v_mfma_f32_16x16x32_bf16 v[114:117], v[184:187], v[192:195], v[114:117]
	v_mfma_f32_16x16x32_bf16 v[98:101], v[184:187], v[200:203], v[98:101]
	v_mfma_f32_16x16x32_bf16 v[82:85], v[184:187], v[208:211], v[82:85]
	v_mfma_f32_16x16x32_bf16 v[66:69], v[184:187], v[218:221], v[66:69]
	v_mfma_f32_16x16x32_bf16 v[118:121], v[180:183], v[196:199], v[118:121]
	v_mfma_f32_16x16x32_bf16 v[102:105], v[180:183], v[204:207], v[102:105]
	v_mfma_f32_16x16x32_bf16 v[86:89], v[180:183], v[212:215], v[86:89]
	v_mfma_f32_16x16x32_bf16 v[70:73], v[180:183], v[222:225], v[70:73]
	v_mfma_f32_16x16x32_bf16 v[114:117], v[188:191], v[196:199], v[114:117]
	v_mfma_f32_16x16x32_bf16 v[98:101], v[188:191], v[204:207], v[98:101]
	v_mfma_f32_16x16x32_bf16 v[82:85], v[188:191], v[212:215], v[82:85]
	v_mfma_f32_16x16x32_bf16 v[66:69], v[188:191], v[222:225], v[66:69]
	s_setprio 0
	s_barrier
	s_add_i32 s53, s53, s12
	v_lshl_add_u64 v[152:153], v[152:153], 0, s[40:41]
	s_mov_b32 m0, s53
	ds_read_b128 v[192:195], v157 offset:49152
	ds_read_b128 v[196:199], v157 offset:50176
	ds_read_b128 v[200:203], v157 offset:51200
	ds_read_b128 v[204:207], v157 offset:52224
	ds_read_b128 v[208:211], v157 offset:53248
	ds_read_b128 v[212:215], v157 offset:54272
	ds_read_b128 v[218:221], v157 offset:55296
	ds_read_b128 v[222:225], v157 offset:56320
	global_load_lds_dwordx4 v[152:153], off
	s_add_i32 m0, s53, 0x2000
	s_add_u32 s34, s34, 0x80080
	v_lshl_add_u64 v[152:153], v[226:227], 0, s[40:41]
	s_addc_u32 s35, s35, 0
	s_add_i32 s53, s62, s12
	global_load_lds_dwordx4 v[152:153], off
	v_lshl_add_u64 v[152:153], s[34:35], 0, v[132:133]
	s_mov_b32 m0, s53
	s_nop 0
	global_load_lds_dwordx4 v[152:153], off
	v_lshl_add_u64 v[152:153], s[34:35], 0, v[136:137]
	s_add_i32 m0, s53, 0x2000
	s_nop 0
	global_load_lds_dwordx4 v[152:153], off
	v_lshl_add_u64 v[152:153], v[228:229], 0, s[40:41]
	s_mov_b32 m0, s59
	s_nop 0
	global_load_lds_dwordx4 v[152:153], off
	v_lshl_add_u64 v[152:153], v[230:231], 0, s[40:41]
	s_mov_b32 m0, s60
	s_nop 0
	global_load_lds_dwordx4 v[152:153], off
	s_waitcnt vmcnt(8)
	s_waitcnt lgkmcnt(0)
	s_barrier
	s_setprio 1
	s_waitcnt lgkmcnt(0)
	v_mfma_f32_16x16x32_bf16 v[62:65], v[160:163], v[192:195], v[62:65]
	v_mfma_f32_16x16x32_bf16 v[46:49], v[160:163], v[200:203], v[46:49]
	v_mfma_f32_16x16x32_bf16 v[30:33], v[160:163], v[208:211], v[30:33]
	v_mfma_f32_16x16x32_bf16 v[14:17], v[160:163], v[218:221], v[14:17]
	v_mfma_f32_16x16x32_bf16 v[58:61], v[168:171], v[192:195], v[58:61]
	v_mfma_f32_16x16x32_bf16 v[42:45], v[168:171], v[200:203], v[42:45]
	v_mfma_f32_16x16x32_bf16 v[26:29], v[168:171], v[208:211], v[26:29]
	v_mfma_f32_16x16x32_bf16 v[10:13], v[168:171], v[218:221], v[10:13]
	v_mfma_f32_16x16x32_bf16 v[62:65], v[164:167], v[196:199], v[62:65]
	v_mfma_f32_16x16x32_bf16 v[46:49], v[164:167], v[204:207], v[46:49]
	v_mfma_f32_16x16x32_bf16 v[30:33], v[164:167], v[212:215], v[30:33]
	v_mfma_f32_16x16x32_bf16 v[14:17], v[164:167], v[222:225], v[14:17]
	v_mfma_f32_16x16x32_bf16 v[58:61], v[172:175], v[196:199], v[58:61]
	v_mfma_f32_16x16x32_bf16 v[42:45], v[172:175], v[204:207], v[42:45]
	v_mfma_f32_16x16x32_bf16 v[26:29], v[172:175], v[212:215], v[26:29]
	v_mfma_f32_16x16x32_bf16 v[10:13], v[172:175], v[222:225], v[10:13]
	s_setprio 0
	s_setprio 1
	v_mfma_f32_16x16x32_bf16 v[54:57], v[176:179], v[192:195], v[54:57]
	v_mfma_f32_16x16x32_bf16 v[38:41], v[176:179], v[200:203], v[38:41]
	v_mfma_f32_16x16x32_bf16 v[22:25], v[176:179], v[208:211], v[22:25]
	v_mfma_f32_16x16x32_bf16 v[6:9], v[176:179], v[218:221], v[6:9]
	v_mfma_f32_16x16x32_bf16 v[50:53], v[184:187], v[192:195], v[50:53]
	v_mfma_f32_16x16x32_bf16 v[34:37], v[184:187], v[200:203], v[34:37]
	v_mfma_f32_16x16x32_bf16 v[18:21], v[184:187], v[208:211], v[18:21]
	v_mfma_f32_16x16x32_bf16 v[2:5], v[184:187], v[218:221], v[2:5]
	v_mfma_f32_16x16x32_bf16 v[54:57], v[180:183], v[196:199], v[54:57]
	v_mfma_f32_16x16x32_bf16 v[38:41], v[180:183], v[204:207], v[38:41]
	v_mfma_f32_16x16x32_bf16 v[22:25], v[180:183], v[212:215], v[22:25]
	v_mfma_f32_16x16x32_bf16 v[6:9], v[180:183], v[222:225], v[6:9]
	v_mfma_f32_16x16x32_bf16 v[50:53], v[188:191], v[196:199], v[50:53]
	v_mfma_f32_16x16x32_bf16 v[34:37], v[188:191], v[204:207], v[34:37]
	v_mfma_f32_16x16x32_bf16 v[18:21], v[188:191], v[212:215], v[18:21]
	v_mfma_f32_16x16x32_bf16 v[2:5], v[188:191], v[222:225], v[2:5]
	s_setprio 0
	s_barrier
	s_add_i32 s74, s74, 2
	s_add_u32 s76, s76, 0x100
	s_addc_u32 s77, s77, 0
	s_add_u32 s36, s36, 0x100
	s_addc_u32 s52, s52, 0
	s_cmp_gt_u32 s74, 29
	s_cbranch_scc0 .LBB0_2462
	s_and_b64 vcc, exec, s[46:47]
	s_cbranch_vccz .LBB0_2465
	s_barrier

.LBB0_2629:
	ds_read_b128 v[146:149], v165
	ds_read_b128 v[150:153], v165 offset:1024
	ds_read_b128 v[168:171], v165 offset:2048
	ds_read_b128 v[172:175], v165 offset:3072
	ds_read_b128 v[176:179], v166
	ds_read_b128 v[180:183], v166 offset:1024
	ds_read_b128 v[184:187], v166 offset:2048
	ds_read_b128 v[188:191], v166 offset:3072
	s_add_u32 s34, s74, 0xfffe0080
	s_addc_u32 s35, s75, -1
	s_cmp_eq_u32 s79, 4
	s_cselect_b32 s77, s0, s35
	s_cselect_b32 s76, s1, s34
	s_cselect_b32 s35, s27, s78
	s_cselect_b32 s34, s37, s52
	v_lshl_add_u64 v[226:227], s[74:75], 0, v[138:139]
	s_add_i32 m0, s33, 0xc000
	ds_read_b128 v[192:195], v167
	ds_read_b128 v[196:199], v167 offset:1024
	ds_read_b128 v[200:203], v167 offset:2048
	ds_read_b128 v[204:207], v167 offset:3072
	ds_read_b128 v[208:211], v167 offset:4096
	ds_read_b128 v[212:215], v167 offset:5120
	ds_read_b128 v[218:221], v167 offset:6144
	ds_read_b128 v[222:225], v167 offset:7168
	global_load_lds_dwordx4 v[226:227], off
	v_lshl_add_u64 v[226:227], s[74:75], 0, v[140:141]
	s_add_i32 m0, s33, 0xe000
	s_nop 0
	global_load_lds_dwordx4 v[226:227], off
	s_waitcnt vmcnt(8)
	s_waitcnt lgkmcnt(0)
	s_barrier
	s_setprio 1
	s_waitcnt lgkmcnt(0)
	v_mfma_f32_16x16x32_bf16 v[126:129], v[146:149], v[192:195], v[126:129]
	v_mfma_f32_16x16x32_bf16 v[114:117], v[146:149], v[200:203], v[114:117]
	v_mfma_f32_16x16x32_bf16 v[98:101], v[146:149], v[208:211], v[98:101]
	v_mfma_f32_16x16x32_bf16 v[82:85], v[146:149], v[218:221], v[82:85]
	v_mfma_f32_16x16x32_bf16 v[122:125], v[168:171], v[192:195], v[122:125]
	v_mfma_f32_16x16x32_bf16 v[106:109], v[168:171], v[200:203], v[106:109]
	v_mfma_f32_16x16x32_bf16 v[90:93], v[168:171], v[208:211], v[90:93]
	v_mfma_f32_16x16x32_bf16 v[74:77], v[168:171], v[218:221], v[74:77]
	v_mfma_f32_16x16x32_bf16 v[126:129], v[150:153], v[196:199], v[126:129]
	v_mfma_f32_16x16x32_bf16 v[114:117], v[150:153], v[204:207], v[114:117]
	v_mfma_f32_16x16x32_bf16 v[98:101], v[150:153], v[212:215], v[98:101]
	v_mfma_f32_16x16x32_bf16 v[82:85], v[150:153], v[222:225], v[82:85]
	v_mfma_f32_16x16x32_bf16 v[122:125], v[172:175], v[196:199], v[122:125]
	v_mfma_f32_16x16x32_bf16 v[106:109], v[172:175], v[204:207], v[106:109]
	v_mfma_f32_16x16x32_bf16 v[90:93], v[172:175], v[212:215], v[90:93]
	v_mfma_f32_16x16x32_bf16 v[74:77], v[172:175], v[222:225], v[74:77]
	s_setprio 0
	s_setprio 1
	v_mfma_f32_16x16x32_bf16 v[118:121], v[176:179], v[192:195], v[118:121]
	v_mfma_f32_16x16x32_bf16 v[102:105], v[176:179], v[200:203], v[102:105]
	v_mfma_f32_16x16x32_bf16 v[86:89], v[176:179], v[208:211], v[86:89]
	v_mfma_f32_16x16x32_bf16 v[70:73], v[176:179], v[218:221], v[70:73]
	v_mfma_f32_16x16x32_bf16 v[110:113], v[184:187], v[192:195], v[110:113]
	v_mfma_f32_16x16x32_bf16 v[94:97], v[184:187], v[200:203], v[94:97]
	v_mfma_f32_16x16x32_bf16 v[78:81], v[184:187], v[208:211], v[78:81]
	v_mfma_f32_16x16x32_bf16 v[66:69], v[184:187], v[218:221], v[66:69]
	v_mfma_f32_16x16x32_bf16 v[118:121], v[180:183], v[196:199], v[118:121]
	v_mfma_f32_16x16x32_bf16 v[102:105], v[180:183], v[204:207], v[102:105]
	v_mfma_f32_16x16x32_bf16 v[86:89], v[180:183], v[212:215], v[86:89]
	v_mfma_f32_16x16x32_bf16 v[70:73], v[180:183], v[222:225], v[70:73]
	v_mfma_f32_16x16x32_bf16 v[110:113], v[188:191], v[196:199], v[110:113]
	v_mfma_f32_16x16x32_bf16 v[94:97], v[188:191], v[204:207], v[94:97]
	v_mfma_f32_16x16x32_bf16 v[78:81], v[188:191], v[212:215], v[78:81]
	v_mfma_f32_16x16x32_bf16 v[66:69], v[188:191], v[222:225], v[66:69]
	s_setprio 0
	s_barrier
	s_add_i32 s53, s70, s12
	v_lshl_add_u64 v[226:227], s[34:35], 0, v[132:133]
	s_mov_b32 m0, s53
	ds_read_b128 v[192:195], v167 offset:16384
	ds_read_b128 v[196:199], v167 offset:17408
	ds_read_b128 v[200:203], v167 offset:18432
	ds_read_b128 v[204:207], v167 offset:19456
	ds_read_b128 v[208:211], v167 offset:20480
	ds_read_b128 v[212:215], v167 offset:21504
	ds_read_b128 v[218:221], v167 offset:22528
	ds_read_b128 v[222:225], v167 offset:23552
	global_load_lds_dwordx4 v[226:227], off
	s_add_i32 m0, s53, 0x2000
	s_add_u32 s54, s34, 0x20000
	v_lshl_add_u64 v[228:229], s[34:35], 0, v[136:137]
	s_addc_u32 s55, s35, 0
	s_add_i32 s53, s71, s12
	global_load_lds_dwordx4 v[228:229], off
	v_lshl_add_u64 v[230:231], s[54:55], 0, v[132:133]
	s_mov_b32 m0, s53
	v_lshl_add_u64 v[232:233], s[76:77], 0, v[134:135]
	global_load_lds_dwordx4 v[230:231], off
	v_lshl_add_u64 v[230:231], s[54:55], 0, v[136:137]
	s_add_i32 m0, s53, 0x2000
	s_nop 0
	global_load_lds_dwordx4 v[230:231], off
	v_lshl_add_u64 v[230:231], s[76:77], 0, v[130:131]
	s_mov_b32 m0, s33
	s_nop 0
	global_load_lds_dwordx4 v[230:231], off
	s_mov_b32 m0, s47
	s_nop 0
	global_load_lds_dwordx4 v[232:233], off
	s_waitcnt vmcnt(8)
	s_waitcnt lgkmcnt(0)
	s_barrier
	s_setprio 1
	s_waitcnt lgkmcnt(0)
	v_mfma_f32_16x16x32_bf16 v[62:65], v[146:149], v[192:195], v[62:65]
	v_mfma_f32_16x16x32_bf16 v[50:53], v[146:149], v[200:203], v[50:53]
	v_mfma_f32_16x16x32_bf16 v[34:37], v[146:149], v[208:211], v[34:37]
	v_mfma_f32_16x16x32_bf16 v[18:21], v[146:149], v[218:221], v[18:21]
	v_mfma_f32_16x16x32_bf16 v[58:61], v[168:171], v[192:195], v[58:61]
	v_mfma_f32_16x16x32_bf16 v[42:45], v[168:171], v[200:203], v[42:45]
	v_mfma_f32_16x16x32_bf16 v[26:29], v[168:171], v[208:211], v[26:29]
	v_mfma_f32_16x16x32_bf16 v[10:13], v[168:171], v[218:221], v[10:13]
	v_mfma_f32_16x16x32_bf16 v[62:65], v[150:153], v[196:199], v[62:65]
	v_mfma_f32_16x16x32_bf16 v[50:53], v[150:153], v[204:207], v[50:53]
	v_mfma_f32_16x16x32_bf16 v[34:37], v[150:153], v[212:215], v[34:37]
	v_mfma_f32_16x16x32_bf16 v[18:21], v[150:153], v[222:225], v[18:21]
	v_mfma_f32_16x16x32_bf16 v[58:61], v[172:175], v[196:199], v[58:61]
	v_mfma_f32_16x16x32_bf16 v[42:45], v[172:175], v[204:207], v[42:45]
	v_mfma_f32_16x16x32_bf16 v[26:29], v[172:175], v[212:215], v[26:29]
	v_mfma_f32_16x16x32_bf16 v[10:13], v[172:175], v[222:225], v[10:13]
	s_setprio 0
	s_setprio 1
	v_mfma_f32_16x16x32_bf16 v[54:57], v[176:179], v[192:195], v[54:57]
	v_mfma_f32_16x16x32_bf16 v[38:41], v[176:179], v[200:203], v[38:41]
	v_mfma_f32_16x16x32_bf16 v[22:25], v[176:179], v[208:211], v[22:25]
	v_mfma_f32_16x16x32_bf16 v[6:9], v[176:179], v[218:221], v[6:9]
	v_mfma_f32_16x16x32_bf16 v[46:49], v[184:187], v[192:195], v[46:49]
	v_mfma_f32_16x16x32_bf16 v[30:33], v[184:187], v[200:203], v[30:33]
	v_mfma_f32_16x16x32_bf16 v[14:17], v[184:187], v[208:211], v[14:17]
	v_mfma_f32_16x16x32_bf16 v[2:5], v[184:187], v[218:221], v[2:5]
	v_mfma_f32_16x16x32_bf16 v[54:57], v[180:183], v[196:199], v[54:57]
	v_mfma_f32_16x16x32_bf16 v[38:41], v[180:183], v[204:207], v[38:41]
	v_mfma_f32_16x16x32_bf16 v[22:25], v[180:183], v[212:215], v[22:25]
	v_mfma_f32_16x16x32_bf16 v[6:9], v[180:183], v[222:225], v[6:9]
	v_mfma_f32_16x16x32_bf16 v[46:49], v[188:191], v[196:199], v[46:49]
	v_mfma_f32_16x16x32_bf16 v[30:33], v[188:191], v[204:207], v[30:33]
	v_mfma_f32_16x16x32_bf16 v[14:17], v[188:191], v[212:215], v[14:17]
	v_mfma_f32_16x16x32_bf16 v[2:5], v[188:191], v[222:225], v[2:5]
	s_setprio 0
	s_barrier
	s_add_i32 s53, 0, 0x18000
	s_add_i32 s62, 0, 0x1c000
	v_add_u32_e32 v172, s53, v162
	v_add_u32_e32 v188, s62, v162
	ds_read_b128 v[146:149], v172
	ds_read_b128 v[150:153], v172 offset:1024
	ds_read_b128 v[168:171], v172 offset:2048
	ds_read_b128 v[172:175], v172 offset:3072
	ds_read_b128 v[176:179], v188
	ds_read_b128 v[180:183], v188 offset:1024
	ds_read_b128 v[184:187], v188 offset:2048
	ds_read_b128 v[188:191], v188 offset:3072
	s_add_u32 s54, s76, 0x20000
	s_addc_u32 s55, s77, 0
	s_mov_b32 m0, s56
	v_lshl_add_u64 v[234:235], s[54:55], 0, v[130:131]
	ds_read_b128 v[192:195], v167 offset:32768
	ds_read_b128 v[196:199], v167 offset:33792
	ds_read_b128 v[200:203], v167 offset:34816
	ds_read_b128 v[204:207], v167 offset:35840
	ds_read_b128 v[208:211], v167 offset:36864
	ds_read_b128 v[212:215], v167 offset:37888
	ds_read_b128 v[218:221], v167 offset:38912
	ds_read_b128 v[222:225], v167 offset:39936
	global_load_lds_dwordx4 v[234:235], off
	v_lshl_add_u64 v[234:235], s[54:55], 0, v[134:135]
	s_mov_b32 m0, s57
	s_nop 0
	global_load_lds_dwordx4 v[234:235], off
	s_waitcnt vmcnt(8)
	s_waitcnt lgkmcnt(0)
	s_barrier
	s_setprio 1
	s_waitcnt lgkmcnt(0)
	v_mfma_f32_16x16x32_bf16 v[126:129], v[146:149], v[192:195], v[126:129]
	v_mfma_f32_16x16x32_bf16 v[114:117], v[146:149], v[200:203], v[114:117]
	v_mfma_f32_16x16x32_bf16 v[98:101], v[146:149], v[208:211], v[98:101]
	v_mfma_f32_16x16x32_bf16 v[82:85], v[146:149], v[218:221], v[82:85]
	v_mfma_f32_16x16x32_bf16 v[122:125], v[168:171], v[192:195], v[122:125]
	v_mfma_f32_16x16x32_bf16 v[106:109], v[168:171], v[200:203], v[106:109]
	v_mfma_f32_16x16x32_bf16 v[90:93], v[168:171], v[208:211], v[90:93]
	v_mfma_f32_16x16x32_bf16 v[74:77], v[168:171], v[218:221], v[74:77]
	v_mfma_f32_16x16x32_bf16 v[126:129], v[150:153], v[196:199], v[126:129]
	v_mfma_f32_16x16x32_bf16 v[114:117], v[150:153], v[204:207], v[114:117]
	v_mfma_f32_16x16x32_bf16 v[98:101], v[150:153], v[212:215], v[98:101]
	v_mfma_f32_16x16x32_bf16 v[82:85], v[150:153], v[222:225], v[82:85]
	v_mfma_f32_16x16x32_bf16 v[122:125], v[172:175], v[196:199], v[122:125]
	v_mfma_f32_16x16x32_bf16 v[106:109], v[172:175], v[204:207], v[106:109]
	v_mfma_f32_16x16x32_bf16 v[90:93], v[172:175], v[212:215], v[90:93]
	v_mfma_f32_16x16x32_bf16 v[74:77], v[172:175], v[222:225], v[74:77]
	s_setprio 0
	s_setprio 1
	v_mfma_f32_16x16x32_bf16 v[118:121], v[176:179], v[192:195], v[118:121]
	v_mfma_f32_16x16x32_bf16 v[102:105], v[176:179], v[200:203], v[102:105]
	v_mfma_f32_16x16x32_bf16 v[86:89], v[176:179], v[208:211], v[86:89]
	v_mfma_f32_16x16x32_bf16 v[70:73], v[176:179], v[218:221], v[70:73]
	v_mfma_f32_16x16x32_bf16 v[110:113], v[184:187], v[192:195], v[110:113]
	v_mfma_f32_16x16x32_bf16 v[94:97], v[184:187], v[200:203], v[94:97]
	v_mfma_f32_16x16x32_bf16 v[78:81], v[184:187], v[208:211], v[78:81]
	v_mfma_f32_16x16x32_bf16 v[66:69], v[184:187], v[218:221], v[66:69]
	v_mfma_f32_16x16x32_bf16 v[118:121], v[180:183], v[196:199], v[118:121]
	v_mfma_f32_16x16x32_bf16 v[102:105], v[180:183], v[204:207], v[102:105]
	v_mfma_f32_16x16x32_bf16 v[86:89], v[180:183], v[212:215], v[86:89]
	v_mfma_f32_16x16x32_bf16 v[70:73], v[180:183], v[222:225], v[70:73]
	v_mfma_f32_16x16x32_bf16 v[110:113], v[188:191], v[196:199], v[110:113]
	v_mfma_f32_16x16x32_bf16 v[94:97], v[188:191], v[204:207], v[94:97]
	v_mfma_f32_16x16x32_bf16 v[78:81], v[188:191], v[212:215], v[78:81]
	v_mfma_f32_16x16x32_bf16 v[66:69], v[188:191], v[222:225], v[66:69]
	s_setprio 0
	s_barrier
	s_add_i32 s53, s53, s12
	v_lshl_add_u64 v[226:227], v[226:227], 0, s[8:9]
	s_mov_b32 m0, s53
	ds_read_b128 v[192:195], v167 offset:49152
	ds_read_b128 v[196:199], v167 offset:50176
	ds_read_b128 v[200:203], v167 offset:51200
	ds_read_b128 v[204:207], v167 offset:52224
	ds_read_b128 v[208:211], v167 offset:53248
	ds_read_b128 v[212:215], v167 offset:54272
	ds_read_b128 v[218:221], v167 offset:55296
	ds_read_b128 v[222:225], v167 offset:56320
	global_load_lds_dwordx4 v[226:227], off
	s_add_i32 m0, s53, 0x2000
	s_add_u32 s34, s34, 0x20080
	v_lshl_add_u64 v[226:227], v[228:229], 0, s[8:9]
	s_addc_u32 s35, s35, 0
	s_add_i32 s53, s62, s12
	global_load_lds_dwordx4 v[226:227], off
	v_lshl_add_u64 v[226:227], s[34:35], 0, v[132:133]
	s_mov_b32 m0, s53
	s_nop 0
	global_load_lds_dwordx4 v[226:227], off
	v_lshl_add_u64 v[226:227], s[34:35], 0, v[136:137]
	s_add_i32 m0, s53, 0x2000
	s_nop 0
	global_load_lds_dwordx4 v[226:227], off
	v_lshl_add_u64 v[226:227], v[230:231], 0, s[8:9]
	s_mov_b32 m0, s59
	s_nop 0
	global_load_lds_dwordx4 v[226:227], off
	v_lshl_add_u64 v[226:227], v[232:233], 0, s[8:9]
	s_mov_b32 m0, s60
	s_nop 0
	global_load_lds_dwordx4 v[226:227], off
	s_waitcnt vmcnt(8)
	s_waitcnt lgkmcnt(0)
	s_barrier
	s_setprio 1
	s_waitcnt lgkmcnt(0)
	v_mfma_f32_16x16x32_bf16 v[62:65], v[146:149], v[192:195], v[62:65]
	v_mfma_f32_16x16x32_bf16 v[50:53], v[146:149], v[200:203], v[50:53]
	v_mfma_f32_16x16x32_bf16 v[34:37], v[146:149], v[208:211], v[34:37]
	v_mfma_f32_16x16x32_bf16 v[18:21], v[146:149], v[218:221], v[18:21]
	v_mfma_f32_16x16x32_bf16 v[58:61], v[168:171], v[192:195], v[58:61]
	v_mfma_f32_16x16x32_bf16 v[42:45], v[168:171], v[200:203], v[42:45]
	v_mfma_f32_16x16x32_bf16 v[26:29], v[168:171], v[208:211], v[26:29]
	v_mfma_f32_16x16x32_bf16 v[10:13], v[168:171], v[218:221], v[10:13]
	v_mfma_f32_16x16x32_bf16 v[62:65], v[150:153], v[196:199], v[62:65]
	v_mfma_f32_16x16x32_bf16 v[50:53], v[150:153], v[204:207], v[50:53]
	v_mfma_f32_16x16x32_bf16 v[34:37], v[150:153], v[212:215], v[34:37]
	v_mfma_f32_16x16x32_bf16 v[18:21], v[150:153], v[222:225], v[18:21]
	v_mfma_f32_16x16x32_bf16 v[58:61], v[172:175], v[196:199], v[58:61]
	v_mfma_f32_16x16x32_bf16 v[42:45], v[172:175], v[204:207], v[42:45]
	v_mfma_f32_16x16x32_bf16 v[26:29], v[172:175], v[212:215], v[26:29]
	v_mfma_f32_16x16x32_bf16 v[10:13], v[172:175], v[222:225], v[10:13]
	s_setprio 0
	s_setprio 1
	v_mfma_f32_16x16x32_bf16 v[54:57], v[176:179], v[192:195], v[54:57]
	v_mfma_f32_16x16x32_bf16 v[38:41], v[176:179], v[200:203], v[38:41]
	v_mfma_f32_16x16x32_bf16 v[22:25], v[176:179], v[208:211], v[22:25]
	v_mfma_f32_16x16x32_bf16 v[6:9], v[176:179], v[218:221], v[6:9]
	v_mfma_f32_16x16x32_bf16 v[46:49], v[184:187], v[192:195], v[46:49]
	v_mfma_f32_16x16x32_bf16 v[30:33], v[184:187], v[200:203], v[30:33]
	v_mfma_f32_16x16x32_bf16 v[14:17], v[184:187], v[208:211], v[14:17]
	v_mfma_f32_16x16x32_bf16 v[2:5], v[184:187], v[218:221], v[2:5]
	v_mfma_f32_16x16x32_bf16 v[54:57], v[180:183], v[196:199], v[54:57]
	v_mfma_f32_16x16x32_bf16 v[38:41], v[180:183], v[204:207], v[38:41]
	v_mfma_f32_16x16x32_bf16 v[22:25], v[180:183], v[212:215], v[22:25]
	v_mfma_f32_16x16x32_bf16 v[6:9], v[180:183], v[222:225], v[6:9]
	v_mfma_f32_16x16x32_bf16 v[46:49], v[188:191], v[196:199], v[46:49]
	v_mfma_f32_16x16x32_bf16 v[30:33], v[188:191], v[204:207], v[30:33]
	v_mfma_f32_16x16x32_bf16 v[14:17], v[188:191], v[212:215], v[14:17]
	v_mfma_f32_16x16x32_bf16 v[2:5], v[188:191], v[222:225], v[2:5]
	s_setprio 0
	s_barrier
	s_add_i32 s79, s79, 2
	s_add_u32 s74, s74, 0x100
	s_addc_u32 s75, s75, 0
	s_add_u32 s52, s52, 0x100
	s_addc_u32 s78, s78, 0
	s_cmp_gt_u32 s79, 5
	s_cbranch_scc0 .LBB0_2629
	s_and_b64 vcc, exec, s[24:25]
	s_cbranch_vccz .LBB0_2632
	s_barrier

.LBB0_2659:
	ds_read_b128 v[146:149], v1
	ds_read_b128 v[160:163], v1 offset:1024
	ds_read_b128 v[164:167], v1 offset:2048
	ds_read_b128 v[168:171], v1 offset:3072
	ds_read_b128 v[172:175], v154
	ds_read_b128 v[176:179], v154 offset:1024
	ds_read_b128 v[180:183], v154 offset:2048
	ds_read_b128 v[184:187], v154 offset:3072
	s_add_u32 s34, s74, 0xfffe0080
	s_addc_u32 s35, s75, -1
	s_cmp_eq_u32 s72, 4
	s_cselect_b32 s77, s0, s35
	s_cselect_b32 s76, s1, s34
	s_cselect_b32 s35, s27, s71
	s_cselect_b32 s34, s37, s52
	v_lshl_add_u64 v[150:151], s[74:75], 0, v[138:139]
	s_add_i32 m0, s33, 0xc000
	ds_read_b128 v[188:191], v155
	ds_read_b128 v[192:195], v155 offset:1024
	ds_read_b128 v[196:199], v155 offset:2048
	ds_read_b128 v[200:203], v155 offset:3072
	ds_read_b128 v[204:207], v155 offset:4096
	ds_read_b128 v[208:211], v155 offset:5120
	ds_read_b128 v[212:215], v155 offset:6144
	ds_read_b128 v[218:221], v155 offset:7168
	global_load_lds_dwordx4 v[150:151], off
	v_lshl_add_u64 v[150:151], s[74:75], 0, v[140:141]
	s_add_i32 m0, s33, 0xe000
	s_nop 0
	global_load_lds_dwordx4 v[150:151], off
	s_waitcnt vmcnt(8)
	s_waitcnt lgkmcnt(0)
	s_barrier
	s_setprio 1
	s_waitcnt lgkmcnt(0)
	v_mfma_f32_16x16x32_bf16 v[126:129], v[146:149], v[188:191], v[126:129]
	v_mfma_f32_16x16x32_bf16 v[110:113], v[146:149], v[196:199], v[110:113]
	v_mfma_f32_16x16x32_bf16 v[94:97], v[146:149], v[204:207], v[94:97]
	v_mfma_f32_16x16x32_bf16 v[78:81], v[146:149], v[212:215], v[78:81]
	v_mfma_f32_16x16x32_bf16 v[122:125], v[164:167], v[188:191], v[122:125]
	v_mfma_f32_16x16x32_bf16 v[106:109], v[164:167], v[196:199], v[106:109]
	v_mfma_f32_16x16x32_bf16 v[90:93], v[164:167], v[204:207], v[90:93]
	v_mfma_f32_16x16x32_bf16 v[74:77], v[164:167], v[212:215], v[74:77]
	v_mfma_f32_16x16x32_bf16 v[126:129], v[160:163], v[192:195], v[126:129]
	v_mfma_f32_16x16x32_bf16 v[110:113], v[160:163], v[200:203], v[110:113]
	v_mfma_f32_16x16x32_bf16 v[94:97], v[160:163], v[208:211], v[94:97]
	v_mfma_f32_16x16x32_bf16 v[78:81], v[160:163], v[218:221], v[78:81]
	v_mfma_f32_16x16x32_bf16 v[122:125], v[168:171], v[192:195], v[122:125]
	v_mfma_f32_16x16x32_bf16 v[106:109], v[168:171], v[200:203], v[106:109]
	v_mfma_f32_16x16x32_bf16 v[90:93], v[168:171], v[208:211], v[90:93]
	v_mfma_f32_16x16x32_bf16 v[74:77], v[168:171], v[218:221], v[74:77]
	s_setprio 0
	s_setprio 1
	v_mfma_f32_16x16x32_bf16 v[118:121], v[172:175], v[188:191], v[118:121]
	v_mfma_f32_16x16x32_bf16 v[102:105], v[172:175], v[196:199], v[102:105]
	v_mfma_f32_16x16x32_bf16 v[86:89], v[172:175], v[204:207], v[86:89]
	v_mfma_f32_16x16x32_bf16 v[70:73], v[172:175], v[212:215], v[70:73]
	v_mfma_f32_16x16x32_bf16 v[114:117], v[180:183], v[188:191], v[114:117]
	v_mfma_f32_16x16x32_bf16 v[98:101], v[180:183], v[196:199], v[98:101]
	v_mfma_f32_16x16x32_bf16 v[82:85], v[180:183], v[204:207], v[82:85]
	v_mfma_f32_16x16x32_bf16 v[66:69], v[180:183], v[212:215], v[66:69]
	v_mfma_f32_16x16x32_bf16 v[118:121], v[176:179], v[192:195], v[118:121]
	v_mfma_f32_16x16x32_bf16 v[102:105], v[176:179], v[200:203], v[102:105]
	v_mfma_f32_16x16x32_bf16 v[86:89], v[176:179], v[208:211], v[86:89]
	v_mfma_f32_16x16x32_bf16 v[70:73], v[176:179], v[218:221], v[70:73]
	v_mfma_f32_16x16x32_bf16 v[114:117], v[184:187], v[192:195], v[114:117]
	v_mfma_f32_16x16x32_bf16 v[98:101], v[184:187], v[200:203], v[98:101]
	v_mfma_f32_16x16x32_bf16 v[82:85], v[184:187], v[208:211], v[82:85]
	v_mfma_f32_16x16x32_bf16 v[66:69], v[184:187], v[218:221], v[66:69]
	s_setprio 0
	s_barrier
	s_add_i32 s53, s60, s13
	v_lshl_add_u64 v[150:151], s[34:35], 0, v[132:133]
	s_mov_b32 m0, s53
	ds_read_b128 v[188:191], v155 offset:16384
	ds_read_b128 v[192:195], v155 offset:17408
	ds_read_b128 v[196:199], v155 offset:18432
	ds_read_b128 v[200:203], v155 offset:19456
	ds_read_b128 v[204:207], v155 offset:20480
	ds_read_b128 v[208:211], v155 offset:21504
	ds_read_b128 v[212:215], v155 offset:22528
	ds_read_b128 v[218:221], v155 offset:23552
	global_load_lds_dwordx4 v[150:151], off
	s_add_i32 m0, s53, 0x2000
	s_add_u32 s62, s34, 0x20000
	v_lshl_add_u64 v[222:223], s[34:35], 0, v[136:137]
	s_addc_u32 s63, s35, 0
	s_add_i32 s53, s61, s13
	global_load_lds_dwordx4 v[222:223], off
	v_lshl_add_u64 v[224:225], s[62:63], 0, v[132:133]
	s_mov_b32 m0, s53
	v_lshl_add_u64 v[226:227], s[76:77], 0, v[134:135]
	global_load_lds_dwordx4 v[224:225], off
	v_lshl_add_u64 v[224:225], s[62:63], 0, v[136:137]
	s_add_i32 m0, s53, 0x2000
	s_nop 0
	global_load_lds_dwordx4 v[224:225], off
	v_lshl_add_u64 v[224:225], s[76:77], 0, v[130:131]
	s_mov_b32 m0, s33
	s_nop 0
	global_load_lds_dwordx4 v[224:225], off
	s_mov_b32 m0, s47
	s_nop 0
	global_load_lds_dwordx4 v[226:227], off
	s_waitcnt vmcnt(8)
	s_waitcnt lgkmcnt(0)
	s_barrier
	s_setprio 1
	s_waitcnt lgkmcnt(0)
	v_mfma_f32_16x16x32_bf16 v[62:65], v[146:149], v[188:191], v[62:65]
	v_mfma_f32_16x16x32_bf16 v[50:53], v[146:149], v[196:199], v[50:53]
	v_mfma_f32_16x16x32_bf16 v[34:37], v[146:149], v[204:207], v[34:37]
	v_mfma_f32_16x16x32_bf16 v[18:21], v[146:149], v[212:215], v[18:21]
	v_mfma_f32_16x16x32_bf16 v[58:61], v[164:167], v[188:191], v[58:61]
	v_mfma_f32_16x16x32_bf16 v[42:45], v[164:167], v[196:199], v[42:45]
	v_mfma_f32_16x16x32_bf16 v[26:29], v[164:167], v[204:207], v[26:29]
	v_mfma_f32_16x16x32_bf16 v[10:13], v[164:167], v[212:215], v[10:13]
	v_mfma_f32_16x16x32_bf16 v[62:65], v[160:163], v[192:195], v[62:65]
	v_mfma_f32_16x16x32_bf16 v[50:53], v[160:163], v[200:203], v[50:53]
	v_mfma_f32_16x16x32_bf16 v[34:37], v[160:163], v[208:211], v[34:37]
	v_mfma_f32_16x16x32_bf16 v[18:21], v[160:163], v[218:221], v[18:21]
	v_mfma_f32_16x16x32_bf16 v[58:61], v[168:171], v[192:195], v[58:61]
	v_mfma_f32_16x16x32_bf16 v[42:45], v[168:171], v[200:203], v[42:45]
	v_mfma_f32_16x16x32_bf16 v[26:29], v[168:171], v[208:211], v[26:29]
	v_mfma_f32_16x16x32_bf16 v[10:13], v[168:171], v[218:221], v[10:13]
	s_setprio 0
	s_setprio 1
	v_mfma_f32_16x16x32_bf16 v[54:57], v[172:175], v[188:191], v[54:57]
	v_mfma_f32_16x16x32_bf16 v[38:41], v[172:175], v[196:199], v[38:41]
	v_mfma_f32_16x16x32_bf16 v[22:25], v[172:175], v[204:207], v[22:25]
	v_mfma_f32_16x16x32_bf16 v[6:9], v[172:175], v[212:215], v[6:9]
	v_mfma_f32_16x16x32_bf16 v[46:49], v[180:183], v[188:191], v[46:49]
	v_mfma_f32_16x16x32_bf16 v[30:33], v[180:183], v[196:199], v[30:33]
	v_mfma_f32_16x16x32_bf16 v[14:17], v[180:183], v[204:207], v[14:17]
	v_mfma_f32_16x16x32_bf16 v[2:5], v[180:183], v[212:215], v[2:5]
	v_mfma_f32_16x16x32_bf16 v[54:57], v[176:179], v[192:195], v[54:57]
	v_mfma_f32_16x16x32_bf16 v[38:41], v[176:179], v[200:203], v[38:41]
	v_mfma_f32_16x16x32_bf16 v[22:25], v[176:179], v[208:211], v[22:25]
	v_mfma_f32_16x16x32_bf16 v[6:9], v[176:179], v[218:221], v[6:9]
	v_mfma_f32_16x16x32_bf16 v[46:49], v[184:187], v[192:195], v[46:49]
	v_mfma_f32_16x16x32_bf16 v[30:33], v[184:187], v[200:203], v[30:33]
	v_mfma_f32_16x16x32_bf16 v[14:17], v[184:187], v[208:211], v[14:17]
	v_mfma_f32_16x16x32_bf16 v[2:5], v[184:187], v[218:221], v[2:5]
	s_setprio 0
	s_barrier
	s_add_i32 s53, 0, 0x18000
	v_add_u32_e32 v156, s53, v153
	s_add_i32 s66, 0, 0x1c000
	ds_read_b128 v[146:149], v156
	ds_read_b128 v[160:163], v156 offset:1024
	ds_read_b128 v[164:167], v156 offset:2048
	ds_read_b128 v[168:171], v156 offset:3072
	v_add_u32_e32 v156, s66, v153
	ds_read_b128 v[172:175], v156
	ds_read_b128 v[176:179], v156 offset:1024
	ds_read_b128 v[180:183], v156 offset:2048
	ds_read_b128 v[184:187], v156 offset:3072
	s_add_u32 s62, s76, 0x20000
	s_addc_u32 s63, s77, 0
	s_mov_b32 m0, s54
	v_lshl_add_u64 v[228:229], s[62:63], 0, v[130:131]
	ds_read_b128 v[188:191], v155 offset:32768
	ds_read_b128 v[192:195], v155 offset:33792
	ds_read_b128 v[196:199], v155 offset:34816
	ds_read_b128 v[200:203], v155 offset:35840
	ds_read_b128 v[204:207], v155 offset:36864
	ds_read_b128 v[208:211], v155 offset:37888
	ds_read_b128 v[212:215], v155 offset:38912
	ds_read_b128 v[218:221], v155 offset:39936
	global_load_lds_dwordx4 v[228:229], off
	v_lshl_add_u64 v[228:229], s[62:63], 0, v[134:135]
	s_mov_b32 m0, s55
	s_nop 0
	global_load_lds_dwordx4 v[228:229], off
	s_waitcnt vmcnt(8)
	s_waitcnt lgkmcnt(0)
	s_barrier
	s_setprio 1
	s_waitcnt lgkmcnt(0)
	v_mfma_f32_16x16x32_bf16 v[126:129], v[146:149], v[188:191], v[126:129]
	v_mfma_f32_16x16x32_bf16 v[110:113], v[146:149], v[196:199], v[110:113]
	v_mfma_f32_16x16x32_bf16 v[94:97], v[146:149], v[204:207], v[94:97]
	v_mfma_f32_16x16x32_bf16 v[78:81], v[146:149], v[212:215], v[78:81]
	v_mfma_f32_16x16x32_bf16 v[122:125], v[164:167], v[188:191], v[122:125]
	v_mfma_f32_16x16x32_bf16 v[106:109], v[164:167], v[196:199], v[106:109]
	v_mfma_f32_16x16x32_bf16 v[90:93], v[164:167], v[204:207], v[90:93]
	v_mfma_f32_16x16x32_bf16 v[74:77], v[164:167], v[212:215], v[74:77]
	v_mfma_f32_16x16x32_bf16 v[126:129], v[160:163], v[192:195], v[126:129]
	v_mfma_f32_16x16x32_bf16 v[110:113], v[160:163], v[200:203], v[110:113]
	v_mfma_f32_16x16x32_bf16 v[94:97], v[160:163], v[208:211], v[94:97]
	v_mfma_f32_16x16x32_bf16 v[78:81], v[160:163], v[218:221], v[78:81]
	v_mfma_f32_16x16x32_bf16 v[122:125], v[168:171], v[192:195], v[122:125]
	v_mfma_f32_16x16x32_bf16 v[106:109], v[168:171], v[200:203], v[106:109]
	v_mfma_f32_16x16x32_bf16 v[90:93], v[168:171], v[208:211], v[90:93]
	v_mfma_f32_16x16x32_bf16 v[74:77], v[168:171], v[218:221], v[74:77]
	s_setprio 0
	s_setprio 1
	v_mfma_f32_16x16x32_bf16 v[118:121], v[172:175], v[188:191], v[118:121]
	v_mfma_f32_16x16x32_bf16 v[102:105], v[172:175], v[196:199], v[102:105]
	v_mfma_f32_16x16x32_bf16 v[86:89], v[172:175], v[204:207], v[86:89]
	v_mfma_f32_16x16x32_bf16 v[70:73], v[172:175], v[212:215], v[70:73]
	v_mfma_f32_16x16x32_bf16 v[114:117], v[180:183], v[188:191], v[114:117]
	v_mfma_f32_16x16x32_bf16 v[98:101], v[180:183], v[196:199], v[98:101]
	v_mfma_f32_16x16x32_bf16 v[82:85], v[180:183], v[204:207], v[82:85]
	v_mfma_f32_16x16x32_bf16 v[66:69], v[180:183], v[212:215], v[66:69]
	v_mfma_f32_16x16x32_bf16 v[118:121], v[176:179], v[192:195], v[118:121]
	v_mfma_f32_16x16x32_bf16 v[102:105], v[176:179], v[200:203], v[102:105]
	v_mfma_f32_16x16x32_bf16 v[86:89], v[176:179], v[208:211], v[86:89]
	v_mfma_f32_16x16x32_bf16 v[70:73], v[176:179], v[218:221], v[70:73]
	v_mfma_f32_16x16x32_bf16 v[114:117], v[184:187], v[192:195], v[114:117]
	v_mfma_f32_16x16x32_bf16 v[98:101], v[184:187], v[200:203], v[98:101]
	v_mfma_f32_16x16x32_bf16 v[82:85], v[184:187], v[208:211], v[82:85]
	v_mfma_f32_16x16x32_bf16 v[66:69], v[184:187], v[218:221], v[66:69]
	s_setprio 0
	s_barrier
	s_add_i32 s53, s53, s13
	v_lshl_add_u64 v[150:151], v[150:151], 0, s[8:9]
	s_mov_b32 m0, s53
	ds_read_b128 v[188:191], v155 offset:49152
	ds_read_b128 v[192:195], v155 offset:50176
	ds_read_b128 v[196:199], v155 offset:51200
	ds_read_b128 v[200:203], v155 offset:52224
	ds_read_b128 v[204:207], v155 offset:53248
	ds_read_b128 v[208:211], v155 offset:54272
	ds_read_b128 v[212:215], v155 offset:55296
	ds_read_b128 v[218:221], v155 offset:56320
	global_load_lds_dwordx4 v[150:151], off
	s_add_i32 m0, s53, 0x2000
	s_add_u32 s34, s34, 0x20080
	v_lshl_add_u64 v[150:151], v[222:223], 0, s[8:9]
	s_addc_u32 s35, s35, 0
	s_add_i32 s53, s66, s13
	global_load_lds_dwordx4 v[150:151], off
	v_lshl_add_u64 v[150:151], s[34:35], 0, v[132:133]
	s_mov_b32 m0, s53
	s_nop 0
	global_load_lds_dwordx4 v[150:151], off
	v_lshl_add_u64 v[150:151], s[34:35], 0, v[136:137]
	s_add_i32 m0, s53, 0x2000
	s_nop 0
	global_load_lds_dwordx4 v[150:151], off
	v_lshl_add_u64 v[150:151], v[224:225], 0, s[8:9]
	s_mov_b32 m0, s57
	s_nop 0
	global_load_lds_dwordx4 v[150:151], off
	v_lshl_add_u64 v[150:151], v[226:227], 0, s[8:9]
	s_mov_b32 m0, s58
	s_nop 0
	global_load_lds_dwordx4 v[150:151], off
	s_waitcnt vmcnt(8)
	s_waitcnt lgkmcnt(0)
	s_barrier
	s_setprio 1
	s_waitcnt lgkmcnt(0)
	v_mfma_f32_16x16x32_bf16 v[62:65], v[146:149], v[188:191], v[62:65]
	v_mfma_f32_16x16x32_bf16 v[50:53], v[146:149], v[196:199], v[50:53]
	v_mfma_f32_16x16x32_bf16 v[34:37], v[146:149], v[204:207], v[34:37]
	v_mfma_f32_16x16x32_bf16 v[18:21], v[146:149], v[212:215], v[18:21]
	v_mfma_f32_16x16x32_bf16 v[58:61], v[164:167], v[188:191], v[58:61]
	v_mfma_f32_16x16x32_bf16 v[42:45], v[164:167], v[196:199], v[42:45]
	v_mfma_f32_16x16x32_bf16 v[26:29], v[164:167], v[204:207], v[26:29]
	v_mfma_f32_16x16x32_bf16 v[10:13], v[164:167], v[212:215], v[10:13]
	v_mfma_f32_16x16x32_bf16 v[62:65], v[160:163], v[192:195], v[62:65]
	v_mfma_f32_16x16x32_bf16 v[50:53], v[160:163], v[200:203], v[50:53]
	v_mfma_f32_16x16x32_bf16 v[34:37], v[160:163], v[208:211], v[34:37]
	v_mfma_f32_16x16x32_bf16 v[18:21], v[160:163], v[218:221], v[18:21]
	v_mfma_f32_16x16x32_bf16 v[58:61], v[168:171], v[192:195], v[58:61]
	v_mfma_f32_16x16x32_bf16 v[42:45], v[168:171], v[200:203], v[42:45]
	v_mfma_f32_16x16x32_bf16 v[26:29], v[168:171], v[208:211], v[26:29]
	v_mfma_f32_16x16x32_bf16 v[10:13], v[168:171], v[218:221], v[10:13]
	s_setprio 0
	s_setprio 1
	v_mfma_f32_16x16x32_bf16 v[54:57], v[172:175], v[188:191], v[54:57]
	v_mfma_f32_16x16x32_bf16 v[38:41], v[172:175], v[196:199], v[38:41]
	v_mfma_f32_16x16x32_bf16 v[22:25], v[172:175], v[204:207], v[22:25]
	v_mfma_f32_16x16x32_bf16 v[6:9], v[172:175], v[212:215], v[6:9]
	v_mfma_f32_16x16x32_bf16 v[46:49], v[180:183], v[188:191], v[46:49]
	v_mfma_f32_16x16x32_bf16 v[30:33], v[180:183], v[196:199], v[30:33]
	v_mfma_f32_16x16x32_bf16 v[14:17], v[180:183], v[204:207], v[14:17]
	v_mfma_f32_16x16x32_bf16 v[2:5], v[180:183], v[212:215], v[2:5]
	v_mfma_f32_16x16x32_bf16 v[54:57], v[176:179], v[192:195], v[54:57]
	v_mfma_f32_16x16x32_bf16 v[38:41], v[176:179], v[200:203], v[38:41]
	v_mfma_f32_16x16x32_bf16 v[22:25], v[176:179], v[208:211], v[22:25]
	v_mfma_f32_16x16x32_bf16 v[6:9], v[176:179], v[218:221], v[6:9]
	v_mfma_f32_16x16x32_bf16 v[46:49], v[184:187], v[192:195], v[46:49]
	v_mfma_f32_16x16x32_bf16 v[30:33], v[184:187], v[200:203], v[30:33]
	v_mfma_f32_16x16x32_bf16 v[14:17], v[184:187], v[208:211], v[14:17]
	v_mfma_f32_16x16x32_bf16 v[2:5], v[184:187], v[218:221], v[2:5]
	s_setprio 0
	s_barrier
	s_add_i32 s72, s72, 2
	s_add_u32 s74, s74, 0x100
	s_addc_u32 s75, s75, 0
	s_add_u32 s52, s52, 0x100
	s_addc_u32 s71, s71, 0
	s_cmp_gt_u32 s72, 5
	s_cbranch_scc0 .LBB0_2659
	s_and_b64 vcc, exec, s[24:25]
	s_cbranch_vccz .LBB0_2662
	s_barrier

.LBB0_2938:
	ds_read_b128 v[130:133], v174
	ds_read_b128 v[134:137], v174 offset:1024
	ds_read_b128 v[138:141], v174 offset:2048
	ds_read_b128 v[158:161], v174 offset:3072
	ds_read_b128 v[162:165], v175
	ds_read_b128 v[166:169], v175 offset:1024
	ds_read_b128 v[178:181], v175 offset:2048
	ds_read_b128 v[182:185], v175 offset:3072
	s_add_u32 s34, s46, 0xfff80080
	s_addc_u32 s35, s47, -1
	s_cmp_eq_u32 s72, 28
	s_cselect_b32 s69, s0, s35
	s_cselect_b32 s68, s1, s34
	s_cselect_b32 s35, s37, s71
	s_cselect_b32 s34, s39, s70
	v_lshl_add_u64 v[170:171], s[46:47], 0, v[150:151]
	s_add_i32 m0, s33, 0xc000
	ds_read_b128 v[186:189], v176
	ds_read_b128 v[190:193], v176 offset:1024
	ds_read_b128 v[194:197], v176 offset:2048
	ds_read_b128 v[198:201], v176 offset:3072
	ds_read_b128 v[202:205], v176 offset:4096
	ds_read_b128 v[206:209], v176 offset:5120
	ds_read_b128 v[210:213], v176 offset:6144
	ds_read_b128 v[218:221], v176 offset:7168
	global_load_lds_dwordx4 v[170:171], off
	v_lshl_add_u64 v[170:171], s[46:47], 0, v[152:153]
	s_add_i32 m0, s33, 0xe000
	s_nop 0
	global_load_lds_dwordx4 v[170:171], off
	s_waitcnt vmcnt(8)
	s_waitcnt lgkmcnt(0)
	s_barrier
	s_setprio 1
	s_waitcnt lgkmcnt(0)
	v_mfma_f32_16x16x32_bf16 v[126:129], v[130:133], v[186:189], v[126:129]
	v_mfma_f32_16x16x32_bf16 v[110:113], v[130:133], v[194:197], v[110:113]
	v_mfma_f32_16x16x32_bf16 v[94:97], v[130:133], v[202:205], v[94:97]
	v_mfma_f32_16x16x32_bf16 v[78:81], v[130:133], v[210:213], v[78:81]
	v_mfma_f32_16x16x32_bf16 v[122:125], v[138:141], v[186:189], v[122:125]
	v_mfma_f32_16x16x32_bf16 v[106:109], v[138:141], v[194:197], v[106:109]
	v_mfma_f32_16x16x32_bf16 v[90:93], v[138:141], v[202:205], v[90:93]
	v_mfma_f32_16x16x32_bf16 v[74:77], v[138:141], v[210:213], v[74:77]
	v_mfma_f32_16x16x32_bf16 v[126:129], v[134:137], v[190:193], v[126:129]
	v_mfma_f32_16x16x32_bf16 v[110:113], v[134:137], v[198:201], v[110:113]
	v_mfma_f32_16x16x32_bf16 v[94:97], v[134:137], v[206:209], v[94:97]
	v_mfma_f32_16x16x32_bf16 v[78:81], v[134:137], v[218:221], v[78:81]
	v_mfma_f32_16x16x32_bf16 v[122:125], v[158:161], v[190:193], v[122:125]
	v_mfma_f32_16x16x32_bf16 v[106:109], v[158:161], v[198:201], v[106:109]
	v_mfma_f32_16x16x32_bf16 v[90:93], v[158:161], v[206:209], v[90:93]
	v_mfma_f32_16x16x32_bf16 v[74:77], v[158:161], v[218:221], v[74:77]
	s_setprio 0
	s_setprio 1
	v_mfma_f32_16x16x32_bf16 v[118:121], v[162:165], v[186:189], v[118:121]
	v_mfma_f32_16x16x32_bf16 v[102:105], v[162:165], v[194:197], v[102:105]
	v_mfma_f32_16x16x32_bf16 v[86:89], v[162:165], v[202:205], v[86:89]
	v_mfma_f32_16x16x32_bf16 v[70:73], v[162:165], v[210:213], v[70:73]
	v_mfma_f32_16x16x32_bf16 v[114:117], v[178:181], v[186:189], v[114:117]
	v_mfma_f32_16x16x32_bf16 v[98:101], v[178:181], v[194:197], v[98:101]
	v_mfma_f32_16x16x32_bf16 v[82:85], v[178:181], v[202:205], v[82:85]
	v_mfma_f32_16x16x32_bf16 v[66:69], v[178:181], v[210:213], v[66:69]
	v_mfma_f32_16x16x32_bf16 v[118:121], v[166:169], v[190:193], v[118:121]
	v_mfma_f32_16x16x32_bf16 v[102:105], v[166:169], v[198:201], v[102:105]
	v_mfma_f32_16x16x32_bf16 v[86:89], v[166:169], v[206:209], v[86:89]
	v_mfma_f32_16x16x32_bf16 v[70:73], v[166:169], v[218:221], v[70:73]
	v_mfma_f32_16x16x32_bf16 v[114:117], v[182:185], v[190:193], v[114:117]
	v_mfma_f32_16x16x32_bf16 v[98:101], v[182:185], v[198:201], v[98:101]
	v_mfma_f32_16x16x32_bf16 v[82:85], v[182:185], v[206:209], v[82:85]
	v_mfma_f32_16x16x32_bf16 v[66:69], v[182:185], v[218:221], v[66:69]
	s_setprio 0
	s_barrier
	s_add_i32 s62, s58, s31
	v_lshl_add_u64 v[170:171], s[34:35], 0, v[144:145]
	s_mov_b32 m0, s62
	ds_read_b128 v[186:189], v176 offset:16384
	ds_read_b128 v[190:193], v176 offset:17408
	ds_read_b128 v[194:197], v176 offset:18432
	ds_read_b128 v[198:201], v176 offset:19456
	ds_read_b128 v[202:205], v176 offset:20480
	ds_read_b128 v[206:209], v176 offset:21504
	ds_read_b128 v[210:213], v176 offset:22528
	ds_read_b128 v[218:221], v176 offset:23552
	global_load_lds_dwordx4 v[170:171], off
	s_add_i32 m0, s62, 0x2000
	s_add_u32 s62, s34, 0x80000
	v_lshl_add_u64 v[214:215], s[34:35], 0, v[148:149]
	s_addc_u32 s63, s35, 0
	s_add_i32 s66, s59, s31
	global_load_lds_dwordx4 v[214:215], off
	v_lshl_add_u64 v[222:223], s[62:63], 0, v[144:145]
	s_mov_b32 m0, s66
	v_lshl_add_u64 v[224:225], s[68:69], 0, v[146:147]
	global_load_lds_dwordx4 v[222:223], off
	v_lshl_add_u64 v[222:223], s[62:63], 0, v[148:149]
	s_add_i32 m0, s66, 0x2000
	s_nop 0
	global_load_lds_dwordx4 v[222:223], off
	v_lshl_add_u64 v[222:223], s[68:69], 0, v[142:143]
	s_mov_b32 m0, s33
	s_nop 0
	global_load_lds_dwordx4 v[222:223], off
	s_mov_b32 m0, s45
	s_nop 0
	global_load_lds_dwordx4 v[224:225], off
	s_waitcnt vmcnt(8)
	s_waitcnt lgkmcnt(0)
	s_barrier
	s_setprio 1
	s_waitcnt lgkmcnt(0)
	v_mfma_f32_16x16x32_bf16 v[62:65], v[130:133], v[186:189], v[62:65]
	v_mfma_f32_16x16x32_bf16 v[50:53], v[130:133], v[194:197], v[50:53]
	v_mfma_f32_16x16x32_bf16 v[38:41], v[130:133], v[202:205], v[38:41]
	v_mfma_f32_16x16x32_bf16 v[14:17], v[130:133], v[210:213], v[14:17]
	v_mfma_f32_16x16x32_bf16 v[58:61], v[138:141], v[186:189], v[58:61]
	v_mfma_f32_16x16x32_bf16 v[42:45], v[138:141], v[194:197], v[42:45]
	v_mfma_f32_16x16x32_bf16 v[34:37], v[138:141], v[202:205], v[34:37]
	v_mfma_f32_16x16x32_bf16 v[10:13], v[138:141], v[210:213], v[10:13]
	v_mfma_f32_16x16x32_bf16 v[62:65], v[134:137], v[190:193], v[62:65]
	v_mfma_f32_16x16x32_bf16 v[50:53], v[134:137], v[198:201], v[50:53]
	v_mfma_f32_16x16x32_bf16 v[38:41], v[134:137], v[206:209], v[38:41]
	v_mfma_f32_16x16x32_bf16 v[14:17], v[134:137], v[218:221], v[14:17]
	v_mfma_f32_16x16x32_bf16 v[58:61], v[158:161], v[190:193], v[58:61]
	v_mfma_f32_16x16x32_bf16 v[42:45], v[158:161], v[198:201], v[42:45]
	v_mfma_f32_16x16x32_bf16 v[34:37], v[158:161], v[206:209], v[34:37]
	v_mfma_f32_16x16x32_bf16 v[10:13], v[158:161], v[218:221], v[10:13]
	s_setprio 0
	s_setprio 1
	v_mfma_f32_16x16x32_bf16 v[54:57], v[162:165], v[186:189], v[54:57]
	v_mfma_f32_16x16x32_bf16 v[30:33], v[162:165], v[194:197], v[30:33]
	v_mfma_f32_16x16x32_bf16 v[22:25], v[162:165], v[202:205], v[22:25]
	v_mfma_f32_16x16x32_bf16 v[6:9], v[162:165], v[210:213], v[6:9]
	v_mfma_f32_16x16x32_bf16 v[46:49], v[178:181], v[186:189], v[46:49]
	v_mfma_f32_16x16x32_bf16 v[26:29], v[178:181], v[194:197], v[26:29]
	v_mfma_f32_16x16x32_bf16 v[18:21], v[178:181], v[202:205], v[18:21]
	v_mfma_f32_16x16x32_bf16 v[2:5], v[178:181], v[210:213], v[2:5]
	v_mfma_f32_16x16x32_bf16 v[54:57], v[166:169], v[190:193], v[54:57]
	v_mfma_f32_16x16x32_bf16 v[30:33], v[166:169], v[198:201], v[30:33]
	v_mfma_f32_16x16x32_bf16 v[22:25], v[166:169], v[206:209], v[22:25]
	v_mfma_f32_16x16x32_bf16 v[6:9], v[166:169], v[218:221], v[6:9]
	v_mfma_f32_16x16x32_bf16 v[46:49], v[182:185], v[190:193], v[46:49]
	v_mfma_f32_16x16x32_bf16 v[26:29], v[182:185], v[198:201], v[26:29]
	v_mfma_f32_16x16x32_bf16 v[18:21], v[182:185], v[206:209], v[18:21]
	v_mfma_f32_16x16x32_bf16 v[2:5], v[182:185], v[218:221], v[2:5]
	s_setprio 0
	s_barrier
	s_add_i32 s66, 0, 0x18000
	s_add_i32 s67, 0, 0x1c000
	v_add_u32_e32 v158, s66, v172
	v_add_u32_e32 v177, s67, v172
	ds_read_b128 v[130:133], v158
	ds_read_b128 v[134:137], v158 offset:1024
	ds_read_b128 v[138:141], v158 offset:2048
	ds_read_b128 v[158:161], v158 offset:3072
	ds_read_b128 v[162:165], v177
	ds_read_b128 v[166:169], v177 offset:1024
	ds_read_b128 v[178:181], v177 offset:2048
	ds_read_b128 v[182:185], v177 offset:3072
	s_add_u32 s62, s68, 0x80000
	s_addc_u32 s63, s69, 0
	s_mov_b32 m0, s52
	v_lshl_add_u64 v[226:227], s[62:63], 0, v[142:143]
	ds_read_b128 v[186:189], v176 offset:32768
	ds_read_b128 v[190:193], v176 offset:33792
	ds_read_b128 v[194:197], v176 offset:34816
	ds_read_b128 v[198:201], v176 offset:35840
	ds_read_b128 v[202:205], v176 offset:36864
	ds_read_b128 v[206:209], v176 offset:37888
	ds_read_b128 v[210:213], v176 offset:38912
	ds_read_b128 v[218:221], v176 offset:39936
	global_load_lds_dwordx4 v[226:227], off
	v_lshl_add_u64 v[226:227], s[62:63], 0, v[146:147]
	s_mov_b32 m0, s53
	s_nop 0
	global_load_lds_dwordx4 v[226:227], off
	s_waitcnt vmcnt(8)
	s_waitcnt lgkmcnt(0)
	s_barrier
	s_setprio 1
	s_waitcnt lgkmcnt(0)
	v_mfma_f32_16x16x32_bf16 v[126:129], v[130:133], v[186:189], v[126:129]
	v_mfma_f32_16x16x32_bf16 v[110:113], v[130:133], v[194:197], v[110:113]
	v_mfma_f32_16x16x32_bf16 v[94:97], v[130:133], v[202:205], v[94:97]
	v_mfma_f32_16x16x32_bf16 v[78:81], v[130:133], v[210:213], v[78:81]
	v_mfma_f32_16x16x32_bf16 v[122:125], v[138:141], v[186:189], v[122:125]
	v_mfma_f32_16x16x32_bf16 v[106:109], v[138:141], v[194:197], v[106:109]
	v_mfma_f32_16x16x32_bf16 v[90:93], v[138:141], v[202:205], v[90:93]
	v_mfma_f32_16x16x32_bf16 v[74:77], v[138:141], v[210:213], v[74:77]
	v_mfma_f32_16x16x32_bf16 v[126:129], v[134:137], v[190:193], v[126:129]
	v_mfma_f32_16x16x32_bf16 v[110:113], v[134:137], v[198:201], v[110:113]
	v_mfma_f32_16x16x32_bf16 v[94:97], v[134:137], v[206:209], v[94:97]
	v_mfma_f32_16x16x32_bf16 v[78:81], v[134:137], v[218:221], v[78:81]
	v_mfma_f32_16x16x32_bf16 v[122:125], v[158:161], v[190:193], v[122:125]
	v_mfma_f32_16x16x32_bf16 v[106:109], v[158:161], v[198:201], v[106:109]
	v_mfma_f32_16x16x32_bf16 v[90:93], v[158:161], v[206:209], v[90:93]
	v_mfma_f32_16x16x32_bf16 v[74:77], v[158:161], v[218:221], v[74:77]
	s_setprio 0
	s_setprio 1
	v_mfma_f32_16x16x32_bf16 v[118:121], v[162:165], v[186:189], v[118:121]
	v_mfma_f32_16x16x32_bf16 v[102:105], v[162:165], v[194:197], v[102:105]
	v_mfma_f32_16x16x32_bf16 v[86:89], v[162:165], v[202:205], v[86:89]
	v_mfma_f32_16x16x32_bf16 v[70:73], v[162:165], v[210:213], v[70:73]
	v_mfma_f32_16x16x32_bf16 v[114:117], v[178:181], v[186:189], v[114:117]
	v_mfma_f32_16x16x32_bf16 v[98:101], v[178:181], v[194:197], v[98:101]
	v_mfma_f32_16x16x32_bf16 v[82:85], v[178:181], v[202:205], v[82:85]
	v_mfma_f32_16x16x32_bf16 v[66:69], v[178:181], v[210:213], v[66:69]
	v_mfma_f32_16x16x32_bf16 v[118:121], v[166:169], v[190:193], v[118:121]
	v_mfma_f32_16x16x32_bf16 v[102:105], v[166:169], v[198:201], v[102:105]
	v_mfma_f32_16x16x32_bf16 v[86:89], v[166:169], v[206:209], v[86:89]
	v_mfma_f32_16x16x32_bf16 v[70:73], v[166:169], v[218:221], v[70:73]
	v_mfma_f32_16x16x32_bf16 v[114:117], v[182:185], v[190:193], v[114:117]
	v_mfma_f32_16x16x32_bf16 v[98:101], v[182:185], v[198:201], v[98:101]
	v_mfma_f32_16x16x32_bf16 v[82:85], v[182:185], v[206:209], v[82:85]
	v_mfma_f32_16x16x32_bf16 v[66:69], v[182:185], v[218:221], v[66:69]
	s_setprio 0
	s_barrier
	s_add_i32 s62, s66, s31
	v_lshl_add_u64 v[170:171], v[170:171], 0, s[24:25]
	s_mov_b32 m0, s62
	ds_read_b128 v[186:189], v176 offset:49152
	ds_read_b128 v[190:193], v176 offset:50176
	ds_read_b128 v[194:197], v176 offset:51200
	ds_read_b128 v[198:201], v176 offset:52224
	ds_read_b128 v[202:205], v176 offset:53248
	ds_read_b128 v[206:209], v176 offset:54272
	ds_read_b128 v[210:213], v176 offset:55296
	ds_read_b128 v[218:221], v176 offset:56320
	global_load_lds_dwordx4 v[170:171], off
	s_add_i32 m0, s62, 0x2000
	s_add_u32 s34, s34, 0x80080
	v_lshl_add_u64 v[170:171], v[214:215], 0, s[24:25]
	s_addc_u32 s35, s35, 0
	s_add_i32 s62, s67, s31
	global_load_lds_dwordx4 v[170:171], off
	v_lshl_add_u64 v[170:171], s[34:35], 0, v[144:145]
	s_mov_b32 m0, s62
	s_nop 0
	global_load_lds_dwordx4 v[170:171], off
	v_lshl_add_u64 v[170:171], s[34:35], 0, v[148:149]
	s_add_i32 m0, s62, 0x2000
	s_nop 0
	global_load_lds_dwordx4 v[170:171], off
	v_lshl_add_u64 v[170:171], v[222:223], 0, s[24:25]
	s_mov_b32 m0, s55
	s_nop 0
	global_load_lds_dwordx4 v[170:171], off
	v_lshl_add_u64 v[170:171], v[224:225], 0, s[24:25]
	s_mov_b32 m0, s56
	s_nop 0
	global_load_lds_dwordx4 v[170:171], off
	s_waitcnt vmcnt(8)
	s_waitcnt lgkmcnt(0)
	s_barrier
	s_setprio 1
	s_waitcnt lgkmcnt(0)
	v_mfma_f32_16x16x32_bf16 v[62:65], v[130:133], v[186:189], v[62:65]
	v_mfma_f32_16x16x32_bf16 v[50:53], v[130:133], v[194:197], v[50:53]
	v_mfma_f32_16x16x32_bf16 v[38:41], v[130:133], v[202:205], v[38:41]
	v_mfma_f32_16x16x32_bf16 v[14:17], v[130:133], v[210:213], v[14:17]
	v_mfma_f32_16x16x32_bf16 v[58:61], v[138:141], v[186:189], v[58:61]
	v_mfma_f32_16x16x32_bf16 v[42:45], v[138:141], v[194:197], v[42:45]
	v_mfma_f32_16x16x32_bf16 v[34:37], v[138:141], v[202:205], v[34:37]
	v_mfma_f32_16x16x32_bf16 v[10:13], v[138:141], v[210:213], v[10:13]
	v_mfma_f32_16x16x32_bf16 v[62:65], v[134:137], v[190:193], v[62:65]
	v_mfma_f32_16x16x32_bf16 v[50:53], v[134:137], v[198:201], v[50:53]
	v_mfma_f32_16x16x32_bf16 v[38:41], v[134:137], v[206:209], v[38:41]
	v_mfma_f32_16x16x32_bf16 v[14:17], v[134:137], v[218:221], v[14:17]
	v_mfma_f32_16x16x32_bf16 v[58:61], v[158:161], v[190:193], v[58:61]
	v_mfma_f32_16x16x32_bf16 v[42:45], v[158:161], v[198:201], v[42:45]
	v_mfma_f32_16x16x32_bf16 v[34:37], v[158:161], v[206:209], v[34:37]
	v_mfma_f32_16x16x32_bf16 v[10:13], v[158:161], v[218:221], v[10:13]
	s_setprio 0
	s_setprio 1
	v_mfma_f32_16x16x32_bf16 v[54:57], v[162:165], v[186:189], v[54:57]
	v_mfma_f32_16x16x32_bf16 v[30:33], v[162:165], v[194:197], v[30:33]
	v_mfma_f32_16x16x32_bf16 v[22:25], v[162:165], v[202:205], v[22:25]
	v_mfma_f32_16x16x32_bf16 v[6:9], v[162:165], v[210:213], v[6:9]
	v_mfma_f32_16x16x32_bf16 v[46:49], v[178:181], v[186:189], v[46:49]
	v_mfma_f32_16x16x32_bf16 v[26:29], v[178:181], v[194:197], v[26:29]
	v_mfma_f32_16x16x32_bf16 v[18:21], v[178:181], v[202:205], v[18:21]
	v_mfma_f32_16x16x32_bf16 v[2:5], v[178:181], v[210:213], v[2:5]
	v_mfma_f32_16x16x32_bf16 v[54:57], v[166:169], v[190:193], v[54:57]
	v_mfma_f32_16x16x32_bf16 v[30:33], v[166:169], v[198:201], v[30:33]
	v_mfma_f32_16x16x32_bf16 v[22:25], v[166:169], v[206:209], v[22:25]
	v_mfma_f32_16x16x32_bf16 v[6:9], v[166:169], v[218:221], v[6:9]
	v_mfma_f32_16x16x32_bf16 v[46:49], v[182:185], v[190:193], v[46:49]
	v_mfma_f32_16x16x32_bf16 v[26:29], v[182:185], v[198:201], v[26:29]
	v_mfma_f32_16x16x32_bf16 v[18:21], v[182:185], v[206:209], v[18:21]
	v_mfma_f32_16x16x32_bf16 v[2:5], v[182:185], v[218:221], v[2:5]
	s_setprio 0
	s_barrier
	s_add_i32 s72, s72, 2
	s_add_u32 s46, s46, 0x100
	s_addc_u32 s47, s47, 0
	s_add_u32 s70, s70, 0x100
	s_addc_u32 s71, s71, 0
	s_cmp_gt_u32 s72, 29
	s_cbranch_scc0 .LBB0_2938
	s_and_b64 vcc, exec, s[26:27]
	s_cbranch_vccz .LBB0_2941
	s_barrier

.LBB0_3067:
	ds_read_b128 v[146:149], v153
	ds_read_b128 v[156:159], v153 offset:1024
	ds_read_b128 v[160:163], v153 offset:2048
	ds_read_b128 v[164:167], v153 offset:3072
	ds_read_b128 v[168:171], v154
	ds_read_b128 v[172:175], v154 offset:1024
	ds_read_b128 v[176:179], v154 offset:2048
	ds_read_b128 v[180:183], v154 offset:3072
	s_add_u32 s34, s44, 0xfff80080
	s_addc_u32 s35, s45, -1
	s_cmp_eq_u32 s71, 28
	s_cselect_b32 s47, s0, s35
	s_cselect_b32 s46, s1, s34
	s_cselect_b32 s35, s27, s70
	s_cselect_b32 s34, s37, s69
	v_lshl_add_u64 v[218:219], s[44:45], 0, v[138:139]
	s_add_i32 m0, s43, 0xc000
	ds_read_b128 v[184:187], v155
	ds_read_b128 v[188:191], v155 offset:1024
	ds_read_b128 v[192:195], v155 offset:2048
	ds_read_b128 v[196:199], v155 offset:3072
	ds_read_b128 v[200:203], v155 offset:4096
	ds_read_b128 v[204:207], v155 offset:5120
	ds_read_b128 v[208:211], v155 offset:6144
	ds_read_b128 v[212:215], v155 offset:7168
	global_load_lds_dwordx4 v[218:219], off
	v_lshl_add_u64 v[218:219], s[44:45], 0, v[140:141]
	s_add_i32 m0, s43, 0xe000
	s_nop 0
	global_load_lds_dwordx4 v[218:219], off
	s_waitcnt vmcnt(8)
	s_waitcnt lgkmcnt(0)
	s_barrier
	s_setprio 1
	s_waitcnt lgkmcnt(0)
	v_mfma_f32_16x16x32_bf16 v[126:129], v[146:149], v[184:187], v[126:129]
	v_mfma_f32_16x16x32_bf16 v[110:113], v[146:149], v[192:195], v[110:113]
	v_mfma_f32_16x16x32_bf16 v[94:97], v[146:149], v[200:203], v[94:97]
	v_mfma_f32_16x16x32_bf16 v[78:81], v[146:149], v[208:211], v[78:81]
	v_mfma_f32_16x16x32_bf16 v[118:121], v[160:163], v[184:187], v[118:121]
	v_mfma_f32_16x16x32_bf16 v[102:105], v[160:163], v[192:195], v[102:105]
	v_mfma_f32_16x16x32_bf16 v[86:89], v[160:163], v[200:203], v[86:89]
	v_mfma_f32_16x16x32_bf16 v[70:73], v[160:163], v[208:211], v[70:73]
	v_mfma_f32_16x16x32_bf16 v[126:129], v[156:159], v[188:191], v[126:129]
	v_mfma_f32_16x16x32_bf16 v[110:113], v[156:159], v[196:199], v[110:113]
	v_mfma_f32_16x16x32_bf16 v[94:97], v[156:159], v[204:207], v[94:97]
	v_mfma_f32_16x16x32_bf16 v[78:81], v[156:159], v[212:215], v[78:81]
	v_mfma_f32_16x16x32_bf16 v[118:121], v[164:167], v[188:191], v[118:121]
	v_mfma_f32_16x16x32_bf16 v[102:105], v[164:167], v[196:199], v[102:105]
	v_mfma_f32_16x16x32_bf16 v[86:89], v[164:167], v[204:207], v[86:89]
	v_mfma_f32_16x16x32_bf16 v[70:73], v[164:167], v[212:215], v[70:73]
	s_setprio 0
	s_setprio 1
	v_mfma_f32_16x16x32_bf16 v[122:125], v[168:171], v[184:187], v[122:125]
	v_mfma_f32_16x16x32_bf16 v[106:109], v[168:171], v[192:195], v[106:109]
	v_mfma_f32_16x16x32_bf16 v[90:93], v[168:171], v[200:203], v[90:93]
	v_mfma_f32_16x16x32_bf16 v[74:77], v[168:171], v[208:211], v[74:77]
	v_mfma_f32_16x16x32_bf16 v[114:117], v[176:179], v[184:187], v[114:117]
	v_mfma_f32_16x16x32_bf16 v[98:101], v[176:179], v[192:195], v[98:101]
	v_mfma_f32_16x16x32_bf16 v[82:85], v[176:179], v[200:203], v[82:85]
	v_mfma_f32_16x16x32_bf16 v[66:69], v[176:179], v[208:211], v[66:69]
	v_mfma_f32_16x16x32_bf16 v[122:125], v[172:175], v[188:191], v[122:125]
	v_mfma_f32_16x16x32_bf16 v[106:109], v[172:175], v[196:199], v[106:109]
	v_mfma_f32_16x16x32_bf16 v[90:93], v[172:175], v[204:207], v[90:93]
	v_mfma_f32_16x16x32_bf16 v[74:77], v[172:175], v[212:215], v[74:77]
	v_mfma_f32_16x16x32_bf16 v[114:117], v[180:183], v[188:191], v[114:117]
	v_mfma_f32_16x16x32_bf16 v[98:101], v[180:183], v[196:199], v[98:101]
	v_mfma_f32_16x16x32_bf16 v[82:85], v[180:183], v[204:207], v[82:85]
	v_mfma_f32_16x16x32_bf16 v[66:69], v[180:183], v[212:215], v[66:69]
	s_setprio 0
	s_barrier
	s_add_i32 s62, s59, s30
	v_lshl_add_u64 v[218:219], s[34:35], 0, v[134:135]
	s_mov_b32 m0, s62
	ds_read_b128 v[184:187], v155 offset:16384
	ds_read_b128 v[188:191], v155 offset:17408
	ds_read_b128 v[192:195], v155 offset:18432
	ds_read_b128 v[196:199], v155 offset:19456
	ds_read_b128 v[200:203], v155 offset:20480
	ds_read_b128 v[204:207], v155 offset:21504
	ds_read_b128 v[208:211], v155 offset:22528
	ds_read_b128 v[212:215], v155 offset:23552
	global_load_lds_dwordx4 v[218:219], off
	s_add_i32 m0, s62, 0x2000
	s_add_u32 s62, s34, 0x80000
	v_lshl_add_u64 v[220:221], s[34:35], 0, v[130:131]
	s_addc_u32 s63, s35, 0
	s_add_i32 s66, s60, s30
	global_load_lds_dwordx4 v[220:221], off
	v_lshl_add_u64 v[222:223], s[62:63], 0, v[134:135]
	s_mov_b32 m0, s66
	v_lshl_add_u64 v[224:225], s[46:47], 0, v[132:133]
	global_load_lds_dwordx4 v[222:223], off
	v_lshl_add_u64 v[222:223], s[62:63], 0, v[130:131]
	s_add_i32 m0, s66, 0x2000
	s_nop 0
	global_load_lds_dwordx4 v[222:223], off
	v_lshl_add_u64 v[222:223], s[46:47], 0, v[136:137]
	s_mov_b32 m0, s43
	s_nop 0
	global_load_lds_dwordx4 v[222:223], off
	s_mov_b32 m0, s52
	s_nop 0
	global_load_lds_dwordx4 v[224:225], off
	s_waitcnt vmcnt(8)
	s_waitcnt lgkmcnt(0)
	s_barrier
	s_setprio 1
	s_waitcnt lgkmcnt(0)
	v_mfma_f32_16x16x32_bf16 v[62:65], v[146:149], v[184:187], v[62:65]
	v_mfma_f32_16x16x32_bf16 v[46:49], v[146:149], v[192:195], v[46:49]
	v_mfma_f32_16x16x32_bf16 v[30:33], v[146:149], v[200:203], v[30:33]
	v_mfma_f32_16x16x32_bf16 v[14:17], v[146:149], v[208:211], v[14:17]
	v_mfma_f32_16x16x32_bf16 v[54:57], v[160:163], v[184:187], v[54:57]
	v_mfma_f32_16x16x32_bf16 v[38:41], v[160:163], v[192:195], v[38:41]
	v_mfma_f32_16x16x32_bf16 v[22:25], v[160:163], v[200:203], v[22:25]
	v_mfma_f32_16x16x32_bf16 v[6:9], v[160:163], v[208:211], v[6:9]
	v_mfma_f32_16x16x32_bf16 v[62:65], v[156:159], v[188:191], v[62:65]
	v_mfma_f32_16x16x32_bf16 v[46:49], v[156:159], v[196:199], v[46:49]
	v_mfma_f32_16x16x32_bf16 v[30:33], v[156:159], v[204:207], v[30:33]
	v_mfma_f32_16x16x32_bf16 v[14:17], v[156:159], v[212:215], v[14:17]
	v_mfma_f32_16x16x32_bf16 v[54:57], v[164:167], v[188:191], v[54:57]
	v_mfma_f32_16x16x32_bf16 v[38:41], v[164:167], v[196:199], v[38:41]
	v_mfma_f32_16x16x32_bf16 v[22:25], v[164:167], v[204:207], v[22:25]
	v_mfma_f32_16x16x32_bf16 v[6:9], v[164:167], v[212:215], v[6:9]
	s_setprio 0
	s_setprio 1
	v_mfma_f32_16x16x32_bf16 v[58:61], v[168:171], v[184:187], v[58:61]
	v_mfma_f32_16x16x32_bf16 v[42:45], v[168:171], v[192:195], v[42:45]
	v_mfma_f32_16x16x32_bf16 v[26:29], v[168:171], v[200:203], v[26:29]
	v_mfma_f32_16x16x32_bf16 v[10:13], v[168:171], v[208:211], v[10:13]
	v_mfma_f32_16x16x32_bf16 v[50:53], v[176:179], v[184:187], v[50:53]
	v_mfma_f32_16x16x32_bf16 v[34:37], v[176:179], v[192:195], v[34:37]
	v_mfma_f32_16x16x32_bf16 v[18:21], v[176:179], v[200:203], v[18:21]
	v_mfma_f32_16x16x32_bf16 v[2:5], v[176:179], v[208:211], v[2:5]
	v_mfma_f32_16x16x32_bf16 v[58:61], v[172:175], v[188:191], v[58:61]
	v_mfma_f32_16x16x32_bf16 v[42:45], v[172:175], v[196:199], v[42:45]
	v_mfma_f32_16x16x32_bf16 v[26:29], v[172:175], v[204:207], v[26:29]
	v_mfma_f32_16x16x32_bf16 v[10:13], v[172:175], v[212:215], v[10:13]
	v_mfma_f32_16x16x32_bf16 v[50:53], v[180:183], v[188:191], v[50:53]
	v_mfma_f32_16x16x32_bf16 v[34:37], v[180:183], v[196:199], v[34:37]
	v_mfma_f32_16x16x32_bf16 v[18:21], v[180:183], v[204:207], v[18:21]
	v_mfma_f32_16x16x32_bf16 v[2:5], v[180:183], v[212:215], v[2:5]
	s_setprio 0
	s_barrier
	s_add_i32 s62, 0, 0x18000
	s_add_i32 s63, 0, 0x1c000
	v_add_u32_e32 v164, s62, v151
	v_add_u32_e32 v180, s63, v151
	ds_read_b128 v[146:149], v164
	ds_read_b128 v[156:159], v164 offset:1024
	ds_read_b128 v[160:163], v164 offset:2048
	ds_read_b128 v[164:167], v164 offset:3072
	ds_read_b128 v[168:171], v180
	ds_read_b128 v[172:175], v180 offset:1024
	ds_read_b128 v[176:179], v180 offset:2048
	ds_read_b128 v[180:183], v180 offset:3072
	s_add_u32 s46, s46, 0x80000
	s_addc_u32 s47, s47, 0
	s_mov_b32 m0, s53
	v_lshl_add_u64 v[226:227], s[46:47], 0, v[136:137]
	ds_read_b128 v[184:187], v155 offset:32768
	ds_read_b128 v[188:191], v155 offset:33792
	ds_read_b128 v[192:195], v155 offset:34816
	ds_read_b128 v[196:199], v155 offset:35840
	ds_read_b128 v[200:203], v155 offset:36864
	ds_read_b128 v[204:207], v155 offset:37888
	ds_read_b128 v[208:211], v155 offset:38912
	ds_read_b128 v[212:215], v155 offset:39936
	global_load_lds_dwordx4 v[226:227], off
	v_lshl_add_u64 v[226:227], s[46:47], 0, v[132:133]
	s_mov_b32 m0, s54
	s_nop 0
	global_load_lds_dwordx4 v[226:227], off
	s_waitcnt vmcnt(8)
	s_waitcnt lgkmcnt(0)
	s_barrier
	s_setprio 1
	s_waitcnt lgkmcnt(0)
	v_mfma_f32_16x16x32_bf16 v[126:129], v[146:149], v[184:187], v[126:129]
	v_mfma_f32_16x16x32_bf16 v[110:113], v[146:149], v[192:195], v[110:113]
	v_mfma_f32_16x16x32_bf16 v[94:97], v[146:149], v[200:203], v[94:97]
	v_mfma_f32_16x16x32_bf16 v[78:81], v[146:149], v[208:211], v[78:81]
	v_mfma_f32_16x16x32_bf16 v[118:121], v[160:163], v[184:187], v[118:121]
	v_mfma_f32_16x16x32_bf16 v[102:105], v[160:163], v[192:195], v[102:105]
	v_mfma_f32_16x16x32_bf16 v[86:89], v[160:163], v[200:203], v[86:89]
	v_mfma_f32_16x16x32_bf16 v[70:73], v[160:163], v[208:211], v[70:73]
	v_mfma_f32_16x16x32_bf16 v[126:129], v[156:159], v[188:191], v[126:129]
	v_mfma_f32_16x16x32_bf16 v[110:113], v[156:159], v[196:199], v[110:113]
	v_mfma_f32_16x16x32_bf16 v[94:97], v[156:159], v[204:207], v[94:97]
	v_mfma_f32_16x16x32_bf16 v[78:81], v[156:159], v[212:215], v[78:81]
	v_mfma_f32_16x16x32_bf16 v[118:121], v[164:167], v[188:191], v[118:121]
	v_mfma_f32_16x16x32_bf16 v[102:105], v[164:167], v[196:199], v[102:105]
	v_mfma_f32_16x16x32_bf16 v[86:89], v[164:167], v[204:207], v[86:89]
	v_mfma_f32_16x16x32_bf16 v[70:73], v[164:167], v[212:215], v[70:73]
	s_setprio 0
	s_setprio 1
	v_mfma_f32_16x16x32_bf16 v[122:125], v[168:171], v[184:187], v[122:125]
	v_mfma_f32_16x16x32_bf16 v[106:109], v[168:171], v[192:195], v[106:109]
	v_mfma_f32_16x16x32_bf16 v[90:93], v[168:171], v[200:203], v[90:93]
	v_mfma_f32_16x16x32_bf16 v[74:77], v[168:171], v[208:211], v[74:77]
	v_mfma_f32_16x16x32_bf16 v[114:117], v[176:179], v[184:187], v[114:117]
	v_mfma_f32_16x16x32_bf16 v[98:101], v[176:179], v[192:195], v[98:101]
	v_mfma_f32_16x16x32_bf16 v[82:85], v[176:179], v[200:203], v[82:85]
	v_mfma_f32_16x16x32_bf16 v[66:69], v[176:179], v[208:211], v[66:69]
	v_mfma_f32_16x16x32_bf16 v[122:125], v[172:175], v[188:191], v[122:125]
	v_mfma_f32_16x16x32_bf16 v[106:109], v[172:175], v[196:199], v[106:109]
	v_mfma_f32_16x16x32_bf16 v[90:93], v[172:175], v[204:207], v[90:93]
	v_mfma_f32_16x16x32_bf16 v[74:77], v[172:175], v[212:215], v[74:77]
	v_mfma_f32_16x16x32_bf16 v[114:117], v[180:183], v[188:191], v[114:117]
	v_mfma_f32_16x16x32_bf16 v[98:101], v[180:183], v[196:199], v[98:101]
	v_mfma_f32_16x16x32_bf16 v[82:85], v[180:183], v[204:207], v[82:85]
	v_mfma_f32_16x16x32_bf16 v[66:69], v[180:183], v[212:215], v[66:69]
	s_setprio 0
	s_barrier
	s_add_i32 s46, s62, s30
	v_lshl_add_u64 v[218:219], v[218:219], 0, s[8:9]
	s_mov_b32 m0, s46
	ds_read_b128 v[184:187], v155 offset:49152
	ds_read_b128 v[188:191], v155 offset:50176
	ds_read_b128 v[192:195], v155 offset:51200
	ds_read_b128 v[196:199], v155 offset:52224
	ds_read_b128 v[200:203], v155 offset:53248
	ds_read_b128 v[204:207], v155 offset:54272
	ds_read_b128 v[208:211], v155 offset:55296
	ds_read_b128 v[212:215], v155 offset:56320
	global_load_lds_dwordx4 v[218:219], off
	s_add_i32 m0, s46, 0x2000
	s_add_u32 s34, s34, 0x80080
	v_lshl_add_u64 v[218:219], v[220:221], 0, s[8:9]
	s_addc_u32 s35, s35, 0
	s_add_i32 s46, s63, s30
	global_load_lds_dwordx4 v[218:219], off
	v_lshl_add_u64 v[218:219], s[34:35], 0, v[134:135]
	s_mov_b32 m0, s46
	s_nop 0
	global_load_lds_dwordx4 v[218:219], off
	v_lshl_add_u64 v[218:219], s[34:35], 0, v[130:131]
	s_add_i32 m0, s46, 0x2000
	s_nop 0
	global_load_lds_dwordx4 v[218:219], off
	v_lshl_add_u64 v[218:219], v[222:223], 0, s[8:9]
	s_mov_b32 m0, s56
	s_nop 0
	global_load_lds_dwordx4 v[218:219], off
	v_lshl_add_u64 v[218:219], v[224:225], 0, s[8:9]
	s_mov_b32 m0, s57
	s_nop 0
	global_load_lds_dwordx4 v[218:219], off
	s_waitcnt vmcnt(8)
	s_waitcnt lgkmcnt(0)
	s_barrier
	s_setprio 1
	s_waitcnt lgkmcnt(0)
	v_mfma_f32_16x16x32_bf16 v[62:65], v[146:149], v[184:187], v[62:65]
	v_mfma_f32_16x16x32_bf16 v[46:49], v[146:149], v[192:195], v[46:49]
	v_mfma_f32_16x16x32_bf16 v[30:33], v[146:149], v[200:203], v[30:33]
	v_mfma_f32_16x16x32_bf16 v[14:17], v[146:149], v[208:211], v[14:17]
	v_mfma_f32_16x16x32_bf16 v[54:57], v[160:163], v[184:187], v[54:57]
	v_mfma_f32_16x16x32_bf16 v[38:41], v[160:163], v[192:195], v[38:41]
	v_mfma_f32_16x16x32_bf16 v[22:25], v[160:163], v[200:203], v[22:25]
	v_mfma_f32_16x16x32_bf16 v[6:9], v[160:163], v[208:211], v[6:9]
	v_mfma_f32_16x16x32_bf16 v[62:65], v[156:159], v[188:191], v[62:65]
	v_mfma_f32_16x16x32_bf16 v[46:49], v[156:159], v[196:199], v[46:49]
	v_mfma_f32_16x16x32_bf16 v[30:33], v[156:159], v[204:207], v[30:33]
	v_mfma_f32_16x16x32_bf16 v[14:17], v[156:159], v[212:215], v[14:17]
	v_mfma_f32_16x16x32_bf16 v[54:57], v[164:167], v[188:191], v[54:57]
	v_mfma_f32_16x16x32_bf16 v[38:41], v[164:167], v[196:199], v[38:41]
	v_mfma_f32_16x16x32_bf16 v[22:25], v[164:167], v[204:207], v[22:25]
	v_mfma_f32_16x16x32_bf16 v[6:9], v[164:167], v[212:215], v[6:9]
	s_setprio 0
	s_setprio 1
	v_mfma_f32_16x16x32_bf16 v[58:61], v[168:171], v[184:187], v[58:61]
	v_mfma_f32_16x16x32_bf16 v[42:45], v[168:171], v[192:195], v[42:45]
	v_mfma_f32_16x16x32_bf16 v[26:29], v[168:171], v[200:203], v[26:29]
	v_mfma_f32_16x16x32_bf16 v[10:13], v[168:171], v[208:211], v[10:13]
	v_mfma_f32_16x16x32_bf16 v[50:53], v[176:179], v[184:187], v[50:53]
	v_mfma_f32_16x16x32_bf16 v[34:37], v[176:179], v[192:195], v[34:37]
	v_mfma_f32_16x16x32_bf16 v[18:21], v[176:179], v[200:203], v[18:21]
	v_mfma_f32_16x16x32_bf16 v[2:5], v[176:179], v[208:211], v[2:5]
	v_mfma_f32_16x16x32_bf16 v[58:61], v[172:175], v[188:191], v[58:61]
	v_mfma_f32_16x16x32_bf16 v[42:45], v[172:175], v[196:199], v[42:45]
	v_mfma_f32_16x16x32_bf16 v[26:29], v[172:175], v[204:207], v[26:29]
	v_mfma_f32_16x16x32_bf16 v[10:13], v[172:175], v[212:215], v[10:13]
	v_mfma_f32_16x16x32_bf16 v[50:53], v[180:183], v[188:191], v[50:53]
	v_mfma_f32_16x16x32_bf16 v[34:37], v[180:183], v[196:199], v[34:37]
	v_mfma_f32_16x16x32_bf16 v[18:21], v[180:183], v[204:207], v[18:21]
	v_mfma_f32_16x16x32_bf16 v[2:5], v[180:183], v[212:215], v[2:5]
	s_setprio 0
	s_barrier
	s_add_i32 s71, s71, 2
	s_add_u32 s44, s44, 0x100
	s_addc_u32 s45, s45, 0
	s_add_u32 s69, s69, 0x100
	s_addc_u32 s70, s70, 0
	s_cmp_gt_u32 s71, 29
	s_cbranch_scc0 .LBB0_3067
	s_and_b64 vcc, exec, s[24:25]
	s_cbranch_vccz .LBB0_3070
	s_barrier

.LBB0_3180:
	ds_read_b128 v[130:133], v174
	ds_read_b128 v[134:137], v174 offset:1024
	ds_read_b128 v[138:141], v174 offset:2048
	ds_read_b128 v[158:161], v174 offset:3072
	ds_read_b128 v[162:165], v175
	ds_read_b128 v[166:169], v175 offset:1024
	ds_read_b128 v[178:181], v175 offset:2048
	ds_read_b128 v[182:185], v175 offset:3072
	s_add_u32 s34, s40, 0xffea0080
	s_addc_u32 s35, s41, -1
	s_cmpk_eq_i32 s60, 0x54
	s_cselect_b32 s43, s5, s35
	s_cselect_b32 s42, s4, s34
	s_cselect_b32 s35, s39, s1
	s_cselect_b32 s34, s38, s0
	v_lshl_add_u64 v[170:171], s[40:41], 0, v[150:151]
	s_add_i32 m0, s33, 0xc000
	ds_read_b128 v[186:189], v176
	ds_read_b128 v[190:193], v176 offset:1024
	ds_read_b128 v[194:197], v176 offset:2048
	ds_read_b128 v[198:201], v176 offset:3072
	ds_read_b128 v[202:205], v176 offset:4096
	ds_read_b128 v[206:209], v176 offset:5120
	ds_read_b128 v[210:213], v176 offset:6144
	ds_read_b128 v[218:221], v176 offset:7168
	global_load_lds_dwordx4 v[170:171], off
	v_lshl_add_u64 v[170:171], s[40:41], 0, v[152:153]
	s_add_i32 m0, s33, 0xe000
	s_nop 0
	global_load_lds_dwordx4 v[170:171], off
	s_waitcnt vmcnt(8)
	s_waitcnt lgkmcnt(0)
	s_barrier
	s_setprio 1
	s_waitcnt lgkmcnt(0)
	v_mfma_f32_16x16x32_bf16 v[126:129], v[130:133], v[186:189], v[126:129]
	v_mfma_f32_16x16x32_bf16 v[110:113], v[130:133], v[194:197], v[110:113]
	v_mfma_f32_16x16x32_bf16 v[94:97], v[130:133], v[202:205], v[94:97]
	v_mfma_f32_16x16x32_bf16 v[78:81], v[130:133], v[210:213], v[78:81]
	v_mfma_f32_16x16x32_bf16 v[122:125], v[138:141], v[186:189], v[122:125]
	v_mfma_f32_16x16x32_bf16 v[106:109], v[138:141], v[194:197], v[106:109]
	v_mfma_f32_16x16x32_bf16 v[90:93], v[138:141], v[202:205], v[90:93]
	v_mfma_f32_16x16x32_bf16 v[74:77], v[138:141], v[210:213], v[74:77]
	v_mfma_f32_16x16x32_bf16 v[126:129], v[134:137], v[190:193], v[126:129]
	v_mfma_f32_16x16x32_bf16 v[110:113], v[134:137], v[198:201], v[110:113]
	v_mfma_f32_16x16x32_bf16 v[94:97], v[134:137], v[206:209], v[94:97]
	v_mfma_f32_16x16x32_bf16 v[78:81], v[134:137], v[218:221], v[78:81]
	v_mfma_f32_16x16x32_bf16 v[122:125], v[158:161], v[190:193], v[122:125]
	v_mfma_f32_16x16x32_bf16 v[106:109], v[158:161], v[198:201], v[106:109]
	v_mfma_f32_16x16x32_bf16 v[90:93], v[158:161], v[206:209], v[90:93]
	v_mfma_f32_16x16x32_bf16 v[74:77], v[158:161], v[218:221], v[74:77]
	s_setprio 0
	s_setprio 1
	v_mfma_f32_16x16x32_bf16 v[118:121], v[162:165], v[186:189], v[118:121]
	v_mfma_f32_16x16x32_bf16 v[102:105], v[162:165], v[194:197], v[102:105]
	v_mfma_f32_16x16x32_bf16 v[86:89], v[162:165], v[202:205], v[86:89]
	v_mfma_f32_16x16x32_bf16 v[70:73], v[162:165], v[210:213], v[70:73]
	v_mfma_f32_16x16x32_bf16 v[114:117], v[178:181], v[186:189], v[114:117]
	v_mfma_f32_16x16x32_bf16 v[98:101], v[178:181], v[194:197], v[98:101]
	v_mfma_f32_16x16x32_bf16 v[82:85], v[178:181], v[202:205], v[82:85]
	v_mfma_f32_16x16x32_bf16 v[66:69], v[178:181], v[210:213], v[66:69]
	v_mfma_f32_16x16x32_bf16 v[118:121], v[166:169], v[190:193], v[118:121]
	v_mfma_f32_16x16x32_bf16 v[102:105], v[166:169], v[198:201], v[102:105]
	v_mfma_f32_16x16x32_bf16 v[86:89], v[166:169], v[206:209], v[86:89]
	v_mfma_f32_16x16x32_bf16 v[70:73], v[166:169], v[218:221], v[70:73]
	v_mfma_f32_16x16x32_bf16 v[114:117], v[182:185], v[190:193], v[114:117]
	v_mfma_f32_16x16x32_bf16 v[98:101], v[182:185], v[198:201], v[98:101]
	v_mfma_f32_16x16x32_bf16 v[82:85], v[182:185], v[206:209], v[82:85]
	v_mfma_f32_16x16x32_bf16 v[66:69], v[182:185], v[218:221], v[66:69]
	s_setprio 0
	s_barrier
	s_add_i32 s61, s53, s31
	v_lshl_add_u64 v[170:171], s[34:35], 0, v[144:145]
	s_mov_b32 m0, s61
	ds_read_b128 v[186:189], v176 offset:16384
	ds_read_b128 v[190:193], v176 offset:17408
	ds_read_b128 v[194:197], v176 offset:18432
	ds_read_b128 v[198:201], v176 offset:19456
	ds_read_b128 v[202:205], v176 offset:20480
	ds_read_b128 v[206:209], v176 offset:21504
	ds_read_b128 v[210:213], v176 offset:22528
	ds_read_b128 v[218:221], v176 offset:23552
	global_load_lds_dwordx4 v[170:171], off
	s_add_i32 m0, s61, 0x2000
	s_add_u32 s62, s34, 0x160000
	v_lshl_add_u64 v[214:215], s[34:35], 0, v[148:149]
	s_addc_u32 s63, s35, 0
	s_add_i32 s61, s54, s31
	global_load_lds_dwordx4 v[214:215], off
	v_lshl_add_u64 v[222:223], s[62:63], 0, v[144:145]
	s_mov_b32 m0, s61
	v_lshl_add_u64 v[224:225], s[42:43], 0, v[146:147]
	global_load_lds_dwordx4 v[222:223], off
	v_lshl_add_u64 v[222:223], s[62:63], 0, v[148:149]
	s_add_i32 m0, s61, 0x2000
	s_nop 0
	global_load_lds_dwordx4 v[222:223], off
	v_lshl_add_u64 v[222:223], s[42:43], 0, v[142:143]
	s_mov_b32 m0, s33
	s_nop 0
	global_load_lds_dwordx4 v[222:223], off
	s_mov_b32 m0, s44
	s_nop 0
	global_load_lds_dwordx4 v[224:225], off
	s_waitcnt vmcnt(8)
	s_waitcnt lgkmcnt(0)
	s_barrier
	s_setprio 1
	s_waitcnt lgkmcnt(0)
	v_mfma_f32_16x16x32_bf16 v[62:65], v[130:133], v[186:189], v[62:65]
	v_mfma_f32_16x16x32_bf16 v[50:53], v[130:133], v[194:197], v[50:53]
	v_mfma_f32_16x16x32_bf16 v[38:41], v[130:133], v[202:205], v[38:41]
	v_mfma_f32_16x16x32_bf16 v[14:17], v[130:133], v[210:213], v[14:17]
	v_mfma_f32_16x16x32_bf16 v[58:61], v[138:141], v[186:189], v[58:61]
	v_mfma_f32_16x16x32_bf16 v[42:45], v[138:141], v[194:197], v[42:45]
	v_mfma_f32_16x16x32_bf16 v[34:37], v[138:141], v[202:205], v[34:37]
	v_mfma_f32_16x16x32_bf16 v[10:13], v[138:141], v[210:213], v[10:13]
	v_mfma_f32_16x16x32_bf16 v[62:65], v[134:137], v[190:193], v[62:65]
	v_mfma_f32_16x16x32_bf16 v[50:53], v[134:137], v[198:201], v[50:53]
	v_mfma_f32_16x16x32_bf16 v[38:41], v[134:137], v[206:209], v[38:41]
	v_mfma_f32_16x16x32_bf16 v[14:17], v[134:137], v[218:221], v[14:17]
	v_mfma_f32_16x16x32_bf16 v[58:61], v[158:161], v[190:193], v[58:61]
	v_mfma_f32_16x16x32_bf16 v[42:45], v[158:161], v[198:201], v[42:45]
	v_mfma_f32_16x16x32_bf16 v[34:37], v[158:161], v[206:209], v[34:37]
	v_mfma_f32_16x16x32_bf16 v[10:13], v[158:161], v[218:221], v[10:13]
	s_setprio 0
	s_setprio 1
	v_mfma_f32_16x16x32_bf16 v[54:57], v[162:165], v[186:189], v[54:57]
	v_mfma_f32_16x16x32_bf16 v[30:33], v[162:165], v[194:197], v[30:33]
	v_mfma_f32_16x16x32_bf16 v[22:25], v[162:165], v[202:205], v[22:25]
	v_mfma_f32_16x16x32_bf16 v[6:9], v[162:165], v[210:213], v[6:9]
	v_mfma_f32_16x16x32_bf16 v[46:49], v[178:181], v[186:189], v[46:49]
	v_mfma_f32_16x16x32_bf16 v[26:29], v[178:181], v[194:197], v[26:29]
	v_mfma_f32_16x16x32_bf16 v[18:21], v[178:181], v[202:205], v[18:21]
	v_mfma_f32_16x16x32_bf16 v[2:5], v[178:181], v[210:213], v[2:5]
	v_mfma_f32_16x16x32_bf16 v[54:57], v[166:169], v[190:193], v[54:57]
	v_mfma_f32_16x16x32_bf16 v[30:33], v[166:169], v[198:201], v[30:33]
	v_mfma_f32_16x16x32_bf16 v[22:25], v[166:169], v[206:209], v[22:25]
	v_mfma_f32_16x16x32_bf16 v[6:9], v[166:169], v[218:221], v[6:9]
	v_mfma_f32_16x16x32_bf16 v[46:49], v[182:185], v[190:193], v[46:49]
	v_mfma_f32_16x16x32_bf16 v[26:29], v[182:185], v[198:201], v[26:29]
	v_mfma_f32_16x16x32_bf16 v[18:21], v[182:185], v[206:209], v[18:21]
	v_mfma_f32_16x16x32_bf16 v[2:5], v[182:185], v[218:221], v[2:5]
	s_setprio 0
	s_barrier
	s_add_i32 s61, 0, 0x18000
	s_add_i32 s62, 0, 0x1c000
	v_add_u32_e32 v158, s61, v172
	v_add_u32_e32 v177, s62, v172
	ds_read_b128 v[130:133], v158
	ds_read_b128 v[134:137], v158 offset:1024
	ds_read_b128 v[138:141], v158 offset:2048
	ds_read_b128 v[158:161], v158 offset:3072
	ds_read_b128 v[162:165], v177
	ds_read_b128 v[166:169], v177 offset:1024
	ds_read_b128 v[178:181], v177 offset:2048
	ds_read_b128 v[182:185], v177 offset:3072
	s_add_u32 s42, s42, 0x160000
	s_addc_u32 s43, s43, 0
	s_mov_b32 m0, s45
	v_lshl_add_u64 v[226:227], s[42:43], 0, v[142:143]
	ds_read_b128 v[186:189], v176 offset:32768
	ds_read_b128 v[190:193], v176 offset:33792
	ds_read_b128 v[194:197], v176 offset:34816
	ds_read_b128 v[198:201], v176 offset:35840
	ds_read_b128 v[202:205], v176 offset:36864
	ds_read_b128 v[206:209], v176 offset:37888
	ds_read_b128 v[210:213], v176 offset:38912
	ds_read_b128 v[218:221], v176 offset:39936
	global_load_lds_dwordx4 v[226:227], off
	v_lshl_add_u64 v[226:227], s[42:43], 0, v[146:147]
	s_mov_b32 m0, s46
	s_nop 0
	global_load_lds_dwordx4 v[226:227], off
	s_waitcnt vmcnt(8)
	s_waitcnt lgkmcnt(0)
	s_barrier
	s_setprio 1
	s_waitcnt lgkmcnt(0)
	v_mfma_f32_16x16x32_bf16 v[126:129], v[130:133], v[186:189], v[126:129]
	v_mfma_f32_16x16x32_bf16 v[110:113], v[130:133], v[194:197], v[110:113]
	v_mfma_f32_16x16x32_bf16 v[94:97], v[130:133], v[202:205], v[94:97]
	v_mfma_f32_16x16x32_bf16 v[78:81], v[130:133], v[210:213], v[78:81]
	v_mfma_f32_16x16x32_bf16 v[122:125], v[138:141], v[186:189], v[122:125]
	v_mfma_f32_16x16x32_bf16 v[106:109], v[138:141], v[194:197], v[106:109]
	v_mfma_f32_16x16x32_bf16 v[90:93], v[138:141], v[202:205], v[90:93]
	v_mfma_f32_16x16x32_bf16 v[74:77], v[138:141], v[210:213], v[74:77]
	v_mfma_f32_16x16x32_bf16 v[126:129], v[134:137], v[190:193], v[126:129]
	v_mfma_f32_16x16x32_bf16 v[110:113], v[134:137], v[198:201], v[110:113]
	v_mfma_f32_16x16x32_bf16 v[94:97], v[134:137], v[206:209], v[94:97]
	v_mfma_f32_16x16x32_bf16 v[78:81], v[134:137], v[218:221], v[78:81]
	v_mfma_f32_16x16x32_bf16 v[122:125], v[158:161], v[190:193], v[122:125]
	v_mfma_f32_16x16x32_bf16 v[106:109], v[158:161], v[198:201], v[106:109]
	v_mfma_f32_16x16x32_bf16 v[90:93], v[158:161], v[206:209], v[90:93]
	v_mfma_f32_16x16x32_bf16 v[74:77], v[158:161], v[218:221], v[74:77]
	s_setprio 0
	s_setprio 1
	v_mfma_f32_16x16x32_bf16 v[118:121], v[162:165], v[186:189], v[118:121]
	v_mfma_f32_16x16x32_bf16 v[102:105], v[162:165], v[194:197], v[102:105]
	v_mfma_f32_16x16x32_bf16 v[86:89], v[162:165], v[202:205], v[86:89]
	v_mfma_f32_16x16x32_bf16 v[70:73], v[162:165], v[210:213], v[70:73]
	v_mfma_f32_16x16x32_bf16 v[114:117], v[178:181], v[186:189], v[114:117]
	v_mfma_f32_16x16x32_bf16 v[98:101], v[178:181], v[194:197], v[98:101]
	v_mfma_f32_16x16x32_bf16 v[82:85], v[178:181], v[202:205], v[82:85]
	v_mfma_f32_16x16x32_bf16 v[66:69], v[178:181], v[210:213], v[66:69]
	v_mfma_f32_16x16x32_bf16 v[118:121], v[166:169], v[190:193], v[118:121]
	v_mfma_f32_16x16x32_bf16 v[102:105], v[166:169], v[198:201], v[102:105]
	v_mfma_f32_16x16x32_bf16 v[86:89], v[166:169], v[206:209], v[86:89]
	v_mfma_f32_16x16x32_bf16 v[70:73], v[166:169], v[218:221], v[70:73]
	v_mfma_f32_16x16x32_bf16 v[114:117], v[182:185], v[190:193], v[114:117]
	v_mfma_f32_16x16x32_bf16 v[98:101], v[182:185], v[198:201], v[98:101]
	v_mfma_f32_16x16x32_bf16 v[82:85], v[182:185], v[206:209], v[82:85]
	v_mfma_f32_16x16x32_bf16 v[66:69], v[182:185], v[218:221], v[66:69]
	s_setprio 0
	s_barrier
	s_add_i32 s42, s61, s31
	v_lshl_add_u64 v[170:171], v[170:171], 0, s[24:25]
	s_mov_b32 m0, s42
	ds_read_b128 v[186:189], v176 offset:49152
	ds_read_b128 v[190:193], v176 offset:50176
	ds_read_b128 v[194:197], v176 offset:51200
	ds_read_b128 v[198:201], v176 offset:52224
	ds_read_b128 v[202:205], v176 offset:53248
	ds_read_b128 v[206:209], v176 offset:54272
	ds_read_b128 v[210:213], v176 offset:55296
	ds_read_b128 v[218:221], v176 offset:56320
	global_load_lds_dwordx4 v[170:171], off
	s_add_i32 m0, s42, 0x2000
	s_add_u32 s34, s34, 0x160080
	v_lshl_add_u64 v[170:171], v[214:215], 0, s[24:25]
	s_addc_u32 s35, s35, 0
	s_add_i32 s42, s62, s31
	global_load_lds_dwordx4 v[170:171], off
	v_lshl_add_u64 v[170:171], s[34:35], 0, v[144:145]
	s_mov_b32 m0, s42
	s_nop 0
	global_load_lds_dwordx4 v[170:171], off
	v_lshl_add_u64 v[170:171], s[34:35], 0, v[148:149]
	s_add_i32 m0, s42, 0x2000
	s_nop 0
	global_load_lds_dwordx4 v[170:171], off
	v_lshl_add_u64 v[170:171], v[222:223], 0, s[24:25]
	s_mov_b32 m0, s48
	s_nop 0
	global_load_lds_dwordx4 v[170:171], off
	v_lshl_add_u64 v[170:171], v[224:225], 0, s[24:25]
	s_mov_b32 m0, s49
	s_nop 0
	global_load_lds_dwordx4 v[170:171], off
	s_waitcnt vmcnt(8)
	s_waitcnt lgkmcnt(0)
	s_barrier
	s_setprio 1
	s_waitcnt lgkmcnt(0)
	v_mfma_f32_16x16x32_bf16 v[62:65], v[130:133], v[186:189], v[62:65]
	v_mfma_f32_16x16x32_bf16 v[50:53], v[130:133], v[194:197], v[50:53]
	v_mfma_f32_16x16x32_bf16 v[38:41], v[130:133], v[202:205], v[38:41]
	v_mfma_f32_16x16x32_bf16 v[14:17], v[130:133], v[210:213], v[14:17]
	v_mfma_f32_16x16x32_bf16 v[58:61], v[138:141], v[186:189], v[58:61]
	v_mfma_f32_16x16x32_bf16 v[42:45], v[138:141], v[194:197], v[42:45]
	v_mfma_f32_16x16x32_bf16 v[34:37], v[138:141], v[202:205], v[34:37]
	v_mfma_f32_16x16x32_bf16 v[10:13], v[138:141], v[210:213], v[10:13]
	v_mfma_f32_16x16x32_bf16 v[62:65], v[134:137], v[190:193], v[62:65]
	v_mfma_f32_16x16x32_bf16 v[50:53], v[134:137], v[198:201], v[50:53]
	v_mfma_f32_16x16x32_bf16 v[38:41], v[134:137], v[206:209], v[38:41]
	v_mfma_f32_16x16x32_bf16 v[14:17], v[134:137], v[218:221], v[14:17]
	v_mfma_f32_16x16x32_bf16 v[58:61], v[158:161], v[190:193], v[58:61]
	v_mfma_f32_16x16x32_bf16 v[42:45], v[158:161], v[198:201], v[42:45]
	v_mfma_f32_16x16x32_bf16 v[34:37], v[158:161], v[206:209], v[34:37]
	v_mfma_f32_16x16x32_bf16 v[10:13], v[158:161], v[218:221], v[10:13]
	s_setprio 0
	s_setprio 1
	v_mfma_f32_16x16x32_bf16 v[54:57], v[162:165], v[186:189], v[54:57]
	v_mfma_f32_16x16x32_bf16 v[30:33], v[162:165], v[194:197], v[30:33]
	v_mfma_f32_16x16x32_bf16 v[22:25], v[162:165], v[202:205], v[22:25]
	v_mfma_f32_16x16x32_bf16 v[6:9], v[162:165], v[210:213], v[6:9]
	v_mfma_f32_16x16x32_bf16 v[46:49], v[178:181], v[186:189], v[46:49]
	v_mfma_f32_16x16x32_bf16 v[26:29], v[178:181], v[194:197], v[26:29]
	v_mfma_f32_16x16x32_bf16 v[18:21], v[178:181], v[202:205], v[18:21]
	v_mfma_f32_16x16x32_bf16 v[2:5], v[178:181], v[210:213], v[2:5]
	v_mfma_f32_16x16x32_bf16 v[54:57], v[166:169], v[190:193], v[54:57]
	v_mfma_f32_16x16x32_bf16 v[30:33], v[166:169], v[198:201], v[30:33]
	v_mfma_f32_16x16x32_bf16 v[22:25], v[166:169], v[206:209], v[22:25]
	v_mfma_f32_16x16x32_bf16 v[6:9], v[166:169], v[218:221], v[6:9]
	v_mfma_f32_16x16x32_bf16 v[46:49], v[182:185], v[190:193], v[46:49]
	v_mfma_f32_16x16x32_bf16 v[26:29], v[182:185], v[198:201], v[26:29]
	v_mfma_f32_16x16x32_bf16 v[18:21], v[182:185], v[206:209], v[18:21]
	v_mfma_f32_16x16x32_bf16 v[2:5], v[182:185], v[218:221], v[2:5]
	s_setprio 0
	s_barrier
	s_add_i32 s60, s60, 2
	s_add_u32 s40, s40, 0x100
	s_addc_u32 s41, s41, 0
	s_add_u32 s0, s0, 0x100
	s_addc_u32 s1, s1, 0
	s_cmpk_gt_u32 s60, 0x55
	s_cbranch_scc0 .LBB0_3180
	s_and_b64 vcc, exec, s[26:27]
	s_cbranch_vccz .LBB0_3183
	s_barrier

.LBB0_3309:
	ds_read_b128 v[146:149], v153
	ds_read_b128 v[156:159], v153 offset:1024
	ds_read_b128 v[160:163], v153 offset:2048
	ds_read_b128 v[164:167], v153 offset:3072
	ds_read_b128 v[168:171], v154
	ds_read_b128 v[172:175], v154 offset:1024
	ds_read_b128 v[176:179], v154 offset:2048
	ds_read_b128 v[180:183], v154 offset:3072
	s_add_u32 s34, s44, 0xfff80080
	s_addc_u32 s35, s45, -1
	s_cmp_eq_u32 s69, 28
	s_cselect_b32 s47, s0, s35
	s_cselect_b32 s46, s1, s34
	s_cselect_b32 s35, s27, s68
	s_cselect_b32 s34, s37, s61
	v_lshl_add_u64 v[218:219], s[44:45], 0, v[138:139]
	s_add_i32 m0, s43, 0xc000
	ds_read_b128 v[184:187], v155
	ds_read_b128 v[188:191], v155 offset:1024
	ds_read_b128 v[192:195], v155 offset:2048
	ds_read_b128 v[196:199], v155 offset:3072
	ds_read_b128 v[200:203], v155 offset:4096
	ds_read_b128 v[204:207], v155 offset:5120
	ds_read_b128 v[208:211], v155 offset:6144
	ds_read_b128 v[212:215], v155 offset:7168
	global_load_lds_dwordx4 v[218:219], off
	v_lshl_add_u64 v[218:219], s[44:45], 0, v[140:141]
	s_add_i32 m0, s43, 0xe000
	s_nop 0
	global_load_lds_dwordx4 v[218:219], off
	s_waitcnt vmcnt(8)
	s_waitcnt lgkmcnt(0)
	s_barrier
	s_setprio 1
	s_waitcnt lgkmcnt(0)
	v_mfma_f32_16x16x32_bf16 v[126:129], v[146:149], v[184:187], v[126:129]
	v_mfma_f32_16x16x32_bf16 v[110:113], v[146:149], v[192:195], v[110:113]
	v_mfma_f32_16x16x32_bf16 v[94:97], v[146:149], v[200:203], v[94:97]
	v_mfma_f32_16x16x32_bf16 v[78:81], v[146:149], v[208:211], v[78:81]
	v_mfma_f32_16x16x32_bf16 v[118:121], v[160:163], v[184:187], v[118:121]
	v_mfma_f32_16x16x32_bf16 v[102:105], v[160:163], v[192:195], v[102:105]
	v_mfma_f32_16x16x32_bf16 v[86:89], v[160:163], v[200:203], v[86:89]
	v_mfma_f32_16x16x32_bf16 v[70:73], v[160:163], v[208:211], v[70:73]
	v_mfma_f32_16x16x32_bf16 v[126:129], v[156:159], v[188:191], v[126:129]
	v_mfma_f32_16x16x32_bf16 v[110:113], v[156:159], v[196:199], v[110:113]
	v_mfma_f32_16x16x32_bf16 v[94:97], v[156:159], v[204:207], v[94:97]
	v_mfma_f32_16x16x32_bf16 v[78:81], v[156:159], v[212:215], v[78:81]
	v_mfma_f32_16x16x32_bf16 v[118:121], v[164:167], v[188:191], v[118:121]
	v_mfma_f32_16x16x32_bf16 v[102:105], v[164:167], v[196:199], v[102:105]
	v_mfma_f32_16x16x32_bf16 v[86:89], v[164:167], v[204:207], v[86:89]
	v_mfma_f32_16x16x32_bf16 v[70:73], v[164:167], v[212:215], v[70:73]
	s_setprio 0
	s_setprio 1
	v_mfma_f32_16x16x32_bf16 v[122:125], v[168:171], v[184:187], v[122:125]
	v_mfma_f32_16x16x32_bf16 v[106:109], v[168:171], v[192:195], v[106:109]
	v_mfma_f32_16x16x32_bf16 v[90:93], v[168:171], v[200:203], v[90:93]
	v_mfma_f32_16x16x32_bf16 v[74:77], v[168:171], v[208:211], v[74:77]
	v_mfma_f32_16x16x32_bf16 v[114:117], v[176:179], v[184:187], v[114:117]
	v_mfma_f32_16x16x32_bf16 v[98:101], v[176:179], v[192:195], v[98:101]
	v_mfma_f32_16x16x32_bf16 v[82:85], v[176:179], v[200:203], v[82:85]
	v_mfma_f32_16x16x32_bf16 v[66:69], v[176:179], v[208:211], v[66:69]
	v_mfma_f32_16x16x32_bf16 v[122:125], v[172:175], v[188:191], v[122:125]
	v_mfma_f32_16x16x32_bf16 v[106:109], v[172:175], v[196:199], v[106:109]
	v_mfma_f32_16x16x32_bf16 v[90:93], v[172:175], v[204:207], v[90:93]
	v_mfma_f32_16x16x32_bf16 v[74:77], v[172:175], v[212:215], v[74:77]
	v_mfma_f32_16x16x32_bf16 v[114:117], v[180:183], v[188:191], v[114:117]
	v_mfma_f32_16x16x32_bf16 v[98:101], v[180:183], v[196:199], v[98:101]
	v_mfma_f32_16x16x32_bf16 v[82:85], v[180:183], v[204:207], v[82:85]
	v_mfma_f32_16x16x32_bf16 v[66:69], v[180:183], v[212:215], v[66:69]
	s_setprio 0
	s_barrier
	s_add_i32 s62, s57, s30
	v_lshl_add_u64 v[218:219], s[34:35], 0, v[134:135]
	s_mov_b32 m0, s62
	ds_read_b128 v[184:187], v155 offset:16384
	ds_read_b128 v[188:191], v155 offset:17408
	ds_read_b128 v[192:195], v155 offset:18432
	ds_read_b128 v[196:199], v155 offset:19456
	ds_read_b128 v[200:203], v155 offset:20480
	ds_read_b128 v[204:207], v155 offset:21504
	ds_read_b128 v[208:211], v155 offset:22528
	ds_read_b128 v[212:215], v155 offset:23552
	global_load_lds_dwordx4 v[218:219], off
	s_add_i32 m0, s62, 0x2000
	s_add_u32 s62, s34, 0x80000
	v_lshl_add_u64 v[220:221], s[34:35], 0, v[130:131]
	s_addc_u32 s63, s35, 0
	s_add_i32 s66, s58, s30
	global_load_lds_dwordx4 v[220:221], off
	v_lshl_add_u64 v[222:223], s[62:63], 0, v[134:135]
	s_mov_b32 m0, s66
	v_lshl_add_u64 v[224:225], s[46:47], 0, v[132:133]
	global_load_lds_dwordx4 v[222:223], off
	v_lshl_add_u64 v[222:223], s[62:63], 0, v[130:131]
	s_add_i32 m0, s66, 0x2000
	s_nop 0
	global_load_lds_dwordx4 v[222:223], off
	v_lshl_add_u64 v[222:223], s[46:47], 0, v[136:137]
	s_mov_b32 m0, s43
	s_nop 0
	global_load_lds_dwordx4 v[222:223], off
	s_mov_b32 m0, s48
	s_nop 0
	global_load_lds_dwordx4 v[224:225], off
	s_waitcnt vmcnt(8)
	s_waitcnt lgkmcnt(0)
	s_barrier
	s_setprio 1
	s_waitcnt lgkmcnt(0)
	v_mfma_f32_16x16x32_bf16 v[62:65], v[146:149], v[184:187], v[62:65]
	v_mfma_f32_16x16x32_bf16 v[46:49], v[146:149], v[192:195], v[46:49]
	v_mfma_f32_16x16x32_bf16 v[30:33], v[146:149], v[200:203], v[30:33]
	v_mfma_f32_16x16x32_bf16 v[14:17], v[146:149], v[208:211], v[14:17]
	v_mfma_f32_16x16x32_bf16 v[54:57], v[160:163], v[184:187], v[54:57]
	v_mfma_f32_16x16x32_bf16 v[38:41], v[160:163], v[192:195], v[38:41]
	v_mfma_f32_16x16x32_bf16 v[22:25], v[160:163], v[200:203], v[22:25]
	v_mfma_f32_16x16x32_bf16 v[6:9], v[160:163], v[208:211], v[6:9]
	v_mfma_f32_16x16x32_bf16 v[62:65], v[156:159], v[188:191], v[62:65]
	v_mfma_f32_16x16x32_bf16 v[46:49], v[156:159], v[196:199], v[46:49]
	v_mfma_f32_16x16x32_bf16 v[30:33], v[156:159], v[204:207], v[30:33]
	v_mfma_f32_16x16x32_bf16 v[14:17], v[156:159], v[212:215], v[14:17]
	v_mfma_f32_16x16x32_bf16 v[54:57], v[164:167], v[188:191], v[54:57]
	v_mfma_f32_16x16x32_bf16 v[38:41], v[164:167], v[196:199], v[38:41]
	v_mfma_f32_16x16x32_bf16 v[22:25], v[164:167], v[204:207], v[22:25]
	v_mfma_f32_16x16x32_bf16 v[6:9], v[164:167], v[212:215], v[6:9]
	s_setprio 0
	s_setprio 1
	v_mfma_f32_16x16x32_bf16 v[58:61], v[168:171], v[184:187], v[58:61]
	v_mfma_f32_16x16x32_bf16 v[42:45], v[168:171], v[192:195], v[42:45]
	v_mfma_f32_16x16x32_bf16 v[26:29], v[168:171], v[200:203], v[26:29]
	v_mfma_f32_16x16x32_bf16 v[10:13], v[168:171], v[208:211], v[10:13]
	v_mfma_f32_16x16x32_bf16 v[50:53], v[176:179], v[184:187], v[50:53]
	v_mfma_f32_16x16x32_bf16 v[34:37], v[176:179], v[192:195], v[34:37]
	v_mfma_f32_16x16x32_bf16 v[18:21], v[176:179], v[200:203], v[18:21]
	v_mfma_f32_16x16x32_bf16 v[2:5], v[176:179], v[208:211], v[2:5]
	v_mfma_f32_16x16x32_bf16 v[58:61], v[172:175], v[188:191], v[58:61]
	v_mfma_f32_16x16x32_bf16 v[42:45], v[172:175], v[196:199], v[42:45]
	v_mfma_f32_16x16x32_bf16 v[26:29], v[172:175], v[204:207], v[26:29]
	v_mfma_f32_16x16x32_bf16 v[10:13], v[172:175], v[212:215], v[10:13]
	v_mfma_f32_16x16x32_bf16 v[50:53], v[180:183], v[188:191], v[50:53]
	v_mfma_f32_16x16x32_bf16 v[34:37], v[180:183], v[196:199], v[34:37]
	v_mfma_f32_16x16x32_bf16 v[18:21], v[180:183], v[204:207], v[18:21]
	v_mfma_f32_16x16x32_bf16 v[2:5], v[180:183], v[212:215], v[2:5]
	s_setprio 0
	s_barrier
	s_add_i32 s62, 0, 0x18000
	s_add_i32 s63, 0, 0x1c000
	v_add_u32_e32 v164, s62, v151
	v_add_u32_e32 v180, s63, v151
	ds_read_b128 v[146:149], v164
	ds_read_b128 v[156:159], v164 offset:1024
	ds_read_b128 v[160:163], v164 offset:2048
	ds_read_b128 v[164:167], v164 offset:3072
	ds_read_b128 v[168:171], v180
	ds_read_b128 v[172:175], v180 offset:1024
	ds_read_b128 v[176:179], v180 offset:2048
	ds_read_b128 v[180:183], v180 offset:3072
	s_add_u32 s46, s46, 0x80000
	s_addc_u32 s47, s47, 0
	s_mov_b32 m0, s49
	v_lshl_add_u64 v[226:227], s[46:47], 0, v[136:137]
	ds_read_b128 v[184:187], v155 offset:32768
	ds_read_b128 v[188:191], v155 offset:33792
	ds_read_b128 v[192:195], v155 offset:34816
	ds_read_b128 v[196:199], v155 offset:35840
	ds_read_b128 v[200:203], v155 offset:36864
	ds_read_b128 v[204:207], v155 offset:37888
	ds_read_b128 v[208:211], v155 offset:38912
	ds_read_b128 v[212:215], v155 offset:39936
	global_load_lds_dwordx4 v[226:227], off
	v_lshl_add_u64 v[226:227], s[46:47], 0, v[132:133]
	s_mov_b32 m0, s52
	s_nop 0
	global_load_lds_dwordx4 v[226:227], off
	s_waitcnt vmcnt(8)
	s_waitcnt lgkmcnt(0)
	s_barrier
	s_setprio 1
	s_waitcnt lgkmcnt(0)
	v_mfma_f32_16x16x32_bf16 v[126:129], v[146:149], v[184:187], v[126:129]
	v_mfma_f32_16x16x32_bf16 v[110:113], v[146:149], v[192:195], v[110:113]
	v_mfma_f32_16x16x32_bf16 v[94:97], v[146:149], v[200:203], v[94:97]
	v_mfma_f32_16x16x32_bf16 v[78:81], v[146:149], v[208:211], v[78:81]
	v_mfma_f32_16x16x32_bf16 v[118:121], v[160:163], v[184:187], v[118:121]
	v_mfma_f32_16x16x32_bf16 v[102:105], v[160:163], v[192:195], v[102:105]
	v_mfma_f32_16x16x32_bf16 v[86:89], v[160:163], v[200:203], v[86:89]
	v_mfma_f32_16x16x32_bf16 v[70:73], v[160:163], v[208:211], v[70:73]
	v_mfma_f32_16x16x32_bf16 v[126:129], v[156:159], v[188:191], v[126:129]
	v_mfma_f32_16x16x32_bf16 v[110:113], v[156:159], v[196:199], v[110:113]
	v_mfma_f32_16x16x32_bf16 v[94:97], v[156:159], v[204:207], v[94:97]
	v_mfma_f32_16x16x32_bf16 v[78:81], v[156:159], v[212:215], v[78:81]
	v_mfma_f32_16x16x32_bf16 v[118:121], v[164:167], v[188:191], v[118:121]
	v_mfma_f32_16x16x32_bf16 v[102:105], v[164:167], v[196:199], v[102:105]
	v_mfma_f32_16x16x32_bf16 v[86:89], v[164:167], v[204:207], v[86:89]
	v_mfma_f32_16x16x32_bf16 v[70:73], v[164:167], v[212:215], v[70:73]
	s_setprio 0
	s_setprio 1
	v_mfma_f32_16x16x32_bf16 v[122:125], v[168:171], v[184:187], v[122:125]
	v_mfma_f32_16x16x32_bf16 v[106:109], v[168:171], v[192:195], v[106:109]
	v_mfma_f32_16x16x32_bf16 v[90:93], v[168:171], v[200:203], v[90:93]
	v_mfma_f32_16x16x32_bf16 v[74:77], v[168:171], v[208:211], v[74:77]
	v_mfma_f32_16x16x32_bf16 v[114:117], v[176:179], v[184:187], v[114:117]
	v_mfma_f32_16x16x32_bf16 v[98:101], v[176:179], v[192:195], v[98:101]
	v_mfma_f32_16x16x32_bf16 v[82:85], v[176:179], v[200:203], v[82:85]
	v_mfma_f32_16x16x32_bf16 v[66:69], v[176:179], v[208:211], v[66:69]
	v_mfma_f32_16x16x32_bf16 v[122:125], v[172:175], v[188:191], v[122:125]
	v_mfma_f32_16x16x32_bf16 v[106:109], v[172:175], v[196:199], v[106:109]
	v_mfma_f32_16x16x32_bf16 v[90:93], v[172:175], v[204:207], v[90:93]
	v_mfma_f32_16x16x32_bf16 v[74:77], v[172:175], v[212:215], v[74:77]
	v_mfma_f32_16x16x32_bf16 v[114:117], v[180:183], v[188:191], v[114:117]
	v_mfma_f32_16x16x32_bf16 v[98:101], v[180:183], v[196:199], v[98:101]
	v_mfma_f32_16x16x32_bf16 v[82:85], v[180:183], v[204:207], v[82:85]
	v_mfma_f32_16x16x32_bf16 v[66:69], v[180:183], v[212:215], v[66:69]
	s_setprio 0
	s_barrier
	s_add_i32 s46, s62, s30
	v_lshl_add_u64 v[218:219], v[218:219], 0, s[8:9]
	s_mov_b32 m0, s46
	ds_read_b128 v[184:187], v155 offset:49152
	ds_read_b128 v[188:191], v155 offset:50176
	ds_read_b128 v[192:195], v155 offset:51200
	ds_read_b128 v[196:199], v155 offset:52224
	ds_read_b128 v[200:203], v155 offset:53248
	ds_read_b128 v[204:207], v155 offset:54272
	ds_read_b128 v[208:211], v155 offset:55296
	ds_read_b128 v[212:215], v155 offset:56320
	global_load_lds_dwordx4 v[218:219], off
	s_add_i32 m0, s46, 0x2000
	s_add_u32 s34, s34, 0x80080
	v_lshl_add_u64 v[218:219], v[220:221], 0, s[8:9]
	s_addc_u32 s35, s35, 0
	s_add_i32 s46, s63, s30
	global_load_lds_dwordx4 v[218:219], off
	v_lshl_add_u64 v[218:219], s[34:35], 0, v[134:135]
	s_mov_b32 m0, s46
	s_nop 0
	global_load_lds_dwordx4 v[218:219], off
	v_lshl_add_u64 v[218:219], s[34:35], 0, v[130:131]
	s_add_i32 m0, s46, 0x2000
	s_nop 0
	global_load_lds_dwordx4 v[218:219], off
	v_lshl_add_u64 v[218:219], v[222:223], 0, s[8:9]
	s_mov_b32 m0, s54
	s_nop 0
	global_load_lds_dwordx4 v[218:219], off
	v_lshl_add_u64 v[218:219], v[224:225], 0, s[8:9]
	s_mov_b32 m0, s55
	s_nop 0
	global_load_lds_dwordx4 v[218:219], off
	s_waitcnt vmcnt(8)
	s_waitcnt lgkmcnt(0)
	s_barrier
	s_setprio 1
	s_waitcnt lgkmcnt(0)
	v_mfma_f32_16x16x32_bf16 v[62:65], v[146:149], v[184:187], v[62:65]
	v_mfma_f32_16x16x32_bf16 v[46:49], v[146:149], v[192:195], v[46:49]
	v_mfma_f32_16x16x32_bf16 v[30:33], v[146:149], v[200:203], v[30:33]
	v_mfma_f32_16x16x32_bf16 v[14:17], v[146:149], v[208:211], v[14:17]
	v_mfma_f32_16x16x32_bf16 v[54:57], v[160:163], v[184:187], v[54:57]
	v_mfma_f32_16x16x32_bf16 v[38:41], v[160:163], v[192:195], v[38:41]
	v_mfma_f32_16x16x32_bf16 v[22:25], v[160:163], v[200:203], v[22:25]
	v_mfma_f32_16x16x32_bf16 v[6:9], v[160:163], v[208:211], v[6:9]
	v_mfma_f32_16x16x32_bf16 v[62:65], v[156:159], v[188:191], v[62:65]
	v_mfma_f32_16x16x32_bf16 v[46:49], v[156:159], v[196:199], v[46:49]
	v_mfma_f32_16x16x32_bf16 v[30:33], v[156:159], v[204:207], v[30:33]
	v_mfma_f32_16x16x32_bf16 v[14:17], v[156:159], v[212:215], v[14:17]
	v_mfma_f32_16x16x32_bf16 v[54:57], v[164:167], v[188:191], v[54:57]
	v_mfma_f32_16x16x32_bf16 v[38:41], v[164:167], v[196:199], v[38:41]
	v_mfma_f32_16x16x32_bf16 v[22:25], v[164:167], v[204:207], v[22:25]
	v_mfma_f32_16x16x32_bf16 v[6:9], v[164:167], v[212:215], v[6:9]
	s_setprio 0
	s_setprio 1
	v_mfma_f32_16x16x32_bf16 v[58:61], v[168:171], v[184:187], v[58:61]
	v_mfma_f32_16x16x32_bf16 v[42:45], v[168:171], v[192:195], v[42:45]
	v_mfma_f32_16x16x32_bf16 v[26:29], v[168:171], v[200:203], v[26:29]
	v_mfma_f32_16x16x32_bf16 v[10:13], v[168:171], v[208:211], v[10:13]
	v_mfma_f32_16x16x32_bf16 v[50:53], v[176:179], v[184:187], v[50:53]
	v_mfma_f32_16x16x32_bf16 v[34:37], v[176:179], v[192:195], v[34:37]
	v_mfma_f32_16x16x32_bf16 v[18:21], v[176:179], v[200:203], v[18:21]
	v_mfma_f32_16x16x32_bf16 v[2:5], v[176:179], v[208:211], v[2:5]
	v_mfma_f32_16x16x32_bf16 v[58:61], v[172:175], v[188:191], v[58:61]
	v_mfma_f32_16x16x32_bf16 v[42:45], v[172:175], v[196:199], v[42:45]
	v_mfma_f32_16x16x32_bf16 v[26:29], v[172:175], v[204:207], v[26:29]
	v_mfma_f32_16x16x32_bf16 v[10:13], v[172:175], v[212:215], v[10:13]
	v_mfma_f32_16x16x32_bf16 v[50:53], v[180:183], v[188:191], v[50:53]
	v_mfma_f32_16x16x32_bf16 v[34:37], v[180:183], v[196:199], v[34:37]
	v_mfma_f32_16x16x32_bf16 v[18:21], v[180:183], v[204:207], v[18:21]
	v_mfma_f32_16x16x32_bf16 v[2:5], v[180:183], v[212:215], v[2:5]
	s_setprio 0
	s_barrier
	s_add_i32 s69, s69, 2
	s_add_u32 s44, s44, 0x100
	s_addc_u32 s45, s45, 0
	s_add_u32 s61, s61, 0x100
	s_addc_u32 s68, s68, 0
	s_cmp_gt_u32 s69, 29
	s_cbranch_scc0 .LBB0_3309
	s_and_b64 vcc, exec, s[24:25]
	s_cbranch_vccz .LBB0_3312
	s_barrier

.LBB0_3533:
	ds_read_b128 v[154:157], v151
	ds_read_b128 v[158:161], v151 offset:1024
	ds_read_b128 v[162:165], v151 offset:2048
	ds_read_b128 v[166:169], v151 offset:3072
	ds_read_b128 v[170:173], v152
	ds_read_b128 v[174:177], v152 offset:1024
	ds_read_b128 v[178:181], v152 offset:2048
	ds_read_b128 v[182:185], v152 offset:3072
	s_add_u32 s34, s44, 0xfff80080
	s_addc_u32 s35, s45, -1
	s_cmp_eq_u32 s68, 28
	s_cselect_b32 s47, s0, s35
	s_cselect_b32 s46, s1, s34
	s_cselect_b32 s35, s27, s61
	s_cselect_b32 s34, s37, s60
	v_lshl_add_u64 v[146:147], s[44:45], 0, v[138:139]
	s_add_i32 m0, s33, 0xc000
	ds_read_b128 v[186:189], v153
	ds_read_b128 v[190:193], v153 offset:1024
	ds_read_b128 v[194:197], v153 offset:2048
	ds_read_b128 v[198:201], v153 offset:3072
	ds_read_b128 v[202:205], v153 offset:4096
	ds_read_b128 v[206:209], v153 offset:5120
	ds_read_b128 v[210:213], v153 offset:6144
	ds_read_b128 v[218:221], v153 offset:7168
	global_load_lds_dwordx4 v[146:147], off
	v_lshl_add_u64 v[146:147], s[44:45], 0, v[140:141]
	s_add_i32 m0, s33, 0xe000
	s_nop 0
	global_load_lds_dwordx4 v[146:147], off
	s_waitcnt vmcnt(8)
	s_waitcnt lgkmcnt(0)
	s_barrier
	s_setprio 1
	s_waitcnt lgkmcnt(0)
	v_mfma_f32_16x16x32_bf16 v[126:129], v[154:157], v[186:189], v[126:129]
	v_mfma_f32_16x16x32_bf16 v[114:117], v[154:157], v[194:197], v[114:117]
	v_mfma_f32_16x16x32_bf16 v[98:101], v[154:157], v[202:205], v[98:101]
	v_mfma_f32_16x16x32_bf16 v[82:85], v[154:157], v[210:213], v[82:85]
	v_mfma_f32_16x16x32_bf16 v[122:125], v[162:165], v[186:189], v[122:125]
	v_mfma_f32_16x16x32_bf16 v[106:109], v[162:165], v[194:197], v[106:109]
	v_mfma_f32_16x16x32_bf16 v[90:93], v[162:165], v[202:205], v[90:93]
	v_mfma_f32_16x16x32_bf16 v[74:77], v[162:165], v[210:213], v[74:77]
	v_mfma_f32_16x16x32_bf16 v[126:129], v[158:161], v[190:193], v[126:129]
	v_mfma_f32_16x16x32_bf16 v[114:117], v[158:161], v[198:201], v[114:117]
	v_mfma_f32_16x16x32_bf16 v[98:101], v[158:161], v[206:209], v[98:101]
	v_mfma_f32_16x16x32_bf16 v[82:85], v[158:161], v[218:221], v[82:85]
	v_mfma_f32_16x16x32_bf16 v[122:125], v[166:169], v[190:193], v[122:125]
	v_mfma_f32_16x16x32_bf16 v[106:109], v[166:169], v[198:201], v[106:109]
	v_mfma_f32_16x16x32_bf16 v[90:93], v[166:169], v[206:209], v[90:93]
	v_mfma_f32_16x16x32_bf16 v[74:77], v[166:169], v[218:221], v[74:77]
	s_setprio 0
	s_setprio 1
	v_mfma_f32_16x16x32_bf16 v[118:121], v[170:173], v[186:189], v[118:121]
	v_mfma_f32_16x16x32_bf16 v[102:105], v[170:173], v[194:197], v[102:105]
	v_mfma_f32_16x16x32_bf16 v[86:89], v[170:173], v[202:205], v[86:89]
	v_mfma_f32_16x16x32_bf16 v[70:73], v[170:173], v[210:213], v[70:73]
	v_mfma_f32_16x16x32_bf16 v[110:113], v[178:181], v[186:189], v[110:113]
	v_mfma_f32_16x16x32_bf16 v[94:97], v[178:181], v[194:197], v[94:97]
	v_mfma_f32_16x16x32_bf16 v[78:81], v[178:181], v[202:205], v[78:81]
	v_mfma_f32_16x16x32_bf16 v[66:69], v[178:181], v[210:213], v[66:69]
	v_mfma_f32_16x16x32_bf16 v[118:121], v[174:177], v[190:193], v[118:121]
	v_mfma_f32_16x16x32_bf16 v[102:105], v[174:177], v[198:201], v[102:105]
	v_mfma_f32_16x16x32_bf16 v[86:89], v[174:177], v[206:209], v[86:89]
	v_mfma_f32_16x16x32_bf16 v[70:73], v[174:177], v[218:221], v[70:73]
	v_mfma_f32_16x16x32_bf16 v[110:113], v[182:185], v[190:193], v[110:113]
	v_mfma_f32_16x16x32_bf16 v[94:97], v[182:185], v[198:201], v[94:97]
	v_mfma_f32_16x16x32_bf16 v[78:81], v[182:185], v[206:209], v[78:81]
	v_mfma_f32_16x16x32_bf16 v[66:69], v[182:185], v[218:221], v[66:69]
	s_setprio 0
	s_barrier
	s_add_i32 s62, s56, s12
	v_lshl_add_u64 v[146:147], s[34:35], 0, v[134:135]
	s_mov_b32 m0, s62
	ds_read_b128 v[186:189], v153 offset:16384
	ds_read_b128 v[190:193], v153 offset:17408
	ds_read_b128 v[194:197], v153 offset:18432
	ds_read_b128 v[198:201], v153 offset:19456
	ds_read_b128 v[202:205], v153 offset:20480
	ds_read_b128 v[206:209], v153 offset:21504
	ds_read_b128 v[210:213], v153 offset:22528
	ds_read_b128 v[218:221], v153 offset:23552
	global_load_lds_dwordx4 v[146:147], off
	s_add_i32 m0, s62, 0x2000
	s_add_u32 s62, s34, 0x80000
	v_lshl_add_u64 v[214:215], s[34:35], 0, v[130:131]
	s_addc_u32 s63, s35, 0
	s_add_i32 s66, s57, s12
	global_load_lds_dwordx4 v[214:215], off
	v_lshl_add_u64 v[222:223], s[62:63], 0, v[134:135]
	s_mov_b32 m0, s66
	v_lshl_add_u64 v[224:225], s[46:47], 0, v[132:133]
	global_load_lds_dwordx4 v[222:223], off
	v_lshl_add_u64 v[222:223], s[62:63], 0, v[130:131]
	s_add_i32 m0, s66, 0x2000
	s_nop 0
	global_load_lds_dwordx4 v[222:223], off
	v_lshl_add_u64 v[222:223], s[46:47], 0, v[136:137]
	s_mov_b32 m0, s33
	s_nop 0
	global_load_lds_dwordx4 v[222:223], off
	s_mov_b32 m0, s43
	s_nop 0
	global_load_lds_dwordx4 v[224:225], off
	s_waitcnt vmcnt(8)
	s_waitcnt lgkmcnt(0)
	s_barrier
	s_setprio 1
	s_waitcnt lgkmcnt(0)
	v_mfma_f32_16x16x32_bf16 v[62:65], v[154:157], v[186:189], v[62:65]
	v_mfma_f32_16x16x32_bf16 v[50:53], v[154:157], v[194:197], v[50:53]
	v_mfma_f32_16x16x32_bf16 v[34:37], v[154:157], v[202:205], v[34:37]
	v_mfma_f32_16x16x32_bf16 v[18:21], v[154:157], v[210:213], v[18:21]
	v_mfma_f32_16x16x32_bf16 v[58:61], v[162:165], v[186:189], v[58:61]
	v_mfma_f32_16x16x32_bf16 v[42:45], v[162:165], v[194:197], v[42:45]
	v_mfma_f32_16x16x32_bf16 v[26:29], v[162:165], v[202:205], v[26:29]
	v_mfma_f32_16x16x32_bf16 v[10:13], v[162:165], v[210:213], v[10:13]
	v_mfma_f32_16x16x32_bf16 v[62:65], v[158:161], v[190:193], v[62:65]
	v_mfma_f32_16x16x32_bf16 v[50:53], v[158:161], v[198:201], v[50:53]
	v_mfma_f32_16x16x32_bf16 v[34:37], v[158:161], v[206:209], v[34:37]
	v_mfma_f32_16x16x32_bf16 v[18:21], v[158:161], v[218:221], v[18:21]
	v_mfma_f32_16x16x32_bf16 v[58:61], v[166:169], v[190:193], v[58:61]
	v_mfma_f32_16x16x32_bf16 v[42:45], v[166:169], v[198:201], v[42:45]
	v_mfma_f32_16x16x32_bf16 v[26:29], v[166:169], v[206:209], v[26:29]
	v_mfma_f32_16x16x32_bf16 v[10:13], v[166:169], v[218:221], v[10:13]
	s_setprio 0
	s_setprio 1
	v_mfma_f32_16x16x32_bf16 v[54:57], v[170:173], v[186:189], v[54:57]
	v_mfma_f32_16x16x32_bf16 v[38:41], v[170:173], v[194:197], v[38:41]
	v_mfma_f32_16x16x32_bf16 v[22:25], v[170:173], v[202:205], v[22:25]
	v_mfma_f32_16x16x32_bf16 v[6:9], v[170:173], v[210:213], v[6:9]
	v_mfma_f32_16x16x32_bf16 v[46:49], v[178:181], v[186:189], v[46:49]
	v_mfma_f32_16x16x32_bf16 v[30:33], v[178:181], v[194:197], v[30:33]
	v_mfma_f32_16x16x32_bf16 v[14:17], v[178:181], v[202:205], v[14:17]
	v_mfma_f32_16x16x32_bf16 v[2:5], v[178:181], v[210:213], v[2:5]
	v_mfma_f32_16x16x32_bf16 v[54:57], v[174:177], v[190:193], v[54:57]
	v_mfma_f32_16x16x32_bf16 v[38:41], v[174:177], v[198:201], v[38:41]
	v_mfma_f32_16x16x32_bf16 v[22:25], v[174:177], v[206:209], v[22:25]
	v_mfma_f32_16x16x32_bf16 v[6:9], v[174:177], v[218:221], v[6:9]
	v_mfma_f32_16x16x32_bf16 v[46:49], v[182:185], v[190:193], v[46:49]
	v_mfma_f32_16x16x32_bf16 v[30:33], v[182:185], v[198:201], v[30:33]
	v_mfma_f32_16x16x32_bf16 v[14:17], v[182:185], v[206:209], v[14:17]
	v_mfma_f32_16x16x32_bf16 v[2:5], v[182:185], v[218:221], v[2:5]
	s_setprio 0
	s_barrier
	s_add_i32 s62, 0, 0x18000
	s_add_i32 s63, 0, 0x1c000
	v_add_u32_e32 v166, s62, v149
	v_add_u32_e32 v182, s63, v149
	ds_read_b128 v[154:157], v166
	ds_read_b128 v[158:161], v166 offset:1024
	ds_read_b128 v[162:165], v166 offset:2048
	ds_read_b128 v[166:169], v166 offset:3072
	ds_read_b128 v[170:173], v182
	ds_read_b128 v[174:177], v182 offset:1024
	ds_read_b128 v[178:181], v182 offset:2048
	ds_read_b128 v[182:185], v182 offset:3072
	s_add_u32 s46, s46, 0x80000
	s_addc_u32 s47, s47, 0
	s_mov_b32 m0, s48
	v_lshl_add_u64 v[226:227], s[46:47], 0, v[136:137]
	ds_read_b128 v[186:189], v153 offset:32768
	ds_read_b128 v[190:193], v153 offset:33792
	ds_read_b128 v[194:197], v153 offset:34816
	ds_read_b128 v[198:201], v153 offset:35840
	ds_read_b128 v[202:205], v153 offset:36864
	ds_read_b128 v[206:209], v153 offset:37888
	ds_read_b128 v[210:213], v153 offset:38912
	ds_read_b128 v[218:221], v153 offset:39936
	global_load_lds_dwordx4 v[226:227], off
	v_lshl_add_u64 v[226:227], s[46:47], 0, v[132:133]
	s_mov_b32 m0, s49
	s_nop 0
	global_load_lds_dwordx4 v[226:227], off
	s_waitcnt vmcnt(8)
	s_waitcnt lgkmcnt(0)
	s_barrier
	s_setprio 1
	s_waitcnt lgkmcnt(0)
	v_mfma_f32_16x16x32_bf16 v[126:129], v[154:157], v[186:189], v[126:129]
	v_mfma_f32_16x16x32_bf16 v[114:117], v[154:157], v[194:197], v[114:117]
	v_mfma_f32_16x16x32_bf16 v[98:101], v[154:157], v[202:205], v[98:101]
	v_mfma_f32_16x16x32_bf16 v[82:85], v[154:157], v[210:213], v[82:85]
	v_mfma_f32_16x16x32_bf16 v[122:125], v[162:165], v[186:189], v[122:125]
	v_mfma_f32_16x16x32_bf16 v[106:109], v[162:165], v[194:197], v[106:109]
	v_mfma_f32_16x16x32_bf16 v[90:93], v[162:165], v[202:205], v[90:93]
	v_mfma_f32_16x16x32_bf16 v[74:77], v[162:165], v[210:213], v[74:77]
	v_mfma_f32_16x16x32_bf16 v[126:129], v[158:161], v[190:193], v[126:129]
	v_mfma_f32_16x16x32_bf16 v[114:117], v[158:161], v[198:201], v[114:117]
	v_mfma_f32_16x16x32_bf16 v[98:101], v[158:161], v[206:209], v[98:101]
	v_mfma_f32_16x16x32_bf16 v[82:85], v[158:161], v[218:221], v[82:85]
	v_mfma_f32_16x16x32_bf16 v[122:125], v[166:169], v[190:193], v[122:125]
	v_mfma_f32_16x16x32_bf16 v[106:109], v[166:169], v[198:201], v[106:109]
	v_mfma_f32_16x16x32_bf16 v[90:93], v[166:169], v[206:209], v[90:93]
	v_mfma_f32_16x16x32_bf16 v[74:77], v[166:169], v[218:221], v[74:77]
	s_setprio 0
	s_setprio 1
	v_mfma_f32_16x16x32_bf16 v[118:121], v[170:173], v[186:189], v[118:121]
	v_mfma_f32_16x16x32_bf16 v[102:105], v[170:173], v[194:197], v[102:105]
	v_mfma_f32_16x16x32_bf16 v[86:89], v[170:173], v[202:205], v[86:89]
	v_mfma_f32_16x16x32_bf16 v[70:73], v[170:173], v[210:213], v[70:73]
	v_mfma_f32_16x16x32_bf16 v[110:113], v[178:181], v[186:189], v[110:113]
	v_mfma_f32_16x16x32_bf16 v[94:97], v[178:181], v[194:197], v[94:97]
	v_mfma_f32_16x16x32_bf16 v[78:81], v[178:181], v[202:205], v[78:81]
	v_mfma_f32_16x16x32_bf16 v[66:69], v[178:181], v[210:213], v[66:69]
	v_mfma_f32_16x16x32_bf16 v[118:121], v[174:177], v[190:193], v[118:121]
	v_mfma_f32_16x16x32_bf16 v[102:105], v[174:177], v[198:201], v[102:105]
	v_mfma_f32_16x16x32_bf16 v[86:89], v[174:177], v[206:209], v[86:89]
	v_mfma_f32_16x16x32_bf16 v[70:73], v[174:177], v[218:221], v[70:73]
	v_mfma_f32_16x16x32_bf16 v[110:113], v[182:185], v[190:193], v[110:113]
	v_mfma_f32_16x16x32_bf16 v[94:97], v[182:185], v[198:201], v[94:97]
	v_mfma_f32_16x16x32_bf16 v[78:81], v[182:185], v[206:209], v[78:81]
	v_mfma_f32_16x16x32_bf16 v[66:69], v[182:185], v[218:221], v[66:69]
	s_setprio 0
	s_barrier
	s_add_i32 s46, s62, s12
	v_lshl_add_u64 v[146:147], v[146:147], 0, s[8:9]
	s_mov_b32 m0, s46
	ds_read_b128 v[186:189], v153 offset:49152
	ds_read_b128 v[190:193], v153 offset:50176
	ds_read_b128 v[194:197], v153 offset:51200
	ds_read_b128 v[198:201], v153 offset:52224
	ds_read_b128 v[202:205], v153 offset:53248
	ds_read_b128 v[206:209], v153 offset:54272
	ds_read_b128 v[210:213], v153 offset:55296
	ds_read_b128 v[218:221], v153 offset:56320
	global_load_lds_dwordx4 v[146:147], off
	s_add_i32 m0, s46, 0x2000
	s_add_u32 s34, s34, 0x80080
	v_lshl_add_u64 v[146:147], v[214:215], 0, s[8:9]
	s_addc_u32 s35, s35, 0
	s_add_i32 s46, s63, s12
	global_load_lds_dwordx4 v[146:147], off
	v_lshl_add_u64 v[146:147], s[34:35], 0, v[134:135]
	s_mov_b32 m0, s46
	s_nop 0
	global_load_lds_dwordx4 v[146:147], off
	v_lshl_add_u64 v[146:147], s[34:35], 0, v[130:131]
	s_add_i32 m0, s46, 0x2000
	s_nop 0
	global_load_lds_dwordx4 v[146:147], off
	v_lshl_add_u64 v[146:147], v[222:223], 0, s[8:9]
	s_mov_b32 m0, s53
	s_nop 0
	global_load_lds_dwordx4 v[146:147], off
	v_lshl_add_u64 v[146:147], v[224:225], 0, s[8:9]
	s_mov_b32 m0, s54
	s_nop 0
	global_load_lds_dwordx4 v[146:147], off
	s_waitcnt vmcnt(8)
	s_waitcnt lgkmcnt(0)
	s_barrier
	s_setprio 1
	s_waitcnt lgkmcnt(0)
	v_mfma_f32_16x16x32_bf16 v[62:65], v[154:157], v[186:189], v[62:65]
	v_mfma_f32_16x16x32_bf16 v[50:53], v[154:157], v[194:197], v[50:53]
	v_mfma_f32_16x16x32_bf16 v[34:37], v[154:157], v[202:205], v[34:37]
	v_mfma_f32_16x16x32_bf16 v[18:21], v[154:157], v[210:213], v[18:21]
	v_mfma_f32_16x16x32_bf16 v[58:61], v[162:165], v[186:189], v[58:61]
	v_mfma_f32_16x16x32_bf16 v[42:45], v[162:165], v[194:197], v[42:45]
	v_mfma_f32_16x16x32_bf16 v[26:29], v[162:165], v[202:205], v[26:29]
	v_mfma_f32_16x16x32_bf16 v[10:13], v[162:165], v[210:213], v[10:13]
	v_mfma_f32_16x16x32_bf16 v[62:65], v[158:161], v[190:193], v[62:65]
	v_mfma_f32_16x16x32_bf16 v[50:53], v[158:161], v[198:201], v[50:53]
	v_mfma_f32_16x16x32_bf16 v[34:37], v[158:161], v[206:209], v[34:37]
	v_mfma_f32_16x16x32_bf16 v[18:21], v[158:161], v[218:221], v[18:21]
	v_mfma_f32_16x16x32_bf16 v[58:61], v[166:169], v[190:193], v[58:61]
	v_mfma_f32_16x16x32_bf16 v[42:45], v[166:169], v[198:201], v[42:45]
	v_mfma_f32_16x16x32_bf16 v[26:29], v[166:169], v[206:209], v[26:29]
	v_mfma_f32_16x16x32_bf16 v[10:13], v[166:169], v[218:221], v[10:13]
	s_setprio 0
	s_setprio 1
	v_mfma_f32_16x16x32_bf16 v[54:57], v[170:173], v[186:189], v[54:57]
	v_mfma_f32_16x16x32_bf16 v[38:41], v[170:173], v[194:197], v[38:41]
	v_mfma_f32_16x16x32_bf16 v[22:25], v[170:173], v[202:205], v[22:25]
	v_mfma_f32_16x16x32_bf16 v[6:9], v[170:173], v[210:213], v[6:9]
	v_mfma_f32_16x16x32_bf16 v[46:49], v[178:181], v[186:189], v[46:49]
	v_mfma_f32_16x16x32_bf16 v[30:33], v[178:181], v[194:197], v[30:33]
	v_mfma_f32_16x16x32_bf16 v[14:17], v[178:181], v[202:205], v[14:17]
	v_mfma_f32_16x16x32_bf16 v[2:5], v[178:181], v[210:213], v[2:5]
	v_mfma_f32_16x16x32_bf16 v[54:57], v[174:177], v[190:193], v[54:57]
	v_mfma_f32_16x16x32_bf16 v[38:41], v[174:177], v[198:201], v[38:41]
	v_mfma_f32_16x16x32_bf16 v[22:25], v[174:177], v[206:209], v[22:25]
	v_mfma_f32_16x16x32_bf16 v[6:9], v[174:177], v[218:221], v[6:9]
	v_mfma_f32_16x16x32_bf16 v[46:49], v[182:185], v[190:193], v[46:49]
	v_mfma_f32_16x16x32_bf16 v[30:33], v[182:185], v[198:201], v[30:33]
	v_mfma_f32_16x16x32_bf16 v[14:17], v[182:185], v[206:209], v[14:17]
	v_mfma_f32_16x16x32_bf16 v[2:5], v[182:185], v[218:221], v[2:5]
	s_setprio 0
	s_barrier
	s_add_i32 s68, s68, 2
	s_add_u32 s44, s44, 0x100
	s_addc_u32 s45, s45, 0
	s_add_u32 s60, s60, 0x100
	s_addc_u32 s61, s61, 0
	s_cmp_gt_u32 s68, 29
	s_cbranch_scc0 .LBB0_3533
	s_and_b64 vcc, exec, s[24:25]
	s_cbranch_vccz .LBB0_3536
	s_barrier

.LBB0_3706:
	ds_read_b128 v[130:133], v174
	ds_read_b128 v[134:137], v174 offset:1024
	ds_read_b128 v[138:141], v174 offset:2048
	ds_read_b128 v[158:161], v174 offset:3072
	ds_read_b128 v[162:165], v175
	ds_read_b128 v[166:169], v175 offset:1024
	ds_read_b128 v[178:181], v175 offset:2048
	ds_read_b128 v[182:185], v175 offset:3072
	s_add_u32 s34, s42, 0xfff80080
	s_addc_u32 s35, s43, -1
	s_cmp_eq_u32 s60, 28
	s_cselect_b32 s45, s0, s35
	s_cselect_b32 s44, s1, s34
	s_cselect_b32 s35, s25, s59
	s_cselect_b32 s34, s27, s58
	v_lshl_add_u64 v[170:171], s[42:43], 0, v[150:151]
	s_add_i32 m0, s41, 0xc000
	ds_read_b128 v[186:189], v176
	ds_read_b128 v[190:193], v176 offset:1024
	ds_read_b128 v[194:197], v176 offset:2048
	ds_read_b128 v[198:201], v176 offset:3072
	ds_read_b128 v[202:205], v176 offset:4096
	ds_read_b128 v[206:209], v176 offset:5120
	ds_read_b128 v[210:213], v176 offset:6144
	ds_read_b128 v[218:221], v176 offset:7168
	global_load_lds_dwordx4 v[170:171], off
	v_lshl_add_u64 v[170:171], s[42:43], 0, v[152:153]
	s_add_i32 m0, s41, 0xe000
	s_nop 0
	global_load_lds_dwordx4 v[170:171], off
	s_waitcnt vmcnt(8)
	s_waitcnt lgkmcnt(0)
	s_barrier
	s_setprio 1
	s_waitcnt lgkmcnt(0)
	v_mfma_f32_16x16x32_bf16 v[126:129], v[130:133], v[186:189], v[126:129]
	v_mfma_f32_16x16x32_bf16 v[110:113], v[130:133], v[194:197], v[110:113]
	v_mfma_f32_16x16x32_bf16 v[94:97], v[130:133], v[202:205], v[94:97]
	v_mfma_f32_16x16x32_bf16 v[78:81], v[130:133], v[210:213], v[78:81]
	v_mfma_f32_16x16x32_bf16 v[122:125], v[138:141], v[186:189], v[122:125]
	v_mfma_f32_16x16x32_bf16 v[106:109], v[138:141], v[194:197], v[106:109]
	v_mfma_f32_16x16x32_bf16 v[90:93], v[138:141], v[202:205], v[90:93]
	v_mfma_f32_16x16x32_bf16 v[74:77], v[138:141], v[210:213], v[74:77]
	v_mfma_f32_16x16x32_bf16 v[126:129], v[134:137], v[190:193], v[126:129]
	v_mfma_f32_16x16x32_bf16 v[110:113], v[134:137], v[198:201], v[110:113]
	v_mfma_f32_16x16x32_bf16 v[94:97], v[134:137], v[206:209], v[94:97]
	v_mfma_f32_16x16x32_bf16 v[78:81], v[134:137], v[218:221], v[78:81]
	v_mfma_f32_16x16x32_bf16 v[122:125], v[158:161], v[190:193], v[122:125]
	v_mfma_f32_16x16x32_bf16 v[106:109], v[158:161], v[198:201], v[106:109]
	v_mfma_f32_16x16x32_bf16 v[90:93], v[158:161], v[206:209], v[90:93]
	v_mfma_f32_16x16x32_bf16 v[74:77], v[158:161], v[218:221], v[74:77]
	s_setprio 0
	s_setprio 1
	v_mfma_f32_16x16x32_bf16 v[118:121], v[162:165], v[186:189], v[118:121]
	v_mfma_f32_16x16x32_bf16 v[102:105], v[162:165], v[194:197], v[102:105]
	v_mfma_f32_16x16x32_bf16 v[86:89], v[162:165], v[202:205], v[86:89]
	v_mfma_f32_16x16x32_bf16 v[70:73], v[162:165], v[210:213], v[70:73]
	v_mfma_f32_16x16x32_bf16 v[114:117], v[178:181], v[186:189], v[114:117]
	v_mfma_f32_16x16x32_bf16 v[98:101], v[178:181], v[194:197], v[98:101]
	v_mfma_f32_16x16x32_bf16 v[82:85], v[178:181], v[202:205], v[82:85]
	v_mfma_f32_16x16x32_bf16 v[66:69], v[178:181], v[210:213], v[66:69]
	v_mfma_f32_16x16x32_bf16 v[118:121], v[166:169], v[190:193], v[118:121]
	v_mfma_f32_16x16x32_bf16 v[102:105], v[166:169], v[198:201], v[102:105]
	v_mfma_f32_16x16x32_bf16 v[86:89], v[166:169], v[206:209], v[86:89]
	v_mfma_f32_16x16x32_bf16 v[70:73], v[166:169], v[218:221], v[70:73]
	v_mfma_f32_16x16x32_bf16 v[114:117], v[182:185], v[190:193], v[114:117]
	v_mfma_f32_16x16x32_bf16 v[98:101], v[182:185], v[198:201], v[98:101]
	v_mfma_f32_16x16x32_bf16 v[82:85], v[182:185], v[206:209], v[82:85]
	v_mfma_f32_16x16x32_bf16 v[66:69], v[182:185], v[218:221], v[66:69]
	s_setprio 0
	s_barrier
	s_add_i32 s61, s54, s46
	v_lshl_add_u64 v[170:171], s[34:35], 0, v[144:145]
	s_mov_b32 m0, s61
	ds_read_b128 v[186:189], v176 offset:16384
	ds_read_b128 v[190:193], v176 offset:17408
	ds_read_b128 v[194:197], v176 offset:18432
	ds_read_b128 v[198:201], v176 offset:19456
	ds_read_b128 v[202:205], v176 offset:20480
	ds_read_b128 v[206:209], v176 offset:21504
	ds_read_b128 v[210:213], v176 offset:22528
	ds_read_b128 v[218:221], v176 offset:23552
	global_load_lds_dwordx4 v[170:171], off
	s_add_i32 m0, s61, 0x2000
	s_add_u32 s62, s34, 0x80000
	v_lshl_add_u64 v[214:215], s[34:35], 0, v[148:149]
	s_addc_u32 s63, s35, 0
	s_add_i32 s61, s55, s46
	global_load_lds_dwordx4 v[214:215], off
	v_lshl_add_u64 v[222:223], s[62:63], 0, v[144:145]
	s_mov_b32 m0, s61
	v_lshl_add_u64 v[224:225], s[44:45], 0, v[146:147]
	global_load_lds_dwordx4 v[222:223], off
	v_lshl_add_u64 v[222:223], s[62:63], 0, v[148:149]
	s_add_i32 m0, s61, 0x2000
	s_nop 0
	global_load_lds_dwordx4 v[222:223], off
	v_lshl_add_u64 v[222:223], s[44:45], 0, v[142:143]
	s_mov_b32 m0, s41
	s_nop 0
	global_load_lds_dwordx4 v[222:223], off
	s_mov_b32 m0, s47
	s_nop 0
	global_load_lds_dwordx4 v[224:225], off
	s_waitcnt vmcnt(8)
	s_waitcnt lgkmcnt(0)
	s_barrier
	s_setprio 1
	s_waitcnt lgkmcnt(0)
	v_mfma_f32_16x16x32_bf16 v[62:65], v[130:133], v[186:189], v[62:65]
	v_mfma_f32_16x16x32_bf16 v[50:53], v[130:133], v[194:197], v[50:53]
	v_mfma_f32_16x16x32_bf16 v[38:41], v[130:133], v[202:205], v[38:41]
	v_mfma_f32_16x16x32_bf16 v[14:17], v[130:133], v[210:213], v[14:17]
	v_mfma_f32_16x16x32_bf16 v[58:61], v[138:141], v[186:189], v[58:61]
	v_mfma_f32_16x16x32_bf16 v[42:45], v[138:141], v[194:197], v[42:45]
	v_mfma_f32_16x16x32_bf16 v[34:37], v[138:141], v[202:205], v[34:37]
	v_mfma_f32_16x16x32_bf16 v[10:13], v[138:141], v[210:213], v[10:13]
	v_mfma_f32_16x16x32_bf16 v[62:65], v[134:137], v[190:193], v[62:65]
	v_mfma_f32_16x16x32_bf16 v[50:53], v[134:137], v[198:201], v[50:53]
	v_mfma_f32_16x16x32_bf16 v[38:41], v[134:137], v[206:209], v[38:41]
	v_mfma_f32_16x16x32_bf16 v[14:17], v[134:137], v[218:221], v[14:17]
	v_mfma_f32_16x16x32_bf16 v[58:61], v[158:161], v[190:193], v[58:61]
	v_mfma_f32_16x16x32_bf16 v[42:45], v[158:161], v[198:201], v[42:45]
	v_mfma_f32_16x16x32_bf16 v[34:37], v[158:161], v[206:209], v[34:37]
	v_mfma_f32_16x16x32_bf16 v[10:13], v[158:161], v[218:221], v[10:13]
	s_setprio 0
	s_setprio 1
	v_mfma_f32_16x16x32_bf16 v[54:57], v[162:165], v[186:189], v[54:57]
	v_mfma_f32_16x16x32_bf16 v[30:33], v[162:165], v[194:197], v[30:33]
	v_mfma_f32_16x16x32_bf16 v[22:25], v[162:165], v[202:205], v[22:25]
	v_mfma_f32_16x16x32_bf16 v[6:9], v[162:165], v[210:213], v[6:9]
	v_mfma_f32_16x16x32_bf16 v[46:49], v[178:181], v[186:189], v[46:49]
	v_mfma_f32_16x16x32_bf16 v[26:29], v[178:181], v[194:197], v[26:29]
	v_mfma_f32_16x16x32_bf16 v[18:21], v[178:181], v[202:205], v[18:21]
	v_mfma_f32_16x16x32_bf16 v[2:5], v[178:181], v[210:213], v[2:5]
	v_mfma_f32_16x16x32_bf16 v[54:57], v[166:169], v[190:193], v[54:57]
	v_mfma_f32_16x16x32_bf16 v[30:33], v[166:169], v[198:201], v[30:33]
	v_mfma_f32_16x16x32_bf16 v[22:25], v[166:169], v[206:209], v[22:25]
	v_mfma_f32_16x16x32_bf16 v[6:9], v[166:169], v[218:221], v[6:9]
	v_mfma_f32_16x16x32_bf16 v[46:49], v[182:185], v[190:193], v[46:49]
	v_mfma_f32_16x16x32_bf16 v[26:29], v[182:185], v[198:201], v[26:29]
	v_mfma_f32_16x16x32_bf16 v[18:21], v[182:185], v[206:209], v[18:21]
	v_mfma_f32_16x16x32_bf16 v[2:5], v[182:185], v[218:221], v[2:5]
	s_setprio 0
	s_barrier
	s_add_i32 s61, 0, 0x18000
	s_add_i32 s62, 0, 0x1c000
	v_add_u32_e32 v158, s61, v172
	v_add_u32_e32 v177, s62, v172
	ds_read_b128 v[130:133], v158
	ds_read_b128 v[134:137], v158 offset:1024
	ds_read_b128 v[138:141], v158 offset:2048
	ds_read_b128 v[158:161], v158 offset:3072
	ds_read_b128 v[162:165], v177
	ds_read_b128 v[166:169], v177 offset:1024
	ds_read_b128 v[178:181], v177 offset:2048
	ds_read_b128 v[182:185], v177 offset:3072
	s_add_u32 s44, s44, 0x80000
	s_addc_u32 s45, s45, 0
	s_mov_b32 m0, s48
	v_lshl_add_u64 v[226:227], s[44:45], 0, v[142:143]
	ds_read_b128 v[186:189], v176 offset:32768
	ds_read_b128 v[190:193], v176 offset:33792
	ds_read_b128 v[194:197], v176 offset:34816
	ds_read_b128 v[198:201], v176 offset:35840
	ds_read_b128 v[202:205], v176 offset:36864
	ds_read_b128 v[206:209], v176 offset:37888
	ds_read_b128 v[210:213], v176 offset:38912
	ds_read_b128 v[218:221], v176 offset:39936
	global_load_lds_dwordx4 v[226:227], off
	v_lshl_add_u64 v[226:227], s[44:45], 0, v[146:147]
	s_mov_b32 m0, s49
	s_nop 0
	global_load_lds_dwordx4 v[226:227], off
	s_waitcnt vmcnt(8)
	s_waitcnt lgkmcnt(0)
	s_barrier
	s_setprio 1
	s_waitcnt lgkmcnt(0)
	v_mfma_f32_16x16x32_bf16 v[126:129], v[130:133], v[186:189], v[126:129]
	v_mfma_f32_16x16x32_bf16 v[110:113], v[130:133], v[194:197], v[110:113]
	v_mfma_f32_16x16x32_bf16 v[94:97], v[130:133], v[202:205], v[94:97]
	v_mfma_f32_16x16x32_bf16 v[78:81], v[130:133], v[210:213], v[78:81]
	v_mfma_f32_16x16x32_bf16 v[122:125], v[138:141], v[186:189], v[122:125]
	v_mfma_f32_16x16x32_bf16 v[106:109], v[138:141], v[194:197], v[106:109]
	v_mfma_f32_16x16x32_bf16 v[90:93], v[138:141], v[202:205], v[90:93]
	v_mfma_f32_16x16x32_bf16 v[74:77], v[138:141], v[210:213], v[74:77]
	v_mfma_f32_16x16x32_bf16 v[126:129], v[134:137], v[190:193], v[126:129]
	v_mfma_f32_16x16x32_bf16 v[110:113], v[134:137], v[198:201], v[110:113]
	v_mfma_f32_16x16x32_bf16 v[94:97], v[134:137], v[206:209], v[94:97]
	v_mfma_f32_16x16x32_bf16 v[78:81], v[134:137], v[218:221], v[78:81]
	v_mfma_f32_16x16x32_bf16 v[122:125], v[158:161], v[190:193], v[122:125]
	v_mfma_f32_16x16x32_bf16 v[106:109], v[158:161], v[198:201], v[106:109]
	v_mfma_f32_16x16x32_bf16 v[90:93], v[158:161], v[206:209], v[90:93]
	v_mfma_f32_16x16x32_bf16 v[74:77], v[158:161], v[218:221], v[74:77]
	s_setprio 0
	s_setprio 1
	v_mfma_f32_16x16x32_bf16 v[118:121], v[162:165], v[186:189], v[118:121]
	v_mfma_f32_16x16x32_bf16 v[102:105], v[162:165], v[194:197], v[102:105]
	v_mfma_f32_16x16x32_bf16 v[86:89], v[162:165], v[202:205], v[86:89]
	v_mfma_f32_16x16x32_bf16 v[70:73], v[162:165], v[210:213], v[70:73]
	v_mfma_f32_16x16x32_bf16 v[114:117], v[178:181], v[186:189], v[114:117]
	v_mfma_f32_16x16x32_bf16 v[98:101], v[178:181], v[194:197], v[98:101]
	v_mfma_f32_16x16x32_bf16 v[82:85], v[178:181], v[202:205], v[82:85]
	v_mfma_f32_16x16x32_bf16 v[66:69], v[178:181], v[210:213], v[66:69]
	v_mfma_f32_16x16x32_bf16 v[118:121], v[166:169], v[190:193], v[118:121]
	v_mfma_f32_16x16x32_bf16 v[102:105], v[166:169], v[198:201], v[102:105]
	v_mfma_f32_16x16x32_bf16 v[86:89], v[166:169], v[206:209], v[86:89]
	v_mfma_f32_16x16x32_bf16 v[70:73], v[166:169], v[218:221], v[70:73]
	v_mfma_f32_16x16x32_bf16 v[114:117], v[182:185], v[190:193], v[114:117]
	v_mfma_f32_16x16x32_bf16 v[98:101], v[182:185], v[198:201], v[98:101]
	v_mfma_f32_16x16x32_bf16 v[82:85], v[182:185], v[206:209], v[82:85]
	v_mfma_f32_16x16x32_bf16 v[66:69], v[182:185], v[218:221], v[66:69]
	s_setprio 0
	s_barrier
	s_add_i32 s44, s61, s46
	v_lshl_add_u64 v[170:171], v[170:171], 0, s[12:13]
	s_mov_b32 m0, s44
	ds_read_b128 v[186:189], v176 offset:49152
	ds_read_b128 v[190:193], v176 offset:50176
	ds_read_b128 v[194:197], v176 offset:51200
	ds_read_b128 v[198:201], v176 offset:52224
	ds_read_b128 v[202:205], v176 offset:53248
	ds_read_b128 v[206:209], v176 offset:54272
	ds_read_b128 v[210:213], v176 offset:55296
	ds_read_b128 v[218:221], v176 offset:56320
	global_load_lds_dwordx4 v[170:171], off
	s_add_i32 m0, s44, 0x2000
	s_add_u32 s34, s34, 0x80080
	v_lshl_add_u64 v[170:171], v[214:215], 0, s[12:13]
	s_addc_u32 s35, s35, 0
	s_add_i32 s44, s62, s46
	global_load_lds_dwordx4 v[170:171], off
	v_lshl_add_u64 v[170:171], s[34:35], 0, v[144:145]
	s_mov_b32 m0, s44
	s_nop 0
	global_load_lds_dwordx4 v[170:171], off
	v_lshl_add_u64 v[170:171], s[34:35], 0, v[148:149]
	s_add_i32 m0, s44, 0x2000
	s_nop 0
	global_load_lds_dwordx4 v[170:171], off
	v_lshl_add_u64 v[170:171], v[222:223], 0, s[12:13]
	s_mov_b32 m0, s51
	s_nop 0
	global_load_lds_dwordx4 v[170:171], off
	v_lshl_add_u64 v[170:171], v[224:225], 0, s[12:13]
	s_mov_b32 m0, s52
	s_nop 0
	global_load_lds_dwordx4 v[170:171], off
	s_waitcnt vmcnt(8)
	s_waitcnt lgkmcnt(0)
	s_barrier
	s_setprio 1
	s_waitcnt lgkmcnt(0)
	v_mfma_f32_16x16x32_bf16 v[62:65], v[130:133], v[186:189], v[62:65]
	v_mfma_f32_16x16x32_bf16 v[50:53], v[130:133], v[194:197], v[50:53]
	v_mfma_f32_16x16x32_bf16 v[38:41], v[130:133], v[202:205], v[38:41]
	v_mfma_f32_16x16x32_bf16 v[14:17], v[130:133], v[210:213], v[14:17]
	v_mfma_f32_16x16x32_bf16 v[58:61], v[138:141], v[186:189], v[58:61]
	v_mfma_f32_16x16x32_bf16 v[42:45], v[138:141], v[194:197], v[42:45]
	v_mfma_f32_16x16x32_bf16 v[34:37], v[138:141], v[202:205], v[34:37]
	v_mfma_f32_16x16x32_bf16 v[10:13], v[138:141], v[210:213], v[10:13]
	v_mfma_f32_16x16x32_bf16 v[62:65], v[134:137], v[190:193], v[62:65]
	v_mfma_f32_16x16x32_bf16 v[50:53], v[134:137], v[198:201], v[50:53]
	v_mfma_f32_16x16x32_bf16 v[38:41], v[134:137], v[206:209], v[38:41]
	v_mfma_f32_16x16x32_bf16 v[14:17], v[134:137], v[218:221], v[14:17]
	v_mfma_f32_16x16x32_bf16 v[58:61], v[158:161], v[190:193], v[58:61]
	v_mfma_f32_16x16x32_bf16 v[42:45], v[158:161], v[198:201], v[42:45]
	v_mfma_f32_16x16x32_bf16 v[34:37], v[158:161], v[206:209], v[34:37]
	v_mfma_f32_16x16x32_bf16 v[10:13], v[158:161], v[218:221], v[10:13]
	s_setprio 0
	s_setprio 1
	v_mfma_f32_16x16x32_bf16 v[54:57], v[162:165], v[186:189], v[54:57]
	v_mfma_f32_16x16x32_bf16 v[30:33], v[162:165], v[194:197], v[30:33]
	v_mfma_f32_16x16x32_bf16 v[22:25], v[162:165], v[202:205], v[22:25]
	v_mfma_f32_16x16x32_bf16 v[6:9], v[162:165], v[210:213], v[6:9]
	v_mfma_f32_16x16x32_bf16 v[46:49], v[178:181], v[186:189], v[46:49]
	v_mfma_f32_16x16x32_bf16 v[26:29], v[178:181], v[194:197], v[26:29]
	v_mfma_f32_16x16x32_bf16 v[18:21], v[178:181], v[202:205], v[18:21]
	v_mfma_f32_16x16x32_bf16 v[2:5], v[178:181], v[210:213], v[2:5]
	v_mfma_f32_16x16x32_bf16 v[54:57], v[166:169], v[190:193], v[54:57]
	v_mfma_f32_16x16x32_bf16 v[30:33], v[166:169], v[198:201], v[30:33]
	v_mfma_f32_16x16x32_bf16 v[22:25], v[166:169], v[206:209], v[22:25]
	v_mfma_f32_16x16x32_bf16 v[6:9], v[166:169], v[218:221], v[6:9]
	v_mfma_f32_16x16x32_bf16 v[46:49], v[182:185], v[190:193], v[46:49]
	v_mfma_f32_16x16x32_bf16 v[26:29], v[182:185], v[198:201], v[26:29]
	v_mfma_f32_16x16x32_bf16 v[18:21], v[182:185], v[206:209], v[18:21]
	v_mfma_f32_16x16x32_bf16 v[2:5], v[182:185], v[218:221], v[2:5]
	s_setprio 0
	s_barrier
	s_add_i32 s60, s60, 2
	s_add_u32 s42, s42, 0x100
	s_addc_u32 s43, s43, 0
	s_add_u32 s58, s58, 0x100
	s_addc_u32 s59, s59, 0
	s_cmp_gt_u32 s60, 29
	s_cbranch_scc0 .LBB0_3706
	s_and_b64 vcc, exec, s[14:15]
	s_cbranch_vccz .LBB0_3709
	s_barrier

.LBB0_3835:
	ds_read_b128 v[146:149], v153
	ds_read_b128 v[156:159], v153 offset:1024
	ds_read_b128 v[160:163], v153 offset:2048
	ds_read_b128 v[164:167], v153 offset:3072
	ds_read_b128 v[168:171], v154
	ds_read_b128 v[172:175], v154 offset:1024
	ds_read_b128 v[176:179], v154 offset:2048
	ds_read_b128 v[180:183], v154 offset:3072
	s_add_u32 s34, s38, 0xfff80080
	s_addc_u32 s35, s39, -1
	s_cmp_eq_u32 s57, 28
	s_cselect_b32 s41, s0, s35
	s_cselect_b32 s40, s1, s34
	s_cselect_b32 s35, s15, s56
	s_cselect_b32 s34, s17, s55
	v_lshl_add_u64 v[218:219], s[38:39], 0, v[138:139]
	s_add_i32 m0, s37, 0xc000
	ds_read_b128 v[184:187], v155
	ds_read_b128 v[188:191], v155 offset:1024
	ds_read_b128 v[192:195], v155 offset:2048
	ds_read_b128 v[196:199], v155 offset:3072
	ds_read_b128 v[200:203], v155 offset:4096
	ds_read_b128 v[204:207], v155 offset:5120
	ds_read_b128 v[208:211], v155 offset:6144
	ds_read_b128 v[212:215], v155 offset:7168
	global_load_lds_dwordx4 v[218:219], off
	v_lshl_add_u64 v[218:219], s[38:39], 0, v[140:141]
	s_add_i32 m0, s37, 0xe000
	s_nop 0
	global_load_lds_dwordx4 v[218:219], off
	s_waitcnt vmcnt(8)
	s_waitcnt lgkmcnt(0)
	s_barrier
	s_setprio 1
	s_waitcnt lgkmcnt(0)
	v_mfma_f32_16x16x32_bf16 v[126:129], v[146:149], v[184:187], v[126:129]
	v_mfma_f32_16x16x32_bf16 v[110:113], v[146:149], v[192:195], v[110:113]
	v_mfma_f32_16x16x32_bf16 v[94:97], v[146:149], v[200:203], v[94:97]
	v_mfma_f32_16x16x32_bf16 v[78:81], v[146:149], v[208:211], v[78:81]
	v_mfma_f32_16x16x32_bf16 v[118:121], v[160:163], v[184:187], v[118:121]
	v_mfma_f32_16x16x32_bf16 v[102:105], v[160:163], v[192:195], v[102:105]
	v_mfma_f32_16x16x32_bf16 v[86:89], v[160:163], v[200:203], v[86:89]
	v_mfma_f32_16x16x32_bf16 v[70:73], v[160:163], v[208:211], v[70:73]
	v_mfma_f32_16x16x32_bf16 v[126:129], v[156:159], v[188:191], v[126:129]
	v_mfma_f32_16x16x32_bf16 v[110:113], v[156:159], v[196:199], v[110:113]
	v_mfma_f32_16x16x32_bf16 v[94:97], v[156:159], v[204:207], v[94:97]
	v_mfma_f32_16x16x32_bf16 v[78:81], v[156:159], v[212:215], v[78:81]
	v_mfma_f32_16x16x32_bf16 v[118:121], v[164:167], v[188:191], v[118:121]
	v_mfma_f32_16x16x32_bf16 v[102:105], v[164:167], v[196:199], v[102:105]
	v_mfma_f32_16x16x32_bf16 v[86:89], v[164:167], v[204:207], v[86:89]
	v_mfma_f32_16x16x32_bf16 v[70:73], v[164:167], v[212:215], v[70:73]
	s_setprio 0
	s_setprio 1
	v_mfma_f32_16x16x32_bf16 v[122:125], v[168:171], v[184:187], v[122:125]
	v_mfma_f32_16x16x32_bf16 v[106:109], v[168:171], v[192:195], v[106:109]
	v_mfma_f32_16x16x32_bf16 v[90:93], v[168:171], v[200:203], v[90:93]
	v_mfma_f32_16x16x32_bf16 v[74:77], v[168:171], v[208:211], v[74:77]
	v_mfma_f32_16x16x32_bf16 v[114:117], v[176:179], v[184:187], v[114:117]
	v_mfma_f32_16x16x32_bf16 v[98:101], v[176:179], v[192:195], v[98:101]
	v_mfma_f32_16x16x32_bf16 v[82:85], v[176:179], v[200:203], v[82:85]
	v_mfma_f32_16x16x32_bf16 v[66:69], v[176:179], v[208:211], v[66:69]
	v_mfma_f32_16x16x32_bf16 v[122:125], v[172:175], v[188:191], v[122:125]
	v_mfma_f32_16x16x32_bf16 v[106:109], v[172:175], v[196:199], v[106:109]
	v_mfma_f32_16x16x32_bf16 v[90:93], v[172:175], v[204:207], v[90:93]
	v_mfma_f32_16x16x32_bf16 v[74:77], v[172:175], v[212:215], v[74:77]
	v_mfma_f32_16x16x32_bf16 v[114:117], v[180:183], v[188:191], v[114:117]
	v_mfma_f32_16x16x32_bf16 v[98:101], v[180:183], v[196:199], v[98:101]
	v_mfma_f32_16x16x32_bf16 v[82:85], v[180:183], v[204:207], v[82:85]
	v_mfma_f32_16x16x32_bf16 v[66:69], v[180:183], v[212:215], v[66:69]
	s_setprio 0
	s_barrier
	s_add_i32 s58, s51, s33
	v_lshl_add_u64 v[218:219], s[34:35], 0, v[134:135]
	s_mov_b32 m0, s58
	ds_read_b128 v[184:187], v155 offset:16384
	ds_read_b128 v[188:191], v155 offset:17408
	ds_read_b128 v[192:195], v155 offset:18432
	ds_read_b128 v[196:199], v155 offset:19456
	ds_read_b128 v[200:203], v155 offset:20480
	ds_read_b128 v[204:207], v155 offset:21504
	ds_read_b128 v[208:211], v155 offset:22528
	ds_read_b128 v[212:215], v155 offset:23552
	global_load_lds_dwordx4 v[218:219], off
	s_add_i32 m0, s58, 0x2000
	s_add_u32 s58, s34, 0x80000
	v_lshl_add_u64 v[220:221], s[34:35], 0, v[130:131]
	s_addc_u32 s59, s35, 0
	s_add_i32 s60, s52, s33
	global_load_lds_dwordx4 v[220:221], off
	v_lshl_add_u64 v[222:223], s[58:59], 0, v[134:135]
	s_mov_b32 m0, s60
	v_lshl_add_u64 v[224:225], s[40:41], 0, v[132:133]
	global_load_lds_dwordx4 v[222:223], off
	v_lshl_add_u64 v[222:223], s[58:59], 0, v[130:131]
	s_add_i32 m0, s60, 0x2000
	s_nop 0
	global_load_lds_dwordx4 v[222:223], off
	v_lshl_add_u64 v[222:223], s[40:41], 0, v[136:137]
	s_mov_b32 m0, s37
	s_nop 0
	global_load_lds_dwordx4 v[222:223], off
	s_mov_b32 m0, s44
	s_nop 0
	global_load_lds_dwordx4 v[224:225], off
	s_waitcnt vmcnt(8)
	s_waitcnt lgkmcnt(0)
	s_barrier
	s_setprio 1
	s_waitcnt lgkmcnt(0)
	v_mfma_f32_16x16x32_bf16 v[62:65], v[146:149], v[184:187], v[62:65]
	v_mfma_f32_16x16x32_bf16 v[46:49], v[146:149], v[192:195], v[46:49]
	v_mfma_f32_16x16x32_bf16 v[30:33], v[146:149], v[200:203], v[30:33]
	v_mfma_f32_16x16x32_bf16 v[14:17], v[146:149], v[208:211], v[14:17]
	v_mfma_f32_16x16x32_bf16 v[54:57], v[160:163], v[184:187], v[54:57]
	v_mfma_f32_16x16x32_bf16 v[38:41], v[160:163], v[192:195], v[38:41]
	v_mfma_f32_16x16x32_bf16 v[22:25], v[160:163], v[200:203], v[22:25]
	v_mfma_f32_16x16x32_bf16 v[6:9], v[160:163], v[208:211], v[6:9]
	v_mfma_f32_16x16x32_bf16 v[62:65], v[156:159], v[188:191], v[62:65]
	v_mfma_f32_16x16x32_bf16 v[46:49], v[156:159], v[196:199], v[46:49]
	v_mfma_f32_16x16x32_bf16 v[30:33], v[156:159], v[204:207], v[30:33]
	v_mfma_f32_16x16x32_bf16 v[14:17], v[156:159], v[212:215], v[14:17]
	v_mfma_f32_16x16x32_bf16 v[54:57], v[164:167], v[188:191], v[54:57]
	v_mfma_f32_16x16x32_bf16 v[38:41], v[164:167], v[196:199], v[38:41]
	v_mfma_f32_16x16x32_bf16 v[22:25], v[164:167], v[204:207], v[22:25]
	v_mfma_f32_16x16x32_bf16 v[6:9], v[164:167], v[212:215], v[6:9]
	s_setprio 0
	s_setprio 1
	v_mfma_f32_16x16x32_bf16 v[58:61], v[168:171], v[184:187], v[58:61]
	v_mfma_f32_16x16x32_bf16 v[42:45], v[168:171], v[192:195], v[42:45]
	v_mfma_f32_16x16x32_bf16 v[26:29], v[168:171], v[200:203], v[26:29]
	v_mfma_f32_16x16x32_bf16 v[10:13], v[168:171], v[208:211], v[10:13]
	v_mfma_f32_16x16x32_bf16 v[50:53], v[176:179], v[184:187], v[50:53]
	v_mfma_f32_16x16x32_bf16 v[34:37], v[176:179], v[192:195], v[34:37]
	v_mfma_f32_16x16x32_bf16 v[18:21], v[176:179], v[200:203], v[18:21]
	v_mfma_f32_16x16x32_bf16 v[2:5], v[176:179], v[208:211], v[2:5]
	v_mfma_f32_16x16x32_bf16 v[58:61], v[172:175], v[188:191], v[58:61]
	v_mfma_f32_16x16x32_bf16 v[42:45], v[172:175], v[196:199], v[42:45]
	v_mfma_f32_16x16x32_bf16 v[26:29], v[172:175], v[204:207], v[26:29]
	v_mfma_f32_16x16x32_bf16 v[10:13], v[172:175], v[212:215], v[10:13]
	v_mfma_f32_16x16x32_bf16 v[50:53], v[180:183], v[188:191], v[50:53]
	v_mfma_f32_16x16x32_bf16 v[34:37], v[180:183], v[196:199], v[34:37]
	v_mfma_f32_16x16x32_bf16 v[18:21], v[180:183], v[204:207], v[18:21]
	v_mfma_f32_16x16x32_bf16 v[2:5], v[180:183], v[212:215], v[2:5]
	s_setprio 0
	s_barrier
	s_add_i32 s58, 0, 0x18000
	s_add_i32 s59, 0, 0x1c000
	v_add_u32_e32 v164, s58, v151
	v_add_u32_e32 v180, s59, v151
	ds_read_b128 v[146:149], v164
	ds_read_b128 v[156:159], v164 offset:1024
	ds_read_b128 v[160:163], v164 offset:2048
	ds_read_b128 v[164:167], v164 offset:3072
	ds_read_b128 v[168:171], v180
	ds_read_b128 v[172:175], v180 offset:1024
	ds_read_b128 v[176:179], v180 offset:2048
	ds_read_b128 v[180:183], v180 offset:3072
	s_add_u32 s40, s40, 0x80000
	s_addc_u32 s41, s41, 0
	s_mov_b32 m0, s45
	v_lshl_add_u64 v[226:227], s[40:41], 0, v[136:137]
	ds_read_b128 v[184:187], v155 offset:32768
	ds_read_b128 v[188:191], v155 offset:33792
	ds_read_b128 v[192:195], v155 offset:34816
	ds_read_b128 v[196:199], v155 offset:35840
	ds_read_b128 v[200:203], v155 offset:36864
	ds_read_b128 v[204:207], v155 offset:37888
	ds_read_b128 v[208:211], v155 offset:38912
	ds_read_b128 v[212:215], v155 offset:39936
	global_load_lds_dwordx4 v[226:227], off
	v_lshl_add_u64 v[226:227], s[40:41], 0, v[132:133]
	s_mov_b32 m0, s46
	s_nop 0
	global_load_lds_dwordx4 v[226:227], off
	s_waitcnt vmcnt(8)
	s_waitcnt lgkmcnt(0)
	s_barrier
	s_setprio 1
	s_waitcnt lgkmcnt(0)
	v_mfma_f32_16x16x32_bf16 v[126:129], v[146:149], v[184:187], v[126:129]
	v_mfma_f32_16x16x32_bf16 v[110:113], v[146:149], v[192:195], v[110:113]
	v_mfma_f32_16x16x32_bf16 v[94:97], v[146:149], v[200:203], v[94:97]
	v_mfma_f32_16x16x32_bf16 v[78:81], v[146:149], v[208:211], v[78:81]
	v_mfma_f32_16x16x32_bf16 v[118:121], v[160:163], v[184:187], v[118:121]
	v_mfma_f32_16x16x32_bf16 v[102:105], v[160:163], v[192:195], v[102:105]
	v_mfma_f32_16x16x32_bf16 v[86:89], v[160:163], v[200:203], v[86:89]
	v_mfma_f32_16x16x32_bf16 v[70:73], v[160:163], v[208:211], v[70:73]
	v_mfma_f32_16x16x32_bf16 v[126:129], v[156:159], v[188:191], v[126:129]
	v_mfma_f32_16x16x32_bf16 v[110:113], v[156:159], v[196:199], v[110:113]
	v_mfma_f32_16x16x32_bf16 v[94:97], v[156:159], v[204:207], v[94:97]
	v_mfma_f32_16x16x32_bf16 v[78:81], v[156:159], v[212:215], v[78:81]
	v_mfma_f32_16x16x32_bf16 v[118:121], v[164:167], v[188:191], v[118:121]
	v_mfma_f32_16x16x32_bf16 v[102:105], v[164:167], v[196:199], v[102:105]
	v_mfma_f32_16x16x32_bf16 v[86:89], v[164:167], v[204:207], v[86:89]
	v_mfma_f32_16x16x32_bf16 v[70:73], v[164:167], v[212:215], v[70:73]
	s_setprio 0
	s_setprio 1
	v_mfma_f32_16x16x32_bf16 v[122:125], v[168:171], v[184:187], v[122:125]
	v_mfma_f32_16x16x32_bf16 v[106:109], v[168:171], v[192:195], v[106:109]
	v_mfma_f32_16x16x32_bf16 v[90:93], v[168:171], v[200:203], v[90:93]
	v_mfma_f32_16x16x32_bf16 v[74:77], v[168:171], v[208:211], v[74:77]
	v_mfma_f32_16x16x32_bf16 v[114:117], v[176:179], v[184:187], v[114:117]
	v_mfma_f32_16x16x32_bf16 v[98:101], v[176:179], v[192:195], v[98:101]
	v_mfma_f32_16x16x32_bf16 v[82:85], v[176:179], v[200:203], v[82:85]
	v_mfma_f32_16x16x32_bf16 v[66:69], v[176:179], v[208:211], v[66:69]
	v_mfma_f32_16x16x32_bf16 v[122:125], v[172:175], v[188:191], v[122:125]
	v_mfma_f32_16x16x32_bf16 v[106:109], v[172:175], v[196:199], v[106:109]
	v_mfma_f32_16x16x32_bf16 v[90:93], v[172:175], v[204:207], v[90:93]
	v_mfma_f32_16x16x32_bf16 v[74:77], v[172:175], v[212:215], v[74:77]
	v_mfma_f32_16x16x32_bf16 v[114:117], v[180:183], v[188:191], v[114:117]
	v_mfma_f32_16x16x32_bf16 v[98:101], v[180:183], v[196:199], v[98:101]
	v_mfma_f32_16x16x32_bf16 v[82:85], v[180:183], v[204:207], v[82:85]
	v_mfma_f32_16x16x32_bf16 v[66:69], v[180:183], v[212:215], v[66:69]
	s_setprio 0
	s_barrier
	s_add_i32 s40, s58, s33
	v_lshl_add_u64 v[218:219], v[218:219], 0, s[8:9]
	s_mov_b32 m0, s40
	ds_read_b128 v[184:187], v155 offset:49152
	ds_read_b128 v[188:191], v155 offset:50176
	ds_read_b128 v[192:195], v155 offset:51200
	ds_read_b128 v[196:199], v155 offset:52224
	ds_read_b128 v[200:203], v155 offset:53248
	ds_read_b128 v[204:207], v155 offset:54272
	ds_read_b128 v[208:211], v155 offset:55296
	ds_read_b128 v[212:215], v155 offset:56320
	global_load_lds_dwordx4 v[218:219], off
	s_add_i32 m0, s40, 0x2000
	s_add_u32 s34, s34, 0x80080
	v_lshl_add_u64 v[218:219], v[220:221], 0, s[8:9]
	s_addc_u32 s35, s35, 0
	s_add_i32 s40, s59, s33
	global_load_lds_dwordx4 v[218:219], off
	v_lshl_add_u64 v[218:219], s[34:35], 0, v[134:135]
	s_mov_b32 m0, s40
	s_nop 0
	global_load_lds_dwordx4 v[218:219], off
	v_lshl_add_u64 v[218:219], s[34:35], 0, v[130:131]
	s_add_i32 m0, s40, 0x2000
	s_nop 0
	global_load_lds_dwordx4 v[218:219], off
	v_lshl_add_u64 v[218:219], v[222:223], 0, s[8:9]
	s_mov_b32 m0, s48
	s_nop 0
	global_load_lds_dwordx4 v[218:219], off
	v_lshl_add_u64 v[218:219], v[224:225], 0, s[8:9]
	s_mov_b32 m0, s49
	s_nop 0
	global_load_lds_dwordx4 v[218:219], off
	s_waitcnt vmcnt(8)
	s_waitcnt lgkmcnt(0)
	s_barrier
	s_setprio 1
	s_waitcnt lgkmcnt(0)
	v_mfma_f32_16x16x32_bf16 v[62:65], v[146:149], v[184:187], v[62:65]
	v_mfma_f32_16x16x32_bf16 v[46:49], v[146:149], v[192:195], v[46:49]
	v_mfma_f32_16x16x32_bf16 v[30:33], v[146:149], v[200:203], v[30:33]
	v_mfma_f32_16x16x32_bf16 v[14:17], v[146:149], v[208:211], v[14:17]
	v_mfma_f32_16x16x32_bf16 v[54:57], v[160:163], v[184:187], v[54:57]
	v_mfma_f32_16x16x32_bf16 v[38:41], v[160:163], v[192:195], v[38:41]
	v_mfma_f32_16x16x32_bf16 v[22:25], v[160:163], v[200:203], v[22:25]
	v_mfma_f32_16x16x32_bf16 v[6:9], v[160:163], v[208:211], v[6:9]
	v_mfma_f32_16x16x32_bf16 v[62:65], v[156:159], v[188:191], v[62:65]
	v_mfma_f32_16x16x32_bf16 v[46:49], v[156:159], v[196:199], v[46:49]
	v_mfma_f32_16x16x32_bf16 v[30:33], v[156:159], v[204:207], v[30:33]
	v_mfma_f32_16x16x32_bf16 v[14:17], v[156:159], v[212:215], v[14:17]
	v_mfma_f32_16x16x32_bf16 v[54:57], v[164:167], v[188:191], v[54:57]
	v_mfma_f32_16x16x32_bf16 v[38:41], v[164:167], v[196:199], v[38:41]
	v_mfma_f32_16x16x32_bf16 v[22:25], v[164:167], v[204:207], v[22:25]
	v_mfma_f32_16x16x32_bf16 v[6:9], v[164:167], v[212:215], v[6:9]
	s_setprio 0
	s_setprio 1
	v_mfma_f32_16x16x32_bf16 v[58:61], v[168:171], v[184:187], v[58:61]
	v_mfma_f32_16x16x32_bf16 v[42:45], v[168:171], v[192:195], v[42:45]
	v_mfma_f32_16x16x32_bf16 v[26:29], v[168:171], v[200:203], v[26:29]
	v_mfma_f32_16x16x32_bf16 v[10:13], v[168:171], v[208:211], v[10:13]
	v_mfma_f32_16x16x32_bf16 v[50:53], v[176:179], v[184:187], v[50:53]
	v_mfma_f32_16x16x32_bf16 v[34:37], v[176:179], v[192:195], v[34:37]
	v_mfma_f32_16x16x32_bf16 v[18:21], v[176:179], v[200:203], v[18:21]
	v_mfma_f32_16x16x32_bf16 v[2:5], v[176:179], v[208:211], v[2:5]
	v_mfma_f32_16x16x32_bf16 v[58:61], v[172:175], v[188:191], v[58:61]
	v_mfma_f32_16x16x32_bf16 v[42:45], v[172:175], v[196:199], v[42:45]
	v_mfma_f32_16x16x32_bf16 v[26:29], v[172:175], v[204:207], v[26:29]
	v_mfma_f32_16x16x32_bf16 v[10:13], v[172:175], v[212:215], v[10:13]
	v_mfma_f32_16x16x32_bf16 v[50:53], v[180:183], v[188:191], v[50:53]
	v_mfma_f32_16x16x32_bf16 v[34:37], v[180:183], v[196:199], v[34:37]
	v_mfma_f32_16x16x32_bf16 v[18:21], v[180:183], v[204:207], v[18:21]
	v_mfma_f32_16x16x32_bf16 v[2:5], v[180:183], v[212:215], v[2:5]
	s_setprio 0
	s_barrier
	s_add_i32 s57, s57, 2
	s_add_u32 s38, s38, 0x100
	s_addc_u32 s39, s39, 0
	s_add_u32 s55, s55, 0x100
	s_addc_u32 s56, s56, 0
	s_cmp_gt_u32 s57, 29
	s_cbranch_scc0 .LBB0_3835
	s_and_b64 vcc, exec, s[12:13]
	s_cbranch_vccz .LBB0_3838
	s_barrier

.LBB0_3930:
	ds_read_b128 v[144:147], v155
	ds_read_b128 v[148:151], v155 offset:1024
	ds_read_b128 v[158:161], v155 offset:2048
	ds_read_b128 v[162:165], v155 offset:3072
	ds_read_b128 v[166:169], v156
	ds_read_b128 v[170:173], v156 offset:1024
	ds_read_b128 v[174:177], v156 offset:2048
	ds_read_b128 v[178:181], v156 offset:3072
	s_add_u32 s20, s18, 0xffea0080
	s_addc_u32 s21, s19, -1
	s_cmpk_eq_i32 s45, 0x54
	s_cselect_b32 s23, s5, s21
	s_cselect_b32 s22, s4, s20
	s_cselect_b32 s21, s17, s1
	s_cselect_b32 s20, s16, s0
	v_lshl_add_u64 v[214:215], s[18:19], 0, v[136:137]
	s_add_i32 m0, s30, 0xc000
	ds_read_b128 v[182:185], v157
	ds_read_b128 v[186:189], v157 offset:1024
	ds_read_b128 v[190:193], v157 offset:2048
	ds_read_b128 v[194:197], v157 offset:3072
	ds_read_b128 v[198:201], v157 offset:4096
	ds_read_b128 v[202:205], v157 offset:5120
	ds_read_b128 v[206:209], v157 offset:6144
	ds_read_b128 v[210:213], v157 offset:7168
	global_load_lds_dwordx4 v[214:215], off
	v_lshl_add_u64 v[214:215], s[18:19], 0, v[138:139]
	s_add_i32 m0, s30, 0xe000
	s_nop 0
	global_load_lds_dwordx4 v[214:215], off
	s_waitcnt vmcnt(8)
	s_waitcnt lgkmcnt(0)
	s_barrier
	s_setprio 1
	s_waitcnt lgkmcnt(0)
	v_mfma_f32_16x16x32_bf16 v[124:127], v[144:147], v[182:185], v[124:127]
	v_mfma_f32_16x16x32_bf16 v[116:119], v[144:147], v[190:193], v[116:119]
	v_mfma_f32_16x16x32_bf16 v[92:95], v[144:147], v[198:201], v[92:95]
	v_mfma_f32_16x16x32_bf16 v[84:87], v[144:147], v[206:209], v[84:87]
	v_mfma_f32_16x16x32_bf16 v[120:123], v[158:161], v[182:185], v[120:123]
	v_mfma_f32_16x16x32_bf16 v[112:115], v[158:161], v[190:193], v[112:115]
	v_mfma_f32_16x16x32_bf16 v[88:91], v[158:161], v[198:201], v[88:91]
	v_mfma_f32_16x16x32_bf16 v[80:83], v[158:161], v[206:209], v[80:83]
	v_mfma_f32_16x16x32_bf16 v[124:127], v[148:151], v[186:189], v[124:127]
	v_mfma_f32_16x16x32_bf16 v[116:119], v[148:151], v[194:197], v[116:119]
	v_mfma_f32_16x16x32_bf16 v[92:95], v[148:151], v[202:205], v[92:95]
	v_mfma_f32_16x16x32_bf16 v[84:87], v[148:151], v[210:213], v[84:87]
	v_mfma_f32_16x16x32_bf16 v[120:123], v[162:165], v[186:189], v[120:123]
	v_mfma_f32_16x16x32_bf16 v[112:115], v[162:165], v[194:197], v[112:115]
	v_mfma_f32_16x16x32_bf16 v[88:91], v[162:165], v[202:205], v[88:91]
	v_mfma_f32_16x16x32_bf16 v[80:83], v[162:165], v[210:213], v[80:83]
	s_setprio 0
	s_setprio 1
	v_mfma_f32_16x16x32_bf16 v[108:111], v[166:169], v[182:185], v[108:111]
	v_mfma_f32_16x16x32_bf16 v[100:103], v[166:169], v[190:193], v[100:103]
	v_mfma_f32_16x16x32_bf16 v[76:79], v[166:169], v[198:201], v[76:79]
	v_mfma_f32_16x16x32_bf16 v[68:71], v[166:169], v[206:209], v[68:71]
	v_mfma_f32_16x16x32_bf16 v[104:107], v[174:177], v[182:185], v[104:107]
	v_mfma_f32_16x16x32_bf16 v[96:99], v[174:177], v[190:193], v[96:99]
	v_mfma_f32_16x16x32_bf16 v[72:75], v[174:177], v[198:201], v[72:75]
	v_mfma_f32_16x16x32_bf16 v[64:67], v[174:177], v[206:209], v[64:67]
	v_mfma_f32_16x16x32_bf16 v[108:111], v[170:173], v[186:189], v[108:111]
	v_mfma_f32_16x16x32_bf16 v[100:103], v[170:173], v[194:197], v[100:103]
	v_mfma_f32_16x16x32_bf16 v[76:79], v[170:173], v[202:205], v[76:79]
	v_mfma_f32_16x16x32_bf16 v[68:71], v[170:173], v[210:213], v[68:71]
	v_mfma_f32_16x16x32_bf16 v[104:107], v[178:181], v[186:189], v[104:107]
	v_mfma_f32_16x16x32_bf16 v[96:99], v[178:181], v[194:197], v[96:99]
	v_mfma_f32_16x16x32_bf16 v[72:75], v[178:181], v[202:205], v[72:75]
	v_mfma_f32_16x16x32_bf16 v[64:67], v[178:181], v[210:213], v[64:67]
	s_setprio 0
	s_barrier
	s_add_i32 s46, s39, s27
	v_lshl_add_u64 v[214:215], s[20:21], 0, v[130:131]
	s_mov_b32 m0, s46
	ds_read_b128 v[182:185], v157 offset:16384
	ds_read_b128 v[186:189], v157 offset:17408
	ds_read_b128 v[190:193], v157 offset:18432
	ds_read_b128 v[194:197], v157 offset:19456
	ds_read_b128 v[198:201], v157 offset:20480
	ds_read_b128 v[202:205], v157 offset:21504
	ds_read_b128 v[206:209], v157 offset:22528
	ds_read_b128 v[210:213], v157 offset:23552
	global_load_lds_dwordx4 v[214:215], off
	s_add_i32 m0, s46, 0x2000
	s_add_u32 s46, s20, 0x160000
	v_lshl_add_u64 v[216:217], s[20:21], 0, v[134:135]
	s_addc_u32 s47, s21, 0
	s_add_i32 s48, s40, s27
	global_load_lds_dwordx4 v[216:217], off
	v_lshl_add_u64 v[218:219], s[46:47], 0, v[130:131]
	s_mov_b32 m0, s48
	v_lshl_add_u64 v[220:221], s[22:23], 0, v[132:133]
	global_load_lds_dwordx4 v[218:219], off
	v_lshl_add_u64 v[218:219], s[46:47], 0, v[134:135]
	s_add_i32 m0, s48, 0x2000
	s_nop 0
	global_load_lds_dwordx4 v[218:219], off
	v_lshl_add_u64 v[218:219], s[22:23], 0, v[128:129]
	s_mov_b32 m0, s30
	s_nop 0
	global_load_lds_dwordx4 v[218:219], off
	s_mov_b32 m0, s31
	s_nop 0
	global_load_lds_dwordx4 v[220:221], off
	s_waitcnt vmcnt(8)
	s_waitcnt lgkmcnt(0)
	s_barrier
	s_setprio 1
	s_waitcnt lgkmcnt(0)
	v_mfma_f32_16x16x32_bf16 v[60:63], v[144:147], v[182:185], v[60:63]
	v_mfma_f32_16x16x32_bf16 v[52:55], v[144:147], v[190:193], v[52:55]
	v_mfma_f32_16x16x32_bf16 v[28:31], v[144:147], v[198:201], v[28:31]
	v_mfma_f32_16x16x32_bf16 v[20:23], v[144:147], v[206:209], v[20:23]
	v_mfma_f32_16x16x32_bf16 v[56:59], v[158:161], v[182:185], v[56:59]
	v_mfma_f32_16x16x32_bf16 v[48:51], v[158:161], v[190:193], v[48:51]
	v_mfma_f32_16x16x32_bf16 v[24:27], v[158:161], v[198:201], v[24:27]
	v_mfma_f32_16x16x32_bf16 v[16:19], v[158:161], v[206:209], v[16:19]
	v_mfma_f32_16x16x32_bf16 v[60:63], v[148:151], v[186:189], v[60:63]
	v_mfma_f32_16x16x32_bf16 v[52:55], v[148:151], v[194:197], v[52:55]
	v_mfma_f32_16x16x32_bf16 v[28:31], v[148:151], v[202:205], v[28:31]
	v_mfma_f32_16x16x32_bf16 v[20:23], v[148:151], v[210:213], v[20:23]
	v_mfma_f32_16x16x32_bf16 v[56:59], v[162:165], v[186:189], v[56:59]
	v_mfma_f32_16x16x32_bf16 v[48:51], v[162:165], v[194:197], v[48:51]
	v_mfma_f32_16x16x32_bf16 v[24:27], v[162:165], v[202:205], v[24:27]
	v_mfma_f32_16x16x32_bf16 v[16:19], v[162:165], v[210:213], v[16:19]
	s_setprio 0
	s_setprio 1
	v_mfma_f32_16x16x32_bf16 v[44:47], v[166:169], v[182:185], v[44:47]
	v_mfma_f32_16x16x32_bf16 v[36:39], v[166:169], v[190:193], v[36:39]
	v_mfma_f32_16x16x32_bf16 v[12:15], v[166:169], v[198:201], v[12:15]
	v_mfma_f32_16x16x32_bf16 v[4:7], v[166:169], v[206:209], v[4:7]
	v_mfma_f32_16x16x32_bf16 v[40:43], v[174:177], v[182:185], v[40:43]
	v_mfma_f32_16x16x32_bf16 v[32:35], v[174:177], v[190:193], v[32:35]
	v_mfma_f32_16x16x32_bf16 v[8:11], v[174:177], v[198:201], v[8:11]
	v_mfma_f32_16x16x32_bf16 v[0:3], v[174:177], v[206:209], v[0:3]
	v_mfma_f32_16x16x32_bf16 v[44:47], v[170:173], v[186:189], v[44:47]
	v_mfma_f32_16x16x32_bf16 v[36:39], v[170:173], v[194:197], v[36:39]
	v_mfma_f32_16x16x32_bf16 v[12:15], v[170:173], v[202:205], v[12:15]
	v_mfma_f32_16x16x32_bf16 v[4:7], v[170:173], v[210:213], v[4:7]
	v_mfma_f32_16x16x32_bf16 v[40:43], v[178:181], v[186:189], v[40:43]
	v_mfma_f32_16x16x32_bf16 v[32:35], v[178:181], v[194:197], v[32:35]
	v_mfma_f32_16x16x32_bf16 v[8:11], v[178:181], v[202:205], v[8:11]
	v_mfma_f32_16x16x32_bf16 v[0:3], v[178:181], v[210:213], v[0:3]
	s_setprio 0
	s_barrier
	s_add_i32 s46, 0, 0x18000
	s_add_i32 s47, 0, 0x1c000
	v_add_u32_e32 v162, s46, v153
	v_add_u32_e32 v178, s47, v153
	ds_read_b128 v[144:147], v162
	ds_read_b128 v[148:151], v162 offset:1024
	ds_read_b128 v[158:161], v162 offset:2048
	ds_read_b128 v[162:165], v162 offset:3072
	ds_read_b128 v[166:169], v178
	ds_read_b128 v[170:173], v178 offset:1024
	ds_read_b128 v[174:177], v178 offset:2048
	ds_read_b128 v[178:181], v178 offset:3072
	s_add_u32 s22, s22, 0x160000
	s_addc_u32 s23, s23, 0
	s_mov_b32 m0, s33
	v_lshl_add_u64 v[222:223], s[22:23], 0, v[128:129]
	ds_read_b128 v[182:185], v157 offset:32768
	ds_read_b128 v[186:189], v157 offset:33792
	ds_read_b128 v[190:193], v157 offset:34816
	ds_read_b128 v[194:197], v157 offset:35840
	ds_read_b128 v[198:201], v157 offset:36864
	ds_read_b128 v[202:205], v157 offset:37888
	ds_read_b128 v[206:209], v157 offset:38912
	ds_read_b128 v[210:213], v157 offset:39936
	global_load_lds_dwordx4 v[222:223], off
	v_lshl_add_u64 v[222:223], s[22:23], 0, v[132:133]
	s_mov_b32 m0, s34
	s_nop 0
	global_load_lds_dwordx4 v[222:223], off
	s_waitcnt vmcnt(8)
	s_waitcnt lgkmcnt(0)
	s_barrier
	s_setprio 1
	s_waitcnt lgkmcnt(0)
	v_mfma_f32_16x16x32_bf16 v[124:127], v[144:147], v[182:185], v[124:127]
	v_mfma_f32_16x16x32_bf16 v[116:119], v[144:147], v[190:193], v[116:119]
	v_mfma_f32_16x16x32_bf16 v[92:95], v[144:147], v[198:201], v[92:95]
	v_mfma_f32_16x16x32_bf16 v[84:87], v[144:147], v[206:209], v[84:87]
	v_mfma_f32_16x16x32_bf16 v[120:123], v[158:161], v[182:185], v[120:123]
	v_mfma_f32_16x16x32_bf16 v[112:115], v[158:161], v[190:193], v[112:115]
	v_mfma_f32_16x16x32_bf16 v[88:91], v[158:161], v[198:201], v[88:91]
	v_mfma_f32_16x16x32_bf16 v[80:83], v[158:161], v[206:209], v[80:83]
	v_mfma_f32_16x16x32_bf16 v[124:127], v[148:151], v[186:189], v[124:127]
	v_mfma_f32_16x16x32_bf16 v[116:119], v[148:151], v[194:197], v[116:119]
	v_mfma_f32_16x16x32_bf16 v[92:95], v[148:151], v[202:205], v[92:95]
	v_mfma_f32_16x16x32_bf16 v[84:87], v[148:151], v[210:213], v[84:87]
	v_mfma_f32_16x16x32_bf16 v[120:123], v[162:165], v[186:189], v[120:123]
	v_mfma_f32_16x16x32_bf16 v[112:115], v[162:165], v[194:197], v[112:115]
	v_mfma_f32_16x16x32_bf16 v[88:91], v[162:165], v[202:205], v[88:91]
	v_mfma_f32_16x16x32_bf16 v[80:83], v[162:165], v[210:213], v[80:83]
	s_setprio 0
	s_setprio 1
	v_mfma_f32_16x16x32_bf16 v[108:111], v[166:169], v[182:185], v[108:111]
	v_mfma_f32_16x16x32_bf16 v[100:103], v[166:169], v[190:193], v[100:103]
	v_mfma_f32_16x16x32_bf16 v[76:79], v[166:169], v[198:201], v[76:79]
	v_mfma_f32_16x16x32_bf16 v[68:71], v[166:169], v[206:209], v[68:71]
	v_mfma_f32_16x16x32_bf16 v[104:107], v[174:177], v[182:185], v[104:107]
	v_mfma_f32_16x16x32_bf16 v[96:99], v[174:177], v[190:193], v[96:99]
	v_mfma_f32_16x16x32_bf16 v[72:75], v[174:177], v[198:201], v[72:75]
	v_mfma_f32_16x16x32_bf16 v[64:67], v[174:177], v[206:209], v[64:67]
	v_mfma_f32_16x16x32_bf16 v[108:111], v[170:173], v[186:189], v[108:111]
	v_mfma_f32_16x16x32_bf16 v[100:103], v[170:173], v[194:197], v[100:103]
	v_mfma_f32_16x16x32_bf16 v[76:79], v[170:173], v[202:205], v[76:79]
	v_mfma_f32_16x16x32_bf16 v[68:71], v[170:173], v[210:213], v[68:71]
	v_mfma_f32_16x16x32_bf16 v[104:107], v[178:181], v[186:189], v[104:107]
	v_mfma_f32_16x16x32_bf16 v[96:99], v[178:181], v[194:197], v[96:99]
	v_mfma_f32_16x16x32_bf16 v[72:75], v[178:181], v[202:205], v[72:75]
	v_mfma_f32_16x16x32_bf16 v[64:67], v[178:181], v[210:213], v[64:67]
	s_setprio 0
	s_barrier
	s_add_i32 s22, s46, s27
	v_lshl_add_u64 v[214:215], v[214:215], 0, s[12:13]
	s_mov_b32 m0, s22
	ds_read_b128 v[182:185], v157 offset:49152
	ds_read_b128 v[186:189], v157 offset:50176
	ds_read_b128 v[190:193], v157 offset:51200
	ds_read_b128 v[194:197], v157 offset:52224
	ds_read_b128 v[198:201], v157 offset:53248
	ds_read_b128 v[202:205], v157 offset:54272
	ds_read_b128 v[206:209], v157 offset:55296
	ds_read_b128 v[210:213], v157 offset:56320
	global_load_lds_dwordx4 v[214:215], off
	s_add_i32 m0, s22, 0x2000
	s_add_u32 s20, s20, 0x160080
	v_lshl_add_u64 v[214:215], v[216:217], 0, s[12:13]
	s_addc_u32 s21, s21, 0
	s_add_i32 s22, s47, s27
	global_load_lds_dwordx4 v[214:215], off
	v_lshl_add_u64 v[214:215], s[20:21], 0, v[130:131]
	s_mov_b32 m0, s22
	s_nop 0
	global_load_lds_dwordx4 v[214:215], off
	v_lshl_add_u64 v[214:215], s[20:21], 0, v[134:135]
	s_add_i32 m0, s22, 0x2000
	s_nop 0
	global_load_lds_dwordx4 v[214:215], off
	v_lshl_add_u64 v[214:215], v[218:219], 0, s[12:13]
	s_mov_b32 m0, s36
	s_nop 0
	global_load_lds_dwordx4 v[214:215], off
	v_lshl_add_u64 v[214:215], v[220:221], 0, s[12:13]
	s_mov_b32 m0, s37
	s_nop 0
	global_load_lds_dwordx4 v[214:215], off
	s_waitcnt vmcnt(8)
	s_waitcnt lgkmcnt(0)
	s_barrier
	s_setprio 1
	s_waitcnt lgkmcnt(0)
	v_mfma_f32_16x16x32_bf16 v[60:63], v[144:147], v[182:185], v[60:63]
	v_mfma_f32_16x16x32_bf16 v[52:55], v[144:147], v[190:193], v[52:55]
	v_mfma_f32_16x16x32_bf16 v[28:31], v[144:147], v[198:201], v[28:31]
	v_mfma_f32_16x16x32_bf16 v[20:23], v[144:147], v[206:209], v[20:23]
	v_mfma_f32_16x16x32_bf16 v[56:59], v[158:161], v[182:185], v[56:59]
	v_mfma_f32_16x16x32_bf16 v[48:51], v[158:161], v[190:193], v[48:51]
	v_mfma_f32_16x16x32_bf16 v[24:27], v[158:161], v[198:201], v[24:27]
	v_mfma_f32_16x16x32_bf16 v[16:19], v[158:161], v[206:209], v[16:19]
	v_mfma_f32_16x16x32_bf16 v[60:63], v[148:151], v[186:189], v[60:63]
	v_mfma_f32_16x16x32_bf16 v[52:55], v[148:151], v[194:197], v[52:55]
	v_mfma_f32_16x16x32_bf16 v[28:31], v[148:151], v[202:205], v[28:31]
	v_mfma_f32_16x16x32_bf16 v[20:23], v[148:151], v[210:213], v[20:23]
	v_mfma_f32_16x16x32_bf16 v[56:59], v[162:165], v[186:189], v[56:59]
	v_mfma_f32_16x16x32_bf16 v[48:51], v[162:165], v[194:197], v[48:51]
	v_mfma_f32_16x16x32_bf16 v[24:27], v[162:165], v[202:205], v[24:27]
	v_mfma_f32_16x16x32_bf16 v[16:19], v[162:165], v[210:213], v[16:19]
	s_setprio 0
	s_setprio 1
	v_mfma_f32_16x16x32_bf16 v[44:47], v[166:169], v[182:185], v[44:47]
	v_mfma_f32_16x16x32_bf16 v[36:39], v[166:169], v[190:193], v[36:39]
	v_mfma_f32_16x16x32_bf16 v[12:15], v[166:169], v[198:201], v[12:15]
	v_mfma_f32_16x16x32_bf16 v[4:7], v[166:169], v[206:209], v[4:7]
	v_mfma_f32_16x16x32_bf16 v[40:43], v[174:177], v[182:185], v[40:43]
	v_mfma_f32_16x16x32_bf16 v[32:35], v[174:177], v[190:193], v[32:35]
	v_mfma_f32_16x16x32_bf16 v[8:11], v[174:177], v[198:201], v[8:11]
	v_mfma_f32_16x16x32_bf16 v[0:3], v[174:177], v[206:209], v[0:3]
	v_mfma_f32_16x16x32_bf16 v[44:47], v[170:173], v[186:189], v[44:47]
	v_mfma_f32_16x16x32_bf16 v[36:39], v[170:173], v[194:197], v[36:39]
	v_mfma_f32_16x16x32_bf16 v[12:15], v[170:173], v[202:205], v[12:15]
	v_mfma_f32_16x16x32_bf16 v[4:7], v[170:173], v[210:213], v[4:7]
	v_mfma_f32_16x16x32_bf16 v[40:43], v[178:181], v[186:189], v[40:43]
	v_mfma_f32_16x16x32_bf16 v[32:35], v[178:181], v[194:197], v[32:35]
	v_mfma_f32_16x16x32_bf16 v[8:11], v[178:181], v[202:205], v[8:11]
	v_mfma_f32_16x16x32_bf16 v[0:3], v[178:181], v[210:213], v[0:3]
	s_setprio 0
	s_barrier
	s_add_i32 s45, s45, 2
	s_add_u32 s18, s18, 0x100
	s_addc_u32 s19, s19, 0
	s_add_u32 s0, s0, 0x100
	s_addc_u32 s1, s1, 0
	s_cmpk_gt_u32 s45, 0x55
	s_cbranch_scc0 .LBB0_3930
	s_and_b64 vcc, exec, s[14:15]
	s_cbranch_vccz .LBB0_3933
	s_barrier
